# fast rcp-based division in silu/sigmoid epilogues and NSA combine, on top of mask fast path, ZB prefetch, pipelined residual epilogues
# speedup vs baseline: 1.0057x; 1.0057x over previous
.LBB0_636:
	s_lshl_b32 s56, s60, 8
	s_ashr_i32 s57, s56, 31
	v_lshl_add_u64 v[6:7], s[56:57], 2, v[146:147]
	global_load_dwordx4 v[130:133], v[6:7], off
	global_load_dwordx4 v[126:129], v[6:7], off offset:16
	global_load_dwordx4 v[206:209], v[6:7], off offset:512
	global_load_dwordx4 v[210:213], v[6:7], off offset:528
	s_cmp_lt_i32 s60, 16
	s_cselect_b64 s[58:59], -1, 0
	s_sub_i32 s0, s60, 28
	s_cmp_lt_u32 s0, 48
	s_cselect_b64 s[8:9], -1, 0
	s_or_b64 s[8:9], s[58:59], s[8:9]
	s_andn2_b64 vcc, exec, s[8:9]
	s_mov_b64 s[8:9], -1
	s_waitcnt vmcnt(0)
	v_pk_mul_f32 v[6:7], v[132:133], s[26:27] op_sel_hi:[1,0]
	v_pk_mul_f32 v[10:11], v[130:131], s[26:27] op_sel_hi:[1,0]
	v_pk_mul_f32 v[14:15], v[128:129], s[26:27] op_sel_hi:[1,0]
	v_pk_mul_f32 v[126:127], v[126:127], s[26:27] op_sel_hi:[1,0]
	v_pk_mul_f32 v[128:129], v[208:209], s[26:27] op_sel_hi:[1,0]
	v_pk_mul_f32 v[130:131], v[206:207], s[26:27] op_sel_hi:[1,0]
	v_pk_mul_f32 v[132:133], v[212:213], s[26:27] op_sel_hi:[1,0]
	v_pk_mul_f32 v[206:207], v[210:211], s[26:27] op_sel_hi:[1,0]
	v_pk_mul_f32 v[106:107], v[162:163], v[6:7]
	v_pk_mul_f32 v[110:111], v[124:125], v[10:11]
	v_pk_mul_f32 v[94:95], v[94:95], v[6:7]
	v_pk_mul_f32 v[98:99], v[120:121], v[10:11]
	v_pk_mul_f32 v[86:87], v[90:91], v[6:7]
	v_pk_mul_f32 v[90:91], v[116:117], v[10:11]
	v_pk_mul_f32 v[74:75], v[114:115], v[6:7]
	v_pk_mul_f32 v[78:79], v[112:113], v[10:11]
	v_pk_mul_f32 v[58:59], v[22:23], v[6:7]
	v_pk_mul_f32 v[62:63], v[108:109], v[10:11]
	v_pk_mul_f32 v[42:43], v[30:31], v[6:7]
	v_pk_mul_f32 v[46:47], v[104:105], v[10:11]
	v_pk_mul_f32 v[22:23], v[54:55], v[6:7]
	v_pk_mul_f32 v[30:31], v[100:101], v[10:11]
	v_pk_mul_f32 v[6:7], v[70:71], v[6:7]
	v_pk_mul_f32 v[10:11], v[96:97], v[10:11]
	v_pk_mul_f32 v[114:115], v[160:161], v[14:15]
	v_pk_mul_f32 v[118:119], v[92:93], v[126:127]
	v_pk_mul_f32 v[96:97], v[122:123], v[14:15]
	v_pk_mul_f32 v[102:103], v[88:89], v[126:127]
	v_pk_mul_f32 v[88:89], v[164:165], v[14:15]
	v_pk_mul_f32 v[84:85], v[84:85], v[126:127]
	v_pk_mul_f32 v[82:83], v[82:83], v[14:15]
	v_pk_mul_f32 v[80:81], v[80:81], v[126:127]
	v_pk_mul_f32 v[66:67], v[18:19], v[14:15]
	v_pk_mul_f32 v[70:71], v[76:77], v[126:127]
	v_pk_mul_f32 v[50:51], v[50:51], v[14:15]
	v_pk_mul_f32 v[54:55], v[72:73], v[126:127]
	v_pk_mul_f32 v[34:35], v[180:181], v[14:15]
	v_pk_mul_f32 v[38:39], v[68:69], v[126:127]
	v_pk_mul_f32 v[14:15], v[186:187], v[14:15]
	v_pk_mul_f32 v[18:19], v[64:65], v[126:127]
	v_pk_mul_f32 v[122:123], v[168:169], v[128:129]
	v_pk_mul_f32 v[124:125], v[60:61], v[130:131]
	v_pk_mul_f32 v[108:109], v[172:173], v[128:129]
	v_pk_mul_f32 v[112:113], v[56:57], v[130:131]
	v_pk_mul_f32 v[76:77], v[26:27], v[128:129]
	v_pk_mul_f32 v[92:93], v[52:53], v[130:131]
	v_pk_mul_f32 v[60:61], v[178:179], v[128:129]
	v_pk_mul_f32 v[64:65], v[48:49], v[130:131]
	v_pk_mul_f32 v[52:53], v[184:185], v[128:129]
	v_pk_mul_f32 v[56:57], v[44:45], v[130:131]
	v_pk_mul_f32 v[44:45], v[190:191], v[128:129]
	v_pk_mul_f32 v[48:49], v[40:41], v[130:131]
	v_pk_mul_f32 v[40:41], v[194:195], v[128:129]
	v_pk_mul_f32 v[36:37], v[36:37], v[130:131]
	v_pk_mul_f32 v[26:27], v[198:199], v[128:129]
	v_pk_mul_f32 v[32:33], v[32:33], v[130:131]
	v_pk_mul_f32 v[126:127], v[166:167], v[132:133]
	v_pk_mul_f32 v[128:129], v[28:29], v[206:207]
	v_pk_mul_f32 v[116:117], v[170:171], v[132:133]
	v_pk_mul_f32 v[120:121], v[24:25], v[206:207]
	v_pk_mul_f32 v[100:101], v[174:175], v[132:133]
	v_pk_mul_f32 v[104:105], v[20:21], v[206:207]
	v_pk_mul_f32 v[68:69], v[176:177], v[132:133]
	v_pk_mul_f32 v[72:73], v[16:17], v[206:207]
	v_pk_mul_f32 v[24:25], v[182:183], v[132:133]
	v_pk_mul_f32 v[28:29], v[12:13], v[206:207]
	v_pk_mul_f32 v[16:17], v[188:189], v[132:133]
	v_pk_mul_f32 v[20:21], v[8:9], v[206:207]
	v_pk_mul_f32 v[8:9], v[192:193], v[132:133]
	v_pk_mul_f32 v[12:13], v[4:5], v[206:207]
	v_pk_mul_f32 v[4:5], v[196:197], v[132:133]
	v_pk_mul_f32 v[0:1], v[0:1], v[206:207]
	s_cbranch_vccz .LBB0_764
	s_cmp_lt_u32 s60, 28
	s_cbranch_scc1 .LBB0_641
	s_and_b64 vcc, exec, s[20:21]
	s_cbranch_vccz .LBB0_640
	v_mul_f32_e32 v3, 0xbfb8aa3b, v110
	v_exp_f32_e32 v130, v3
	v_mul_f32_e32 v3, 0xbfb8aa3b, v111
	v_exp_f32_e32 v131, v3
	v_mul_f32_e32 v132, 0xbfb8aa3b, v118
	v_exp_f32_e32 v132, v132
	v_mad_i64_i32 v[164:165], s[8:9], v2, s82, v[148:149]
	v_pk_add_f32 v[130:131], v[130:131], 1.0 op_sel_hi:[1,0]
	s_nop 0
	s_nop 0
	v_mul_f32_e32 v133, 0xbfb8aa3b, v119
	v_rcp_f32_e32 v3, v131
	s_nop 0
	v_mul_f32_e32 v131, 1.0, v3
	v_exp_f32_e32 v133, v133
	s_nop 0
	v_pk_add_f32 v[132:133], v[132:133], 1.0 op_sel_hi:[1,0]
	v_rcp_f32_e32 v3, v130
	s_nop 0
	v_mul_f32_e32 v130, 1.0, v3
	v_rcp_f32_e32 v3, v133
	s_nop 0
	v_mul_f32_e32 v161, 1.0, v3
	v_mul_f32_e32 v160, 0xbfb8aa3b, v106
	v_exp_f32_e32 v162, v160
	v_mul_f32_e32 v160, 0xbfb8aa3b, v107
	v_exp_f32_e32 v163, v160
	v_rcp_f32_e32 v3, v132
	s_nop 0
	v_mul_f32_e32 v160, 1.0, v3
	v_pk_add_f32 v[162:163], v[162:163], 1.0 op_sel_hi:[1,0]
	v_mul_f32_e32 v3, 0xbfb8aa3b, v114
	v_exp_f32_e32 v166, v3
	v_mul_f32_e32 v142, 0xbfb8aa3b, v115
	v_exp_f32_e32 v167, v142
	v_rcp_f32_e32 v3, v163
	s_nop 0
	v_mul_f32_e32 v133, 1.0, v3
	v_pk_add_f32 v[166:167], v[166:167], 1.0 op_sel_hi:[1,0]
	v_rcp_f32_e32 v3, v162
	s_nop 0
	v_mul_f32_e32 v132, 1.0, v3
	global_store_dwordx4 v[164:165], v[130:133], off
	s_nop 1
	v_rcp_f32_e32 v3, v167
	s_nop 0
	v_mul_f32_e32 v163, 1.0, v3
	v_mul_f32_e32 v130, 0xbfb8aa3b, v98
	v_mul_f32_e32 v131, 0xbfb8aa3b, v99
	v_exp_f32_e32 v130, v130
	v_exp_f32_e32 v131, v131
	v_rcp_f32_e32 v3, v166
	s_nop 0
	v_mul_f32_e32 v162, 1.0, v3
	v_or_b32_e32 v3, 16, v2
	global_store_dwordx4 v[164:165], v[160:163], off offset:16
	v_pk_add_f32 v[130:131], v[130:131], 1.0 op_sel_hi:[1,0]
	v_mad_i64_i32 v[164:165], s[8:9], v3, s82, v[148:149]
	v_mul_f32_e32 v3, 0xbfb8aa3b, v102
	v_exp_f32_e32 v132, v3
	v_mul_f32_e32 v133, 0xbfb8aa3b, v103
	v_exp_f32_e32 v133, v133
	v_rcp_f32_e32 v3, v131
	s_nop 0
	v_mul_f32_e32 v131, 1.0, v3
	v_pk_add_f32 v[132:133], v[132:133], 1.0 op_sel_hi:[1,0]
	v_rcp_f32_e32 v3, v130
	s_nop 0
	v_mul_f32_e32 v130, 1.0, v3
	v_rcp_f32_e32 v3, v133
	s_nop 0
	v_mul_f32_e32 v161, 1.0, v3
	v_mul_f32_e32 v142, 0xbfb8aa3b, v94
	v_exp_f32_e32 v162, v142
	v_mul_f32_e32 v142, 0xbfb8aa3b, v95
	v_exp_f32_e32 v163, v142
	v_rcp_f32_e32 v3, v132
	s_nop 0
	v_mul_f32_e32 v160, 1.0, v3
	v_pk_add_f32 v[162:163], v[162:163], 1.0 op_sel_hi:[1,0]
	v_mul_f32_e32 v3, 0xbfb8aa3b, v96
	v_exp_f32_e32 v166, v3
	v_mul_f32_e32 v142, 0xbfb8aa3b, v97
	v_exp_f32_e32 v167, v142
	v_rcp_f32_e32 v3, v163
	s_nop 0
	v_mul_f32_e32 v133, 1.0, v3
	v_pk_add_f32 v[166:167], v[166:167], 1.0 op_sel_hi:[1,0]
	v_rcp_f32_e32 v3, v162
	s_nop 0
	v_mul_f32_e32 v132, 1.0, v3
	global_store_dwordx4 v[164:165], v[130:133], off
	s_nop 1
	v_rcp_f32_e32 v3, v167
	s_nop 0
	v_mul_f32_e32 v163, 1.0, v3
	v_mul_f32_e32 v130, 0xbfb8aa3b, v90
	v_mul_f32_e32 v131, 0xbfb8aa3b, v91
	v_exp_f32_e32 v130, v130
	v_exp_f32_e32 v131, v131
	v_rcp_f32_e32 v3, v166
	s_nop 0
	v_mul_f32_e32 v162, 1.0, v3
	v_or_b32_e32 v3, 32, v2
	global_store_dwordx4 v[164:165], v[160:163], off offset:16
	v_pk_add_f32 v[130:131], v[130:131], 1.0 op_sel_hi:[1,0]
	v_mad_i64_i32 v[164:165], s[8:9], v3, s82, v[148:149]
	v_mul_f32_e32 v3, 0xbfb8aa3b, v84
	v_exp_f32_e32 v132, v3
	v_mul_f32_e32 v133, 0xbfb8aa3b, v85
	v_exp_f32_e32 v133, v133
	v_rcp_f32_e32 v3, v131
	s_nop 0
	v_mul_f32_e32 v131, 1.0, v3
	v_pk_add_f32 v[132:133], v[132:133], 1.0 op_sel_hi:[1,0]
	v_rcp_f32_e32 v3, v130
	s_nop 0
	v_mul_f32_e32 v130, 1.0, v3
	v_rcp_f32_e32 v3, v133
	s_nop 0
	v_mul_f32_e32 v161, 1.0, v3
	v_mul_f32_e32 v142, 0xbfb8aa3b, v86
	v_exp_f32_e32 v162, v142
	v_mul_f32_e32 v142, 0xbfb8aa3b, v87
	v_exp_f32_e32 v163, v142
	v_rcp_f32_e32 v3, v132
	s_nop 0
	v_mul_f32_e32 v160, 1.0, v3
	v_pk_add_f32 v[162:163], v[162:163], 1.0 op_sel_hi:[1,0]
	v_mul_f32_e32 v3, 0xbfb8aa3b, v88
	v_exp_f32_e32 v166, v3
	v_mul_f32_e32 v142, 0xbfb8aa3b, v89
	v_exp_f32_e32 v167, v142
	v_rcp_f32_e32 v3, v163
	s_nop 0
	v_mul_f32_e32 v133, 1.0, v3
	v_pk_add_f32 v[166:167], v[166:167], 1.0 op_sel_hi:[1,0]
	v_rcp_f32_e32 v3, v162
	s_nop 0
	v_mul_f32_e32 v132, 1.0, v3
	global_store_dwordx4 v[164:165], v[130:133], off
	s_nop 1
	v_rcp_f32_e32 v3, v167
	s_nop 0
	v_mul_f32_e32 v163, 1.0, v3
	v_mul_f32_e32 v130, 0xbfb8aa3b, v78
	v_mul_f32_e32 v131, 0xbfb8aa3b, v79
	v_exp_f32_e32 v130, v130
	v_exp_f32_e32 v131, v131
	v_rcp_f32_e32 v3, v166
	s_nop 0
	v_mul_f32_e32 v162, 1.0, v3
	v_or_b32_e32 v3, 48, v2
	global_store_dwordx4 v[164:165], v[160:163], off offset:16
	v_pk_add_f32 v[130:131], v[130:131], 1.0 op_sel_hi:[1,0]
	v_mad_i64_i32 v[164:165], s[8:9], v3, s82, v[148:149]
	v_mul_f32_e32 v3, 0xbfb8aa3b, v80
	v_exp_f32_e32 v132, v3
	v_mul_f32_e32 v133, 0xbfb8aa3b, v81
	v_exp_f32_e32 v133, v133
	v_rcp_f32_e32 v3, v131
	s_nop 0
	v_mul_f32_e32 v131, 1.0, v3
	v_pk_add_f32 v[132:133], v[132:133], 1.0 op_sel_hi:[1,0]
	v_rcp_f32_e32 v3, v130
	s_nop 0
	v_mul_f32_e32 v130, 1.0, v3
	v_rcp_f32_e32 v3, v133
	s_nop 0
	v_mul_f32_e32 v161, 1.0, v3
	v_mul_f32_e32 v142, 0xbfb8aa3b, v74
	v_exp_f32_e32 v162, v142
	v_mul_f32_e32 v142, 0xbfb8aa3b, v75
	v_exp_f32_e32 v163, v142
	v_rcp_f32_e32 v3, v132
	s_nop 0
	v_mul_f32_e32 v160, 1.0, v3
	v_pk_add_f32 v[162:163], v[162:163], 1.0 op_sel_hi:[1,0]
	v_mul_f32_e32 v3, 0xbfb8aa3b, v82
	v_exp_f32_e32 v166, v3
	v_mul_f32_e32 v142, 0xbfb8aa3b, v83
	v_exp_f32_e32 v167, v142
	v_rcp_f32_e32 v3, v163
	s_nop 0
	v_mul_f32_e32 v133, 1.0, v3
	v_pk_add_f32 v[166:167], v[166:167], 1.0 op_sel_hi:[1,0]
	v_rcp_f32_e32 v3, v162
	s_nop 0
	v_mul_f32_e32 v132, 1.0, v3
	global_store_dwordx4 v[164:165], v[130:133], off
	s_nop 1
	v_rcp_f32_e32 v3, v167
	s_nop 0
	v_mul_f32_e32 v163, 1.0, v3
	v_mul_f32_e32 v130, 0xbfb8aa3b, v62
	v_mul_f32_e32 v131, 0xbfb8aa3b, v63
	v_exp_f32_e32 v130, v130
	v_exp_f32_e32 v131, v131
	v_rcp_f32_e32 v3, v166
	s_nop 0
	v_mul_f32_e32 v162, 1.0, v3
	v_add_u32_e32 v3, 0x80, v2
	global_store_dwordx4 v[164:165], v[160:163], off offset:16
	v_pk_add_f32 v[130:131], v[130:131], 1.0 op_sel_hi:[1,0]
	v_mad_i64_i32 v[164:165], s[8:9], v3, s82, v[148:149]
	v_mul_f32_e32 v3, 0xbfb8aa3b, v70
	v_exp_f32_e32 v132, v3
	v_mul_f32_e32 v133, 0xbfb8aa3b, v71
	v_exp_f32_e32 v133, v133
	v_rcp_f32_e32 v3, v131
	s_nop 0
	v_mul_f32_e32 v131, 1.0, v3
	v_pk_add_f32 v[132:133], v[132:133], 1.0 op_sel_hi:[1,0]
	v_rcp_f32_e32 v3, v130
	s_nop 0
	v_mul_f32_e32 v130, 1.0, v3
	v_rcp_f32_e32 v3, v133
	s_nop 0
	v_mul_f32_e32 v161, 1.0, v3
	v_mul_f32_e32 v142, 0xbfb8aa3b, v58
	v_exp_f32_e32 v162, v142
	v_mul_f32_e32 v142, 0xbfb8aa3b, v59
	v_exp_f32_e32 v163, v142
	v_rcp_f32_e32 v3, v132
	s_nop 0
	v_mul_f32_e32 v160, 1.0, v3
	v_pk_add_f32 v[162:163], v[162:163], 1.0 op_sel_hi:[1,0]
	v_mul_f32_e32 v3, 0xbfb8aa3b, v66
	v_exp_f32_e32 v166, v3
	v_mul_f32_e32 v142, 0xbfb8aa3b, v67
	v_exp_f32_e32 v167, v142
	v_rcp_f32_e32 v3, v163
	s_nop 0
	v_mul_f32_e32 v133, 1.0, v3
	v_pk_add_f32 v[166:167], v[166:167], 1.0 op_sel_hi:[1,0]
	v_rcp_f32_e32 v3, v162
	s_nop 0
	v_mul_f32_e32 v132, 1.0, v3
	global_store_dwordx4 v[164:165], v[130:133], off
	s_nop 1
	v_rcp_f32_e32 v3, v167
	s_nop 0
	v_mul_f32_e32 v163, 1.0, v3
	v_mul_f32_e32 v130, 0xbfb8aa3b, v46
	v_mul_f32_e32 v131, 0xbfb8aa3b, v47
	v_exp_f32_e32 v130, v130
	v_exp_f32_e32 v131, v131
	v_rcp_f32_e32 v3, v166
	s_nop 0
	v_mul_f32_e32 v162, 1.0, v3
	v_add_u32_e32 v3, 0x90, v2
	global_store_dwordx4 v[164:165], v[160:163], off offset:16
	v_pk_add_f32 v[130:131], v[130:131], 1.0 op_sel_hi:[1,0]
	v_mad_i64_i32 v[164:165], s[8:9], v3, s82, v[148:149]
	v_mul_f32_e32 v3, 0xbfb8aa3b, v54
	v_exp_f32_e32 v132, v3
	v_mul_f32_e32 v133, 0xbfb8aa3b, v55
	v_exp_f32_e32 v133, v133
	v_rcp_f32_e32 v3, v131
	s_nop 0
	v_mul_f32_e32 v131, 1.0, v3
	v_pk_add_f32 v[132:133], v[132:133], 1.0 op_sel_hi:[1,0]
	v_rcp_f32_e32 v3, v130
	s_nop 0
	v_mul_f32_e32 v130, 1.0, v3
	v_rcp_f32_e32 v3, v133
	s_nop 0
	v_mul_f32_e32 v161, 1.0, v3
	v_mul_f32_e32 v142, 0xbfb8aa3b, v42
	v_exp_f32_e32 v162, v142
	v_mul_f32_e32 v142, 0xbfb8aa3b, v43
	v_exp_f32_e32 v163, v142
	v_rcp_f32_e32 v3, v132
	s_nop 0
	v_mul_f32_e32 v160, 1.0, v3
	v_pk_add_f32 v[162:163], v[162:163], 1.0 op_sel_hi:[1,0]
	v_mul_f32_e32 v3, 0xbfb8aa3b, v50
	v_exp_f32_e32 v166, v3
	v_mul_f32_e32 v142, 0xbfb8aa3b, v51
	v_exp_f32_e32 v167, v142
	v_rcp_f32_e32 v3, v163
	s_nop 0
	v_mul_f32_e32 v133, 1.0, v3
	v_pk_add_f32 v[166:167], v[166:167], 1.0 op_sel_hi:[1,0]
	v_rcp_f32_e32 v3, v162
	s_nop 0
	v_mul_f32_e32 v132, 1.0, v3
	global_store_dwordx4 v[164:165], v[130:133], off
	s_nop 1
	v_rcp_f32_e32 v3, v167
	s_nop 0
	v_mul_f32_e32 v163, 1.0, v3
	v_mul_f32_e32 v130, 0xbfb8aa3b, v30
	v_mul_f32_e32 v131, 0xbfb8aa3b, v31
	v_exp_f32_e32 v130, v130
	v_exp_f32_e32 v131, v131
	v_rcp_f32_e32 v3, v166
	s_nop 0
	v_mul_f32_e32 v162, 1.0, v3
	v_add_u32_e32 v3, 0xa0, v2
	global_store_dwordx4 v[164:165], v[160:163], off offset:16
	v_pk_add_f32 v[130:131], v[130:131], 1.0 op_sel_hi:[1,0]
	v_mad_i64_i32 v[164:165], s[8:9], v3, s82, v[148:149]
	v_mul_f32_e32 v3, 0xbfb8aa3b, v38
	v_exp_f32_e32 v132, v3
	v_mul_f32_e32 v133, 0xbfb8aa3b, v39
	v_exp_f32_e32 v133, v133
	v_rcp_f32_e32 v3, v131
	s_nop 0
	v_mul_f32_e32 v131, 1.0, v3
	v_pk_add_f32 v[132:133], v[132:133], 1.0 op_sel_hi:[1,0]
	v_rcp_f32_e32 v3, v130
	s_nop 0
	v_mul_f32_e32 v130, 1.0, v3
	v_rcp_f32_e32 v3, v133
	s_nop 0
	v_mul_f32_e32 v161, 1.0, v3
	v_mul_f32_e32 v142, 0xbfb8aa3b, v22
	v_exp_f32_e32 v162, v142
	v_mul_f32_e32 v142, 0xbfb8aa3b, v23
	v_exp_f32_e32 v163, v142
	v_rcp_f32_e32 v3, v132
	s_nop 0
	v_mul_f32_e32 v160, 1.0, v3
	v_pk_add_f32 v[162:163], v[162:163], 1.0 op_sel_hi:[1,0]
	v_mul_f32_e32 v3, 0xbfb8aa3b, v34
	v_exp_f32_e32 v166, v3
	v_mul_f32_e32 v142, 0xbfb8aa3b, v35
	v_exp_f32_e32 v167, v142
	v_rcp_f32_e32 v3, v163
	s_nop 0
	v_mul_f32_e32 v133, 1.0, v3
	v_pk_add_f32 v[166:167], v[166:167], 1.0 op_sel_hi:[1,0]
	v_rcp_f32_e32 v3, v162
	s_nop 0
	v_mul_f32_e32 v132, 1.0, v3
	global_store_dwordx4 v[164:165], v[130:133], off
	s_nop 1
	v_rcp_f32_e32 v3, v167
	s_nop 0
	v_mul_f32_e32 v163, 1.0, v3
	v_mul_f32_e32 v130, 0xbfb8aa3b, v10
	v_mul_f32_e32 v131, 0xbfb8aa3b, v11
	v_exp_f32_e32 v130, v130
	v_exp_f32_e32 v131, v131
	v_rcp_f32_e32 v3, v166
	s_nop 0
	v_mul_f32_e32 v162, 1.0, v3
	v_add_u32_e32 v3, 0xb0, v2
	global_store_dwordx4 v[164:165], v[160:163], off offset:16
	v_pk_add_f32 v[130:131], v[130:131], 1.0 op_sel_hi:[1,0]
	v_mad_i64_i32 v[164:165], s[8:9], v3, s82, v[148:149]
	v_mul_f32_e32 v3, 0xbfb8aa3b, v18
	v_exp_f32_e32 v132, v3
	v_mul_f32_e32 v133, 0xbfb8aa3b, v19
	v_exp_f32_e32 v133, v133
	v_rcp_f32_e32 v3, v131
	s_nop 0
	v_mul_f32_e32 v131, 1.0, v3
	v_pk_add_f32 v[132:133], v[132:133], 1.0 op_sel_hi:[1,0]
	v_rcp_f32_e32 v3, v130
	s_nop 0
	v_mul_f32_e32 v130, 1.0, v3
	v_rcp_f32_e32 v3, v133
	s_nop 0
	v_mul_f32_e32 v161, 1.0, v3
	v_mul_f32_e32 v142, 0xbfb8aa3b, v6
	v_exp_f32_e32 v162, v142
	v_mul_f32_e32 v142, 0xbfb8aa3b, v7
	v_exp_f32_e32 v163, v142
	v_rcp_f32_e32 v3, v132
	s_nop 0
	v_mul_f32_e32 v160, 1.0, v3
	v_pk_add_f32 v[162:163], v[162:163], 1.0 op_sel_hi:[1,0]
	v_mul_f32_e32 v3, 0xbfb8aa3b, v14
	v_exp_f32_e32 v166, v3
	v_mul_f32_e32 v142, 0xbfb8aa3b, v15
	v_exp_f32_e32 v167, v142
	v_rcp_f32_e32 v3, v163
	s_nop 0
	v_mul_f32_e32 v133, 1.0, v3
	v_pk_add_f32 v[166:167], v[166:167], 1.0 op_sel_hi:[1,0]
	v_rcp_f32_e32 v3, v162
	s_nop 0
	v_mul_f32_e32 v132, 1.0, v3
	global_store_dwordx4 v[164:165], v[130:133], off
	s_nop 1
	v_rcp_f32_e32 v3, v167
	s_nop 0
	v_mul_f32_e32 v163, 1.0, v3
	v_rcp_f32_e32 v3, v166
	s_nop 0
	v_mul_f32_e32 v162, 1.0, v3
	global_store_dwordx4 v[164:165], v[160:163], off offset:16

.LBB0_843:
	s_lshl_b32 s6, s1, 8
	s_ashr_i32 s7, s6, 31
	v_lshl_add_u64 v[52:53], s[6:7], 2, v[152:153]
	global_load_dwordx4 v[68:71], v[52:53], off
	global_load_dwordx4 v[64:67], v[52:53], off offset:16
	global_load_dwordx4 v[48:51], v[52:53], off offset:528
	s_nop 0
	global_load_dwordx4 v[52:55], v[52:53], off offset:512
	v_lshl_add_u32 v162, s0, 8, v166
	v_ashrrev_i32_e32 v163, 31, v162
	s_cmp_gt_i32 s1, 0
	v_lshlrev_b64 v[160:161], 9, v[162:163]
	s_cselect_b64 s[6:7], -1, 0
	s_cmp_lg_u64 s[6:7], 0
	s_subb_u32 s0, s1, 0
	s_lshl_b32 s0, s0, 8
	s_ashr_i32 s1, s0, 31
	v_lshl_add_u64 v[164:165], s[0:1], 1, v[154:155]
	v_lshl_add_u64 v[160:161], v[164:165], 0, v[160:161]
	s_waitcnt vmcnt(0)
	v_pk_add_f32 v[140:141], v[140:141], v[68:69]
	s_nop 0
	v_mul_f32_e32 v163, 0xbfb8aa3b, v140
	v_mul_f32_e32 v171, 0xbfb8aa3b, v141
	v_pk_add_f32 v[136:137], v[136:137], v[64:65]
	v_exp_f32_e32 v172, v163
	v_exp_f32_e32 v173, v171
	v_mul_f32_e32 v174, 0xbfb8aa3b, v136
	v_mul_f32_e32 v175, 0xbfb8aa3b, v137
	v_exp_f32_e32 v174, v174
	v_exp_f32_e32 v175, v175
	v_pk_add_f32 v[142:143], v[142:143], v[70:71]
	v_pk_add_f32 v[172:173], v[172:173], 1.0 op_sel_hi:[1,0]
	v_mul_f32_e32 v176, 0xbfb8aa3b, v142
	v_mul_f32_e32 v177, 0xbfb8aa3b, v143
	v_exp_f32_e32 v176, v176
	v_exp_f32_e32 v177, v177
	v_pk_add_f32 v[174:175], v[174:175], 1.0 op_sel_hi:[1,0]
	v_pk_add_f32 v[176:177], v[176:177], 1.0 op_sel_hi:[1,0]
	s_mov_b64 vcc, s[0:1]
	v_rcp_f32_e32 v163, v173
	s_nop 0
	v_mul_f32_e32 v163, v141, v163
	s_mov_b64 vcc, s[6:7]
	v_rcp_f32_e32 v141, v172
	s_nop 0
	v_mul_f32_e32 v171, v140, v141
	v_rcp_f32_e32 v140, v175
	s_nop 0
	v_mul_f32_e32 v172, v137, v140
	s_mov_b64 vcc, s[8:9]
	s_mov_b64 vcc, s[10:11]
	v_rcp_f32_e32 v137, v174
	s_nop 0
	v_mul_f32_e32 v173, v136, v137
	v_pk_add_f32 v[138:139], v[138:139], v[66:67]
	v_rcp_f32_e32 v136, v177
	s_nop 0
	v_mul_f32_e32 v143, v143, v136
	v_mul_f32_e32 v136, 0xbfb8aa3b, v138
	v_mul_f32_e32 v137, 0xbfb8aa3b, v139
	v_exp_f32_e32 v136, v136
	v_exp_f32_e32 v137, v137
	s_nop 0
	v_pk_add_f32 v[136:137], v[136:137], 1.0 op_sel_hi:[1,0]
	v_rcp_f32_e32 v140, v176
	s_nop 0
	v_mul_f32_e32 v142, v142, v140
	v_rcp_f32_e32 v140, v137
	s_nop 0
	v_mul_f32_e32 v139, v139, v140
	v_pk_add_f32 v[132:133], v[132:133], v[52:53]
	v_rcp_f32_e32 v137, v136
	s_nop 0
	v_mul_f32_e32 v174, v138, v137
	v_mul_f32_e32 v136, 0xbfb8aa3b, v132
	v_exp_f32_e32 v140, v136
	v_mul_f32_e32 v136, 0xbfb8aa3b, v133
	v_exp_f32_e32 v141, v136
	v_cvt_pk_bf16_f32 v137, v142, v143
	v_cvt_pk_bf16_f32 v136, v171, v163
	v_cvt_pk_bf16_f32 v138, v173, v172
	v_pk_add_f32 v[140:141], v[140:141], 1.0 op_sel_hi:[1,0]
	v_cvt_pk_bf16_f32 v139, v174, v139
	global_store_dwordx4 v[160:161], v[136:139], off
	v_pk_add_f32 v[128:129], v[128:129], v[48:49]
	v_pk_add_f32 v[134:135], v[134:135], v[54:55]
	v_rcp_f32_e32 v136, v141
	s_nop 0
	v_mul_f32_e32 v141, v133, v136
	v_mul_f32_e32 v136, 0xbfb8aa3b, v128
	v_mul_f32_e32 v137, 0xbfb8aa3b, v129
	v_exp_f32_e32 v136, v136
	v_exp_f32_e32 v137, v137
	s_nop 0
	v_pk_add_f32 v[136:137], v[136:137], 1.0 op_sel_hi:[1,0]
	v_rcp_f32_e32 v133, v140
	s_nop 0
	v_mul_f32_e32 v139, v132, v133
	v_pk_add_f32 v[130:131], v[130:131], v[50:51]
	v_rcp_f32_e32 v132, v137
	s_nop 0
	v_mul_f32_e32 v137, v129, v132
	v_mul_f32_e32 v132, 0xbfb8aa3b, v134
	v_mul_f32_e32 v133, 0xbfb8aa3b, v135
	v_exp_f32_e32 v132, v132
	v_exp_f32_e32 v133, v133
	s_nop 0
	v_pk_add_f32 v[132:133], v[132:133], 1.0 op_sel_hi:[1,0]
	v_rcp_f32_e32 v129, v136
	s_nop 0
	v_mul_f32_e32 v136, v128, v129
	v_pk_add_f32 v[120:121], v[120:121], v[64:65]
	v_rcp_f32_e32 v128, v133
	s_nop 0
	v_mul_f32_e32 v133, v135, v128
	v_mul_f32_e32 v129, 0xbfb8aa3b, v131
	v_mul_f32_e32 v128, 0xbfb8aa3b, v130
	v_exp_f32_e32 v128, v128
	v_exp_f32_e32 v129, v129
	s_nop 0
	v_pk_add_f32 v[128:129], v[128:129], 1.0 op_sel_hi:[1,0]
	v_rcp_f32_e32 v135, v132
	s_nop 0
	v_mul_f32_e32 v132, v134, v135
	v_pk_add_f32 v[126:127], v[126:127], v[70:71]
	v_rcp_f32_e32 v134, v129
	s_nop 0
	v_mul_f32_e32 v131, v131, v134
	v_pk_add_f32 v[122:123], v[122:123], v[66:67]
	v_rcp_f32_e32 v129, v128
	s_nop 0
	v_mul_f32_e32 v134, v130, v129
	v_cvt_pk_bf16_f32 v129, v132, v133
	v_pk_add_f32 v[132:133], v[124:125], v[68:69]
	v_cvt_pk_bf16_f32 v128, v139, v141
	v_mul_f32_e32 v124, 0xbfb8aa3b, v132
	v_mul_f32_e32 v125, 0xbfb8aa3b, v133
	v_exp_f32_e32 v124, v124
	v_exp_f32_e32 v125, v125
	v_cvt_pk_bf16_f32 v130, v136, v137
	v_cvt_pk_bf16_f32 v131, v134, v131
	global_store_dwordx4 v[160:161], v[128:131], off offset:256
	v_pk_add_f32 v[116:117], v[116:117], v[52:53]
	v_pk_add_f32 v[112:113], v[112:113], v[48:49]
	v_pk_add_f32 v[130:131], v[124:125], 1.0 op_sel_hi:[1,0]
	v_or_b32_e32 v128, 16, v162
	v_ashrrev_i32_e32 v129, 31, v128
	v_lshlrev_b64 v[124:125], 9, v[128:129]
	v_lshl_add_u64 v[124:125], v[164:165], 0, v[124:125]
	v_rcp_f32_e32 v128, v131
	s_nop 0
	v_mul_f32_e32 v133, v133, v128
	v_mul_f32_e32 v129, 0xbfb8aa3b, v121
	v_mul_f32_e32 v128, 0xbfb8aa3b, v120
	v_exp_f32_e32 v128, v128
	v_exp_f32_e32 v129, v129
	s_nop 0
	v_pk_add_f32 v[128:129], v[128:129], 1.0 op_sel_hi:[1,0]
	v_rcp_f32_e32 v131, v130
	s_nop 0
	v_mul_f32_e32 v132, v132, v131
	v_pk_add_f32 v[118:119], v[118:119], v[54:55]
	v_rcp_f32_e32 v130, v129
	s_nop 0
	v_mul_f32_e32 v129, v121, v130
	v_mul_f32_e32 v130, 0xbfb8aa3b, v126
	v_mul_f32_e32 v131, 0xbfb8aa3b, v127
	v_exp_f32_e32 v130, v130
	v_exp_f32_e32 v131, v131
	s_nop 0
	v_pk_add_f32 v[130:131], v[130:131], 1.0 op_sel_hi:[1,0]
	v_rcp_f32_e32 v121, v128
	s_nop 0
	v_mul_f32_e32 v128, v120, v121
	v_pk_add_f32 v[114:115], v[114:115], v[50:51]
	v_rcp_f32_e32 v120, v131
	s_nop 0
	v_mul_f32_e32 v131, v127, v120
	v_mul_f32_e32 v121, 0xbfb8aa3b, v123
	v_mul_f32_e32 v120, 0xbfb8aa3b, v122
	v_exp_f32_e32 v120, v120
	v_exp_f32_e32 v121, v121
	s_nop 0
	v_pk_add_f32 v[120:121], v[120:121], 1.0 op_sel_hi:[1,0]
	v_rcp_f32_e32 v127, v130
	s_nop 0
	v_mul_f32_e32 v130, v126, v127
	v_pk_add_f32 v[104:105], v[104:105], v[64:65]
	v_rcp_f32_e32 v126, v121
	s_nop 0
	v_mul_f32_e32 v123, v123, v126
	v_pk_add_f32 v[110:111], v[110:111], v[70:71]
	v_rcp_f32_e32 v121, v120
	s_nop 0
	v_mul_f32_e32 v134, v122, v121
	v_mul_f32_e32 v120, 0xbfb8aa3b, v116
	v_exp_f32_e32 v126, v120
	v_mul_f32_e32 v120, 0xbfb8aa3b, v117
	v_exp_f32_e32 v127, v120
	v_cvt_pk_bf16_f32 v122, v128, v129
	v_cvt_pk_bf16_f32 v120, v132, v133
	v_cvt_pk_bf16_f32 v121, v130, v131
	v_pk_add_f32 v[126:127], v[126:127], 1.0 op_sel_hi:[1,0]
	v_cvt_pk_bf16_f32 v123, v134, v123
	global_store_dwordx4 v[124:125], v[120:123], off
	v_pk_add_f32 v[106:107], v[106:107], v[66:67]
	v_pk_add_f32 v[100:101], v[100:101], v[52:53]
	v_rcp_f32_e32 v120, v127
	s_nop 0
	v_mul_f32_e32 v127, v117, v120
	v_mul_f32_e32 v120, 0xbfb8aa3b, v112
	v_mul_f32_e32 v121, 0xbfb8aa3b, v113
	v_exp_f32_e32 v120, v120
	v_exp_f32_e32 v121, v121
	s_nop 0
	v_pk_add_f32 v[120:121], v[120:121], 1.0 op_sel_hi:[1,0]
	v_rcp_f32_e32 v117, v126
	s_nop 0
	v_mul_f32_e32 v123, v116, v117
	v_pk_add_f32 v[96:97], v[96:97], v[48:49]
	v_rcp_f32_e32 v116, v121
	s_nop 0
	v_mul_f32_e32 v121, v113, v116
	v_mul_f32_e32 v116, 0xbfb8aa3b, v118
	v_mul_f32_e32 v117, 0xbfb8aa3b, v119
	v_exp_f32_e32 v116, v116
	v_exp_f32_e32 v117, v117
	s_nop 0
	v_pk_add_f32 v[116:117], v[116:117], 1.0 op_sel_hi:[1,0]
	v_rcp_f32_e32 v113, v120
	s_nop 0
	v_mul_f32_e32 v120, v112, v113
	v_pk_add_f32 v[102:103], v[102:103], v[54:55]
	v_rcp_f32_e32 v112, v117
	s_nop 0
	v_mul_f32_e32 v117, v119, v112
	v_mul_f32_e32 v113, 0xbfb8aa3b, v115
	v_mul_f32_e32 v112, 0xbfb8aa3b, v114
	v_exp_f32_e32 v112, v112
	v_exp_f32_e32 v113, v113
	s_nop 0
	v_pk_add_f32 v[112:113], v[112:113], 1.0 op_sel_hi:[1,0]
	v_rcp_f32_e32 v119, v116
	s_nop 0
	v_mul_f32_e32 v116, v118, v119
	v_pk_add_f32 v[98:99], v[98:99], v[50:51]
	v_rcp_f32_e32 v118, v113
	s_nop 0
	v_mul_f32_e32 v115, v115, v118
	v_pk_add_f32 v[88:89], v[88:89], v[64:65]
	v_rcp_f32_e32 v113, v112
	s_nop 0
	v_mul_f32_e32 v118, v114, v113
	v_cvt_pk_bf16_f32 v113, v116, v117
	v_pk_add_f32 v[116:117], v[108:109], v[68:69]
	v_cvt_pk_bf16_f32 v112, v123, v127
	v_mul_f32_e32 v108, 0xbfb8aa3b, v116
	v_mul_f32_e32 v109, 0xbfb8aa3b, v117
	v_exp_f32_e32 v108, v108
	v_exp_f32_e32 v109, v109
	v_cvt_pk_bf16_f32 v114, v120, v121
	v_cvt_pk_bf16_f32 v115, v118, v115
	global_store_dwordx4 v[124:125], v[112:115], off offset:256
	v_pk_add_f32 v[94:95], v[94:95], v[70:71]
	v_pk_add_f32 v[90:91], v[90:91], v[66:67]
	v_pk_add_f32 v[114:115], v[108:109], 1.0 op_sel_hi:[1,0]
	v_or_b32_e32 v112, 32, v162
	v_ashrrev_i32_e32 v113, 31, v112
	v_lshlrev_b64 v[108:109], 9, v[112:113]
	v_lshl_add_u64 v[108:109], v[164:165], 0, v[108:109]
	v_rcp_f32_e32 v112, v115
	s_nop 0
	v_mul_f32_e32 v117, v117, v112
	v_mul_f32_e32 v113, 0xbfb8aa3b, v105
	v_mul_f32_e32 v112, 0xbfb8aa3b, v104
	v_exp_f32_e32 v112, v112
	v_exp_f32_e32 v113, v113
	s_nop 0
	v_pk_add_f32 v[112:113], v[112:113], 1.0 op_sel_hi:[1,0]
	v_rcp_f32_e32 v115, v114
	s_nop 0
	v_mul_f32_e32 v116, v116, v115
	v_pk_add_f32 v[84:85], v[84:85], v[52:53]
	v_rcp_f32_e32 v114, v113
	s_nop 0
	v_mul_f32_e32 v113, v105, v114
	v_mul_f32_e32 v114, 0xbfb8aa3b, v110
	v_mul_f32_e32 v115, 0xbfb8aa3b, v111
	v_exp_f32_e32 v114, v114
	v_exp_f32_e32 v115, v115
	s_nop 0
	v_pk_add_f32 v[114:115], v[114:115], 1.0 op_sel_hi:[1,0]
	v_rcp_f32_e32 v105, v112
	s_nop 0
	v_mul_f32_e32 v112, v104, v105
	v_pk_add_f32 v[80:81], v[80:81], v[48:49]
	v_rcp_f32_e32 v104, v115
	s_nop 0
	v_mul_f32_e32 v115, v111, v104
	v_mul_f32_e32 v105, 0xbfb8aa3b, v107
	v_mul_f32_e32 v104, 0xbfb8aa3b, v106
	v_exp_f32_e32 v104, v104
	v_exp_f32_e32 v105, v105
	s_nop 0
	v_pk_add_f32 v[104:105], v[104:105], 1.0 op_sel_hi:[1,0]
	v_rcp_f32_e32 v111, v114
	s_nop 0
	v_mul_f32_e32 v114, v110, v111
	v_pk_add_f32 v[86:87], v[86:87], v[54:55]
	v_rcp_f32_e32 v110, v105
	s_nop 0
	v_mul_f32_e32 v107, v107, v110
	v_pk_add_f32 v[82:83], v[82:83], v[50:51]
	v_rcp_f32_e32 v105, v104
	s_nop 0
	v_mul_f32_e32 v118, v106, v105
	v_mul_f32_e32 v104, 0xbfb8aa3b, v100
	v_exp_f32_e32 v110, v104
	v_mul_f32_e32 v104, 0xbfb8aa3b, v101
	v_exp_f32_e32 v111, v104
	v_cvt_pk_bf16_f32 v106, v112, v113
	v_cvt_pk_bf16_f32 v104, v116, v117
	v_cvt_pk_bf16_f32 v105, v114, v115
	v_pk_add_f32 v[110:111], v[110:111], 1.0 op_sel_hi:[1,0]
	v_cvt_pk_bf16_f32 v107, v118, v107
	global_store_dwordx4 v[108:109], v[104:107], off
	v_pk_add_f32 v[72:73], v[72:73], v[64:65]
	v_pk_add_f32 v[78:79], v[78:79], v[70:71]
	v_rcp_f32_e32 v104, v111
	s_nop 0
	v_mul_f32_e32 v111, v101, v104
	v_mul_f32_e32 v104, 0xbfb8aa3b, v96
	v_mul_f32_e32 v105, 0xbfb8aa3b, v97
	v_exp_f32_e32 v104, v104
	v_exp_f32_e32 v105, v105
	s_nop 0
	v_pk_add_f32 v[104:105], v[104:105], 1.0 op_sel_hi:[1,0]
	v_rcp_f32_e32 v101, v110
	s_nop 0
	v_mul_f32_e32 v107, v100, v101
	v_pk_add_f32 v[74:75], v[74:75], v[66:67]
	v_rcp_f32_e32 v100, v105
	s_nop 0
	v_mul_f32_e32 v105, v97, v100
	v_mul_f32_e32 v100, 0xbfb8aa3b, v102
	v_mul_f32_e32 v101, 0xbfb8aa3b, v103
	v_exp_f32_e32 v100, v100
	v_exp_f32_e32 v101, v101
	s_nop 0
	v_pk_add_f32 v[100:101], v[100:101], 1.0 op_sel_hi:[1,0]
	v_rcp_f32_e32 v97, v104
	s_nop 0
	v_mul_f32_e32 v104, v96, v97
	v_pk_add_f32 v[60:61], v[60:61], v[52:53]
	v_rcp_f32_e32 v96, v101
	s_nop 0
	v_mul_f32_e32 v101, v103, v96
	v_mul_f32_e32 v97, 0xbfb8aa3b, v99
	v_mul_f32_e32 v96, 0xbfb8aa3b, v98
	v_exp_f32_e32 v96, v96
	v_exp_f32_e32 v97, v97
	s_nop 0
	v_pk_add_f32 v[96:97], v[96:97], 1.0 op_sel_hi:[1,0]
	v_rcp_f32_e32 v103, v100
	s_nop 0
	v_mul_f32_e32 v100, v102, v103
	v_pk_add_f32 v[56:57], v[56:57], v[48:49]
	v_rcp_f32_e32 v102, v97
	s_nop 0
	v_mul_f32_e32 v99, v99, v102
	v_pk_add_f32 v[62:63], v[62:63], v[54:55]
	v_rcp_f32_e32 v97, v96
	s_nop 0
	v_mul_f32_e32 v102, v98, v97
	v_cvt_pk_bf16_f32 v97, v100, v101
	v_pk_add_f32 v[100:101], v[92:93], v[68:69]
	v_cvt_pk_bf16_f32 v96, v107, v111
	v_mul_f32_e32 v92, 0xbfb8aa3b, v100
	v_mul_f32_e32 v93, 0xbfb8aa3b, v101
	v_exp_f32_e32 v92, v92
	v_exp_f32_e32 v93, v93
	v_cvt_pk_bf16_f32 v98, v104, v105
	v_cvt_pk_bf16_f32 v99, v102, v99
	global_store_dwordx4 v[108:109], v[96:99], off offset:256
	v_pk_add_f32 v[58:59], v[58:59], v[50:51]
	v_pk_add_f32 v[40:41], v[40:41], v[64:65]
	v_pk_add_f32 v[98:99], v[92:93], 1.0 op_sel_hi:[1,0]
	v_or_b32_e32 v96, 48, v162
	v_ashrrev_i32_e32 v97, 31, v96
	v_lshlrev_b64 v[92:93], 9, v[96:97]
	v_lshl_add_u64 v[92:93], v[164:165], 0, v[92:93]
	v_rcp_f32_e32 v96, v99
	s_nop 0
	v_mul_f32_e32 v101, v101, v96
	v_mul_f32_e32 v97, 0xbfb8aa3b, v89
	v_mul_f32_e32 v96, 0xbfb8aa3b, v88
	v_exp_f32_e32 v96, v96
	v_exp_f32_e32 v97, v97
	s_nop 0
	v_pk_add_f32 v[96:97], v[96:97], 1.0 op_sel_hi:[1,0]
	v_rcp_f32_e32 v99, v98
	s_nop 0
	v_mul_f32_e32 v100, v100, v99
	v_pk_add_f32 v[46:47], v[46:47], v[70:71]
	v_rcp_f32_e32 v98, v97
	s_nop 0
	v_mul_f32_e32 v97, v89, v98
	v_mul_f32_e32 v98, 0xbfb8aa3b, v94
	v_mul_f32_e32 v99, 0xbfb8aa3b, v95
	v_exp_f32_e32 v98, v98
	v_exp_f32_e32 v99, v99
	s_nop 0
	v_pk_add_f32 v[98:99], v[98:99], 1.0 op_sel_hi:[1,0]
	v_rcp_f32_e32 v89, v96
	s_nop 0
	v_mul_f32_e32 v96, v88, v89
	v_pk_add_f32 v[42:43], v[42:43], v[66:67]
	v_rcp_f32_e32 v88, v99
	s_nop 0
	v_mul_f32_e32 v99, v95, v88
	v_mul_f32_e32 v89, 0xbfb8aa3b, v91
	v_mul_f32_e32 v88, 0xbfb8aa3b, v90
	v_exp_f32_e32 v88, v88
	v_exp_f32_e32 v89, v89
	s_nop 0
	v_pk_add_f32 v[88:89], v[88:89], 1.0 op_sel_hi:[1,0]
	v_rcp_f32_e32 v95, v98
	s_nop 0
	v_mul_f32_e32 v98, v94, v95
	v_pk_add_f32 v[36:37], v[36:37], v[52:53]
	v_rcp_f32_e32 v94, v89
	s_nop 0
	v_mul_f32_e32 v91, v91, v94
	v_pk_add_f32 v[32:33], v[32:33], v[48:49]
	v_rcp_f32_e32 v89, v88
	s_nop 0
	v_mul_f32_e32 v102, v90, v89
	v_mul_f32_e32 v88, 0xbfb8aa3b, v84
	v_exp_f32_e32 v94, v88
	v_mul_f32_e32 v88, 0xbfb8aa3b, v85
	v_exp_f32_e32 v95, v88
	v_cvt_pk_bf16_f32 v90, v96, v97
	v_cvt_pk_bf16_f32 v88, v100, v101
	v_cvt_pk_bf16_f32 v89, v98, v99
	v_pk_add_f32 v[94:95], v[94:95], 1.0 op_sel_hi:[1,0]
	v_cvt_pk_bf16_f32 v91, v102, v91
	global_store_dwordx4 v[92:93], v[88:91], off
	v_pk_add_f32 v[38:39], v[38:39], v[54:55]
	v_pk_add_f32 v[34:35], v[34:35], v[50:51]
	v_rcp_f32_e32 v88, v95
	s_nop 0
	v_mul_f32_e32 v95, v85, v88
	v_mul_f32_e32 v88, 0xbfb8aa3b, v80
	v_mul_f32_e32 v89, 0xbfb8aa3b, v81
	v_exp_f32_e32 v88, v88
	v_exp_f32_e32 v89, v89
	s_nop 0
	v_pk_add_f32 v[88:89], v[88:89], 1.0 op_sel_hi:[1,0]
	v_rcp_f32_e32 v85, v94
	s_nop 0
	v_mul_f32_e32 v91, v84, v85
	v_pk_add_f32 v[24:25], v[24:25], v[64:65]
	v_rcp_f32_e32 v84, v89
	s_nop 0
	v_mul_f32_e32 v89, v81, v84
	v_mul_f32_e32 v84, 0xbfb8aa3b, v86
	v_mul_f32_e32 v85, 0xbfb8aa3b, v87
	v_exp_f32_e32 v84, v84
	v_exp_f32_e32 v85, v85
	s_nop 0
	v_pk_add_f32 v[84:85], v[84:85], 1.0 op_sel_hi:[1,0]
	v_rcp_f32_e32 v81, v88
	s_nop 0
	v_mul_f32_e32 v88, v80, v81
	v_pk_add_f32 v[30:31], v[30:31], v[70:71]
	v_rcp_f32_e32 v80, v85
	s_nop 0
	v_mul_f32_e32 v87, v87, v80
	v_mul_f32_e32 v81, 0xbfb8aa3b, v83
	v_mul_f32_e32 v80, 0xbfb8aa3b, v82
	v_exp_f32_e32 v80, v80
	v_exp_f32_e32 v81, v81
	s_nop 0
	v_pk_add_f32 v[80:81], v[80:81], 1.0 op_sel_hi:[1,0]
	v_rcp_f32_e32 v85, v84
	s_nop 0
	v_mul_f32_e32 v86, v86, v85
	v_pk_add_f32 v[26:27], v[26:27], v[66:67]
	v_rcp_f32_e32 v84, v81
	s_nop 0
	v_mul_f32_e32 v83, v83, v84
	v_pk_add_f32 v[20:21], v[20:21], v[52:53]
	v_pk_add_f32 v[84:85], v[76:77], v[68:69]
	v_rcp_f32_e32 v81, v80
	s_nop 0
	v_mul_f32_e32 v90, v82, v81
	v_mul_f32_e32 v76, 0xbfb8aa3b, v84
	v_mul_f32_e32 v77, 0xbfb8aa3b, v85
	v_exp_f32_e32 v76, v76
	v_exp_f32_e32 v77, v77
	v_cvt_pk_bf16_f32 v81, v86, v87
	v_cvt_pk_bf16_f32 v82, v88, v89
	v_cvt_pk_bf16_f32 v80, v91, v95
	v_pk_add_f32 v[86:87], v[76:77], 1.0 op_sel_hi:[1,0]
	v_cvt_pk_bf16_f32 v83, v90, v83
	global_store_dwordx4 v[92:93], v[80:83], off offset:256
	v_lshl_add_u64 v[76:77], v[160:161], 0, s[26:27]
	v_pk_add_f32 v[16:17], v[16:17], v[48:49]
	v_rcp_f32_e32 v80, v87
	s_nop 0
	v_mul_f32_e32 v85, v85, v80
	v_mul_f32_e32 v80, 0xbfb8aa3b, v72
	v_mul_f32_e32 v81, 0xbfb8aa3b, v73
	v_exp_f32_e32 v80, v80
	v_exp_f32_e32 v81, v81
	s_nop 0
	v_pk_add_f32 v[80:81], v[80:81], 1.0 op_sel_hi:[1,0]
	v_rcp_f32_e32 v82, v86
	s_nop 0
	v_mul_f32_e32 v84, v84, v82
	v_pk_add_f32 v[22:23], v[22:23], v[54:55]
	v_rcp_f32_e32 v82, v81
	s_nop 0
	v_mul_f32_e32 v81, v73, v82
	v_mul_f32_e32 v82, 0xbfb8aa3b, v78
	v_mul_f32_e32 v83, 0xbfb8aa3b, v79
	v_exp_f32_e32 v82, v82
	v_exp_f32_e32 v83, v83
	s_nop 0
	v_pk_add_f32 v[82:83], v[82:83], 1.0 op_sel_hi:[1,0]
	v_rcp_f32_e32 v73, v80
	s_nop 0
	v_mul_f32_e32 v80, v72, v73
	v_pk_add_f32 v[18:19], v[18:19], v[50:51]
	v_rcp_f32_e32 v72, v83
	s_nop 0
	v_mul_f32_e32 v83, v79, v72
	v_mul_f32_e32 v73, 0xbfb8aa3b, v75
	v_mul_f32_e32 v72, 0xbfb8aa3b, v74
	v_exp_f32_e32 v72, v72
	v_exp_f32_e32 v73, v73
	s_nop 0
	v_pk_add_f32 v[72:73], v[72:73], 1.0 op_sel_hi:[1,0]
	v_rcp_f32_e32 v79, v82
	s_nop 0
	v_mul_f32_e32 v82, v78, v79
	v_pk_add_f32 v[8:9], v[8:9], v[64:65]
	v_rcp_f32_e32 v78, v73
	s_nop 0
	v_mul_f32_e32 v75, v75, v78
	v_pk_add_f32 v[14:15], v[14:15], v[70:71]
	v_rcp_f32_e32 v73, v72
	s_nop 0
	v_mul_f32_e32 v86, v74, v73
	v_mul_f32_e32 v73, 0xbfb8aa3b, v60
	v_exp_f32_e32 v78, v73
	v_mul_f32_e32 v73, 0xbfb8aa3b, v61
	v_exp_f32_e32 v79, v73
	v_cvt_pk_bf16_f32 v73, v82, v83
	v_cvt_pk_bf16_f32 v74, v80, v81
	v_add_co_u32_e32 v80, vcc, s65, v160
	v_pk_add_f32 v[78:79], v[78:79], 1.0 op_sel_hi:[1,0]
	v_cvt_pk_bf16_f32 v72, v84, v85
	v_cvt_pk_bf16_f32 v75, v86, v75
	v_addc_co_u32_e32 v81, vcc, 0, v161, vcc
	global_store_dwordx4 v[80:81], v[72:75], off
	v_pk_add_f32 v[10:11], v[10:11], v[66:67]
	v_pk_add_f32 v[4:5], v[4:5], v[52:53]
	v_rcp_f32_e32 v72, v79
	s_nop 0
	v_mul_f32_e32 v79, v61, v72
	v_mul_f32_e32 v72, 0xbfb8aa3b, v56
	v_mul_f32_e32 v73, 0xbfb8aa3b, v57
	v_exp_f32_e32 v72, v72
	v_exp_f32_e32 v73, v73
	s_nop 0
	v_pk_add_f32 v[72:73], v[72:73], 1.0 op_sel_hi:[1,0]
	v_rcp_f32_e32 v61, v78
	s_nop 0
	v_mul_f32_e32 v75, v60, v61
	v_pk_add_f32 v[0:1], v[0:1], v[48:49]
	v_rcp_f32_e32 v60, v73
	s_nop 0
	v_mul_f32_e32 v73, v57, v60
	v_mul_f32_e32 v60, 0xbfb8aa3b, v62
	v_mul_f32_e32 v61, 0xbfb8aa3b, v63
	v_exp_f32_e32 v60, v60
	v_exp_f32_e32 v61, v61
	s_nop 0
	v_pk_add_f32 v[60:61], v[60:61], 1.0 op_sel_hi:[1,0]
	v_rcp_f32_e32 v57, v72
	s_nop 0
	v_mul_f32_e32 v72, v56, v57
	v_pk_add_f32 v[6:7], v[6:7], v[54:55]
	v_rcp_f32_e32 v56, v61
	s_nop 0
	v_mul_f32_e32 v63, v63, v56
	v_mul_f32_e32 v57, 0xbfb8aa3b, v59
	v_mul_f32_e32 v56, 0xbfb8aa3b, v58
	v_exp_f32_e32 v56, v56
	v_exp_f32_e32 v57, v57
	s_nop 0
	v_pk_add_f32 v[56:57], v[56:57], 1.0 op_sel_hi:[1,0]
	v_rcp_f32_e32 v61, v60
	s_nop 0
	v_mul_f32_e32 v62, v62, v61
	v_pk_add_f32 v[2:3], v[2:3], v[50:51]
	v_rcp_f32_e32 v60, v57
	s_nop 0
	v_mul_f32_e32 v59, v59, v60
	v_pk_add_f32 v[60:61], v[44:45], v[68:69]
	v_rcp_f32_e32 v57, v56
	s_nop 0
	v_mul_f32_e32 v74, v58, v57
	v_mul_f32_e32 v44, 0xbfb8aa3b, v60
	v_mul_f32_e32 v45, 0xbfb8aa3b, v61
	v_exp_f32_e32 v44, v44
	v_exp_f32_e32 v45, v45
	v_cvt_pk_bf16_f32 v57, v62, v63
	v_cvt_pk_bf16_f32 v58, v72, v73
	v_cvt_pk_bf16_f32 v56, v75, v79
	v_pk_add_f32 v[62:63], v[44:45], 1.0 op_sel_hi:[1,0]
	v_cvt_pk_bf16_f32 v59, v74, v59
	global_store_dwordx4 v[76:77], v[56:59], off offset:256
	v_lshl_add_u64 v[44:45], v[160:161], 0, s[28:29]
	s_nop 0
	v_rcp_f32_e32 v56, v63
	s_nop 0
	v_mul_f32_e32 v61, v61, v56
	v_mul_f32_e32 v56, 0xbfb8aa3b, v40
	v_mul_f32_e32 v57, 0xbfb8aa3b, v41
	v_exp_f32_e32 v56, v56
	v_exp_f32_e32 v57, v57
	s_nop 0
	v_pk_add_f32 v[56:57], v[56:57], 1.0 op_sel_hi:[1,0]
	v_rcp_f32_e32 v58, v62
	s_nop 0
	v_mul_f32_e32 v60, v60, v58
	v_rcp_f32_e32 v58, v57
	s_nop 0
	v_mul_f32_e32 v57, v41, v58
	v_mul_f32_e32 v58, 0xbfb8aa3b, v46
	v_mul_f32_e32 v59, 0xbfb8aa3b, v47
	v_exp_f32_e32 v58, v58
	v_exp_f32_e32 v59, v59
	s_nop 0
	v_pk_add_f32 v[58:59], v[58:59], 1.0 op_sel_hi:[1,0]
	v_rcp_f32_e32 v41, v56
	s_nop 0
	v_mul_f32_e32 v56, v40, v41
	v_rcp_f32_e32 v40, v59
	s_nop 0
	v_mul_f32_e32 v59, v47, v40
	v_mul_f32_e32 v41, 0xbfb8aa3b, v43
	v_mul_f32_e32 v40, 0xbfb8aa3b, v42
	v_exp_f32_e32 v40, v40
	v_exp_f32_e32 v41, v41
	s_nop 0
	v_pk_add_f32 v[40:41], v[40:41], 1.0 op_sel_hi:[1,0]
	v_rcp_f32_e32 v47, v58
	s_nop 0
	v_mul_f32_e32 v58, v46, v47
	v_rcp_f32_e32 v46, v41
	s_nop 0
	v_mul_f32_e32 v43, v43, v46
	v_rcp_f32_e32 v41, v40
	s_nop 0
	v_mul_f32_e32 v62, v42, v41
	v_mul_f32_e32 v41, 0xbfb8aa3b, v36
	v_exp_f32_e32 v46, v41
	v_mul_f32_e32 v41, 0xbfb8aa3b, v37
	v_exp_f32_e32 v47, v41
	v_cvt_pk_bf16_f32 v41, v58, v59
	v_cvt_pk_bf16_f32 v42, v56, v57
	v_add_co_u32_e32 v56, vcc, s66, v160
	v_pk_add_f32 v[46:47], v[46:47], 1.0 op_sel_hi:[1,0]
	v_cvt_pk_bf16_f32 v40, v60, v61
	v_cvt_pk_bf16_f32 v43, v62, v43
	v_addc_co_u32_e32 v57, vcc, 0, v161, vcc
	global_store_dwordx4 v[56:57], v[40:43], off
	s_nop 1
	v_rcp_f32_e32 v40, v47
	s_nop 0
	v_mul_f32_e32 v47, v37, v40
	v_mul_f32_e32 v40, 0xbfb8aa3b, v32
	v_mul_f32_e32 v41, 0xbfb8aa3b, v33
	v_exp_f32_e32 v40, v40
	v_exp_f32_e32 v41, v41
	s_nop 0
	v_pk_add_f32 v[40:41], v[40:41], 1.0 op_sel_hi:[1,0]
	v_rcp_f32_e32 v37, v46
	s_nop 0
	v_mul_f32_e32 v43, v36, v37
	v_rcp_f32_e32 v36, v41
	s_nop 0
	v_mul_f32_e32 v41, v33, v36
	v_mul_f32_e32 v36, 0xbfb8aa3b, v38
	v_mul_f32_e32 v37, 0xbfb8aa3b, v39
	v_exp_f32_e32 v36, v36
	v_exp_f32_e32 v37, v37
	s_nop 0
	v_pk_add_f32 v[36:37], v[36:37], 1.0 op_sel_hi:[1,0]
	v_rcp_f32_e32 v33, v40
	s_nop 0
	v_mul_f32_e32 v40, v32, v33
	v_rcp_f32_e32 v32, v37
	s_nop 0
	v_mul_f32_e32 v39, v39, v32
	v_mul_f32_e32 v33, 0xbfb8aa3b, v35
	v_mul_f32_e32 v32, 0xbfb8aa3b, v34
	v_exp_f32_e32 v32, v32
	v_exp_f32_e32 v33, v33
	s_nop 0
	v_pk_add_f32 v[32:33], v[32:33], 1.0 op_sel_hi:[1,0]
	v_rcp_f32_e32 v37, v36
	s_nop 0
	v_mul_f32_e32 v38, v38, v37
	v_rcp_f32_e32 v36, v33
	s_nop 0
	v_mul_f32_e32 v35, v35, v36
	v_pk_add_f32 v[36:37], v[28:29], v[68:69]
	v_rcp_f32_e32 v33, v32
	s_nop 0
	v_mul_f32_e32 v42, v34, v33
	v_mul_f32_e32 v28, 0xbfb8aa3b, v36
	v_mul_f32_e32 v29, 0xbfb8aa3b, v37
	v_exp_f32_e32 v28, v28
	v_exp_f32_e32 v29, v29
	v_cvt_pk_bf16_f32 v33, v38, v39
	v_cvt_pk_bf16_f32 v34, v40, v41
	v_cvt_pk_bf16_f32 v32, v43, v47
	v_pk_add_f32 v[38:39], v[28:29], 1.0 op_sel_hi:[1,0]
	v_cvt_pk_bf16_f32 v35, v42, v35
	global_store_dwordx4 v[44:45], v[32:35], off offset:256
	v_lshl_add_u64 v[28:29], v[160:161], 0, s[46:47]
	s_nop 0
	v_rcp_f32_e32 v32, v39
	s_nop 0
	v_mul_f32_e32 v37, v37, v32
	v_mul_f32_e32 v32, 0xbfb8aa3b, v24
	v_mul_f32_e32 v33, 0xbfb8aa3b, v25
	v_exp_f32_e32 v32, v32
	v_exp_f32_e32 v33, v33
	s_nop 0
	v_pk_add_f32 v[32:33], v[32:33], 1.0 op_sel_hi:[1,0]
	v_rcp_f32_e32 v34, v38
	s_nop 0
	v_mul_f32_e32 v36, v36, v34
	v_rcp_f32_e32 v34, v33
	s_nop 0
	v_mul_f32_e32 v33, v25, v34
	v_mul_f32_e32 v34, 0xbfb8aa3b, v30
	v_mul_f32_e32 v35, 0xbfb8aa3b, v31
	v_exp_f32_e32 v34, v34
	v_exp_f32_e32 v35, v35
	s_nop 0
	v_pk_add_f32 v[34:35], v[34:35], 1.0 op_sel_hi:[1,0]
	v_rcp_f32_e32 v25, v32
	s_nop 0
	v_mul_f32_e32 v32, v24, v25
	v_rcp_f32_e32 v24, v35
	s_nop 0
	v_mul_f32_e32 v35, v31, v24
	v_mul_f32_e32 v25, 0xbfb8aa3b, v27
	v_mul_f32_e32 v24, 0xbfb8aa3b, v26
	v_exp_f32_e32 v24, v24
	v_exp_f32_e32 v25, v25
	s_nop 0
	v_pk_add_f32 v[24:25], v[24:25], 1.0 op_sel_hi:[1,0]
	v_rcp_f32_e32 v31, v34
	s_nop 0
	v_mul_f32_e32 v34, v30, v31
	v_rcp_f32_e32 v30, v25
	s_nop 0
	v_mul_f32_e32 v27, v27, v30
	v_rcp_f32_e32 v25, v24
	s_nop 0
	v_mul_f32_e32 v38, v26, v25
	v_mul_f32_e32 v25, 0xbfb8aa3b, v20
	v_exp_f32_e32 v30, v25
	v_mul_f32_e32 v25, 0xbfb8aa3b, v21
	v_exp_f32_e32 v31, v25
	v_cvt_pk_bf16_f32 v25, v34, v35
	v_cvt_pk_bf16_f32 v26, v32, v33
	v_add_co_u32_e32 v32, vcc, s67, v160
	v_pk_add_f32 v[30:31], v[30:31], 1.0 op_sel_hi:[1,0]
	v_cvt_pk_bf16_f32 v24, v36, v37
	v_cvt_pk_bf16_f32 v27, v38, v27
	v_addc_co_u32_e32 v33, vcc, 0, v161, vcc
	global_store_dwordx4 v[32:33], v[24:27], off
	s_nop 1
	v_rcp_f32_e32 v24, v31
	s_nop 0
	v_mul_f32_e32 v31, v21, v24
	v_mul_f32_e32 v24, 0xbfb8aa3b, v16
	v_mul_f32_e32 v25, 0xbfb8aa3b, v17
	v_exp_f32_e32 v24, v24
	v_exp_f32_e32 v25, v25
	s_nop 0
	v_pk_add_f32 v[24:25], v[24:25], 1.0 op_sel_hi:[1,0]
	v_rcp_f32_e32 v21, v30
	s_nop 0
	v_mul_f32_e32 v27, v20, v21
	v_rcp_f32_e32 v20, v25
	s_nop 0
	v_mul_f32_e32 v25, v17, v20
	v_mul_f32_e32 v20, 0xbfb8aa3b, v22
	v_mul_f32_e32 v21, 0xbfb8aa3b, v23
	v_exp_f32_e32 v20, v20
	v_exp_f32_e32 v21, v21
	s_nop 0
	v_pk_add_f32 v[20:21], v[20:21], 1.0 op_sel_hi:[1,0]
	v_rcp_f32_e32 v17, v24
	s_nop 0
	v_mul_f32_e32 v24, v16, v17
	v_rcp_f32_e32 v16, v21
	s_nop 0
	v_mul_f32_e32 v23, v23, v16
	v_mul_f32_e32 v17, 0xbfb8aa3b, v19
	v_mul_f32_e32 v16, 0xbfb8aa3b, v18
	v_exp_f32_e32 v16, v16
	v_exp_f32_e32 v17, v17
	s_nop 0
	v_pk_add_f32 v[16:17], v[16:17], 1.0 op_sel_hi:[1,0]
	v_rcp_f32_e32 v21, v20
	s_nop 0
	v_mul_f32_e32 v22, v22, v21
	v_rcp_f32_e32 v20, v17
	s_nop 0
	v_mul_f32_e32 v19, v19, v20
	v_pk_add_f32 v[20:21], v[12:13], v[68:69]
	v_rcp_f32_e32 v17, v16
	s_nop 0
	v_mul_f32_e32 v26, v18, v17
	v_mul_f32_e32 v12, 0xbfb8aa3b, v20
	v_mul_f32_e32 v13, 0xbfb8aa3b, v21
	v_exp_f32_e32 v12, v12
	v_exp_f32_e32 v13, v13
	v_cvt_pk_bf16_f32 v17, v22, v23
	v_cvt_pk_bf16_f32 v18, v24, v25
	v_cvt_pk_bf16_f32 v16, v27, v31
	v_pk_add_f32 v[22:23], v[12:13], 1.0 op_sel_hi:[1,0]
	v_cvt_pk_bf16_f32 v19, v26, v19
	global_store_dwordx4 v[28:29], v[16:19], off offset:256
	v_lshl_add_u64 v[12:13], v[160:161], 0, s[52:53]
	s_nop 0
	v_rcp_f32_e32 v16, v23
	s_nop 0
	v_mul_f32_e32 v21, v21, v16
	v_mul_f32_e32 v16, 0xbfb8aa3b, v8
	v_mul_f32_e32 v17, 0xbfb8aa3b, v9
	v_exp_f32_e32 v16, v16
	v_exp_f32_e32 v17, v17
	s_nop 0
	v_pk_add_f32 v[16:17], v[16:17], 1.0 op_sel_hi:[1,0]
	v_rcp_f32_e32 v18, v22
	s_nop 0
	v_mul_f32_e32 v20, v20, v18
	v_rcp_f32_e32 v18, v17
	s_nop 0
	v_mul_f32_e32 v17, v9, v18
	v_mul_f32_e32 v18, 0xbfb8aa3b, v14
	v_mul_f32_e32 v19, 0xbfb8aa3b, v15
	v_exp_f32_e32 v18, v18
	v_exp_f32_e32 v19, v19
	s_nop 0
	v_pk_add_f32 v[18:19], v[18:19], 1.0 op_sel_hi:[1,0]
	v_rcp_f32_e32 v9, v16
	s_nop 0
	v_mul_f32_e32 v16, v8, v9
	v_rcp_f32_e32 v8, v19
	s_nop 0
	v_mul_f32_e32 v19, v15, v8
	v_mul_f32_e32 v9, 0xbfb8aa3b, v11
	v_mul_f32_e32 v8, 0xbfb8aa3b, v10
	v_exp_f32_e32 v8, v8
	v_exp_f32_e32 v9, v9
	s_nop 0
	v_pk_add_f32 v[8:9], v[8:9], 1.0 op_sel_hi:[1,0]
	v_rcp_f32_e32 v15, v18
	s_nop 0
	v_mul_f32_e32 v18, v14, v15
	v_rcp_f32_e32 v14, v9
	s_nop 0
	v_mul_f32_e32 v11, v11, v14
	v_rcp_f32_e32 v9, v8
	s_nop 0
	v_mul_f32_e32 v22, v10, v9
	v_mul_f32_e32 v9, 0xbfb8aa3b, v4
	v_exp_f32_e32 v14, v9
	v_mul_f32_e32 v9, 0xbfb8aa3b, v5
	v_exp_f32_e32 v15, v9
	v_cvt_pk_bf16_f32 v9, v18, v19
	v_cvt_pk_bf16_f32 v10, v16, v17
	v_add_co_u32_e32 v16, vcc, s76, v160
	v_pk_add_f32 v[14:15], v[14:15], 1.0 op_sel_hi:[1,0]
	v_cvt_pk_bf16_f32 v8, v20, v21
	v_cvt_pk_bf16_f32 v11, v22, v11
	v_addc_co_u32_e32 v17, vcc, 0, v161, vcc
	global_store_dwordx4 v[16:17], v[8:11], off
	s_nop 1
	v_rcp_f32_e32 v8, v15
	s_nop 0
	v_mul_f32_e32 v15, v5, v8
	v_mul_f32_e32 v8, 0xbfb8aa3b, v0
	v_mul_f32_e32 v9, 0xbfb8aa3b, v1
	v_exp_f32_e32 v8, v8
	v_exp_f32_e32 v9, v9
	s_nop 0
	v_pk_add_f32 v[8:9], v[8:9], 1.0 op_sel_hi:[1,0]
	v_rcp_f32_e32 v5, v14
	s_nop 0
	v_mul_f32_e32 v11, v4, v5
	v_rcp_f32_e32 v4, v9
	s_nop 0
	v_mul_f32_e32 v9, v1, v4
	v_mul_f32_e32 v4, 0xbfb8aa3b, v6
	v_mul_f32_e32 v5, 0xbfb8aa3b, v7
	v_exp_f32_e32 v4, v4
	v_exp_f32_e32 v5, v5
	s_nop 0
	v_pk_add_f32 v[4:5], v[4:5], 1.0 op_sel_hi:[1,0]
	v_rcp_f32_e32 v1, v8
	s_nop 0
	v_mul_f32_e32 v8, v0, v1
	v_rcp_f32_e32 v0, v5
	s_nop 0
	v_mul_f32_e32 v5, v7, v0
	v_mul_f32_e32 v1, 0xbfb8aa3b, v3
	v_mul_f32_e32 v0, 0xbfb8aa3b, v2
	v_exp_f32_e32 v0, v0
	v_exp_f32_e32 v1, v1
	s_nop 0
	v_pk_add_f32 v[0:1], v[0:1], 1.0 op_sel_hi:[1,0]
	v_rcp_f32_e32 v7, v4
	s_nop 0
	v_mul_f32_e32 v4, v6, v7
	v_rcp_f32_e32 v6, v1
	s_nop 0
	v_mul_f32_e32 v3, v3, v6
	s_mov_b64 s[0:1], -1
	v_rcp_f32_e32 v1, v0
	s_nop 0
	v_mul_f32_e32 v6, v2, v1
	v_cvt_pk_bf16_f32 v0, v11, v15
	v_cvt_pk_bf16_f32 v1, v4, v5
	v_cvt_pk_bf16_f32 v2, v8, v9
	v_cvt_pk_bf16_f32 v3, v6, v3
	global_store_dwordx4 v[12:13], v[0:3], off offset:256
	s_waitcnt vmcnt(0)
	s_andn2_b64 vcc, exec, s[54:55]
	s_cbranch_vccnz .LBB0_831
	s_andn2_b64 vcc, exec, s[20:21]
	s_cbranch_vccnz .LBB0_830
	s_barrier
	s_branch .LBB0_830

.LBB0_869:
	s_lshl_b32 s6, s1, 8
	s_ashr_i32 s7, s6, 31
	v_lshl_add_u64 v[28:29], s[6:7], 2, v[152:153]
	global_load_dwordx4 v[44:47], v[28:29], off
	global_load_dwordx4 v[40:43], v[28:29], off offset:16
	global_load_dwordx4 v[24:27], v[28:29], off offset:528
	s_nop 0
	global_load_dwordx4 v[28:31], v[28:29], off offset:512
	s_cmp_gt_i32 s1, 0
	v_lshl_add_u32 v162, s0, 8, v168
	s_cselect_b64 s[6:7], -1, 0
	v_ashrrev_i32_e32 v163, 31, v162
	s_cmp_lg_u64 s[6:7], 0
	v_lshlrev_b64 v[160:161], 9, v[162:163]
	s_subb_u32 s0, s1, 0
	s_lshl_b32 s0, s0, 8
	s_ashr_i32 s1, s0, 31
	v_lshl_add_u64 v[164:165], s[0:1], 1, v[154:155]
	v_lshl_add_u64 v[160:161], v[164:165], 0, v[160:161]
	s_waitcnt vmcnt(0)
	v_pk_add_f32 v[140:141], v[140:141], v[44:45]
	v_pk_add_f32 v[166:167], v[136:137], v[40:41]
	v_mul_f32_e32 v136, 0xbfb8aa3b, v140
	v_mul_f32_e32 v137, 0xbfb8aa3b, v141
	v_pk_add_f32 v[142:143], v[142:143], v[46:47]
	v_exp_f32_e32 v174, v136
	v_exp_f32_e32 v175, v137
	v_mul_f32_e32 v178, 0xbfb8aa3b, v142
	v_mul_f32_e32 v179, 0xbfb8aa3b, v143
	v_mul_f32_e32 v163, 0xbfb8aa3b, v166
	v_mul_f32_e32 v173, 0xbfb8aa3b, v167
	v_exp_f32_e32 v178, v178
	v_exp_f32_e32 v179, v179
	v_exp_f32_e32 v176, v163
	v_exp_f32_e32 v177, v173
	v_pk_add_f32 v[174:175], v[174:175], 1.0 op_sel_hi:[1,0]
	v_pk_add_f32 v[136:137], v[138:139], v[42:43]
	v_pk_add_f32 v[138:139], v[178:179], 1.0 op_sel_hi:[1,0]
	v_pk_add_f32 v[176:177], v[176:177], 1.0 op_sel_hi:[1,0]
	s_mov_b64 vcc, s[10:11]
	v_rcp_f32_e32 v163, v175
	s_nop 0
	v_mul_f32_e32 v163, v141, v163
	v_rcp_f32_e32 v141, v174
	s_nop 0
	v_mul_f32_e32 v173, v140, v141
	s_mov_b64 vcc, s[8:9]
	s_mov_b64 vcc, s[0:1]
	v_rcp_f32_e32 v140, v177
	s_nop 0
	v_mul_f32_e32 v167, v167, v140
	s_mov_b64 vcc, s[6:7]
	v_rcp_f32_e32 v140, v176
	s_nop 0
	v_mul_f32_e32 v166, v166, v140
	v_rcp_f32_e32 v140, v139
	s_nop 0
	v_mul_f32_e32 v139, v143, v140
	v_mul_f32_e32 v140, 0xbfb8aa3b, v136
	v_mul_f32_e32 v141, 0xbfb8aa3b, v137
	v_exp_f32_e32 v140, v140
	v_exp_f32_e32 v141, v141
	s_nop 0
	v_pk_add_f32 v[140:141], v[140:141], 1.0 op_sel_hi:[1,0]
	v_rcp_f32_e32 v143, v138
	s_nop 0
	v_mul_f32_e32 v138, v142, v143
	v_rcp_f32_e32 v142, v141
	s_nop 0
	v_mul_f32_e32 v176, v137, v142
	v_rcp_f32_e32 v137, v140
	s_nop 0
	v_mul_f32_e32 v174, v136, v137
	v_pk_add_f32 v[140:141], v[132:133], v[28:29]
	v_cvt_pk_bf16_f32 v136, v173, v163
	v_mul_f32_e32 v132, 0xbfb8aa3b, v140
	v_mul_f32_e32 v133, 0xbfb8aa3b, v141
	v_exp_f32_e32 v132, v132
	v_exp_f32_e32 v133, v133
	v_cvt_pk_bf16_f32 v137, v138, v139
	v_cvt_pk_bf16_f32 v138, v166, v167
	v_cvt_pk_bf16_f32 v139, v174, v176
	v_pk_add_f32 v[142:143], v[132:133], 1.0 op_sel_hi:[1,0]
	v_pk_add_f32 v[132:133], v[134:135], v[30:31]
	global_store_dwordx4 v[160:161], v[136:139], off
	v_pk_add_f32 v[126:127], v[126:127], v[46:47]
	v_pk_add_f32 v[110:111], v[110:111], v[46:47]
	v_rcp_f32_e32 v134, v143
	s_nop 0
	v_mul_f32_e32 v139, v141, v134
	v_pk_add_f32 v[134:135], v[128:129], v[24:25]
	v_mul_f32_e32 v128, 0xbfb8aa3b, v134
	v_mul_f32_e32 v129, 0xbfb8aa3b, v135
	v_exp_f32_e32 v128, v128
	v_exp_f32_e32 v129, v129
	s_nop 0
	v_pk_add_f32 v[136:137], v[128:129], 1.0 op_sel_hi:[1,0]
	v_rcp_f32_e32 v128, v142
	s_nop 0
	v_mul_f32_e32 v138, v140, v128
	v_pk_add_f32 v[128:129], v[130:131], v[26:27]
	v_pk_add_f32 v[94:95], v[94:95], v[46:47]
	v_rcp_f32_e32 v130, v137
	s_nop 0
	v_mul_f32_e32 v137, v135, v130
	v_mul_f32_e32 v130, 0xbfb8aa3b, v132
	v_mul_f32_e32 v131, 0xbfb8aa3b, v133
	v_exp_f32_e32 v130, v130
	v_exp_f32_e32 v131, v131
	s_nop 0
	v_pk_add_f32 v[130:131], v[130:131], 1.0 op_sel_hi:[1,0]
	v_rcp_f32_e32 v135, v136
	s_nop 0
	v_mul_f32_e32 v136, v134, v135
	v_pk_add_f32 v[78:79], v[78:79], v[46:47]
	v_rcp_f32_e32 v134, v131
	s_nop 0
	v_mul_f32_e32 v131, v133, v134
	v_mul_f32_e32 v134, 0xbfb8aa3b, v128
	v_mul_f32_e32 v135, 0xbfb8aa3b, v129
	v_exp_f32_e32 v134, v134
	v_exp_f32_e32 v135, v135
	s_nop 0
	v_pk_add_f32 v[134:135], v[134:135], 1.0 op_sel_hi:[1,0]
	v_rcp_f32_e32 v133, v130
	s_nop 0
	v_mul_f32_e32 v130, v132, v133
	s_mov_b32 s6, 0x10000
	v_rcp_f32_e32 v132, v135
	s_nop 0
	v_mul_f32_e32 v132, v129, v132
	v_pk_add_f32 v[62:63], v[62:63], v[46:47]
	v_rcp_f32_e32 v129, v134
	s_nop 0
	v_mul_f32_e32 v133, v128, v129
	v_cvt_pk_bf16_f32 v129, v130, v131
	v_cvt_pk_bf16_f32 v131, v133, v132
	v_pk_add_f32 v[132:133], v[124:125], v[44:45]
	v_cvt_pk_bf16_f32 v128, v138, v139
	v_mul_f32_e32 v124, 0xbfb8aa3b, v132
	v_mul_f32_e32 v125, 0xbfb8aa3b, v133
	v_exp_f32_e32 v124, v124
	v_exp_f32_e32 v125, v125
	v_cvt_pk_bf16_f32 v130, v136, v137
	global_store_dwordx4 v[160:161], v[128:131], off offset:256
	v_pk_add_f32 v[38:39], v[38:39], v[46:47]
	v_pk_add_f32 v[14:15], v[14:15], v[46:47]
	v_pk_add_f32 v[130:131], v[124:125], 1.0 op_sel_hi:[1,0]
	v_or_b32_e32 v128, 16, v162
	v_ashrrev_i32_e32 v129, 31, v128
	v_lshlrev_b64 v[124:125], 9, v[128:129]
	v_lshl_add_u64 v[124:125], v[164:165], 0, v[124:125]
	v_rcp_f32_e32 v128, v131
	s_nop 0
	v_mul_f32_e32 v131, v133, v128
	v_pk_add_f32 v[128:129], v[120:121], v[40:41]
	v_mul_f32_e32 v120, 0xbfb8aa3b, v128
	v_mul_f32_e32 v121, 0xbfb8aa3b, v129
	v_exp_f32_e32 v120, v120
	v_exp_f32_e32 v121, v121
	s_nop 0
	v_pk_add_f32 v[134:135], v[120:121], 1.0 op_sel_hi:[1,0]
	v_rcp_f32_e32 v120, v130
	s_nop 0
	v_mul_f32_e32 v130, v132, v120
	v_pk_add_f32 v[120:121], v[122:123], v[42:43]
	v_rcp_f32_e32 v122, v135
	s_nop 0
	v_mul_f32_e32 v135, v129, v122
	v_mul_f32_e32 v122, 0xbfb8aa3b, v126
	v_mul_f32_e32 v123, 0xbfb8aa3b, v127
	v_exp_f32_e32 v122, v122
	v_exp_f32_e32 v123, v123
	s_nop 0
	v_pk_add_f32 v[122:123], v[122:123], 1.0 op_sel_hi:[1,0]
	v_rcp_f32_e32 v129, v134
	s_nop 0
	v_mul_f32_e32 v133, v128, v129
	v_rcp_f32_e32 v128, v123
	s_nop 0
	v_mul_f32_e32 v123, v127, v128
	v_mul_f32_e32 v128, 0xbfb8aa3b, v120
	v_mul_f32_e32 v129, 0xbfb8aa3b, v121
	v_exp_f32_e32 v128, v128
	v_exp_f32_e32 v129, v129
	s_nop 0
	v_pk_add_f32 v[128:129], v[128:129], 1.0 op_sel_hi:[1,0]
	v_rcp_f32_e32 v127, v122
	s_nop 0
	v_mul_f32_e32 v122, v126, v127
	v_rcp_f32_e32 v126, v129
	s_nop 0
	v_mul_f32_e32 v136, v121, v126
	v_pk_add_f32 v[126:127], v[116:117], v[28:29]
	v_rcp_f32_e32 v121, v128
	s_nop 0
	v_mul_f32_e32 v132, v120, v121
	v_mul_f32_e32 v116, 0xbfb8aa3b, v126
	v_mul_f32_e32 v117, 0xbfb8aa3b, v127
	v_exp_f32_e32 v116, v116
	v_exp_f32_e32 v117, v117
	v_cvt_pk_bf16_f32 v120, v130, v131
	v_cvt_pk_bf16_f32 v121, v122, v123
	v_cvt_pk_bf16_f32 v122, v133, v135
	v_pk_add_f32 v[128:129], v[116:117], 1.0 op_sel_hi:[1,0]
	v_pk_add_f32 v[116:117], v[118:119], v[30:31]
	v_cvt_pk_bf16_f32 v123, v132, v136
	global_store_dwordx4 v[124:125], v[120:123], off
	v_rcp_f32_e32 v118, v129
	s_nop 0
	v_mul_f32_e32 v123, v127, v118
	v_pk_add_f32 v[118:119], v[112:113], v[24:25]
	v_mul_f32_e32 v112, 0xbfb8aa3b, v118
	v_mul_f32_e32 v113, 0xbfb8aa3b, v119
	v_exp_f32_e32 v112, v112
	v_exp_f32_e32 v113, v113
	s_nop 0
	v_pk_add_f32 v[120:121], v[112:113], 1.0 op_sel_hi:[1,0]
	v_rcp_f32_e32 v112, v128
	s_nop 0
	v_mul_f32_e32 v122, v126, v112
	v_pk_add_f32 v[112:113], v[114:115], v[26:27]
	v_rcp_f32_e32 v114, v121
	s_nop 0
	v_mul_f32_e32 v121, v119, v114
	v_mul_f32_e32 v114, 0xbfb8aa3b, v116
	v_mul_f32_e32 v115, 0xbfb8aa3b, v117
	v_exp_f32_e32 v114, v114
	v_exp_f32_e32 v115, v115
	s_nop 0
	v_pk_add_f32 v[114:115], v[114:115], 1.0 op_sel_hi:[1,0]
	v_rcp_f32_e32 v119, v120
	s_nop 0
	v_mul_f32_e32 v120, v118, v119
	v_rcp_f32_e32 v118, v115
	s_nop 0
	v_mul_f32_e32 v115, v117, v118
	v_mul_f32_e32 v118, 0xbfb8aa3b, v112
	v_mul_f32_e32 v119, 0xbfb8aa3b, v113
	v_exp_f32_e32 v118, v118
	v_exp_f32_e32 v119, v119
	s_nop 0
	v_pk_add_f32 v[118:119], v[118:119], 1.0 op_sel_hi:[1,0]
	v_rcp_f32_e32 v117, v114
	s_nop 0
	v_mul_f32_e32 v114, v116, v117
	v_rcp_f32_e32 v116, v119
	s_nop 0
	v_mul_f32_e32 v116, v113, v116
	v_rcp_f32_e32 v113, v118
	s_nop 0
	v_mul_f32_e32 v117, v112, v113
	v_cvt_pk_bf16_f32 v113, v114, v115
	v_cvt_pk_bf16_f32 v115, v117, v116
	v_pk_add_f32 v[116:117], v[108:109], v[44:45]
	v_cvt_pk_bf16_f32 v112, v122, v123
	v_mul_f32_e32 v108, 0xbfb8aa3b, v116
	v_mul_f32_e32 v109, 0xbfb8aa3b, v117
	v_exp_f32_e32 v108, v108
	v_exp_f32_e32 v109, v109
	v_cvt_pk_bf16_f32 v114, v120, v121
	global_store_dwordx4 v[124:125], v[112:115], off offset:256
	s_nop 1
	v_pk_add_f32 v[114:115], v[108:109], 1.0 op_sel_hi:[1,0]
	v_or_b32_e32 v112, 32, v162
	v_ashrrev_i32_e32 v113, 31, v112
	v_lshlrev_b64 v[108:109], 9, v[112:113]
	v_lshl_add_u64 v[108:109], v[164:165], 0, v[108:109]
	v_rcp_f32_e32 v112, v115
	s_nop 0
	v_mul_f32_e32 v115, v117, v112
	v_pk_add_f32 v[112:113], v[104:105], v[40:41]
	v_mul_f32_e32 v104, 0xbfb8aa3b, v112
	v_mul_f32_e32 v105, 0xbfb8aa3b, v113
	v_exp_f32_e32 v104, v104
	v_exp_f32_e32 v105, v105
	s_nop 0
	v_pk_add_f32 v[118:119], v[104:105], 1.0 op_sel_hi:[1,0]
	v_rcp_f32_e32 v104, v114
	s_nop 0
	v_mul_f32_e32 v114, v116, v104
	v_pk_add_f32 v[104:105], v[106:107], v[42:43]
	v_rcp_f32_e32 v106, v119
	s_nop 0
	v_mul_f32_e32 v119, v113, v106
	v_mul_f32_e32 v106, 0xbfb8aa3b, v110
	v_mul_f32_e32 v107, 0xbfb8aa3b, v111
	v_exp_f32_e32 v106, v106
	v_exp_f32_e32 v107, v107
	s_nop 0
	v_pk_add_f32 v[106:107], v[106:107], 1.0 op_sel_hi:[1,0]
	v_rcp_f32_e32 v113, v118
	s_nop 0
	v_mul_f32_e32 v117, v112, v113
	v_rcp_f32_e32 v112, v107
	s_nop 0
	v_mul_f32_e32 v107, v111, v112
	v_mul_f32_e32 v112, 0xbfb8aa3b, v104
	v_mul_f32_e32 v113, 0xbfb8aa3b, v105
	v_exp_f32_e32 v112, v112
	v_exp_f32_e32 v113, v113
	s_nop 0
	v_pk_add_f32 v[112:113], v[112:113], 1.0 op_sel_hi:[1,0]
	v_rcp_f32_e32 v111, v106
	s_nop 0
	v_mul_f32_e32 v106, v110, v111
	v_rcp_f32_e32 v110, v113
	s_nop 0
	v_mul_f32_e32 v120, v105, v110
	v_pk_add_f32 v[110:111], v[100:101], v[28:29]
	v_rcp_f32_e32 v105, v112
	s_nop 0
	v_mul_f32_e32 v116, v104, v105
	v_mul_f32_e32 v100, 0xbfb8aa3b, v110
	v_mul_f32_e32 v101, 0xbfb8aa3b, v111
	v_exp_f32_e32 v100, v100
	v_exp_f32_e32 v101, v101
	v_cvt_pk_bf16_f32 v104, v114, v115
	v_cvt_pk_bf16_f32 v105, v106, v107
	v_cvt_pk_bf16_f32 v106, v117, v119
	v_pk_add_f32 v[112:113], v[100:101], 1.0 op_sel_hi:[1,0]
	v_pk_add_f32 v[100:101], v[102:103], v[30:31]
	v_cvt_pk_bf16_f32 v107, v116, v120
	global_store_dwordx4 v[108:109], v[104:107], off
	v_rcp_f32_e32 v102, v113
	s_nop 0
	v_mul_f32_e32 v107, v111, v102
	v_pk_add_f32 v[102:103], v[96:97], v[24:25]
	v_mul_f32_e32 v96, 0xbfb8aa3b, v102
	v_mul_f32_e32 v97, 0xbfb8aa3b, v103
	v_exp_f32_e32 v96, v96
	v_exp_f32_e32 v97, v97
	s_nop 0
	v_pk_add_f32 v[104:105], v[96:97], 1.0 op_sel_hi:[1,0]
	v_rcp_f32_e32 v96, v112
	s_nop 0
	v_mul_f32_e32 v106, v110, v96
	v_pk_add_f32 v[96:97], v[98:99], v[26:27]
	v_rcp_f32_e32 v98, v105
	s_nop 0
	v_mul_f32_e32 v105, v103, v98
	v_mul_f32_e32 v98, 0xbfb8aa3b, v100
	v_mul_f32_e32 v99, 0xbfb8aa3b, v101
	v_exp_f32_e32 v98, v98
	v_exp_f32_e32 v99, v99
	s_nop 0
	v_pk_add_f32 v[98:99], v[98:99], 1.0 op_sel_hi:[1,0]
	v_rcp_f32_e32 v103, v104
	s_nop 0
	v_mul_f32_e32 v104, v102, v103
	v_rcp_f32_e32 v102, v99
	s_nop 0
	v_mul_f32_e32 v99, v101, v102
	v_mul_f32_e32 v102, 0xbfb8aa3b, v96
	v_mul_f32_e32 v103, 0xbfb8aa3b, v97
	v_exp_f32_e32 v102, v102
	v_exp_f32_e32 v103, v103
	s_nop 0
	v_pk_add_f32 v[102:103], v[102:103], 1.0 op_sel_hi:[1,0]
	v_rcp_f32_e32 v101, v98
	s_nop 0
	v_mul_f32_e32 v98, v100, v101
	v_rcp_f32_e32 v100, v103
	s_nop 0
	v_mul_f32_e32 v100, v97, v100
	v_rcp_f32_e32 v97, v102
	s_nop 0
	v_mul_f32_e32 v101, v96, v97
	v_cvt_pk_bf16_f32 v97, v98, v99
	v_cvt_pk_bf16_f32 v99, v101, v100
	v_pk_add_f32 v[100:101], v[92:93], v[44:45]
	v_cvt_pk_bf16_f32 v96, v106, v107
	v_mul_f32_e32 v92, 0xbfb8aa3b, v100
	v_mul_f32_e32 v93, 0xbfb8aa3b, v101
	v_exp_f32_e32 v92, v92
	v_exp_f32_e32 v93, v93
	v_cvt_pk_bf16_f32 v98, v104, v105
	global_store_dwordx4 v[108:109], v[96:99], off offset:256
	s_nop 1
	v_pk_add_f32 v[98:99], v[92:93], 1.0 op_sel_hi:[1,0]
	v_or_b32_e32 v96, 48, v162
	v_ashrrev_i32_e32 v97, 31, v96
	v_lshlrev_b64 v[92:93], 9, v[96:97]
	v_lshl_add_u64 v[92:93], v[164:165], 0, v[92:93]
	v_rcp_f32_e32 v96, v99
	s_nop 0
	v_mul_f32_e32 v99, v101, v96
	v_pk_add_f32 v[96:97], v[88:89], v[40:41]
	v_mul_f32_e32 v88, 0xbfb8aa3b, v96
	v_mul_f32_e32 v89, 0xbfb8aa3b, v97
	v_exp_f32_e32 v88, v88
	v_exp_f32_e32 v89, v89
	s_nop 0
	v_pk_add_f32 v[102:103], v[88:89], 1.0 op_sel_hi:[1,0]
	v_rcp_f32_e32 v88, v98
	s_nop 0
	v_mul_f32_e32 v98, v100, v88
	v_pk_add_f32 v[88:89], v[90:91], v[42:43]
	v_rcp_f32_e32 v90, v103
	s_nop 0
	v_mul_f32_e32 v103, v97, v90
	v_mul_f32_e32 v90, 0xbfb8aa3b, v94
	v_mul_f32_e32 v91, 0xbfb8aa3b, v95
	v_exp_f32_e32 v90, v90
	v_exp_f32_e32 v91, v91
	s_nop 0
	v_pk_add_f32 v[90:91], v[90:91], 1.0 op_sel_hi:[1,0]
	v_rcp_f32_e32 v97, v102
	s_nop 0
	v_mul_f32_e32 v101, v96, v97
	v_rcp_f32_e32 v96, v91
	s_nop 0
	v_mul_f32_e32 v91, v95, v96
	v_mul_f32_e32 v96, 0xbfb8aa3b, v88
	v_mul_f32_e32 v97, 0xbfb8aa3b, v89
	v_exp_f32_e32 v96, v96
	v_exp_f32_e32 v97, v97
	s_nop 0
	v_pk_add_f32 v[96:97], v[96:97], 1.0 op_sel_hi:[1,0]
	v_rcp_f32_e32 v95, v90
	s_nop 0
	v_mul_f32_e32 v90, v94, v95
	v_rcp_f32_e32 v94, v97
	s_nop 0
	v_mul_f32_e32 v104, v89, v94
	v_pk_add_f32 v[94:95], v[84:85], v[28:29]
	v_rcp_f32_e32 v89, v96
	s_nop 0
	v_mul_f32_e32 v100, v88, v89
	v_mul_f32_e32 v84, 0xbfb8aa3b, v94
	v_mul_f32_e32 v85, 0xbfb8aa3b, v95
	v_exp_f32_e32 v84, v84
	v_exp_f32_e32 v85, v85
	v_cvt_pk_bf16_f32 v88, v98, v99
	v_cvt_pk_bf16_f32 v89, v90, v91
	v_cvt_pk_bf16_f32 v90, v101, v103
	v_pk_add_f32 v[96:97], v[84:85], 1.0 op_sel_hi:[1,0]
	v_pk_add_f32 v[84:85], v[86:87], v[30:31]
	v_cvt_pk_bf16_f32 v91, v100, v104
	global_store_dwordx4 v[92:93], v[88:91], off
	v_rcp_f32_e32 v86, v97
	s_nop 0
	v_mul_f32_e32 v91, v95, v86
	v_pk_add_f32 v[86:87], v[80:81], v[24:25]
	v_mul_f32_e32 v80, 0xbfb8aa3b, v86
	v_mul_f32_e32 v81, 0xbfb8aa3b, v87
	v_exp_f32_e32 v80, v80
	v_exp_f32_e32 v81, v81
	s_nop 0
	v_pk_add_f32 v[88:89], v[80:81], 1.0 op_sel_hi:[1,0]
	v_rcp_f32_e32 v80, v96
	s_nop 0
	v_mul_f32_e32 v90, v94, v80
	v_pk_add_f32 v[80:81], v[82:83], v[26:27]
	v_rcp_f32_e32 v82, v89
	s_nop 0
	v_mul_f32_e32 v89, v87, v82
	v_mul_f32_e32 v82, 0xbfb8aa3b, v84
	v_mul_f32_e32 v83, 0xbfb8aa3b, v85
	v_exp_f32_e32 v82, v82
	v_exp_f32_e32 v83, v83
	s_nop 0
	v_pk_add_f32 v[82:83], v[82:83], 1.0 op_sel_hi:[1,0]
	v_rcp_f32_e32 v87, v88
	s_nop 0
	v_mul_f32_e32 v88, v86, v87
	v_rcp_f32_e32 v86, v83
	s_nop 0
	v_mul_f32_e32 v83, v85, v86
	v_mul_f32_e32 v86, 0xbfb8aa3b, v80
	v_mul_f32_e32 v87, 0xbfb8aa3b, v81
	v_exp_f32_e32 v86, v86
	v_exp_f32_e32 v87, v87
	s_nop 0
	v_pk_add_f32 v[86:87], v[86:87], 1.0 op_sel_hi:[1,0]
	v_rcp_f32_e32 v85, v82
	s_nop 0
	v_mul_f32_e32 v82, v84, v85
	v_rcp_f32_e32 v84, v87
	s_nop 0
	v_mul_f32_e32 v87, v81, v84
	v_pk_add_f32 v[84:85], v[76:77], v[44:45]
	v_rcp_f32_e32 v81, v86
	s_nop 0
	v_mul_f32_e32 v86, v80, v81
	v_mul_f32_e32 v76, 0xbfb8aa3b, v84
	v_mul_f32_e32 v77, 0xbfb8aa3b, v85
	v_exp_f32_e32 v76, v76
	v_exp_f32_e32 v77, v77
	v_cvt_pk_bf16_f32 v80, v90, v91
	v_cvt_pk_bf16_f32 v81, v82, v83
	v_cvt_pk_bf16_f32 v82, v88, v89
	v_cvt_pk_bf16_f32 v83, v86, v87
	global_store_dwordx4 v[92:93], v[80:83], off offset:256
	s_nop 1
	v_pk_add_f32 v[80:81], v[76:77], 1.0 op_sel_hi:[1,0]
	s_nop 0
	s_mov_b64 s[0:1], 0x10000
	v_lshl_add_u64 v[76:77], v[160:161], 0, s[0:1]
	v_rcp_f32_e32 v82, v81
	s_nop 0
	v_mul_f32_e32 v85, v85, v82
	v_pk_add_f32 v[82:83], v[72:73], v[40:41]
	v_mul_f32_e32 v72, 0xbfb8aa3b, v82
	v_mul_f32_e32 v73, 0xbfb8aa3b, v83
	v_exp_f32_e32 v72, v72
	v_exp_f32_e32 v73, v73
	s_nop 0
	v_pk_add_f32 v[86:87], v[72:73], 1.0 op_sel_hi:[1,0]
	v_rcp_f32_e32 v72, v80
	s_nop 0
	v_mul_f32_e32 v84, v84, v72
	v_pk_add_f32 v[72:73], v[74:75], v[42:43]
	v_rcp_f32_e32 v74, v87
	s_nop 0
	v_mul_f32_e32 v83, v83, v74
	v_mul_f32_e32 v74, 0xbfb8aa3b, v78
	v_mul_f32_e32 v75, 0xbfb8aa3b, v79
	v_exp_f32_e32 v74, v74
	v_exp_f32_e32 v75, v75
	s_nop 0
	v_pk_add_f32 v[74:75], v[74:75], 1.0 op_sel_hi:[1,0]
	v_rcp_f32_e32 v80, v86
	s_nop 0
	v_mul_f32_e32 v82, v82, v80
	v_rcp_f32_e32 v80, v75
	s_nop 0
	v_mul_f32_e32 v75, v79, v80
	v_mul_f32_e32 v80, 0xbfb8aa3b, v72
	v_mul_f32_e32 v81, 0xbfb8aa3b, v73
	v_exp_f32_e32 v80, v80
	v_exp_f32_e32 v81, v81
	s_nop 0
	v_pk_add_f32 v[80:81], v[80:81], 1.0 op_sel_hi:[1,0]
	v_rcp_f32_e32 v79, v74
	s_nop 0
	v_mul_f32_e32 v74, v78, v79
	v_rcp_f32_e32 v78, v81
	s_nop 0
	v_mul_f32_e32 v81, v73, v78
	v_pk_add_f32 v[78:79], v[68:69], v[28:29]
	v_rcp_f32_e32 v73, v80
	s_nop 0
	v_mul_f32_e32 v80, v72, v73
	v_mul_f32_e32 v68, 0xbfb8aa3b, v78
	v_mul_f32_e32 v69, 0xbfb8aa3b, v79
	v_exp_f32_e32 v68, v68
	v_exp_f32_e32 v69, v69
	v_cvt_pk_bf16_f32 v73, v74, v75
	v_cvt_pk_bf16_f32 v75, v80, v81
	v_cvt_pk_bf16_f32 v74, v82, v83
	v_pk_add_f32 v[80:81], v[68:69], 1.0 op_sel_hi:[1,0]
	v_add_co_u32_e32 v68, vcc, s6, v160
	v_cvt_pk_bf16_f32 v72, v84, v85
	s_nop 1
	v_addc_co_u32_e32 v69, vcc, 0, v161, vcc
	global_store_dwordx4 v[68:69], v[72:75], off
	v_pk_add_f32 v[68:69], v[70:71], v[30:31]
	v_rcp_f32_e32 v70, v81
	s_nop 0
	v_mul_f32_e32 v75, v79, v70
	v_pk_add_f32 v[70:71], v[64:65], v[24:25]
	v_mul_f32_e32 v64, 0xbfb8aa3b, v70
	v_mul_f32_e32 v65, 0xbfb8aa3b, v71
	v_exp_f32_e32 v64, v64
	v_exp_f32_e32 v65, v65
	s_nop 0
	v_pk_add_f32 v[72:73], v[64:65], 1.0 op_sel_hi:[1,0]
	v_rcp_f32_e32 v64, v80
	s_nop 0
	v_mul_f32_e32 v74, v78, v64
	v_pk_add_f32 v[64:65], v[66:67], v[26:27]
	s_mov_b32 s6, 0x12000
	v_rcp_f32_e32 v66, v73
	s_nop 0
	v_mul_f32_e32 v73, v71, v66
	v_mul_f32_e32 v66, 0xbfb8aa3b, v68
	v_mul_f32_e32 v67, 0xbfb8aa3b, v69
	v_exp_f32_e32 v66, v66
	v_exp_f32_e32 v67, v67
	s_nop 0
	v_pk_add_f32 v[66:67], v[66:67], 1.0 op_sel_hi:[1,0]
	v_rcp_f32_e32 v71, v72
	s_nop 0
	v_mul_f32_e32 v72, v70, v71
	v_rcp_f32_e32 v70, v67
	s_nop 0
	v_mul_f32_e32 v67, v69, v70
	v_mul_f32_e32 v70, 0xbfb8aa3b, v64
	v_mul_f32_e32 v71, 0xbfb8aa3b, v65
	v_exp_f32_e32 v70, v70
	v_exp_f32_e32 v71, v71
	s_nop 0
	v_pk_add_f32 v[70:71], v[70:71], 1.0 op_sel_hi:[1,0]
	v_rcp_f32_e32 v69, v66
	s_nop 0
	v_mul_f32_e32 v66, v68, v69
	v_rcp_f32_e32 v68, v71
	s_nop 0
	v_mul_f32_e32 v71, v65, v68
	v_pk_add_f32 v[68:69], v[60:61], v[44:45]
	v_rcp_f32_e32 v65, v70
	s_nop 0
	v_mul_f32_e32 v70, v64, v65
	v_mul_f32_e32 v60, 0xbfb8aa3b, v68
	v_mul_f32_e32 v61, 0xbfb8aa3b, v69
	v_exp_f32_e32 v60, v60
	v_exp_f32_e32 v61, v61
	v_cvt_pk_bf16_f32 v64, v74, v75
	v_cvt_pk_bf16_f32 v65, v66, v67
	v_cvt_pk_bf16_f32 v66, v72, v73
	v_cvt_pk_bf16_f32 v67, v70, v71
	global_store_dwordx4 v[76:77], v[64:67], off offset:256
	s_nop 1
	v_pk_add_f32 v[64:65], v[60:61], 1.0 op_sel_hi:[1,0]
	s_nop 0
	s_mov_b64 s[0:1], 0x12000
	v_lshl_add_u64 v[60:61], v[160:161], 0, s[0:1]
	v_rcp_f32_e32 v66, v65
	s_nop 0
	v_mul_f32_e32 v69, v69, v66
	v_pk_add_f32 v[66:67], v[56:57], v[40:41]
	v_mul_f32_e32 v56, 0xbfb8aa3b, v66
	v_mul_f32_e32 v57, 0xbfb8aa3b, v67
	v_exp_f32_e32 v56, v56
	v_exp_f32_e32 v57, v57
	s_nop 0
	v_pk_add_f32 v[70:71], v[56:57], 1.0 op_sel_hi:[1,0]
	v_rcp_f32_e32 v56, v64
	s_nop 0
	v_mul_f32_e32 v68, v68, v56
	v_pk_add_f32 v[56:57], v[58:59], v[42:43]
	v_rcp_f32_e32 v58, v71
	s_nop 0
	v_mul_f32_e32 v67, v67, v58
	v_mul_f32_e32 v58, 0xbfb8aa3b, v62
	v_mul_f32_e32 v59, 0xbfb8aa3b, v63
	v_exp_f32_e32 v58, v58
	v_exp_f32_e32 v59, v59
	s_nop 0
	v_pk_add_f32 v[58:59], v[58:59], 1.0 op_sel_hi:[1,0]
	v_rcp_f32_e32 v64, v70
	s_nop 0
	v_mul_f32_e32 v66, v66, v64
	v_rcp_f32_e32 v64, v59
	s_nop 0
	v_mul_f32_e32 v59, v63, v64
	v_mul_f32_e32 v64, 0xbfb8aa3b, v56
	v_mul_f32_e32 v65, 0xbfb8aa3b, v57
	v_exp_f32_e32 v64, v64
	v_exp_f32_e32 v65, v65
	s_nop 0
	v_pk_add_f32 v[64:65], v[64:65], 1.0 op_sel_hi:[1,0]
	v_rcp_f32_e32 v63, v58
	s_nop 0
	v_mul_f32_e32 v58, v62, v63
	v_rcp_f32_e32 v62, v65
	s_nop 0
	v_mul_f32_e32 v65, v57, v62
	v_pk_add_f32 v[62:63], v[52:53], v[28:29]
	v_rcp_f32_e32 v57, v64
	s_nop 0
	v_mul_f32_e32 v64, v56, v57
	v_mul_f32_e32 v52, 0xbfb8aa3b, v62
	v_mul_f32_e32 v53, 0xbfb8aa3b, v63
	v_exp_f32_e32 v52, v52
	v_exp_f32_e32 v53, v53
	v_cvt_pk_bf16_f32 v57, v58, v59
	v_cvt_pk_bf16_f32 v59, v64, v65
	v_cvt_pk_bf16_f32 v58, v66, v67
	v_pk_add_f32 v[64:65], v[52:53], 1.0 op_sel_hi:[1,0]
	v_add_co_u32_e32 v52, vcc, s6, v160
	v_cvt_pk_bf16_f32 v56, v68, v69
	s_nop 1
	v_addc_co_u32_e32 v53, vcc, 0, v161, vcc
	global_store_dwordx4 v[52:53], v[56:59], off
	v_pk_add_f32 v[52:53], v[54:55], v[30:31]
	v_rcp_f32_e32 v54, v65
	s_nop 0
	v_mul_f32_e32 v59, v63, v54
	v_pk_add_f32 v[54:55], v[48:49], v[24:25]
	v_mul_f32_e32 v48, 0xbfb8aa3b, v54
	v_mul_f32_e32 v49, 0xbfb8aa3b, v55
	v_exp_f32_e32 v48, v48
	v_exp_f32_e32 v49, v49
	s_nop 0
	v_pk_add_f32 v[56:57], v[48:49], 1.0 op_sel_hi:[1,0]
	v_rcp_f32_e32 v48, v64
	s_nop 0
	v_mul_f32_e32 v58, v62, v48
	v_pk_add_f32 v[48:49], v[50:51], v[26:27]
	s_mov_b32 s6, 0x14000
	v_rcp_f32_e32 v50, v57
	s_nop 0
	v_mul_f32_e32 v57, v55, v50
	v_mul_f32_e32 v50, 0xbfb8aa3b, v52
	v_mul_f32_e32 v51, 0xbfb8aa3b, v53
	v_exp_f32_e32 v50, v50
	v_exp_f32_e32 v51, v51
	s_nop 0
	v_pk_add_f32 v[50:51], v[50:51], 1.0 op_sel_hi:[1,0]
	v_rcp_f32_e32 v55, v56
	s_nop 0
	v_mul_f32_e32 v56, v54, v55
	v_rcp_f32_e32 v54, v51
	s_nop 0
	v_mul_f32_e32 v51, v53, v54
	v_mul_f32_e32 v54, 0xbfb8aa3b, v48
	v_mul_f32_e32 v55, 0xbfb8aa3b, v49
	v_exp_f32_e32 v54, v54
	v_exp_f32_e32 v55, v55
	s_nop 0
	v_pk_add_f32 v[54:55], v[54:55], 1.0 op_sel_hi:[1,0]
	v_rcp_f32_e32 v53, v50
	s_nop 0
	v_mul_f32_e32 v50, v52, v53
	v_rcp_f32_e32 v52, v55
	s_nop 0
	v_mul_f32_e32 v55, v49, v52
	v_pk_add_f32 v[52:53], v[36:37], v[44:45]
	v_rcp_f32_e32 v49, v54
	s_nop 0
	v_mul_f32_e32 v54, v48, v49
	v_mul_f32_e32 v36, 0xbfb8aa3b, v52
	v_mul_f32_e32 v37, 0xbfb8aa3b, v53
	v_exp_f32_e32 v36, v36
	v_exp_f32_e32 v37, v37
	v_cvt_pk_bf16_f32 v48, v58, v59
	v_cvt_pk_bf16_f32 v49, v50, v51
	v_cvt_pk_bf16_f32 v50, v56, v57
	v_cvt_pk_bf16_f32 v51, v54, v55
	global_store_dwordx4 v[60:61], v[48:51], off offset:256
	s_nop 1
	v_pk_add_f32 v[48:49], v[36:37], 1.0 op_sel_hi:[1,0]
	s_nop 0
	s_mov_b64 s[0:1], 0x14000
	v_lshl_add_u64 v[36:37], v[160:161], 0, s[0:1]
	v_rcp_f32_e32 v50, v49
	s_nop 0
	v_mul_f32_e32 v53, v53, v50
	v_pk_add_f32 v[50:51], v[32:33], v[40:41]
	v_mul_f32_e32 v32, 0xbfb8aa3b, v50
	v_mul_f32_e32 v33, 0xbfb8aa3b, v51
	v_exp_f32_e32 v32, v32
	v_exp_f32_e32 v33, v33
	s_nop 0
	v_pk_add_f32 v[54:55], v[32:33], 1.0 op_sel_hi:[1,0]
	v_rcp_f32_e32 v32, v48
	s_nop 0
	v_mul_f32_e32 v52, v52, v32
	v_pk_add_f32 v[32:33], v[34:35], v[42:43]
	v_rcp_f32_e32 v34, v55
	s_nop 0
	v_mul_f32_e32 v51, v51, v34
	v_mul_f32_e32 v34, 0xbfb8aa3b, v38
	v_mul_f32_e32 v35, 0xbfb8aa3b, v39
	v_exp_f32_e32 v34, v34
	v_exp_f32_e32 v35, v35
	s_nop 0
	v_pk_add_f32 v[34:35], v[34:35], 1.0 op_sel_hi:[1,0]
	v_rcp_f32_e32 v48, v54
	s_nop 0
	v_mul_f32_e32 v50, v50, v48
	v_rcp_f32_e32 v48, v35
	s_nop 0
	v_mul_f32_e32 v35, v39, v48
	v_mul_f32_e32 v48, 0xbfb8aa3b, v32
	v_mul_f32_e32 v49, 0xbfb8aa3b, v33
	v_exp_f32_e32 v48, v48
	v_exp_f32_e32 v49, v49
	s_nop 0
	v_pk_add_f32 v[48:49], v[48:49], 1.0 op_sel_hi:[1,0]
	v_rcp_f32_e32 v39, v34
	s_nop 0
	v_mul_f32_e32 v34, v38, v39
	v_rcp_f32_e32 v38, v49
	s_nop 0
	v_mul_f32_e32 v49, v33, v38
	v_pk_add_f32 v[38:39], v[20:21], v[28:29]
	v_rcp_f32_e32 v33, v48
	s_nop 0
	v_mul_f32_e32 v48, v32, v33
	v_mul_f32_e32 v20, 0xbfb8aa3b, v38
	v_mul_f32_e32 v21, 0xbfb8aa3b, v39
	v_exp_f32_e32 v20, v20
	v_exp_f32_e32 v21, v21
	v_cvt_pk_bf16_f32 v33, v34, v35
	v_cvt_pk_bf16_f32 v35, v48, v49
	v_cvt_pk_bf16_f32 v34, v50, v51
	v_pk_add_f32 v[48:49], v[20:21], 1.0 op_sel_hi:[1,0]
	v_add_co_u32_e32 v20, vcc, s6, v160
	v_cvt_pk_bf16_f32 v32, v52, v53
	s_nop 1
	v_addc_co_u32_e32 v21, vcc, 0, v161, vcc
	global_store_dwordx4 v[20:21], v[32:35], off
	v_pk_add_f32 v[20:21], v[22:23], v[30:31]
	v_rcp_f32_e32 v22, v49
	s_nop 0
	v_mul_f32_e32 v35, v39, v22
	v_pk_add_f32 v[22:23], v[16:17], v[24:25]
	v_mul_f32_e32 v16, 0xbfb8aa3b, v22
	v_mul_f32_e32 v17, 0xbfb8aa3b, v23
	v_exp_f32_e32 v16, v16
	v_exp_f32_e32 v17, v17
	s_nop 0
	v_pk_add_f32 v[32:33], v[16:17], 1.0 op_sel_hi:[1,0]
	v_rcp_f32_e32 v16, v48
	s_nop 0
	v_mul_f32_e32 v34, v38, v16
	v_pk_add_f32 v[16:17], v[18:19], v[26:27]
	s_mov_b32 s6, 0x16000
	v_rcp_f32_e32 v18, v33
	s_nop 0
	v_mul_f32_e32 v33, v23, v18
	v_mul_f32_e32 v18, 0xbfb8aa3b, v20
	v_mul_f32_e32 v19, 0xbfb8aa3b, v21
	v_exp_f32_e32 v18, v18
	v_exp_f32_e32 v19, v19
	s_nop 0
	v_pk_add_f32 v[18:19], v[18:19], 1.0 op_sel_hi:[1,0]
	v_rcp_f32_e32 v23, v32
	s_nop 0
	v_mul_f32_e32 v32, v22, v23
	v_rcp_f32_e32 v22, v19
	s_nop 0
	v_mul_f32_e32 v19, v21, v22
	v_mul_f32_e32 v22, 0xbfb8aa3b, v16
	v_mul_f32_e32 v23, 0xbfb8aa3b, v17
	v_exp_f32_e32 v22, v22
	v_exp_f32_e32 v23, v23
	s_nop 0
	v_pk_add_f32 v[22:23], v[22:23], 1.0 op_sel_hi:[1,0]
	v_rcp_f32_e32 v21, v18
	s_nop 0
	v_mul_f32_e32 v18, v20, v21
	v_rcp_f32_e32 v20, v23
	s_nop 0
	v_mul_f32_e32 v23, v17, v20
	v_pk_add_f32 v[20:21], v[12:13], v[44:45]
	v_rcp_f32_e32 v17, v22
	s_nop 0
	v_mul_f32_e32 v22, v16, v17
	v_mul_f32_e32 v12, 0xbfb8aa3b, v20
	v_mul_f32_e32 v13, 0xbfb8aa3b, v21
	v_exp_f32_e32 v12, v12
	v_exp_f32_e32 v13, v13
	v_cvt_pk_bf16_f32 v17, v18, v19
	v_cvt_pk_bf16_f32 v19, v22, v23
	v_cvt_pk_bf16_f32 v18, v32, v33
	v_pk_add_f32 v[22:23], v[12:13], 1.0 op_sel_hi:[1,0]
	v_cvt_pk_bf16_f32 v16, v34, v35
	global_store_dwordx4 v[36:37], v[16:19], off offset:256
	v_lshl_add_u64 v[12:13], v[160:161], 0, s[46:47]
	s_nop 0
	v_rcp_f32_e32 v16, v23
	s_nop 0
	v_mul_f32_e32 v21, v21, v16
	v_pk_add_f32 v[16:17], v[8:9], v[40:41]
	v_mul_f32_e32 v8, 0xbfb8aa3b, v16
	v_mul_f32_e32 v9, 0xbfb8aa3b, v17
	v_exp_f32_e32 v8, v8
	v_exp_f32_e32 v9, v9
	s_nop 0
	v_pk_add_f32 v[18:19], v[8:9], 1.0 op_sel_hi:[1,0]
	v_rcp_f32_e32 v8, v22
	s_nop 0
	v_mul_f32_e32 v20, v20, v8
	v_pk_add_f32 v[8:9], v[10:11], v[42:43]
	v_rcp_f32_e32 v10, v19
	s_nop 0
	v_mul_f32_e32 v19, v17, v10
	v_mul_f32_e32 v10, 0xbfb8aa3b, v14
	v_mul_f32_e32 v11, 0xbfb8aa3b, v15
	v_exp_f32_e32 v10, v10
	v_exp_f32_e32 v11, v11
	s_nop 0
	v_pk_add_f32 v[10:11], v[10:11], 1.0 op_sel_hi:[1,0]
	v_rcp_f32_e32 v17, v18
	s_nop 0
	v_mul_f32_e32 v18, v16, v17
	v_rcp_f32_e32 v16, v11
	s_nop 0
	v_mul_f32_e32 v11, v15, v16
	v_mul_f32_e32 v16, 0xbfb8aa3b, v8
	v_mul_f32_e32 v17, 0xbfb8aa3b, v9
	v_exp_f32_e32 v16, v16
	v_exp_f32_e32 v17, v17
	s_nop 0
	v_pk_add_f32 v[16:17], v[16:17], 1.0 op_sel_hi:[1,0]
	v_rcp_f32_e32 v15, v10
	s_nop 0
	v_mul_f32_e32 v10, v14, v15
	v_rcp_f32_e32 v14, v17
	s_nop 0
	v_mul_f32_e32 v17, v9, v14
	v_pk_add_f32 v[14:15], v[4:5], v[28:29]
	v_rcp_f32_e32 v9, v16
	s_nop 0
	v_mul_f32_e32 v16, v8, v9
	v_mul_f32_e32 v4, 0xbfb8aa3b, v14
	v_mul_f32_e32 v5, 0xbfb8aa3b, v15
	v_exp_f32_e32 v4, v4
	v_exp_f32_e32 v5, v5
	v_cvt_pk_bf16_f32 v9, v10, v11
	v_cvt_pk_bf16_f32 v11, v16, v17
	v_cvt_pk_bf16_f32 v10, v18, v19
	v_pk_add_f32 v[16:17], v[4:5], 1.0 op_sel_hi:[1,0]
	v_add_co_u32_e32 v4, vcc, s6, v160
	v_cvt_pk_bf16_f32 v8, v20, v21
	s_nop 1
	v_addc_co_u32_e32 v5, vcc, 0, v161, vcc
	global_store_dwordx4 v[4:5], v[8:11], off
	v_pk_add_f32 v[4:5], v[6:7], v[30:31]
	v_rcp_f32_e32 v6, v17
	s_nop 0
	v_mul_f32_e32 v11, v15, v6
	v_pk_add_f32 v[6:7], v[0:1], v[24:25]
	v_mul_f32_e32 v0, 0xbfb8aa3b, v6
	v_mul_f32_e32 v1, 0xbfb8aa3b, v7
	v_exp_f32_e32 v0, v0
	v_exp_f32_e32 v1, v1
	s_nop 0
	v_pk_add_f32 v[8:9], v[0:1], 1.0 op_sel_hi:[1,0]
	v_rcp_f32_e32 v0, v16
	s_nop 0
	v_mul_f32_e32 v10, v14, v0
	v_pk_add_f32 v[0:1], v[2:3], v[26:27]
	v_rcp_f32_e32 v2, v9
	s_nop 0
	v_mul_f32_e32 v9, v7, v2
	v_mul_f32_e32 v2, 0xbfb8aa3b, v4
	v_mul_f32_e32 v3, 0xbfb8aa3b, v5
	v_exp_f32_e32 v2, v2
	v_exp_f32_e32 v3, v3
	s_nop 0
	v_pk_add_f32 v[2:3], v[2:3], 1.0 op_sel_hi:[1,0]
	v_rcp_f32_e32 v7, v8
	s_nop 0
	v_mul_f32_e32 v8, v6, v7
	v_rcp_f32_e32 v6, v3
	s_nop 0
	v_mul_f32_e32 v3, v5, v6
	v_mul_f32_e32 v6, 0xbfb8aa3b, v0
	v_mul_f32_e32 v7, 0xbfb8aa3b, v1
	v_exp_f32_e32 v6, v6
	v_exp_f32_e32 v7, v7
	s_nop 0
	v_pk_add_f32 v[6:7], v[6:7], 1.0 op_sel_hi:[1,0]
	v_rcp_f32_e32 v5, v2
	s_nop 0
	v_mul_f32_e32 v2, v4, v5
	v_rcp_f32_e32 v4, v7
	s_nop 0
	v_mul_f32_e32 v4, v1, v4
	s_mov_b64 s[0:1], -1
	v_rcp_f32_e32 v1, v6
	s_nop 0
	v_mul_f32_e32 v5, v0, v1
	v_cvt_pk_bf16_f32 v0, v10, v11
	v_cvt_pk_bf16_f32 v1, v2, v3
	v_cvt_pk_bf16_f32 v2, v8, v9
	v_cvt_pk_bf16_f32 v3, v5, v4
	global_store_dwordx4 v[12:13], v[0:3], off offset:256
	s_waitcnt vmcnt(0)
	s_andn2_b64 vcc, exec, s[52:53]
	s_cbranch_vccnz .LBB0_857
	s_andn2_b64 vcc, exec, s[24:25]
	s_cbranch_vccnz .LBB0_856
	s_barrier
	s_branch .LBB0_856

.LBB0_897:
	s_andn2_b64 vcc, exec, s[28:29]
	s_cbranch_vccnz .LBB0_899
	global_load_dwordx4 v[102:105], v[74:75], off offset:16
	global_load_dwordx4 v[106:109], v[74:75], off
	v_mad_i64_i32 v[62:63], s[0:1], v2, s87, v[72:73]
	s_waitcnt vmcnt(0)
	v_pk_mul_f32 v[104:105], v[104:105], s[52:53] op_sel_hi:[1,0]
	v_pk_mul_f32 v[106:107], v[106:107], s[52:53] op_sel_hi:[1,0]
	v_pk_mul_f32 v[102:103], v[102:103], s[52:53] op_sel_hi:[1,0]
	v_pk_mul_f32 v[0:1], v[0:1], v[106:107]
	v_pk_mul_f32 v[108:109], v[108:109], s[52:53] op_sel_hi:[1,0]
	v_mul_f32_e32 v0, 0xbfb8aa3b, v0
	v_mul_f32_e32 v1, 0xbfb8aa3b, v1
	v_pk_mul_f32 v[14:15], v[60:61], v[102:103]
	v_pk_mul_f32 v[60:61], v[84:85], v[104:105]
	v_pk_mul_f32 v[84:85], v[32:33], v[102:103]
	v_exp_f32_e32 v0, v0
	v_exp_f32_e32 v1, v1
	v_pk_mul_f32 v[50:51], v[10:11], v[104:105]
	v_pk_mul_f32 v[10:11], v[54:55], v[108:109]
	v_pk_mul_f32 v[54:55], v[82:83], v[108:109]
	v_mul_f32_e32 v3, 0xbfb8aa3b, v84
	v_mul_f32_e32 v83, 0xbfb8aa3b, v85
	v_exp_f32_e32 v82, v3
	v_exp_f32_e32 v83, v83
	v_pk_add_f32 v[0:1], v[0:1], 1.0 op_sel_hi:[1,0]
	v_pk_mul_f32 v[38:39], v[52:53], v[102:103]
	v_pk_mul_f32 v[52:53], v[40:41], v[102:103]
	v_pk_mul_f32 v[40:41], v[86:87], v[108:109]
	v_pk_mul_f32 v[86:87], v[80:81], v[108:109]
	v_pk_mul_f32 v[58:59], v[36:37], v[102:103]
	v_pk_mul_f32 v[36:37], v[90:91], v[108:109]
	v_pk_add_f32 v[82:83], v[82:83], 1.0 op_sel_hi:[1,0]
	v_pk_mul_f32 v[32:33], v[92:93], v[108:109]
	v_mul_f32_e32 v3, 0xbfb8aa3b, v86
	v_pk_mul_f32 v[46:47], v[48:49], v[102:103]
	v_pk_mul_f32 v[48:49], v[94:95], v[104:105]
	v_pk_mul_f32 v[42:43], v[18:19], v[104:105]
	v_pk_mul_f32 v[18:19], v[28:29], v[106:107]
	v_pk_mul_f32 v[28:29], v[96:97], v[108:109]
	v_pk_mul_f32 v[30:31], v[56:57], v[102:103]
	v_pk_mul_f32 v[44:45], v[44:45], v[102:103]
	v_pk_mul_f32 v[56:57], v[88:89], v[104:105]
	v_pk_mul_f32 v[6:7], v[6:7], v[104:105]
	v_pk_mul_f32 v[22:23], v[22:23], v[104:105]
	v_pk_mul_f32 v[34:35], v[34:35], v[104:105]
	s_mov_b64 vcc, s[0:1]
	v_rcp_f32_e32 v80, v1
	s_nop 0
	v_mul_f32_e32 v81, 1.0, v80
	s_mov_b64 vcc, s[4:5]
	v_rcp_f32_e32 v1, v0
	s_nop 0
	v_mul_f32_e32 v80, 1.0, v1
	v_mul_f32_e32 v1, 0xbfb8aa3b, v87
	v_rcp_f32_e32 v0, v83
	s_nop 0
	v_mul_f32_e32 v85, 1.0, v0
	v_exp_f32_e32 v0, v3
	v_exp_f32_e32 v1, v1
	s_nop 0
	v_pk_add_f32 v[0:1], v[0:1], 1.0 op_sel_hi:[1,0]
	s_mov_b64 vcc, s[6:7]
	v_rcp_f32_e32 v3, v82
	s_nop 0
	v_mul_f32_e32 v84, 1.0, v3
	v_mul_f32_e32 v3, 0xbfb8aa3b, v60
	v_exp_f32_e32 v60, v3
	v_mul_f32_e32 v61, 0xbfb8aa3b, v61
	v_exp_f32_e32 v61, v61
	v_rcp_f32_e32 v3, v1
	s_nop 0
	v_mul_f32_e32 v83, 1.0, v3
	v_pk_add_f32 v[60:61], v[60:61], 1.0 op_sel_hi:[1,0]
	v_rcp_f32_e32 v1, v0
	s_nop 0
	v_mul_f32_e32 v82, 1.0, v1
	global_store_dwordx4 v[62:63], v[80:83], off
	v_rcp_f32_e32 v0, v61
	s_nop 0
	v_mul_f32_e32 v87, 1.0, v0
	v_pk_mul_f32 v[4:5], v[4:5], v[106:107]
	v_mul_f32_e32 v0, 0xbfb8aa3b, v4
	v_mul_f32_e32 v1, 0xbfb8aa3b, v5
	v_exp_f32_e32 v0, v0
	v_exp_f32_e32 v1, v1
	v_rcp_f32_e32 v3, v60
	s_nop 0
	v_mul_f32_e32 v86, 1.0, v3
	v_or_b32_e32 v3, 16, v2
	v_mad_i64_i32 v[4:5], s[0:1], v3, s87, v[72:73]
	v_pk_add_f32 v[0:1], v[0:1], 1.0 op_sel_hi:[1,0]
	v_mul_f32_e32 v3, 0xbfb8aa3b, v58
	v_exp_f32_e32 v58, v3
	global_store_dwordx4 v[62:63], v[84:87], off offset:16
	v_mul_f32_e32 v59, 0xbfb8aa3b, v59
	v_exp_f32_e32 v59, v59
	v_rcp_f32_e32 v3, v1
	s_nop 0
	v_mul_f32_e32 v61, 1.0, v3
	v_pk_add_f32 v[58:59], v[58:59], 1.0 op_sel_hi:[1,0]
	v_rcp_f32_e32 v1, v0
	s_nop 0
	v_mul_f32_e32 v60, 1.0, v1
	v_rcp_f32_e32 v0, v59
	s_nop 0
	v_mul_f32_e32 v59, 1.0, v0
	v_mul_f32_e32 v0, 0xbfb8aa3b, v54
	v_mul_f32_e32 v1, 0xbfb8aa3b, v55
	v_exp_f32_e32 v0, v0
	v_exp_f32_e32 v1, v1
	v_rcp_f32_e32 v3, v58
	s_nop 0
	v_mul_f32_e32 v58, 1.0, v3
	v_pk_add_f32 v[0:1], v[0:1], 1.0 op_sel_hi:[1,0]
	v_mul_f32_e32 v3, 0xbfb8aa3b, v56
	v_exp_f32_e32 v54, v3
	v_mul_f32_e32 v55, 0xbfb8aa3b, v57
	v_exp_f32_e32 v55, v55
	v_rcp_f32_e32 v3, v1
	s_nop 0
	v_mul_f32_e32 v63, 1.0, v3
	v_pk_add_f32 v[54:55], v[54:55], 1.0 op_sel_hi:[1,0]
	v_rcp_f32_e32 v1, v0
	s_nop 0
	v_mul_f32_e32 v62, 1.0, v1
	global_store_dwordx4 v[4:5], v[60:63], off
	v_pk_mul_f32 v[8:9], v[8:9], v[106:107]
	v_pk_mul_f32 v[12:13], v[12:13], v[106:107]
	v_rcp_f32_e32 v0, v55
	s_nop 0
	v_mul_f32_e32 v61, 1.0, v0
	v_mul_f32_e32 v0, 0xbfb8aa3b, v8
	v_mul_f32_e32 v1, 0xbfb8aa3b, v9
	v_exp_f32_e32 v0, v0
	v_exp_f32_e32 v1, v1
	v_rcp_f32_e32 v3, v54
	s_nop 0
	v_mul_f32_e32 v60, 1.0, v3
	v_or_b32_e32 v3, 32, v2
	global_store_dwordx4 v[4:5], v[58:61], off offset:16
	v_pk_add_f32 v[0:1], v[0:1], 1.0 op_sel_hi:[1,0]
	v_mad_i64_i32 v[4:5], s[0:1], v3, s87, v[72:73]
	v_mul_f32_e32 v3, 0xbfb8aa3b, v52
	v_exp_f32_e32 v8, v3
	v_mul_f32_e32 v9, 0xbfb8aa3b, v53
	v_exp_f32_e32 v9, v9
	v_rcp_f32_e32 v3, v1
	s_nop 0
	v_mul_f32_e32 v55, 1.0, v3
	v_pk_add_f32 v[8:9], v[8:9], 1.0 op_sel_hi:[1,0]
	v_rcp_f32_e32 v1, v0
	s_nop 0
	v_mul_f32_e32 v54, 1.0, v1
	v_rcp_f32_e32 v0, v9
	s_nop 0
	v_mul_f32_e32 v53, 1.0, v0
	v_mul_f32_e32 v0, 0xbfb8aa3b, v40
	v_mul_f32_e32 v1, 0xbfb8aa3b, v41
	v_exp_f32_e32 v0, v0
	v_exp_f32_e32 v1, v1
	v_rcp_f32_e32 v3, v8
	s_nop 0
	v_mul_f32_e32 v52, 1.0, v3
	v_pk_add_f32 v[0:1], v[0:1], 1.0 op_sel_hi:[1,0]
	v_mul_f32_e32 v3, 0xbfb8aa3b, v50
	v_exp_f32_e32 v8, v3
	v_pk_mul_f32 v[16:17], v[16:17], v[106:107]
	v_pk_mul_f32 v[20:21], v[20:21], v[106:107]
	v_mul_f32_e32 v9, 0xbfb8aa3b, v51
	v_exp_f32_e32 v9, v9
	v_rcp_f32_e32 v3, v1
	s_nop 0
	v_mul_f32_e32 v57, 1.0, v3
	v_pk_add_f32 v[8:9], v[8:9], 1.0 op_sel_hi:[1,0]
	v_rcp_f32_e32 v1, v0
	s_nop 0
	v_mul_f32_e32 v56, 1.0, v1
	global_store_dwordx4 v[4:5], v[54:57], off
	v_pk_mul_f32 v[24:25], v[24:25], v[106:107]
	v_pk_mul_f32 v[26:27], v[26:27], v[108:109]
	v_rcp_f32_e32 v0, v9
	s_nop 0
	v_mul_f32_e32 v55, 1.0, v0
	v_mul_f32_e32 v0, 0xbfb8aa3b, v12
	v_mul_f32_e32 v1, 0xbfb8aa3b, v13
	v_exp_f32_e32 v0, v0
	v_exp_f32_e32 v1, v1
	v_rcp_f32_e32 v3, v8
	s_nop 0
	v_mul_f32_e32 v54, 1.0, v3
	v_or_b32_e32 v3, 48, v2
	global_store_dwordx4 v[4:5], v[52:55], off offset:16
	v_pk_add_f32 v[0:1], v[0:1], 1.0 op_sel_hi:[1,0]
	v_mad_i64_i32 v[4:5], s[0:1], v3, s87, v[72:73]
	v_mul_f32_e32 v3, 0xbfb8aa3b, v44
	v_exp_f32_e32 v8, v3
	v_mul_f32_e32 v10, 0xbfb8aa3b, v10
	v_mul_f32_e32 v9, 0xbfb8aa3b, v45
	v_exp_f32_e32 v9, v9
	v_rcp_f32_e32 v3, v1
	s_nop 0
	v_mul_f32_e32 v51, 1.0, v3
	v_pk_add_f32 v[8:9], v[8:9], 1.0 op_sel_hi:[1,0]
	v_rcp_f32_e32 v1, v0
	s_nop 0
	v_mul_f32_e32 v50, 1.0, v1
	v_rcp_f32_e32 v0, v9
	s_nop 0
	v_mul_f32_e32 v55, 1.0, v0
	v_mul_f32_e32 v0, 0xbfb8aa3b, v36
	v_mul_f32_e32 v1, 0xbfb8aa3b, v37
	v_exp_f32_e32 v0, v0
	v_exp_f32_e32 v1, v1
	v_rcp_f32_e32 v3, v8
	s_nop 0
	v_mul_f32_e32 v54, 1.0, v3
	v_pk_add_f32 v[0:1], v[0:1], 1.0 op_sel_hi:[1,0]
	v_mul_f32_e32 v3, 0xbfb8aa3b, v48
	v_exp_f32_e32 v8, v3
	v_mul_f32_e32 v11, 0xbfb8aa3b, v11
	v_exp_f32_e32 v10, v10
	v_mul_f32_e32 v9, 0xbfb8aa3b, v49
	v_exp_f32_e32 v9, v9
	v_rcp_f32_e32 v3, v1
	s_nop 0
	v_mul_f32_e32 v53, 1.0, v3
	v_pk_add_f32 v[8:9], v[8:9], 1.0 op_sel_hi:[1,0]
	v_rcp_f32_e32 v1, v0
	s_nop 0
	v_mul_f32_e32 v52, 1.0, v1
	v_rcp_f32_e32 v0, v9
	s_nop 0
	v_mul_f32_e32 v57, 1.0, v0
	global_store_dwordx4 v[4:5], v[50:53], off
	v_mul_f32_e32 v0, 0xbfb8aa3b, v16
	v_mul_f32_e32 v1, 0xbfb8aa3b, v17
	v_exp_f32_e32 v0, v0
	v_exp_f32_e32 v1, v1
	v_rcp_f32_e32 v3, v8
	s_nop 0
	v_mul_f32_e32 v56, 1.0, v3
	v_add_u32_e32 v3, 0x80, v2
	global_store_dwordx4 v[4:5], v[54:57], off offset:16
	v_pk_add_f32 v[0:1], v[0:1], 1.0 op_sel_hi:[1,0]
	v_mad_i64_i32 v[4:5], s[0:1], v3, s87, v[72:73]
	v_mul_f32_e32 v3, 0xbfb8aa3b, v46
	v_exp_f32_e32 v8, v3
	v_exp_f32_e32 v11, v11
	v_mul_f32_e32 v9, 0xbfb8aa3b, v47
	v_exp_f32_e32 v9, v9
	v_rcp_f32_e32 v3, v1
	s_nop 0
	v_mul_f32_e32 v45, 1.0, v3
	v_pk_add_f32 v[8:9], v[8:9], 1.0 op_sel_hi:[1,0]
	v_rcp_f32_e32 v1, v0
	s_nop 0
	v_mul_f32_e32 v44, 1.0, v1
	v_rcp_f32_e32 v0, v9
	s_nop 0
	v_mul_f32_e32 v41, 1.0, v0
	v_mul_f32_e32 v0, 0xbfb8aa3b, v32
	v_mul_f32_e32 v1, 0xbfb8aa3b, v33
	v_exp_f32_e32 v0, v0
	v_exp_f32_e32 v1, v1
	v_rcp_f32_e32 v3, v8
	s_nop 0
	v_mul_f32_e32 v40, 1.0, v3
	v_pk_add_f32 v[0:1], v[0:1], 1.0 op_sel_hi:[1,0]
	v_mul_f32_e32 v3, 0xbfb8aa3b, v42
	v_exp_f32_e32 v8, v3
	v_pk_add_f32 v[10:11], v[10:11], 1.0 op_sel_hi:[1,0]
	v_mul_f32_e32 v7, 0xbfb8aa3b, v7
	v_mul_f32_e32 v9, 0xbfb8aa3b, v43
	v_exp_f32_e32 v9, v9
	v_rcp_f32_e32 v3, v1
	s_nop 0
	v_mul_f32_e32 v47, 1.0, v3
	v_pk_add_f32 v[8:9], v[8:9], 1.0 op_sel_hi:[1,0]
	v_rcp_f32_e32 v1, v0
	s_nop 0
	v_mul_f32_e32 v46, 1.0, v1
	v_rcp_f32_e32 v0, v9
	s_nop 0
	v_mul_f32_e32 v43, 1.0, v0
	global_store_dwordx4 v[4:5], v[44:47], off
	v_mul_f32_e32 v0, 0xbfb8aa3b, v20
	v_mul_f32_e32 v1, 0xbfb8aa3b, v21
	v_exp_f32_e32 v0, v0
	v_exp_f32_e32 v1, v1
	v_rcp_f32_e32 v3, v8
	s_nop 0
	v_mul_f32_e32 v42, 1.0, v3
	v_add_u32_e32 v3, 0x90, v2
	global_store_dwordx4 v[4:5], v[40:43], off offset:16
	v_pk_add_f32 v[0:1], v[0:1], 1.0 op_sel_hi:[1,0]
	v_mad_i64_i32 v[4:5], s[0:1], v3, s87, v[72:73]
	v_mul_f32_e32 v3, 0xbfb8aa3b, v38
	v_exp_f32_e32 v8, v3
	v_exp_f32_e32 v7, v7
	v_mul_f32_e32 v9, 0xbfb8aa3b, v39
	v_exp_f32_e32 v9, v9
	v_rcp_f32_e32 v3, v1
	s_nop 0
	v_mul_f32_e32 v37, 1.0, v3
	v_pk_add_f32 v[8:9], v[8:9], 1.0 op_sel_hi:[1,0]
	v_rcp_f32_e32 v1, v0
	s_nop 0
	v_mul_f32_e32 v36, 1.0, v1
	v_rcp_f32_e32 v0, v9
	s_nop 0
	v_mul_f32_e32 v33, 1.0, v0
	v_mul_f32_e32 v0, 0xbfb8aa3b, v28
	v_mul_f32_e32 v1, 0xbfb8aa3b, v29
	v_exp_f32_e32 v0, v0
	v_exp_f32_e32 v1, v1
	v_rcp_f32_e32 v3, v8
	s_nop 0
	v_mul_f32_e32 v32, 1.0, v3
	v_pk_add_f32 v[0:1], v[0:1], 1.0 op_sel_hi:[1,0]
	v_mul_f32_e32 v3, 0xbfb8aa3b, v34
	v_exp_f32_e32 v8, v3
	v_mul_f32_e32 v9, 0xbfb8aa3b, v35
	v_exp_f32_e32 v9, v9
	v_rcp_f32_e32 v3, v1
	s_nop 0
	v_mul_f32_e32 v39, 1.0, v3
	v_pk_add_f32 v[8:9], v[8:9], 1.0 op_sel_hi:[1,0]
	v_rcp_f32_e32 v1, v0
	s_nop 0
	v_mul_f32_e32 v38, 1.0, v1
	v_rcp_f32_e32 v0, v9
	s_nop 0
	v_mul_f32_e32 v35, 1.0, v0
	global_store_dwordx4 v[4:5], v[36:39], off
	v_mul_f32_e32 v0, 0xbfb8aa3b, v24
	v_mul_f32_e32 v1, 0xbfb8aa3b, v25
	v_exp_f32_e32 v0, v0
	v_exp_f32_e32 v1, v1
	v_rcp_f32_e32 v3, v8
	s_nop 0
	v_mul_f32_e32 v34, 1.0, v3
	v_add_u32_e32 v3, 0xa0, v2
	global_store_dwordx4 v[4:5], v[32:35], off offset:16
	v_pk_add_f32 v[0:1], v[0:1], 1.0 op_sel_hi:[1,0]
	v_mad_i64_i32 v[4:5], s[0:1], v3, s87, v[72:73]
	v_mul_f32_e32 v3, 0xbfb8aa3b, v30
	v_exp_f32_e32 v8, v3
	v_add_u32_e32 v2, 0xb0, v2
	v_mul_f32_e32 v9, 0xbfb8aa3b, v31
	v_exp_f32_e32 v9, v9
	v_rcp_f32_e32 v3, v1
	s_nop 0
	v_mul_f32_e32 v25, 1.0, v3
	v_pk_add_f32 v[8:9], v[8:9], 1.0 op_sel_hi:[1,0]
	v_rcp_f32_e32 v1, v0
	s_nop 0
	v_mul_f32_e32 v24, 1.0, v1
	v_rcp_f32_e32 v0, v9
	s_nop 0
	v_mul_f32_e32 v21, 1.0, v0
	v_mul_f32_e32 v0, 0xbfb8aa3b, v26
	v_mul_f32_e32 v1, 0xbfb8aa3b, v27
	v_exp_f32_e32 v0, v0
	v_exp_f32_e32 v1, v1
	v_rcp_f32_e32 v3, v8
	s_nop 0
	v_mul_f32_e32 v20, 1.0, v3
	v_pk_add_f32 v[0:1], v[0:1], 1.0 op_sel_hi:[1,0]
	v_mul_f32_e32 v3, 0xbfb8aa3b, v22
	v_exp_f32_e32 v8, v3
	v_mul_f32_e32 v9, 0xbfb8aa3b, v23
	v_exp_f32_e32 v9, v9
	v_rcp_f32_e32 v3, v1
	s_nop 0
	v_mul_f32_e32 v27, 1.0, v3
	v_pk_add_f32 v[8:9], v[8:9], 1.0 op_sel_hi:[1,0]
	v_rcp_f32_e32 v1, v0
	s_nop 0
	v_mul_f32_e32 v26, 1.0, v1
	v_rcp_f32_e32 v0, v9
	s_nop 0
	v_mul_f32_e32 v23, 1.0, v0
	global_store_dwordx4 v[4:5], v[24:27], off
	v_mul_f32_e32 v0, 0xbfb8aa3b, v18
	v_mul_f32_e32 v1, 0xbfb8aa3b, v19
	v_exp_f32_e32 v0, v0
	v_exp_f32_e32 v1, v1
	v_rcp_f32_e32 v3, v8
	s_nop 0
	v_mul_f32_e32 v22, 1.0, v3
	global_store_dwordx4 v[4:5], v[20:23], off offset:16
	v_mad_i64_i32 v[8:9], s[0:1], v2, s87, v[72:73]
	v_pk_add_f32 v[0:1], v[0:1], 1.0 op_sel_hi:[1,0]
	v_mul_f32_e32 v2, 0xbfb8aa3b, v14
	v_exp_f32_e32 v2, v2
	v_rcp_f32_e32 v3, v1
	s_nop 0
	v_mul_f32_e32 v1, 1.0, v3
	v_mul_f32_e32 v3, 0xbfb8aa3b, v15
	v_exp_f32_e32 v3, v3
	s_nop 0
	v_pk_add_f32 v[2:3], v[2:3], 1.0 op_sel_hi:[1,0]
	v_rcp_f32_e32 v4, v0
	s_nop 0
	v_mul_f32_e32 v0, 1.0, v4
	v_rcp_f32_e32 v4, v3
	s_nop 0
	v_mul_f32_e32 v5, 1.0, v4
	v_rcp_f32_e32 v3, v2
	s_nop 0
	v_mul_f32_e32 v4, 1.0, v3
	v_mul_f32_e32 v2, 0xbfb8aa3b, v6
	v_exp_f32_e32 v6, v2
	v_rcp_f32_e32 v2, v11
	s_nop 0
	v_mul_f32_e32 v3, 1.0, v2
	v_pk_add_f32 v[6:7], v[6:7], 1.0 op_sel_hi:[1,0]
	v_rcp_f32_e32 v2, v10
	s_nop 0
	v_mul_f32_e32 v2, 1.0, v2
	global_store_dwordx4 v[8:9], v[0:3], off
	s_nop 1
	v_rcp_f32_e32 v0, v7
	s_nop 0
	v_mul_f32_e32 v7, 1.0, v0
	v_rcp_f32_e32 v0, v6
	s_nop 0
	v_mul_f32_e32 v6, 1.0, v0
	global_store_dwordx4 v[8:9], v[4:7], off offset:16

.LBB0_1058:
	ds_bpermute_b32 v0, v191, v170
	s_waitcnt vmcnt(0)
	v_mov_b32_e32 v8, v177
	s_add_i32 s18, s18, s74
	v_and_b32_e32 v4, 31, v8
	s_waitcnt lgkmcnt(0)
	v_add_f32_e32 v0, v170, v0
	s_add_i32 s19, s19, 1
	v_rcp_f32_e32 v2, v0
	s_nop 0
	v_mul_f32_e32 v2, 1.0, v2
	v_cmp_lt_f32_e32 vcc, 0, v0
	v_mul_u32_u24_e32 v6, 0x110, v4
	s_cmpk_gt_i32 s18, 0x7ff
	v_cndmask_b32_e32 v0, 0, v2, vcc
	v_pk_mul_f32 v[2:3], v[64:65], v[0:1] op_sel_hi:[1,0]
	v_pk_mul_f32 v[4:5], v[66:67], v[0:1] op_sel_hi:[1,0]
	v_cvt_pk_bf16_f32 v2, v2, v3
	v_cvt_pk_bf16_f32 v3, v4, v5
	v_ashrrev_i32_e32 v4, 2, v8
	v_and_b32_e32 v4, -8, v4
	v_add3_u32 v9, s95, v6, v4
	v_pk_mul_f32 v[4:5], v[68:69], v[0:1] op_sel_hi:[1,0]
	v_pk_mul_f32 v[6:7], v[70:71], v[0:1] op_sel_hi:[1,0]
	v_cvt_pk_bf16_f32 v4, v4, v5
	v_cvt_pk_bf16_f32 v5, v6, v7
	ds_write2_b64 v9, v[2:3], v[4:5] offset1:2
	v_pk_mul_f32 v[2:3], v[72:73], v[0:1] op_sel_hi:[1,0]
	v_pk_mul_f32 v[4:5], v[74:75], v[0:1] op_sel_hi:[1,0]
	v_cvt_pk_bf16_f32 v2, v2, v3
	v_cvt_pk_bf16_f32 v3, v4, v5
	v_pk_mul_f32 v[4:5], v[76:77], v[0:1] op_sel_hi:[1,0]
	v_pk_mul_f32 v[6:7], v[78:79], v[0:1] op_sel_hi:[1,0]
	v_cvt_pk_bf16_f32 v4, v4, v5
	v_cvt_pk_bf16_f32 v5, v6, v7
	ds_write2_b64 v9, v[2:3], v[4:5] offset0:4 offset1:6
	v_pk_mul_f32 v[2:3], v[48:49], v[0:1] op_sel_hi:[1,0]
	v_pk_mul_f32 v[4:5], v[50:51], v[0:1] op_sel_hi:[1,0]
	v_cvt_pk_bf16_f32 v2, v2, v3
	v_cvt_pk_bf16_f32 v3, v4, v5
	v_pk_mul_f32 v[4:5], v[52:53], v[0:1] op_sel_hi:[1,0]
	v_pk_mul_f32 v[6:7], v[54:55], v[0:1] op_sel_hi:[1,0]
	v_cvt_pk_bf16_f32 v4, v4, v5
	v_cvt_pk_bf16_f32 v5, v6, v7
	ds_write2_b64 v9, v[2:3], v[4:5] offset0:8 offset1:10
	v_pk_mul_f32 v[2:3], v[56:57], v[0:1] op_sel_hi:[1,0]
	v_pk_mul_f32 v[4:5], v[58:59], v[0:1] op_sel_hi:[1,0]
	v_cvt_pk_bf16_f32 v2, v2, v3
	v_cvt_pk_bf16_f32 v3, v4, v5
	v_pk_mul_f32 v[4:5], v[60:61], v[0:1] op_sel_hi:[1,0]
	v_pk_mul_f32 v[6:7], v[62:63], v[0:1] op_sel_hi:[1,0]
	v_cvt_pk_bf16_f32 v4, v4, v5
	v_cvt_pk_bf16_f32 v5, v6, v7
	ds_write2_b64 v9, v[2:3], v[4:5] offset0:12 offset1:14
	v_pk_mul_f32 v[2:3], v[32:33], v[0:1] op_sel_hi:[1,0]
	v_pk_mul_f32 v[4:5], v[34:35], v[0:1] op_sel_hi:[1,0]
	v_cvt_pk_bf16_f32 v2, v2, v3
	v_cvt_pk_bf16_f32 v3, v4, v5
	v_pk_mul_f32 v[4:5], v[36:37], v[0:1] op_sel_hi:[1,0]
	v_pk_mul_f32 v[6:7], v[38:39], v[0:1] op_sel_hi:[1,0]
	v_cvt_pk_bf16_f32 v4, v4, v5
	v_cvt_pk_bf16_f32 v5, v6, v7
	ds_write2_b64 v9, v[2:3], v[4:5] offset0:16 offset1:18
	v_pk_mul_f32 v[2:3], v[40:41], v[0:1] op_sel_hi:[1,0]
	v_pk_mul_f32 v[4:5], v[42:43], v[0:1] op_sel_hi:[1,0]
	v_cvt_pk_bf16_f32 v2, v2, v3
	v_cvt_pk_bf16_f32 v3, v4, v5
	v_pk_mul_f32 v[4:5], v[44:45], v[0:1] op_sel_hi:[1,0]
	v_pk_mul_f32 v[6:7], v[46:47], v[0:1] op_sel_hi:[1,0]
	v_cvt_pk_bf16_f32 v4, v4, v5
	v_cvt_pk_bf16_f32 v5, v6, v7
	ds_write2_b64 v9, v[2:3], v[4:5] offset0:20 offset1:22
	v_pk_mul_f32 v[2:3], v[16:17], v[0:1] op_sel_hi:[1,0]
	v_pk_mul_f32 v[4:5], v[18:19], v[0:1] op_sel_hi:[1,0]
	v_cvt_pk_bf16_f32 v2, v2, v3
	v_cvt_pk_bf16_f32 v3, v4, v5
	v_pk_mul_f32 v[4:5], v[20:21], v[0:1] op_sel_hi:[1,0]
	v_pk_mul_f32 v[6:7], v[22:23], v[0:1] op_sel_hi:[1,0]
	v_cvt_pk_bf16_f32 v4, v4, v5
	v_cvt_pk_bf16_f32 v5, v6, v7
	ds_write2_b64 v9, v[2:3], v[4:5] offset0:24 offset1:26
	v_pk_mul_f32 v[2:3], v[24:25], v[0:1] op_sel_hi:[1,0]
	v_pk_mul_f32 v[4:5], v[26:27], v[0:1] op_sel_hi:[1,0]
	v_cvt_pk_bf16_f32 v2, v2, v3
	v_cvt_pk_bf16_f32 v3, v4, v5
	v_pk_mul_f32 v[4:5], v[28:29], v[0:1] op_sel_hi:[1,0]
	v_pk_mul_f32 v[6:7], v[30:31], v[0:1] op_sel_hi:[1,0]
	v_cvt_pk_bf16_f32 v4, v4, v5
	v_cvt_pk_bf16_f32 v5, v6, v7
	ds_write2_b64 v9, v[2:3], v[4:5] offset0:28 offset1:30
	v_ashrrev_i32_e32 v2, 7, v8
	v_ashrrev_i32_e32 v3, 31, v2
	v_ashrrev_i32_e32 v29, 4, v8
	v_lshl_add_u64 v[2:3], s[80:81], 0, v[2:3]
	v_mov_b64_e32 v[20:21], s[48:49]
	v_lshlrev_b32_e32 v0, 4, v8
	v_and_or_b32 v6, v29, 7, s34
	v_mad_u64_u32 v[4:5], s[0:1], v2, s76, v[20:21]
	v_and_b32_e32 v18, 0xf0, v0
	v_mad_i32_i24 v5, v3, s76, v5
	v_lshlrev_b32_e32 v0, 8, v6
	v_lshl_add_u64 v[4:5], v[4:5], 0, v[0:1]
	v_mov_b32_e32 v19, v1
	v_lshl_add_u64 v[4:5], v[4:5], 0, v[18:19]
	v_add_co_u32_e32 v4, vcc, s86, v4
	s_waitcnt lgkmcnt(0)
	v_mov_b64_e32 v[22:23], s[50:51]
	s_nop 0
	v_addc_co_u32_e32 v5, vcc, 0, v5, vcc
	global_load_dwordx4 v[10:13], v[4:5], off
	global_load_dwordx4 v[40:43], v[4:5], off offset:1024
	v_add_co_u32_e32 v68, vcc, 0x6000, v4
	s_nop 1
	v_addc_co_u32_e32 v69, vcc, 0, v5, vcc
	global_load_dwordx4 v[44:47], v[68:69], off
	global_load_dwordx4 v[48:51], v[68:69], off offset:1024
	v_add_co_u32_e32 v68, vcc, 0xc000, v4
	s_nop 1
	v_addc_co_u32_e32 v69, vcc, 0, v5, vcc
	global_load_dwordx4 v[52:55], v[68:69], off
	global_load_dwordx4 v[56:59], v[68:69], off offset:1024
	v_add_co_u32_e32 v68, vcc, 0x12000, v4
	s_nop 1
	v_addc_co_u32_e32 v69, vcc, 0, v5, vcc
	global_load_dwordx4 v[60:63], v[68:69], off
	global_load_dwordx4 v[64:67], v[68:69], off offset:1024
	v_mad_u64_u32 v[4:5], s[0:1], v2, s77, v[22:23]
	v_mad_i32_i24 v5, v3, s77, v5
	v_lshlrev_b64 v[2:3], 13, v[2:3]
	v_lshl_add_u64 v[2:3], s[44:45], 0, v[2:3]
	v_lshlrev_b32_e32 v24, 2, v6
	v_mov_b32_e32 v25, v1
	v_lshl_add_u64 v[2:3], v[2:3], 0, v[0:1]
	v_lshl_add_u64 v[4:5], v[4:5], 0, v[24:25]
	v_lshl_add_u64 v[26:27], v[2:3], 0, v[18:19]
	global_load_dword v28, v[4:5], off offset:256
	global_load_dwordx4 v[6:9], v[26:27], off
	v_mul_lo_u32 v4, v29, s94
	v_add3_u32 v30, s95, v18, v4
	ds_read_b128 v[14:17], v30
	s_waitcnt vmcnt(2)
	v_lshlrev_b32_e32 v31, 16, v10
	v_and_b32_e32 v10, 0xffff0000, v10
	v_mul_f32_e32 v2, 0xbfb8aa3b, v31
	v_mul_f32_e32 v3, 0xbfb8aa3b, v10
	v_exp_f32_e32 v2, v2
	v_exp_f32_e32 v3, v3
	s_nop 0
	v_pk_add_f32 v[32:33], v[2:3], 1.0 op_sel_hi:[1,0]
	s_nop 0
	ds_read_b128 v[2:5], v30 offset:1088
	s_waitcnt lgkmcnt(1)
	v_lshlrev_b32_e32 v34, 16, v14
	v_and_b32_e32 v35, 0xffff0000, v14
	v_rcp_f32_e32 v14, v33
	s_nop 0
	v_mul_f32_e32 v33, v10, v14
	v_and_b32_e32 v38, 0xffff0000, v11
	v_rcp_f32_e32 v10, v32
	s_nop 0
	v_mul_f32_e32 v32, v31, v10
	v_lshlrev_b32_e32 v31, 16, v11
	v_mul_f32_e32 v11, 0xbfb8aa3b, v31
	v_exp_f32_e32 v36, v11
	v_mul_f32_e32 v11, 0xbfb8aa3b, v38
	v_exp_f32_e32 v37, v11
	s_waitcnt vmcnt(1)
	v_pk_mul_f32 v[34:35], v[28:29], v[34:35] op_sel_hi:[0,1]
	s_waitcnt vmcnt(0)
	v_lshlrev_b32_e32 v10, 16, v6
	v_and_b32_e32 v11, 0xffff0000, v6
	v_pk_fma_f32 v[10:11], v[34:35], v[32:33], v[10:11]
	v_lshlrev_b32_e32 v14, 16, v15
	v_cvt_pk_bf16_f32 v6, v10, v11
	v_pk_add_f32 v[10:11], v[36:37], 1.0 op_sel_hi:[1,0]
	v_and_b32_e32 v15, 0xffff0000, v15
	v_pk_mul_f32 v[14:15], v[28:29], v[14:15] op_sel_hi:[0,1]
	v_rcp_f32_e32 v32, v11
	s_nop 0
	v_mul_f32_e32 v11, v38, v32
	v_rcp_f32_e32 v32, v10
	s_nop 0
	v_mul_f32_e32 v10, v31, v32
	v_lshlrev_b32_e32 v31, 16, v12
	v_and_b32_e32 v12, 0xffff0000, v12
	v_mul_f32_e32 v33, 0xbfb8aa3b, v31
	v_exp_f32_e32 v34, v33
	v_mul_f32_e32 v33, 0xbfb8aa3b, v12
	v_exp_f32_e32 v35, v33
	v_lshlrev_b32_e32 v32, 16, v7
	v_and_b32_e32 v33, 0xffff0000, v7
	v_pk_fma_f32 v[10:11], v[14:15], v[10:11], v[32:33]
	v_lshlrev_b32_e32 v14, 16, v16
	v_cvt_pk_bf16_f32 v7, v10, v11
	v_pk_add_f32 v[10:11], v[34:35], 1.0 op_sel_hi:[1,0]
	v_and_b32_e32 v15, 0xffff0000, v16
	v_pk_mul_f32 v[14:15], v[28:29], v[14:15] op_sel_hi:[0,1]
	v_rcp_f32_e32 v16, v11
	s_nop 0
	v_mul_f32_e32 v11, v12, v16
	v_lshlrev_b32_e32 v16, 16, v13
	v_rcp_f32_e32 v12, v10
	s_nop 0
	v_mul_f32_e32 v10, v31, v12
	v_and_b32_e32 v31, 0xffff0000, v13
	v_mul_f32_e32 v13, 0xbfb8aa3b, v16
	v_exp_f32_e32 v32, v13
	v_mul_f32_e32 v13, 0xbfb8aa3b, v31
	v_exp_f32_e32 v33, v13
	v_lshlrev_b32_e32 v12, 16, v8
	v_and_b32_e32 v13, 0xffff0000, v8
	v_pk_fma_f32 v[10:11], v[14:15], v[10:11], v[12:13]
	v_lshlrev_b32_e32 v12, 16, v17
	v_cvt_pk_bf16_f32 v8, v10, v11
	v_pk_add_f32 v[10:11], v[32:33], 1.0 op_sel_hi:[1,0]
	v_and_b32_e32 v13, 0xffff0000, v17
	v_pk_mul_f32 v[12:13], v[28:29], v[12:13] op_sel_hi:[0,1]
	s_waitcnt lgkmcnt(0)
	v_and_b32_e32 v33, 0xffff0000, v2
	v_rcp_f32_e32 v14, v11
	s_nop 0
	v_mul_f32_e32 v11, v31, v14
	v_rcp_f32_e32 v14, v10
	s_nop 0
	v_mul_f32_e32 v10, v16, v14
	v_lshlrev_b32_e32 v14, 16, v9
	v_and_b32_e32 v15, 0xffff0000, v9
	v_pk_fma_f32 v[10:11], v[12:13], v[10:11], v[14:15]
	v_mov_b32_e32 v13, v1
	v_cvt_pk_bf16_f32 v9, v10, v11
	global_store_dwordx4 v[26:27], v[6:9], off
	v_mov_b32_e32 v17, v1
	v_lshlrev_b32_e32 v32, 16, v2
	v_add_u32_e32 v8, 4, v29
	v_ashrrev_i32_e32 v6, 3, v8
	v_ashrrev_i32_e32 v7, 31, v6
	v_lshl_add_u64 v[10:11], s[80:81], 0, v[6:7]
	v_and_or_b32 v16, v8, 7, s34
	v_mad_u64_u32 v[6:7], s[0:1], v10, s76, v[20:21]
	v_mad_i32_i24 v7, v11, s76, v7
	v_lshlrev_b32_e32 v12, 8, v16
	v_lshl_add_u64 v[6:7], v[6:7], 0, v[12:13]
	v_lshl_add_u64 v[6:7], v[6:7], 0, v[18:19]
	v_add_co_u32_e32 v6, vcc, s86, v6
	v_mad_u64_u32 v[14:15], s[0:1], v10, s77, v[22:23]
	s_nop 0
	v_addc_co_u32_e32 v7, vcc, 0, v7, vcc
	global_load_dwordx4 v[6:9], v[6:7], off
	v_mad_i32_i24 v15, v11, s77, v15
	v_lshlrev_b32_e32 v16, 2, v16
	v_lshl_add_u64 v[14:15], v[14:15], 0, v[16:17]
	global_load_dword v14, v[14:15], off offset:256
	v_lshlrev_b64 v[10:11], 13, v[10:11]
	v_lshl_add_u64 v[10:11], s[44:45], 0, v[10:11]
	v_lshl_add_u64 v[10:11], v[10:11], 0, v[12:13]
	v_lshl_add_u64 v[16:17], v[10:11], 0, v[18:19]
	global_load_dwordx4 v[10:13], v[16:17], off
	s_waitcnt vmcnt(2)
	v_lshlrev_b32_e32 v15, 16, v6
	v_and_b32_e32 v6, 0xffff0000, v6
	v_mul_f32_e32 v26, 0xbfb8aa3b, v15
	v_mul_f32_e32 v27, 0xbfb8aa3b, v6
	v_exp_f32_e32 v26, v26
	v_exp_f32_e32 v27, v27
	s_waitcnt vmcnt(1)
	v_pk_mul_f32 v[32:33], v[14:15], v[32:33] op_sel_hi:[0,1]
	v_pk_add_f32 v[26:27], v[26:27], 1.0 op_sel_hi:[1,0]
	s_nop 0
	s_nop 0
	v_rcp_f32_e32 v2, v27
	s_nop 0
	v_mul_f32_e32 v27, v6, v2
	v_rcp_f32_e32 v2, v26
	s_nop 0
	v_mul_f32_e32 v26, v15, v2
	v_lshlrev_b32_e32 v15, 16, v7
	v_and_b32_e32 v28, 0xffff0000, v7
	v_mul_f32_e32 v2, 0xbfb8aa3b, v15
	v_exp_f32_e32 v34, v2
	v_mul_f32_e32 v2, 0xbfb8aa3b, v28
	v_exp_f32_e32 v35, v2
	s_waitcnt vmcnt(0)
	v_lshlrev_b32_e32 v6, 16, v10
	v_and_b32_e32 v7, 0xffff0000, v10
	v_pk_fma_f32 v[6:7], v[32:33], v[26:27], v[6:7]
	v_lshlrev_b32_e32 v26, 16, v3
	v_cvt_pk_bf16_f32 v2, v6, v7
	v_pk_add_f32 v[6:7], v[34:35], 1.0 op_sel_hi:[1,0]
	v_and_b32_e32 v27, 0xffff0000, v3
	v_pk_mul_f32 v[26:27], v[14:15], v[26:27] op_sel_hi:[0,1]
	v_rcp_f32_e32 v3, v7
	s_nop 0
	v_mul_f32_e32 v7, v28, v3
	v_rcp_f32_e32 v3, v6
	s_nop 0
	v_mul_f32_e32 v6, v15, v3
	v_lshlrev_b32_e32 v15, 16, v8
	v_and_b32_e32 v8, 0xffff0000, v8
	v_mul_f32_e32 v3, 0xbfb8aa3b, v15
	v_exp_f32_e32 v32, v3
	v_mul_f32_e32 v3, 0xbfb8aa3b, v8
	v_exp_f32_e32 v33, v3
	v_lshlrev_b32_e32 v10, 16, v11
	v_and_b32_e32 v11, 0xffff0000, v11
	v_pk_fma_f32 v[6:7], v[26:27], v[6:7], v[10:11]
	v_lshlrev_b32_e32 v10, 16, v4
	v_cvt_pk_bf16_f32 v3, v6, v7
	v_pk_add_f32 v[6:7], v[32:33], 1.0 op_sel_hi:[1,0]
	v_and_b32_e32 v11, 0xffff0000, v4
	v_pk_mul_f32 v[10:11], v[14:15], v[10:11] op_sel_hi:[0,1]
	v_rcp_f32_e32 v4, v7
	s_nop 0
	v_mul_f32_e32 v7, v8, v4
	v_and_b32_e32 v28, 0xffff0000, v9
	v_rcp_f32_e32 v4, v6
	s_nop 0
	v_mul_f32_e32 v6, v15, v4
	v_lshlrev_b32_e32 v15, 16, v9
	v_mul_f32_e32 v4, 0xbfb8aa3b, v15
	v_exp_f32_e32 v26, v4
	v_mul_f32_e32 v4, 0xbfb8aa3b, v28
	v_exp_f32_e32 v27, v4
	v_lshlrev_b32_e32 v8, 16, v12
	v_and_b32_e32 v9, 0xffff0000, v12
	v_pk_fma_f32 v[6:7], v[10:11], v[6:7], v[8:9]
	v_lshlrev_b32_e32 v8, 16, v5
	v_cvt_pk_bf16_f32 v4, v6, v7
	v_pk_add_f32 v[6:7], v[26:27], 1.0 op_sel_hi:[1,0]
	v_and_b32_e32 v9, 0xffff0000, v5
	v_pk_mul_f32 v[8:9], v[14:15], v[8:9] op_sel_hi:[0,1]
	v_rcp_f32_e32 v5, v7
	s_nop 0
	v_mul_f32_e32 v7, v28, v5
	v_rcp_f32_e32 v5, v6
	s_nop 0
	v_mul_f32_e32 v6, v15, v5
	v_lshlrev_b32_e32 v10, 16, v13
	v_and_b32_e32 v11, 0xffff0000, v13
	v_pk_fma_f32 v[6:7], v[8:9], v[6:7], v[10:11]
	s_nop 0
	v_cvt_pk_bf16_f32 v5, v6, v7
	global_store_dwordx4 v[16:17], v[2:5], off
	ds_read_b128 v[14:17], v30 offset:2176
	s_nop 0
	v_add_u32_e32 v2, 8, v29
	v_ashrrev_i32_e32 v2, 3, v2
	v_ashrrev_i32_e32 v3, 31, v2
	v_lshl_add_u64 v[2:3], s[80:81], 0, v[2:3]
	v_mad_u64_u32 v[4:5], s[0:1], v2, s76, v[20:21]
	v_mad_i32_i24 v5, v3, s76, v5
	v_lshl_add_u64 v[4:5], v[4:5], 0, v[0:1]
	v_lshl_add_u64 v[4:5], v[4:5], 0, v[18:19]
	v_add_co_u32_e32 v4, vcc, s86, v4
	s_nop 1
	v_addc_co_u32_e32 v5, vcc, 0, v5, vcc
	global_load_dwordx4 v[10:13], v[4:5], off
	v_mad_u64_u32 v[4:5], s[0:1], v2, s77, v[22:23]
	v_mad_i32_i24 v5, v3, s77, v5
	v_lshlrev_b64 v[2:3], 13, v[2:3]
	v_lshl_add_u64 v[2:3], s[44:45], 0, v[2:3]
	v_lshl_add_u64 v[2:3], v[2:3], 0, v[0:1]
	v_lshl_add_u64 v[4:5], v[4:5], 0, v[24:25]
	v_lshl_add_u64 v[26:27], v[2:3], 0, v[18:19]
	global_load_dword v28, v[4:5], off offset:256
	global_load_dwordx4 v[6:9], v[26:27], off
	s_waitcnt vmcnt(2)
	v_lshlrev_b32_e32 v31, 16, v10
	v_and_b32_e32 v10, 0xffff0000, v10
	v_mul_f32_e32 v2, 0xbfb8aa3b, v31
	v_mul_f32_e32 v3, 0xbfb8aa3b, v10
	v_exp_f32_e32 v2, v2
	v_exp_f32_e32 v3, v3
	s_nop 0
	v_pk_add_f32 v[32:33], v[2:3], 1.0 op_sel_hi:[1,0]
	s_nop 0
	ds_read_b128 v[2:5], v30 offset:3264
	s_waitcnt lgkmcnt(1)
	v_lshlrev_b32_e32 v34, 16, v14
	v_and_b32_e32 v35, 0xffff0000, v14
	v_rcp_f32_e32 v14, v33
	s_nop 0
	v_mul_f32_e32 v33, v10, v14
	v_and_b32_e32 v38, 0xffff0000, v11
	v_rcp_f32_e32 v10, v32
	s_nop 0
	v_mul_f32_e32 v32, v31, v10
	v_lshlrev_b32_e32 v31, 16, v11
	v_mul_f32_e32 v11, 0xbfb8aa3b, v31
	v_exp_f32_e32 v36, v11
	v_mul_f32_e32 v11, 0xbfb8aa3b, v38
	v_exp_f32_e32 v37, v11
	s_waitcnt vmcnt(1)
	v_pk_mul_f32 v[34:35], v[28:29], v[34:35] op_sel_hi:[0,1]
	s_waitcnt vmcnt(0)
	v_lshlrev_b32_e32 v10, 16, v6
	v_and_b32_e32 v11, 0xffff0000, v6
	v_pk_fma_f32 v[10:11], v[34:35], v[32:33], v[10:11]
	v_lshlrev_b32_e32 v14, 16, v15
	v_cvt_pk_bf16_f32 v6, v10, v11
	v_pk_add_f32 v[10:11], v[36:37], 1.0 op_sel_hi:[1,0]
	v_and_b32_e32 v15, 0xffff0000, v15
	v_pk_mul_f32 v[14:15], v[28:29], v[14:15] op_sel_hi:[0,1]
	v_rcp_f32_e32 v32, v11
	s_nop 0
	v_mul_f32_e32 v11, v38, v32
	v_rcp_f32_e32 v32, v10
	s_nop 0
	v_mul_f32_e32 v10, v31, v32
	v_lshlrev_b32_e32 v31, 16, v12
	v_and_b32_e32 v12, 0xffff0000, v12
	v_mul_f32_e32 v33, 0xbfb8aa3b, v31
	v_exp_f32_e32 v34, v33
	v_mul_f32_e32 v33, 0xbfb8aa3b, v12
	v_exp_f32_e32 v35, v33
	v_lshlrev_b32_e32 v32, 16, v7
	v_and_b32_e32 v33, 0xffff0000, v7
	v_pk_fma_f32 v[10:11], v[14:15], v[10:11], v[32:33]
	v_lshlrev_b32_e32 v14, 16, v16
	v_cvt_pk_bf16_f32 v7, v10, v11
	v_pk_add_f32 v[10:11], v[34:35], 1.0 op_sel_hi:[1,0]
	v_and_b32_e32 v15, 0xffff0000, v16
	v_pk_mul_f32 v[14:15], v[28:29], v[14:15] op_sel_hi:[0,1]
	v_rcp_f32_e32 v16, v11
	s_nop 0
	v_mul_f32_e32 v11, v12, v16
	v_lshlrev_b32_e32 v16, 16, v13
	v_rcp_f32_e32 v12, v10
	s_nop 0
	v_mul_f32_e32 v10, v31, v12
	v_and_b32_e32 v31, 0xffff0000, v13
	v_mul_f32_e32 v13, 0xbfb8aa3b, v16
	v_exp_f32_e32 v32, v13
	v_mul_f32_e32 v13, 0xbfb8aa3b, v31
	v_exp_f32_e32 v33, v13
	v_lshlrev_b32_e32 v12, 16, v8
	v_and_b32_e32 v13, 0xffff0000, v8
	v_pk_fma_f32 v[10:11], v[14:15], v[10:11], v[12:13]
	v_lshlrev_b32_e32 v12, 16, v17
	v_cvt_pk_bf16_f32 v8, v10, v11
	v_pk_add_f32 v[10:11], v[32:33], 1.0 op_sel_hi:[1,0]
	v_and_b32_e32 v13, 0xffff0000, v17
	v_pk_mul_f32 v[12:13], v[28:29], v[12:13] op_sel_hi:[0,1]
	s_waitcnt lgkmcnt(0)
	v_and_b32_e32 v33, 0xffff0000, v2
	v_rcp_f32_e32 v14, v11
	s_nop 0
	v_mul_f32_e32 v11, v31, v14
	v_rcp_f32_e32 v14, v10
	s_nop 0
	v_mul_f32_e32 v10, v16, v14
	v_lshlrev_b32_e32 v14, 16, v9
	v_and_b32_e32 v15, 0xffff0000, v9
	v_pk_fma_f32 v[10:11], v[12:13], v[10:11], v[14:15]
	v_mov_b32_e32 v13, v1
	v_cvt_pk_bf16_f32 v9, v10, v11
	global_store_dwordx4 v[26:27], v[6:9], off
	v_mov_b32_e32 v17, v1
	v_lshlrev_b32_e32 v32, 16, v2
	v_add_u32_e32 v8, 12, v29
	v_ashrrev_i32_e32 v6, 3, v8
	v_ashrrev_i32_e32 v7, 31, v6
	v_lshl_add_u64 v[10:11], s[80:81], 0, v[6:7]
	v_and_or_b32 v16, v8, 7, s34
	v_mad_u64_u32 v[6:7], s[0:1], v10, s76, v[20:21]
	v_mad_i32_i24 v7, v11, s76, v7
	v_lshlrev_b32_e32 v12, 8, v16
	v_lshl_add_u64 v[6:7], v[6:7], 0, v[12:13]
	v_lshl_add_u64 v[6:7], v[6:7], 0, v[18:19]
	v_add_co_u32_e32 v6, vcc, s86, v6
	v_mad_u64_u32 v[14:15], s[0:1], v10, s77, v[22:23]
	s_nop 0
	v_addc_co_u32_e32 v7, vcc, 0, v7, vcc
	global_load_dwordx4 v[6:9], v[6:7], off
	v_mad_i32_i24 v15, v11, s77, v15
	v_lshlrev_b32_e32 v16, 2, v16
	v_lshl_add_u64 v[14:15], v[14:15], 0, v[16:17]
	global_load_dword v14, v[14:15], off offset:256
	v_lshlrev_b64 v[10:11], 13, v[10:11]
	v_lshl_add_u64 v[10:11], s[44:45], 0, v[10:11]
	v_lshl_add_u64 v[10:11], v[10:11], 0, v[12:13]
	v_lshl_add_u64 v[16:17], v[10:11], 0, v[18:19]
	global_load_dwordx4 v[10:13], v[16:17], off
	s_waitcnt vmcnt(2)
	v_lshlrev_b32_e32 v15, 16, v6
	v_and_b32_e32 v6, 0xffff0000, v6
	v_mul_f32_e32 v26, 0xbfb8aa3b, v15
	v_mul_f32_e32 v27, 0xbfb8aa3b, v6
	v_exp_f32_e32 v26, v26
	v_exp_f32_e32 v27, v27
	s_waitcnt vmcnt(1)
	v_pk_mul_f32 v[32:33], v[14:15], v[32:33] op_sel_hi:[0,1]
	v_pk_add_f32 v[26:27], v[26:27], 1.0 op_sel_hi:[1,0]
	s_nop 0
	s_nop 0
	v_rcp_f32_e32 v2, v27
	s_nop 0
	v_mul_f32_e32 v27, v6, v2
	v_rcp_f32_e32 v2, v26
	s_nop 0
	v_mul_f32_e32 v26, v15, v2
	v_lshlrev_b32_e32 v15, 16, v7
	v_and_b32_e32 v28, 0xffff0000, v7
	v_mul_f32_e32 v2, 0xbfb8aa3b, v15
	v_exp_f32_e32 v34, v2
	v_mul_f32_e32 v2, 0xbfb8aa3b, v28
	v_exp_f32_e32 v35, v2
	s_waitcnt vmcnt(0)
	v_lshlrev_b32_e32 v6, 16, v10
	v_and_b32_e32 v7, 0xffff0000, v10
	v_pk_fma_f32 v[6:7], v[32:33], v[26:27], v[6:7]
	v_lshlrev_b32_e32 v26, 16, v3
	v_cvt_pk_bf16_f32 v2, v6, v7
	v_pk_add_f32 v[6:7], v[34:35], 1.0 op_sel_hi:[1,0]
	v_and_b32_e32 v27, 0xffff0000, v3
	v_pk_mul_f32 v[26:27], v[14:15], v[26:27] op_sel_hi:[0,1]
	v_rcp_f32_e32 v3, v7
	s_nop 0
	v_mul_f32_e32 v7, v28, v3
	v_rcp_f32_e32 v3, v6
	s_nop 0
	v_mul_f32_e32 v6, v15, v3
	v_lshlrev_b32_e32 v15, 16, v8
	v_and_b32_e32 v8, 0xffff0000, v8
	v_mul_f32_e32 v3, 0xbfb8aa3b, v15
	v_exp_f32_e32 v32, v3
	v_mul_f32_e32 v3, 0xbfb8aa3b, v8
	v_exp_f32_e32 v33, v3
	v_lshlrev_b32_e32 v10, 16, v11
	v_and_b32_e32 v11, 0xffff0000, v11
	v_pk_fma_f32 v[6:7], v[26:27], v[6:7], v[10:11]
	v_lshlrev_b32_e32 v10, 16, v4
	v_cvt_pk_bf16_f32 v3, v6, v7
	v_pk_add_f32 v[6:7], v[32:33], 1.0 op_sel_hi:[1,0]
	v_and_b32_e32 v11, 0xffff0000, v4
	v_pk_mul_f32 v[10:11], v[14:15], v[10:11] op_sel_hi:[0,1]
	v_rcp_f32_e32 v4, v7
	s_nop 0
	v_mul_f32_e32 v7, v8, v4
	v_and_b32_e32 v28, 0xffff0000, v9
	v_rcp_f32_e32 v4, v6
	s_nop 0
	v_mul_f32_e32 v6, v15, v4
	v_lshlrev_b32_e32 v15, 16, v9
	v_mul_f32_e32 v4, 0xbfb8aa3b, v15
	v_exp_f32_e32 v26, v4
	v_mul_f32_e32 v4, 0xbfb8aa3b, v28
	v_exp_f32_e32 v27, v4
	v_lshlrev_b32_e32 v8, 16, v12
	v_and_b32_e32 v9, 0xffff0000, v12
	v_pk_fma_f32 v[6:7], v[10:11], v[6:7], v[8:9]
	v_lshlrev_b32_e32 v8, 16, v5
	v_cvt_pk_bf16_f32 v4, v6, v7
	v_pk_add_f32 v[6:7], v[26:27], 1.0 op_sel_hi:[1,0]
	v_and_b32_e32 v9, 0xffff0000, v5
	v_pk_mul_f32 v[8:9], v[14:15], v[8:9] op_sel_hi:[0,1]
	v_rcp_f32_e32 v5, v7
	s_nop 0
	v_mul_f32_e32 v7, v28, v5
	v_rcp_f32_e32 v5, v6
	s_nop 0
	v_mul_f32_e32 v6, v15, v5
	v_lshlrev_b32_e32 v10, 16, v13
	v_and_b32_e32 v11, 0xffff0000, v13
	v_pk_fma_f32 v[6:7], v[8:9], v[6:7], v[10:11]
	s_nop 0
	v_cvt_pk_bf16_f32 v5, v6, v7
	global_store_dwordx4 v[16:17], v[2:5], off
	ds_read_b128 v[14:17], v30 offset:4352
	s_nop 0
	v_add_u32_e32 v2, 16, v29
	v_ashrrev_i32_e32 v2, 3, v2
	v_ashrrev_i32_e32 v3, 31, v2
	v_lshl_add_u64 v[2:3], s[80:81], 0, v[2:3]
	v_mad_u64_u32 v[4:5], s[0:1], v2, s76, v[20:21]
	v_mad_i32_i24 v5, v3, s76, v5
	v_lshl_add_u64 v[4:5], v[4:5], 0, v[0:1]
	v_lshl_add_u64 v[4:5], v[4:5], 0, v[18:19]
	v_add_co_u32_e32 v4, vcc, s86, v4
	s_nop 1
	v_addc_co_u32_e32 v5, vcc, 0, v5, vcc
	global_load_dwordx4 v[10:13], v[4:5], off
	v_mad_u64_u32 v[4:5], s[0:1], v2, s77, v[22:23]
	v_mad_i32_i24 v5, v3, s77, v5
	v_lshlrev_b64 v[2:3], 13, v[2:3]
	v_lshl_add_u64 v[2:3], s[44:45], 0, v[2:3]
	v_lshl_add_u64 v[2:3], v[2:3], 0, v[0:1]
	v_lshl_add_u64 v[4:5], v[4:5], 0, v[24:25]
	v_lshl_add_u64 v[26:27], v[2:3], 0, v[18:19]
	global_load_dword v28, v[4:5], off offset:256
	global_load_dwordx4 v[6:9], v[26:27], off
	s_waitcnt vmcnt(2)
	v_lshlrev_b32_e32 v31, 16, v10
	v_and_b32_e32 v10, 0xffff0000, v10
	v_mul_f32_e32 v2, 0xbfb8aa3b, v31
	v_mul_f32_e32 v3, 0xbfb8aa3b, v10
	v_exp_f32_e32 v2, v2
	v_exp_f32_e32 v3, v3
	s_nop 0
	v_pk_add_f32 v[32:33], v[2:3], 1.0 op_sel_hi:[1,0]
	s_nop 0
	ds_read_b128 v[2:5], v30 offset:5440
	s_waitcnt lgkmcnt(1)
	v_lshlrev_b32_e32 v34, 16, v14
	v_and_b32_e32 v35, 0xffff0000, v14
	v_rcp_f32_e32 v14, v33
	s_nop 0
	v_mul_f32_e32 v33, v10, v14
	v_and_b32_e32 v38, 0xffff0000, v11
	v_rcp_f32_e32 v10, v32
	s_nop 0
	v_mul_f32_e32 v32, v31, v10
	v_lshlrev_b32_e32 v31, 16, v11
	v_mul_f32_e32 v11, 0xbfb8aa3b, v31
	v_exp_f32_e32 v36, v11
	v_mul_f32_e32 v11, 0xbfb8aa3b, v38
	v_exp_f32_e32 v37, v11
	s_waitcnt vmcnt(1)
	v_pk_mul_f32 v[34:35], v[28:29], v[34:35] op_sel_hi:[0,1]
	s_waitcnt vmcnt(0)
	v_lshlrev_b32_e32 v10, 16, v6
	v_and_b32_e32 v11, 0xffff0000, v6
	v_pk_fma_f32 v[10:11], v[34:35], v[32:33], v[10:11]
	v_lshlrev_b32_e32 v14, 16, v15
	v_cvt_pk_bf16_f32 v6, v10, v11
	v_pk_add_f32 v[10:11], v[36:37], 1.0 op_sel_hi:[1,0]
	v_and_b32_e32 v15, 0xffff0000, v15
	v_pk_mul_f32 v[14:15], v[28:29], v[14:15] op_sel_hi:[0,1]
	v_rcp_f32_e32 v32, v11
	s_nop 0
	v_mul_f32_e32 v11, v38, v32
	v_rcp_f32_e32 v32, v10
	s_nop 0
	v_mul_f32_e32 v10, v31, v32
	v_lshlrev_b32_e32 v31, 16, v12
	v_and_b32_e32 v12, 0xffff0000, v12
	v_mul_f32_e32 v33, 0xbfb8aa3b, v31
	v_exp_f32_e32 v34, v33
	v_mul_f32_e32 v33, 0xbfb8aa3b, v12
	v_exp_f32_e32 v35, v33
	v_lshlrev_b32_e32 v32, 16, v7
	v_and_b32_e32 v33, 0xffff0000, v7
	v_pk_fma_f32 v[10:11], v[14:15], v[10:11], v[32:33]
	v_lshlrev_b32_e32 v14, 16, v16
	v_cvt_pk_bf16_f32 v7, v10, v11
	v_pk_add_f32 v[10:11], v[34:35], 1.0 op_sel_hi:[1,0]
	v_and_b32_e32 v15, 0xffff0000, v16
	v_pk_mul_f32 v[14:15], v[28:29], v[14:15] op_sel_hi:[0,1]
	v_rcp_f32_e32 v16, v11
	s_nop 0
	v_mul_f32_e32 v11, v12, v16
	v_lshlrev_b32_e32 v16, 16, v13
	v_rcp_f32_e32 v12, v10
	s_nop 0
	v_mul_f32_e32 v10, v31, v12
	v_and_b32_e32 v31, 0xffff0000, v13
	v_mul_f32_e32 v13, 0xbfb8aa3b, v16
	v_exp_f32_e32 v32, v13
	v_mul_f32_e32 v13, 0xbfb8aa3b, v31
	v_exp_f32_e32 v33, v13
	v_lshlrev_b32_e32 v12, 16, v8
	v_and_b32_e32 v13, 0xffff0000, v8
	v_pk_fma_f32 v[10:11], v[14:15], v[10:11], v[12:13]
	v_lshlrev_b32_e32 v12, 16, v17
	v_cvt_pk_bf16_f32 v8, v10, v11
	v_pk_add_f32 v[10:11], v[32:33], 1.0 op_sel_hi:[1,0]
	v_and_b32_e32 v13, 0xffff0000, v17
	v_pk_mul_f32 v[12:13], v[28:29], v[12:13] op_sel_hi:[0,1]
	s_waitcnt lgkmcnt(0)
	v_and_b32_e32 v33, 0xffff0000, v2
	v_rcp_f32_e32 v14, v11
	s_nop 0
	v_mul_f32_e32 v11, v31, v14
	v_rcp_f32_e32 v14, v10
	s_nop 0
	v_mul_f32_e32 v10, v16, v14
	v_lshlrev_b32_e32 v14, 16, v9
	v_and_b32_e32 v15, 0xffff0000, v9
	v_pk_fma_f32 v[10:11], v[12:13], v[10:11], v[14:15]
	v_mov_b32_e32 v13, v1
	v_cvt_pk_bf16_f32 v9, v10, v11
	global_store_dwordx4 v[26:27], v[6:9], off
	v_mov_b32_e32 v17, v1
	v_lshlrev_b32_e32 v32, 16, v2
	v_add_u32_e32 v8, 20, v29
	v_ashrrev_i32_e32 v6, 3, v8
	v_ashrrev_i32_e32 v7, 31, v6
	v_lshl_add_u64 v[10:11], s[80:81], 0, v[6:7]
	v_and_or_b32 v16, v8, 7, s34
	v_mad_u64_u32 v[6:7], s[0:1], v10, s76, v[20:21]
	v_mad_i32_i24 v7, v11, s76, v7
	v_lshlrev_b32_e32 v12, 8, v16
	v_lshl_add_u64 v[6:7], v[6:7], 0, v[12:13]
	v_lshl_add_u64 v[6:7], v[6:7], 0, v[18:19]
	v_add_co_u32_e32 v6, vcc, s86, v6
	v_mad_u64_u32 v[14:15], s[0:1], v10, s77, v[22:23]
	s_nop 0
	v_addc_co_u32_e32 v7, vcc, 0, v7, vcc
	global_load_dwordx4 v[6:9], v[6:7], off
	v_mad_i32_i24 v15, v11, s77, v15
	v_lshlrev_b32_e32 v16, 2, v16
	v_lshl_add_u64 v[14:15], v[14:15], 0, v[16:17]
	global_load_dword v14, v[14:15], off offset:256
	v_lshlrev_b64 v[10:11], 13, v[10:11]
	v_lshl_add_u64 v[10:11], s[44:45], 0, v[10:11]
	v_lshl_add_u64 v[10:11], v[10:11], 0, v[12:13]
	v_lshl_add_u64 v[16:17], v[10:11], 0, v[18:19]
	global_load_dwordx4 v[10:13], v[16:17], off
	s_waitcnt vmcnt(2)
	v_lshlrev_b32_e32 v15, 16, v6
	v_and_b32_e32 v6, 0xffff0000, v6
	v_mul_f32_e32 v26, 0xbfb8aa3b, v15
	v_mul_f32_e32 v27, 0xbfb8aa3b, v6
	v_exp_f32_e32 v26, v26
	v_exp_f32_e32 v27, v27
	s_waitcnt vmcnt(1)
	v_pk_mul_f32 v[32:33], v[14:15], v[32:33] op_sel_hi:[0,1]
	v_pk_add_f32 v[26:27], v[26:27], 1.0 op_sel_hi:[1,0]
	s_nop 0
	s_nop 0
	v_rcp_f32_e32 v2, v27
	s_nop 0
	v_mul_f32_e32 v27, v6, v2
	v_rcp_f32_e32 v2, v26
	s_nop 0
	v_mul_f32_e32 v26, v15, v2
	v_lshlrev_b32_e32 v15, 16, v7
	v_and_b32_e32 v28, 0xffff0000, v7
	v_mul_f32_e32 v2, 0xbfb8aa3b, v15
	v_exp_f32_e32 v34, v2
	v_mul_f32_e32 v2, 0xbfb8aa3b, v28
	v_exp_f32_e32 v35, v2
	s_waitcnt vmcnt(0)
	v_lshlrev_b32_e32 v6, 16, v10
	v_and_b32_e32 v7, 0xffff0000, v10
	v_pk_fma_f32 v[6:7], v[32:33], v[26:27], v[6:7]
	v_lshlrev_b32_e32 v26, 16, v3
	v_cvt_pk_bf16_f32 v2, v6, v7
	v_pk_add_f32 v[6:7], v[34:35], 1.0 op_sel_hi:[1,0]
	v_and_b32_e32 v27, 0xffff0000, v3
	v_pk_mul_f32 v[26:27], v[14:15], v[26:27] op_sel_hi:[0,1]
	v_rcp_f32_e32 v3, v7
	s_nop 0
	v_mul_f32_e32 v7, v28, v3
	v_rcp_f32_e32 v3, v6
	s_nop 0
	v_mul_f32_e32 v6, v15, v3
	v_lshlrev_b32_e32 v15, 16, v8
	v_and_b32_e32 v8, 0xffff0000, v8
	v_mul_f32_e32 v3, 0xbfb8aa3b, v15
	v_exp_f32_e32 v32, v3
	v_mul_f32_e32 v3, 0xbfb8aa3b, v8
	v_exp_f32_e32 v33, v3
	v_lshlrev_b32_e32 v10, 16, v11
	v_and_b32_e32 v11, 0xffff0000, v11
	v_pk_fma_f32 v[6:7], v[26:27], v[6:7], v[10:11]
	v_lshlrev_b32_e32 v10, 16, v4
	v_cvt_pk_bf16_f32 v3, v6, v7
	v_pk_add_f32 v[6:7], v[32:33], 1.0 op_sel_hi:[1,0]
	v_and_b32_e32 v11, 0xffff0000, v4
	v_pk_mul_f32 v[10:11], v[14:15], v[10:11] op_sel_hi:[0,1]
	v_rcp_f32_e32 v4, v7
	s_nop 0
	v_mul_f32_e32 v7, v8, v4
	v_and_b32_e32 v28, 0xffff0000, v9
	v_rcp_f32_e32 v4, v6
	s_nop 0
	v_mul_f32_e32 v6, v15, v4
	v_lshlrev_b32_e32 v15, 16, v9
	v_mul_f32_e32 v4, 0xbfb8aa3b, v15
	v_exp_f32_e32 v26, v4
	v_mul_f32_e32 v4, 0xbfb8aa3b, v28
	v_exp_f32_e32 v27, v4
	v_lshlrev_b32_e32 v8, 16, v12
	v_and_b32_e32 v9, 0xffff0000, v12
	v_pk_fma_f32 v[6:7], v[10:11], v[6:7], v[8:9]
	v_lshlrev_b32_e32 v8, 16, v5
	v_cvt_pk_bf16_f32 v4, v6, v7
	v_pk_add_f32 v[6:7], v[26:27], 1.0 op_sel_hi:[1,0]
	v_and_b32_e32 v9, 0xffff0000, v5
	v_pk_mul_f32 v[8:9], v[14:15], v[8:9] op_sel_hi:[0,1]
	v_rcp_f32_e32 v5, v7
	s_nop 0
	v_mul_f32_e32 v7, v28, v5
	v_rcp_f32_e32 v5, v6
	s_nop 0
	v_mul_f32_e32 v6, v15, v5
	v_lshlrev_b32_e32 v10, 16, v13
	v_and_b32_e32 v11, 0xffff0000, v13
	v_pk_fma_f32 v[6:7], v[8:9], v[6:7], v[10:11]
	s_nop 0
	v_cvt_pk_bf16_f32 v5, v6, v7
	global_store_dwordx4 v[16:17], v[2:5], off
	ds_read_b128 v[14:17], v30 offset:6528
	s_nop 0
	v_add_u32_e32 v2, 24, v29
	v_ashrrev_i32_e32 v2, 3, v2
	v_ashrrev_i32_e32 v3, 31, v2
	v_lshl_add_u64 v[2:3], s[80:81], 0, v[2:3]
	v_mad_u64_u32 v[4:5], s[0:1], v2, s76, v[20:21]
	v_mad_i32_i24 v5, v3, s76, v5
	v_lshl_add_u64 v[4:5], v[4:5], 0, v[0:1]
	v_lshl_add_u64 v[4:5], v[4:5], 0, v[18:19]
	v_add_co_u32_e32 v4, vcc, s86, v4
	s_nop 1
	v_addc_co_u32_e32 v5, vcc, 0, v5, vcc
	global_load_dwordx4 v[10:13], v[4:5], off
	v_mad_u64_u32 v[4:5], s[0:1], v2, s77, v[22:23]
	v_mad_i32_i24 v5, v3, s77, v5
	v_lshl_add_u64 v[4:5], v[4:5], 0, v[24:25]
	global_load_dword v26, v[4:5], off offset:256
	v_lshlrev_b64 v[2:3], 13, v[2:3]
	v_lshl_add_u64 v[2:3], s[44:45], 0, v[2:3]
	v_lshl_add_u64 v[2:3], v[2:3], 0, v[0:1]
	v_lshl_add_u64 v[24:25], v[2:3], 0, v[18:19]
	global_load_dwordx4 v[6:9], v[24:25], off
	s_waitcnt vmcnt(2)
	v_lshlrev_b32_e32 v0, 16, v10
	v_and_b32_e32 v10, 0xffff0000, v10
	v_mul_f32_e32 v2, 0xbfb8aa3b, v0
	v_mul_f32_e32 v3, 0xbfb8aa3b, v10
	v_exp_f32_e32 v2, v2
	v_exp_f32_e32 v3, v3
	s_nop 0
	v_pk_add_f32 v[32:33], v[2:3], 1.0 op_sel_hi:[1,0]
	s_nop 0
	ds_read_b128 v[2:5], v30 offset:7616
	s_waitcnt lgkmcnt(1)
	v_lshlrev_b32_e32 v30, 16, v14
	v_and_b32_e32 v31, 0xffff0000, v14
	s_waitcnt vmcnt(1)
	v_pk_mul_f32 v[30:31], v[26:27], v[30:31] op_sel_hi:[0,1]
	v_rcp_f32_e32 v14, v33
	s_nop 0
	v_mul_f32_e32 v33, v10, v14
	v_rcp_f32_e32 v10, v32
	s_nop 0
	v_mul_f32_e32 v32, v0, v10
	v_lshlrev_b32_e32 v0, 16, v11
	v_and_b32_e32 v27, 0xffff0000, v11
	v_mul_f32_e32 v11, 0xbfb8aa3b, v0
	v_exp_f32_e32 v34, v11
	v_mul_f32_e32 v11, 0xbfb8aa3b, v27
	v_exp_f32_e32 v35, v11
	s_waitcnt vmcnt(0)
	v_lshlrev_b32_e32 v10, 16, v6
	v_and_b32_e32 v11, 0xffff0000, v6
	v_pk_fma_f32 v[10:11], v[30:31], v[32:33], v[10:11]
	v_lshlrev_b32_e32 v14, 16, v15
	v_cvt_pk_bf16_f32 v6, v10, v11
	v_pk_add_f32 v[10:11], v[34:35], 1.0 op_sel_hi:[1,0]
	v_and_b32_e32 v15, 0xffff0000, v15
	v_pk_mul_f32 v[14:15], v[26:27], v[14:15] op_sel_hi:[0,1]
	v_rcp_f32_e32 v28, v11
	s_nop 0
	v_mul_f32_e32 v11, v27, v28
	v_rcp_f32_e32 v27, v10
	s_nop 0
	v_mul_f32_e32 v10, v0, v27
	v_lshlrev_b32_e32 v0, 16, v12
	v_and_b32_e32 v12, 0xffff0000, v12
	v_mul_f32_e32 v27, 0xbfb8aa3b, v0
	v_exp_f32_e32 v32, v27
	v_mul_f32_e32 v27, 0xbfb8aa3b, v12
	v_exp_f32_e32 v33, v27
	v_lshlrev_b32_e32 v30, 16, v7
	v_and_b32_e32 v31, 0xffff0000, v7
	v_pk_fma_f32 v[10:11], v[14:15], v[10:11], v[30:31]
	v_lshlrev_b32_e32 v14, 16, v16
	v_cvt_pk_bf16_f32 v7, v10, v11
	v_pk_add_f32 v[10:11], v[32:33], 1.0 op_sel_hi:[1,0]
	v_and_b32_e32 v15, 0xffff0000, v16
	v_pk_mul_f32 v[14:15], v[26:27], v[14:15] op_sel_hi:[0,1]
	v_rcp_f32_e32 v16, v11
	s_nop 0
	v_mul_f32_e32 v11, v12, v16
	v_rcp_f32_e32 v12, v10
	s_nop 0
	v_mul_f32_e32 v10, v0, v12
	v_lshlrev_b32_e32 v0, 16, v13
	v_and_b32_e32 v16, 0xffff0000, v13
	v_mul_f32_e32 v13, 0xbfb8aa3b, v0
	v_exp_f32_e32 v30, v13
	v_mul_f32_e32 v13, 0xbfb8aa3b, v16
	v_exp_f32_e32 v31, v13
	v_lshlrev_b32_e32 v12, 16, v8
	v_and_b32_e32 v13, 0xffff0000, v8
	v_pk_fma_f32 v[10:11], v[14:15], v[10:11], v[12:13]
	v_lshlrev_b32_e32 v12, 16, v17
	v_cvt_pk_bf16_f32 v8, v10, v11
	v_pk_add_f32 v[10:11], v[30:31], 1.0 op_sel_hi:[1,0]
	v_and_b32_e32 v13, 0xffff0000, v17
	v_pk_mul_f32 v[12:13], v[26:27], v[12:13] op_sel_hi:[0,1]
	v_rcp_f32_e32 v14, v11
	s_nop 0
	v_mul_f32_e32 v11, v16, v14
	v_rcp_f32_e32 v14, v10
	s_nop 0
	v_mul_f32_e32 v10, v0, v14
	v_lshlrev_b32_e32 v14, 16, v9
	v_and_b32_e32 v15, 0xffff0000, v9
	v_pk_fma_f32 v[10:11], v[12:13], v[10:11], v[14:15]
	v_add_u32_e32 v0, 28, v29
	v_cvt_pk_bf16_f32 v9, v10, v11
	global_store_dwordx4 v[24:25], v[6:9], off
	v_and_or_b32 v14, v0, 7, s34
	v_mov_b32_e32 v15, v1
	v_ashrrev_i32_e32 v6, 3, v0
	v_ashrrev_i32_e32 v7, 31, v6
	v_lshl_add_u64 v[10:11], s[80:81], 0, v[6:7]
	v_mad_u64_u32 v[6:7], s[0:1], v10, s76, v[20:21]
	v_mad_i32_i24 v7, v11, s76, v7
	v_lshlrev_b32_e32 v0, 8, v14
	v_lshl_add_u64 v[6:7], v[6:7], 0, v[0:1]
	v_lshl_add_u64 v[6:7], v[6:7], 0, v[18:19]
	v_add_co_u32_e32 v6, vcc, s86, v6
	v_mad_u64_u32 v[12:13], s[0:1], v10, s77, v[22:23]
	s_nop 0
	v_addc_co_u32_e32 v7, vcc, 0, v7, vcc
	global_load_dwordx4 v[6:9], v[6:7], off
	v_mad_i32_i24 v13, v11, s77, v13
	v_lshlrev_b32_e32 v14, 2, v14
	v_lshl_add_u64 v[12:13], v[12:13], 0, v[14:15]
	global_load_dword v14, v[12:13], off offset:256
	v_lshlrev_b64 v[10:11], 13, v[10:11]
	v_lshl_add_u64 v[10:11], s[44:45], 0, v[10:11]
	v_lshl_add_u64 v[10:11], v[10:11], 0, v[0:1]
	v_lshl_add_u64 v[16:17], v[10:11], 0, v[18:19]
	global_load_dwordx4 v[10:13], v[16:17], off
	s_waitcnt lgkmcnt(0)
	v_lshlrev_b32_e32 v20, 16, v2
	v_and_b32_e32 v21, 0xffff0000, v2
	s_waitcnt vmcnt(2)
	v_lshlrev_b32_e32 v0, 16, v6
	v_and_b32_e32 v6, 0xffff0000, v6
	v_mul_f32_e32 v15, 0xbfb8aa3b, v0
	v_exp_f32_e32 v18, v15
	v_mul_f32_e32 v15, 0xbfb8aa3b, v6
	v_exp_f32_e32 v19, v15
	s_nop 0
	v_pk_add_f32 v[18:19], v[18:19], 1.0 op_sel_hi:[1,0]
	s_nop 0
	s_waitcnt vmcnt(1)
	v_pk_mul_f32 v[20:21], v[14:15], v[20:21] op_sel_hi:[0,1]
	v_rcp_f32_e32 v2, v19
	s_nop 0
	v_mul_f32_e32 v19, v6, v2
	v_rcp_f32_e32 v2, v18
	s_nop 0
	v_mul_f32_e32 v18, v0, v2
	v_lshlrev_b32_e32 v0, 16, v7
	v_and_b32_e32 v15, 0xffff0000, v7
	v_mul_f32_e32 v2, 0xbfb8aa3b, v0
	v_exp_f32_e32 v22, v2
	v_mul_f32_e32 v2, 0xbfb8aa3b, v15
	v_exp_f32_e32 v23, v2
	s_waitcnt vmcnt(0)
	v_lshlrev_b32_e32 v6, 16, v10
	v_and_b32_e32 v7, 0xffff0000, v10
	v_pk_fma_f32 v[6:7], v[20:21], v[18:19], v[6:7]
	v_lshlrev_b32_e32 v18, 16, v3
	v_cvt_pk_bf16_f32 v2, v6, v7
	v_pk_add_f32 v[6:7], v[22:23], 1.0 op_sel_hi:[1,0]
	v_and_b32_e32 v19, 0xffff0000, v3
	v_pk_mul_f32 v[18:19], v[14:15], v[18:19] op_sel_hi:[0,1]
	v_rcp_f32_e32 v3, v7
	s_nop 0
	v_mul_f32_e32 v7, v15, v3
	v_rcp_f32_e32 v3, v6
	s_nop 0
	v_mul_f32_e32 v6, v0, v3
	v_lshlrev_b32_e32 v0, 16, v8
	v_and_b32_e32 v8, 0xffff0000, v8
	v_mul_f32_e32 v3, 0xbfb8aa3b, v0
	v_exp_f32_e32 v20, v3
	v_mul_f32_e32 v3, 0xbfb8aa3b, v8
	v_exp_f32_e32 v21, v3
	v_lshlrev_b32_e32 v10, 16, v11
	v_and_b32_e32 v11, 0xffff0000, v11
	v_pk_fma_f32 v[6:7], v[18:19], v[6:7], v[10:11]
	v_lshlrev_b32_e32 v10, 16, v4
	v_cvt_pk_bf16_f32 v3, v6, v7
	v_pk_add_f32 v[6:7], v[20:21], 1.0 op_sel_hi:[1,0]
	v_and_b32_e32 v11, 0xffff0000, v4
	v_pk_mul_f32 v[10:11], v[14:15], v[10:11] op_sel_hi:[0,1]
	v_rcp_f32_e32 v4, v7
	s_nop 0
	v_mul_f32_e32 v7, v8, v4
	v_rcp_f32_e32 v4, v6
	s_nop 0
	v_mul_f32_e32 v6, v0, v4
	v_lshlrev_b32_e32 v0, 16, v9
	v_and_b32_e32 v15, 0xffff0000, v9
	v_mul_f32_e32 v4, 0xbfb8aa3b, v0
	v_exp_f32_e32 v18, v4
	v_mul_f32_e32 v4, 0xbfb8aa3b, v15
	v_exp_f32_e32 v19, v4
	v_lshlrev_b32_e32 v8, 16, v12
	v_and_b32_e32 v9, 0xffff0000, v12
	v_pk_fma_f32 v[6:7], v[10:11], v[6:7], v[8:9]
	v_lshlrev_b32_e32 v8, 16, v5
	v_cvt_pk_bf16_f32 v4, v6, v7
	v_pk_add_f32 v[6:7], v[18:19], 1.0 op_sel_hi:[1,0]
	v_and_b32_e32 v9, 0xffff0000, v5
	v_pk_mul_f32 v[8:9], v[14:15], v[8:9] op_sel_hi:[0,1]
	v_rcp_f32_e32 v5, v7
	s_nop 0
	v_mul_f32_e32 v7, v15, v5
	v_rcp_f32_e32 v5, v6
	s_nop 0
	v_mul_f32_e32 v6, v0, v5
	v_lshlrev_b32_e32 v10, 16, v13
	v_and_b32_e32 v11, 0xffff0000, v13
	v_pk_fma_f32 v[6:7], v[8:9], v[6:7], v[10:11]
	s_nop 0
	v_cvt_pk_bf16_f32 v5, v6, v7
	global_store_dwordx4 v[16:17], v[2:5], off
	s_barrier
	s_cbranch_scc1 .LBB0_1246

.LBB0_1089:
	s_waitcnt lgkmcnt(0)
	v_add_f32_e32 v2, v66, v67
	v_mov_b32_e32 v50, 0
	v_rcp_f32_e32 v3, v2
	s_nop 0
	v_mul_f32_e32 v3, 1.0, v3
	v_cmp_lt_f32_e32 vcc, 0, v2
	v_lshl_add_u64 v[134:135], s[14:15], 0, v[164:165]
	s_add_i32 s20, 0, 0x1bb04
	v_cndmask_b32_e32 v139, 0, v3, vcc
	s_mov_b32 s14, 0
	v_mov_b32_e32 v51, v50
	v_mov_b32_e32 v52, v50
	v_mov_b32_e32 v53, v50
	v_mov_b32_e32 v54, v50
	v_mov_b32_e32 v55, v50
	v_mov_b32_e32 v56, v50
	v_mov_b32_e32 v57, v50
	v_mov_b32_e32 v58, v50
	v_mov_b32_e32 v59, v50
	v_mov_b32_e32 v60, v50
	v_mov_b32_e32 v61, v50
	v_mov_b32_e32 v62, v50
	v_mov_b32_e32 v63, v50
	v_mov_b32_e32 v64, v50
	v_mov_b32_e32 v65, v50
	v_mov_b32_e32 v34, v50
	v_mov_b32_e32 v35, v50
	v_mov_b32_e32 v36, v50
	v_mov_b32_e32 v37, v50
	v_mov_b32_e32 v38, v50
	v_mov_b32_e32 v39, v50
	v_mov_b32_e32 v40, v50
	v_mov_b32_e32 v41, v50
	v_mov_b32_e32 v42, v50
	v_mov_b32_e32 v43, v50
	v_mov_b32_e32 v44, v50
	v_mov_b32_e32 v45, v50
	v_mov_b32_e32 v46, v50
	v_mov_b32_e32 v47, v50
	v_mov_b32_e32 v48, v50
	v_mov_b32_e32 v49, v50
	v_mov_b32_e32 v18, v50
	v_mov_b32_e32 v19, v50
	v_mov_b32_e32 v20, v50
	v_mov_b32_e32 v21, v50
	v_mov_b32_e32 v22, v50
	v_mov_b32_e32 v23, v50
	v_mov_b32_e32 v24, v50
	v_mov_b32_e32 v25, v50
	v_mov_b32_e32 v26, v50
	v_mov_b32_e32 v27, v50
	v_mov_b32_e32 v28, v50
	v_mov_b32_e32 v29, v50
	v_mov_b32_e32 v30, v50
	v_mov_b32_e32 v31, v50
	v_mov_b32_e32 v32, v50
	v_mov_b32_e32 v33, v50
	v_mov_b32_e32 v2, v50
	v_mov_b32_e32 v3, v50
	v_mov_b32_e32 v4, v50
	v_mov_b32_e32 v5, v50
	v_mov_b32_e32 v6, v50
	v_mov_b32_e32 v7, v50
	v_mov_b32_e32 v8, v50
	v_mov_b32_e32 v9, v50
	v_mov_b32_e32 v10, v50
	v_mov_b32_e32 v11, v50
	v_mov_b32_e32 v12, v50
	v_mov_b32_e32 v13, v50
	v_mov_b32_e32 v14, v50
	v_mov_b32_e32 v15, v50
	v_mov_b32_e32 v16, v50
	v_mov_b32_e32 v17, v50
	v_mov_b32_e32 v118, v50
	v_mov_b32_e32 v119, v50
	v_mov_b32_e32 v120, v50
	v_mov_b32_e32 v121, v50
	v_mov_b32_e32 v126, v50
	v_mov_b32_e32 v127, v50
	v_mov_b32_e32 v128, v50
	v_mov_b32_e32 v129, v50
	v_mov_b32_e32 v114, v50
	v_mov_b32_e32 v115, v50
	v_mov_b32_e32 v116, v50
	v_mov_b32_e32 v117, v50
	v_mov_b32_e32 v122, v50
	v_mov_b32_e32 v123, v50
	v_mov_b32_e32 v124, v50
	v_mov_b32_e32 v125, v50

.LBB0_1164:
	v_mov_b32_e32 v0, v177
	v_cvt_pk_bf16_f32 v50, v50, v51
	v_and_b32_e32 v66, 31, v0
	v_cvt_pk_bf16_f32 v51, v52, v53
	v_ashrrev_i32_e32 v52, 2, v0
	v_mul_u32_u24_e32 v66, 0x110, v66
	v_and_b32_e32 v52, -8, v52
	v_add3_u32 v66, s95, v66, v52
	v_cvt_pk_bf16_f32 v2, v2, v3
	v_cvt_pk_bf16_f32 v3, v4, v5
	v_cvt_pk_bf16_f32 v4, v6, v7
	v_cvt_pk_bf16_f32 v5, v8, v9
	s_add_i32 s12, s67, s93
	ds_write2_b64 v66, v[2:3], v[4:5] offset0:24 offset1:26
	v_cvt_pk_bf16_f32 v2, v10, v11
	v_cvt_pk_bf16_f32 v3, v12, v13
	v_cvt_pk_bf16_f32 v4, v14, v15
	v_cvt_pk_bf16_f32 v5, v16, v17
	ds_write2_b64 v66, v[2:3], v[4:5] offset0:28 offset1:30
	s_lshl_b64 s[0:1], s[62:63], 12
	s_ashr_i32 s13, s12, 31
	v_lshlrev_b32_e32 v2, 4, v0
	s_add_u32 s80, s0, s12
	v_and_b32_e32 v14, 0xf0, v2
	v_ashrrev_i32_e32 v2, 7, v0
	s_addc_u32 s81, s1, s13
	v_ashrrev_i32_e32 v3, 31, v2
	v_cvt_pk_bf16_f32 v18, v18, v19
	v_cvt_pk_bf16_f32 v19, v20, v21
	v_cvt_pk_bf16_f32 v21, v24, v25
	v_ashrrev_i32_e32 v25, 4, v0
	v_lshl_add_u64 v[2:3], s[80:81], 0, v[2:3]
	v_mov_b64_e32 v[16:17], s[48:49]
	v_cvt_pk_bf16_f32 v52, v54, v55
	v_cvt_pk_bf16_f32 v53, v56, v57
	v_cvt_pk_bf16_f32 v34, v34, v35
	v_cvt_pk_bf16_f32 v35, v36, v37
	v_cvt_pk_bf16_f32 v36, v38, v39
	v_cvt_pk_bf16_f32 v37, v40, v41
	v_cvt_pk_bf16_f32 v20, v22, v23
	v_and_or_b32 v10, v25, 7, s34
	v_mad_u64_u32 v[4:5], s[0:1], v2, s76, v[16:17]
	ds_write2_b64 v66, v[50:51], v[52:53] offset1:2
	v_cvt_pk_bf16_f32 v50, v58, v59
	v_cvt_pk_bf16_f32 v51, v60, v61
	v_cvt_pk_bf16_f32 v52, v62, v63
	v_cvt_pk_bf16_f32 v53, v64, v65
	ds_write2_b64 v66, v[34:35], v[36:37] offset0:8 offset1:10
	v_cvt_pk_bf16_f32 v34, v42, v43
	v_cvt_pk_bf16_f32 v35, v44, v45
	v_cvt_pk_bf16_f32 v36, v46, v47
	v_cvt_pk_bf16_f32 v37, v48, v49
	ds_write2_b64 v66, v[18:19], v[20:21] offset0:16 offset1:18
	v_cvt_pk_bf16_f32 v18, v26, v27
	v_cvt_pk_bf16_f32 v19, v28, v29
	v_cvt_pk_bf16_f32 v20, v30, v31
	v_cvt_pk_bf16_f32 v21, v32, v33
	v_mad_i32_i24 v5, v3, s76, v5
	v_lshlrev_b32_e32 v0, 8, v10
	ds_write2_b64 v66, v[50:51], v[52:53] offset0:4 offset1:6
	ds_write2_b64 v66, v[34:35], v[36:37] offset0:12 offset1:14
	ds_write2_b64 v66, v[18:19], v[20:21] offset0:20 offset1:22
	v_lshl_add_u64 v[4:5], v[4:5], 0, v[0:1]
	v_mov_b32_e32 v15, v1
	s_waitcnt lgkmcnt(0)
	v_lshl_add_u64 v[4:5], v[4:5], 0, v[14:15]
	global_load_dwordx4 v[6:9], v[4:5], off
	global_load_dwordx4 v[40:43], v[4:5], off offset:1024
	v_add_co_u32_e32 v68, vcc, 0x6000, v4
	s_nop 1
	v_addc_co_u32_e32 v69, vcc, 0, v5, vcc
	global_load_dwordx4 v[44:47], v[68:69], off
	global_load_dwordx4 v[48:51], v[68:69], off offset:1024
	v_add_co_u32_e32 v68, vcc, 0xc000, v4
	s_nop 1
	v_addc_co_u32_e32 v69, vcc, 0, v5, vcc
	global_load_dwordx4 v[52:55], v[68:69], off
	global_load_dwordx4 v[56:59], v[68:69], off offset:1024
	v_add_co_u32_e32 v68, vcc, 0x12000, v4
	s_nop 1
	v_addc_co_u32_e32 v69, vcc, 0, v5, vcc
	global_load_dwordx4 v[60:63], v[68:69], off
	global_load_dwordx4 v[64:67], v[68:69], off offset:1024
	v_mov_b64_e32 v[18:19], s[50:51]
	v_mad_u64_u32 v[4:5], s[0:1], v2, s77, v[18:19]
	v_mad_i32_i24 v5, v3, s77, v5
	v_lshlrev_b32_e32 v20, 2, v10
	v_mov_b32_e32 v21, v1
	v_lshl_add_u64 v[4:5], v[4:5], 0, v[20:21]
	global_load_dword v24, v[4:5], off
	v_mul_lo_u32 v4, v25, s94
	v_lshlrev_b64 v[2:3], 13, v[2:3]
	v_add3_u32 v26, s95, v14, v4
	v_lshl_add_u64 v[2:3], s[44:45], 0, v[2:3]
	v_lshl_add_u64 v[22:23], v[2:3], 0, v[0:1]
	ds_read_b128 v[10:13], v26
	ds_read_b128 v[2:5], v26 offset:1088
	s_waitcnt lgkmcnt(1)
	v_lshlrev_b32_e32 v30, 16, v10
	v_and_b32_e32 v31, 0xffff0000, v10
	s_waitcnt vmcnt(1)
	v_lshlrev_b32_e32 v27, 16, v6
	v_and_b32_e32 v6, 0xffff0000, v6
	v_mul_f32_e32 v28, 0xbfb8aa3b, v27
	v_mul_f32_e32 v29, 0xbfb8aa3b, v6
	v_exp_f32_e32 v28, v28
	v_exp_f32_e32 v29, v29
	s_waitcnt vmcnt(0)
	v_pk_mul_f32 v[30:31], v[24:25], v[30:31] op_sel_hi:[0,1]
	v_pk_add_f32 v[28:29], v[28:29], 1.0 op_sel_hi:[1,0]
	s_nop 0
	v_rcp_f32_e32 v10, v29
	s_nop 0
	v_mul_f32_e32 v29, v6, v10
	v_and_b32_e32 v35, 0xffff0000, v7
	v_lshlrev_b32_e32 v34, 16, v7
	v_mul_f32_e32 v7, 0xbfb8aa3b, v34
	v_exp_f32_e32 v32, v7
	v_mul_f32_e32 v7, 0xbfb8aa3b, v35
	v_exp_f32_e32 v33, v7
	v_rcp_f32_e32 v6, v28
	s_nop 0
	v_mul_f32_e32 v28, v27, v6
	v_pk_fma_f32 v[6:7], v[30:31], v[28:29], 0 op_sel_hi:[1,1,0]
	v_lshlrev_b32_e32 v10, 16, v11
	v_pk_add_f32 v[28:29], v[32:33], 1.0 op_sel_hi:[1,0]
	v_cvt_pk_bf16_f32 v6, v6, v7
	v_and_b32_e32 v11, 0xffff0000, v11
	v_pk_mul_f32 v[10:11], v[24:25], v[10:11] op_sel_hi:[0,1]
	v_rcp_f32_e32 v7, v29
	s_nop 0
	v_mul_f32_e32 v29, v35, v7
	v_lshlrev_b32_e32 v27, 16, v8
	v_and_b32_e32 v8, 0xffff0000, v8
	v_mul_f32_e32 v30, 0xbfb8aa3b, v27
	v_mul_f32_e32 v31, 0xbfb8aa3b, v8
	v_exp_f32_e32 v30, v30
	v_exp_f32_e32 v31, v31
	v_rcp_f32_e32 v7, v28
	s_nop 0
	v_mul_f32_e32 v28, v34, v7
	v_pk_fma_f32 v[10:11], v[10:11], v[28:29], 0 op_sel_hi:[1,1,0]
	v_lshlrev_b32_e32 v28, 16, v12
	v_cvt_pk_bf16_f32 v7, v10, v11
	v_pk_add_f32 v[10:11], v[30:31], 1.0 op_sel_hi:[1,0]
	v_and_b32_e32 v29, 0xffff0000, v12
	v_pk_mul_f32 v[28:29], v[24:25], v[28:29] op_sel_hi:[0,1]
	v_rcp_f32_e32 v12, v11
	s_nop 0
	v_mul_f32_e32 v11, v8, v12
	v_lshlrev_b32_e32 v32, 16, v9
	v_and_b32_e32 v33, 0xffff0000, v9
	v_mul_f32_e32 v9, 0xbfb8aa3b, v32
	v_exp_f32_e32 v30, v9
	v_mul_f32_e32 v9, 0xbfb8aa3b, v33
	v_exp_f32_e32 v31, v9
	v_rcp_f32_e32 v8, v10
	s_nop 0
	v_mul_f32_e32 v10, v27, v8
	v_pk_fma_f32 v[8:9], v[28:29], v[10:11], 0 op_sel_hi:[1,1,0]
	v_lshlrev_b32_e32 v12, 16, v13
	v_pk_add_f32 v[10:11], v[30:31], 1.0 op_sel_hi:[1,0]
	v_cvt_pk_bf16_f32 v8, v8, v9
	v_and_b32_e32 v13, 0xffff0000, v13
	v_pk_mul_f32 v[12:13], v[24:25], v[12:13] op_sel_hi:[0,1]
	v_rcp_f32_e32 v9, v11
	s_nop 0
	v_mul_f32_e32 v11, v33, v9
	v_rcp_f32_e32 v9, v10
	s_nop 0
	v_mul_f32_e32 v10, v32, v9
	v_pk_fma_f32 v[10:11], v[12:13], v[10:11], 0 op_sel_hi:[1,1,0]
	v_mov_b32_e32 v13, v1
	v_cvt_pk_bf16_f32 v9, v10, v11
	v_lshl_add_u64 v[10:11], v[22:23], 0, v[14:15]
	global_store_dwordx4 v[10:11], v[6:9], off
	v_mov_b32_e32 v29, v1
	s_nop 0
	v_add_u32_e32 v8, 4, v25
	v_ashrrev_i32_e32 v6, 3, v8
	v_ashrrev_i32_e32 v7, 31, v6
	v_lshl_add_u64 v[10:11], s[80:81], 0, v[6:7]
	v_and_or_b32 v24, v8, 7, s34
	v_mad_u64_u32 v[6:7], s[0:1], v10, s76, v[16:17]
	v_mad_i32_i24 v7, v11, s76, v7
	v_lshlrev_b32_e32 v12, 8, v24
	v_lshl_add_u64 v[6:7], v[6:7], 0, v[12:13]
	v_lshl_add_u64 v[6:7], v[6:7], 0, v[14:15]
	global_load_dwordx4 v[6:9], v[6:7], off
	v_mad_u64_u32 v[22:23], s[0:1], v10, s77, v[18:19]
	v_mad_i32_i24 v23, v11, s77, v23
	v_lshlrev_b32_e32 v28, 2, v24
	v_lshl_add_u64 v[22:23], v[22:23], 0, v[28:29]
	global_load_dword v22, v[22:23], off
	v_lshlrev_b64 v[10:11], 13, v[10:11]
	v_lshl_add_u64 v[10:11], s[44:45], 0, v[10:11]
	v_lshl_add_u64 v[10:11], v[10:11], 0, v[12:13]
	s_waitcnt vmcnt(1)
	v_lshlrev_b32_e32 v23, 16, v6
	v_and_b32_e32 v6, 0xffff0000, v6
	v_mul_f32_e32 v24, 0xbfb8aa3b, v23
	v_exp_f32_e32 v28, v24
	v_mul_f32_e32 v24, 0xbfb8aa3b, v6
	v_exp_f32_e32 v29, v24
	s_nop 0
	v_pk_add_f32 v[12:13], v[28:29], 1.0 op_sel_hi:[1,0]
	s_nop 0
	s_waitcnt lgkmcnt(0)
	v_lshlrev_b32_e32 v28, 16, v2
	v_and_b32_e32 v29, 0xffff0000, v2
	s_waitcnt vmcnt(0)
	v_pk_mul_f32 v[28:29], v[22:23], v[28:29] op_sel_hi:[0,1]
	v_rcp_f32_e32 v2, v13
	s_nop 0
	v_mul_f32_e32 v13, v6, v2
	v_lshlrev_b32_e32 v24, 16, v7
	v_and_b32_e32 v27, 0xffff0000, v7
	v_mul_f32_e32 v6, 0xbfb8aa3b, v24
	v_mul_f32_e32 v7, 0xbfb8aa3b, v27
	v_exp_f32_e32 v6, v6
	v_exp_f32_e32 v7, v7
	v_rcp_f32_e32 v2, v12
	s_nop 0
	v_mul_f32_e32 v12, v23, v2
	v_pk_fma_f32 v[12:13], v[28:29], v[12:13], 0 op_sel_hi:[1,1,0]
	v_pk_add_f32 v[6:7], v[6:7], 1.0 op_sel_hi:[1,0]
	s_nop 0
	v_cvt_pk_bf16_f32 v2, v12, v13
	v_lshlrev_b32_e32 v12, 16, v3
	v_and_b32_e32 v13, 0xffff0000, v3
	v_pk_mul_f32 v[12:13], v[22:23], v[12:13] op_sel_hi:[0,1]
	v_rcp_f32_e32 v3, v7
	s_nop 0
	v_mul_f32_e32 v7, v27, v3
	v_lshlrev_b32_e32 v23, 16, v8
	v_and_b32_e32 v8, 0xffff0000, v8
	v_mul_f32_e32 v27, 0xbfb8aa3b, v23
	v_exp_f32_e32 v28, v27
	v_mul_f32_e32 v27, 0xbfb8aa3b, v8
	v_exp_f32_e32 v29, v27
	v_rcp_f32_e32 v3, v6
	s_nop 0
	v_mul_f32_e32 v6, v24, v3
	v_pk_fma_f32 v[6:7], v[12:13], v[6:7], 0 op_sel_hi:[1,1,0]
	v_lshlrev_b32_e32 v12, 16, v4
	v_cvt_pk_bf16_f32 v3, v6, v7
	v_pk_add_f32 v[6:7], v[28:29], 1.0 op_sel_hi:[1,0]
	v_and_b32_e32 v13, 0xffff0000, v4
	v_pk_mul_f32 v[12:13], v[22:23], v[12:13] op_sel_hi:[0,1]
	v_rcp_f32_e32 v4, v7
	s_nop 0
	v_mul_f32_e32 v7, v8, v4
	v_lshlrev_b32_e32 v24, 16, v9
	v_and_b32_e32 v27, 0xffff0000, v9
	v_mul_f32_e32 v8, 0xbfb8aa3b, v24
	v_mul_f32_e32 v9, 0xbfb8aa3b, v27
	v_exp_f32_e32 v8, v8
	v_exp_f32_e32 v9, v9
	v_rcp_f32_e32 v4, v6
	s_nop 0
	v_mul_f32_e32 v6, v23, v4
	v_pk_fma_f32 v[6:7], v[12:13], v[6:7], 0 op_sel_hi:[1,1,0]
	s_nop 0
	v_cvt_pk_bf16_f32 v4, v6, v7
	v_pk_add_f32 v[6:7], v[8:9], 1.0 op_sel_hi:[1,0]
	v_lshlrev_b32_e32 v8, 16, v5
	v_and_b32_e32 v9, 0xffff0000, v5
	v_pk_mul_f32 v[8:9], v[22:23], v[8:9] op_sel_hi:[0,1]
	v_rcp_f32_e32 v5, v7
	s_nop 0
	v_mul_f32_e32 v7, v27, v5
	v_rcp_f32_e32 v5, v6
	s_nop 0
	v_mul_f32_e32 v6, v24, v5
	v_pk_fma_f32 v[6:7], v[8:9], v[6:7], 0 op_sel_hi:[1,1,0]
	s_nop 0
	v_cvt_pk_bf16_f32 v5, v6, v7
	v_lshl_add_u64 v[6:7], v[10:11], 0, v[14:15]
	global_store_dwordx4 v[6:7], v[2:5], off
	ds_read_b128 v[6:9], v26 offset:2176
	s_nop 0
	v_add_u32_e32 v2, 8, v25
	v_ashrrev_i32_e32 v2, 3, v2
	v_ashrrev_i32_e32 v3, 31, v2
	v_lshl_add_u64 v[2:3], s[80:81], 0, v[2:3]
	v_mad_u64_u32 v[4:5], s[0:1], v2, s76, v[16:17]
	v_mad_i32_i24 v5, v3, s76, v5
	v_lshl_add_u64 v[4:5], v[4:5], 0, v[0:1]
	v_lshl_add_u64 v[4:5], v[4:5], 0, v[14:15]
	global_load_dwordx4 v[10:13], v[4:5], off
	v_mad_u64_u32 v[4:5], s[0:1], v2, s77, v[18:19]
	v_mad_i32_i24 v5, v3, s77, v5
	v_lshl_add_u64 v[4:5], v[4:5], 0, v[20:21]
	global_load_dword v24, v[4:5], off
	v_lshlrev_b64 v[2:3], 13, v[2:3]
	v_lshl_add_u64 v[2:3], s[44:45], 0, v[2:3]
	v_lshl_add_u64 v[22:23], v[2:3], 0, v[0:1]
	s_waitcnt vmcnt(1)
	v_lshlrev_b32_e32 v27, 16, v10
	v_and_b32_e32 v10, 0xffff0000, v10
	v_mul_f32_e32 v4, 0xbfb8aa3b, v27
	v_mul_f32_e32 v5, 0xbfb8aa3b, v10
	v_exp_f32_e32 v4, v4
	v_exp_f32_e32 v5, v5
	s_nop 0
	v_pk_add_f32 v[28:29], v[4:5], 1.0 op_sel_hi:[1,0]
	s_nop 0
	ds_read_b128 v[2:5], v26 offset:3264
	s_waitcnt lgkmcnt(1)
	v_lshlrev_b32_e32 v30, 16, v6
	v_and_b32_e32 v31, 0xffff0000, v6
	v_rcp_f32_e32 v6, v29
	s_nop 0
	v_mul_f32_e32 v29, v10, v6
	s_waitcnt vmcnt(0)
	v_pk_mul_f32 v[30:31], v[24:25], v[30:31] op_sel_hi:[0,1]
	v_lshlrev_b32_e32 v32, 16, v11
	v_and_b32_e32 v33, 0xffff0000, v11
	v_mul_f32_e32 v10, 0xbfb8aa3b, v32
	v_mul_f32_e32 v11, 0xbfb8aa3b, v33
	v_exp_f32_e32 v10, v10
	v_exp_f32_e32 v11, v11
	v_rcp_f32_e32 v6, v28
	s_nop 0
	v_mul_f32_e32 v28, v27, v6
	v_pk_fma_f32 v[28:29], v[30:31], v[28:29], 0 op_sel_hi:[1,1,0]
	v_pk_add_f32 v[10:11], v[10:11], 1.0 op_sel_hi:[1,0]
	s_nop 0
	v_cvt_pk_bf16_f32 v6, v28, v29
	v_lshlrev_b32_e32 v28, 16, v7
	v_and_b32_e32 v29, 0xffff0000, v7
	v_rcp_f32_e32 v7, v11
	s_nop 0
	v_mul_f32_e32 v11, v33, v7
	v_pk_mul_f32 v[28:29], v[24:25], v[28:29] op_sel_hi:[0,1]
	v_lshlrev_b32_e32 v27, 16, v12
	v_and_b32_e32 v12, 0xffff0000, v12
	v_mul_f32_e32 v30, 0xbfb8aa3b, v27
	v_mul_f32_e32 v31, 0xbfb8aa3b, v12
	v_exp_f32_e32 v30, v30
	v_exp_f32_e32 v31, v31
	v_rcp_f32_e32 v7, v10
	s_nop 0
	v_mul_f32_e32 v10, v32, v7
	v_pk_fma_f32 v[10:11], v[28:29], v[10:11], 0 op_sel_hi:[1,1,0]
	v_lshlrev_b32_e32 v28, 16, v8
	v_cvt_pk_bf16_f32 v7, v10, v11
	v_pk_add_f32 v[10:11], v[30:31], 1.0 op_sel_hi:[1,0]
	v_and_b32_e32 v29, 0xffff0000, v8
	v_pk_mul_f32 v[28:29], v[24:25], v[28:29] op_sel_hi:[0,1]
	v_rcp_f32_e32 v8, v11
	s_nop 0
	v_mul_f32_e32 v11, v12, v8
	v_lshlrev_b32_e32 v30, 16, v13
	v_and_b32_e32 v31, 0xffff0000, v13
	v_mul_f32_e32 v12, 0xbfb8aa3b, v30
	v_mul_f32_e32 v13, 0xbfb8aa3b, v31
	v_exp_f32_e32 v12, v12
	v_exp_f32_e32 v13, v13
	v_rcp_f32_e32 v8, v10
	s_nop 0
	v_mul_f32_e32 v10, v27, v8
	v_pk_fma_f32 v[10:11], v[28:29], v[10:11], 0 op_sel_hi:[1,1,0]
	s_nop 0
	v_cvt_pk_bf16_f32 v8, v10, v11
	v_pk_add_f32 v[10:11], v[12:13], 1.0 op_sel_hi:[1,0]
	v_lshlrev_b32_e32 v12, 16, v9
	v_and_b32_e32 v13, 0xffff0000, v9
	v_pk_mul_f32 v[12:13], v[24:25], v[12:13] op_sel_hi:[0,1]
	v_rcp_f32_e32 v9, v11
	s_nop 0
	v_mul_f32_e32 v11, v31, v9
	v_rcp_f32_e32 v9, v10
	s_nop 0
	v_mul_f32_e32 v10, v30, v9
	v_pk_fma_f32 v[10:11], v[12:13], v[10:11], 0 op_sel_hi:[1,1,0]
	v_mov_b32_e32 v13, v1
	v_cvt_pk_bf16_f32 v9, v10, v11
	v_lshl_add_u64 v[10:11], v[22:23], 0, v[14:15]
	global_store_dwordx4 v[10:11], v[6:9], off
	v_mov_b32_e32 v29, v1
	s_nop 0
	v_add_u32_e32 v8, 12, v25
	v_ashrrev_i32_e32 v6, 3, v8
	v_ashrrev_i32_e32 v7, 31, v6
	v_lshl_add_u64 v[10:11], s[80:81], 0, v[6:7]
	v_and_or_b32 v24, v8, 7, s34
	v_mad_u64_u32 v[6:7], s[0:1], v10, s76, v[16:17]
	v_mad_i32_i24 v7, v11, s76, v7
	v_lshlrev_b32_e32 v12, 8, v24
	v_lshl_add_u64 v[6:7], v[6:7], 0, v[12:13]
	v_lshl_add_u64 v[6:7], v[6:7], 0, v[14:15]
	global_load_dwordx4 v[6:9], v[6:7], off
	v_mad_u64_u32 v[22:23], s[0:1], v10, s77, v[18:19]
	v_mad_i32_i24 v23, v11, s77, v23
	v_lshlrev_b32_e32 v28, 2, v24
	v_lshl_add_u64 v[22:23], v[22:23], 0, v[28:29]
	global_load_dword v22, v[22:23], off
	v_lshlrev_b64 v[10:11], 13, v[10:11]
	v_lshl_add_u64 v[10:11], s[44:45], 0, v[10:11]
	v_lshl_add_u64 v[10:11], v[10:11], 0, v[12:13]
	s_waitcnt vmcnt(1)
	v_lshlrev_b32_e32 v23, 16, v6
	v_and_b32_e32 v6, 0xffff0000, v6
	v_mul_f32_e32 v24, 0xbfb8aa3b, v23
	v_exp_f32_e32 v28, v24
	v_mul_f32_e32 v24, 0xbfb8aa3b, v6
	v_exp_f32_e32 v29, v24
	s_nop 0
	v_pk_add_f32 v[12:13], v[28:29], 1.0 op_sel_hi:[1,0]
	s_nop 0
	s_waitcnt lgkmcnt(0)
	v_lshlrev_b32_e32 v28, 16, v2
	v_and_b32_e32 v29, 0xffff0000, v2
	s_waitcnt vmcnt(0)
	v_pk_mul_f32 v[28:29], v[22:23], v[28:29] op_sel_hi:[0,1]
	v_rcp_f32_e32 v2, v13
	s_nop 0
	v_mul_f32_e32 v13, v6, v2
	v_lshlrev_b32_e32 v24, 16, v7
	v_and_b32_e32 v27, 0xffff0000, v7
	v_mul_f32_e32 v6, 0xbfb8aa3b, v24
	v_mul_f32_e32 v7, 0xbfb8aa3b, v27
	v_exp_f32_e32 v6, v6
	v_exp_f32_e32 v7, v7
	v_rcp_f32_e32 v2, v12
	s_nop 0
	v_mul_f32_e32 v12, v23, v2
	v_pk_fma_f32 v[12:13], v[28:29], v[12:13], 0 op_sel_hi:[1,1,0]
	v_pk_add_f32 v[6:7], v[6:7], 1.0 op_sel_hi:[1,0]
	s_nop 0
	v_cvt_pk_bf16_f32 v2, v12, v13
	v_lshlrev_b32_e32 v12, 16, v3
	v_and_b32_e32 v13, 0xffff0000, v3
	v_pk_mul_f32 v[12:13], v[22:23], v[12:13] op_sel_hi:[0,1]
	v_rcp_f32_e32 v3, v7
	s_nop 0
	v_mul_f32_e32 v7, v27, v3
	v_lshlrev_b32_e32 v23, 16, v8
	v_and_b32_e32 v8, 0xffff0000, v8
	v_mul_f32_e32 v27, 0xbfb8aa3b, v23
	v_exp_f32_e32 v28, v27
	v_mul_f32_e32 v27, 0xbfb8aa3b, v8
	v_exp_f32_e32 v29, v27
	v_rcp_f32_e32 v3, v6
	s_nop 0
	v_mul_f32_e32 v6, v24, v3
	v_pk_fma_f32 v[6:7], v[12:13], v[6:7], 0 op_sel_hi:[1,1,0]
	v_lshlrev_b32_e32 v12, 16, v4
	v_cvt_pk_bf16_f32 v3, v6, v7
	v_pk_add_f32 v[6:7], v[28:29], 1.0 op_sel_hi:[1,0]
	v_and_b32_e32 v13, 0xffff0000, v4
	v_pk_mul_f32 v[12:13], v[22:23], v[12:13] op_sel_hi:[0,1]
	v_rcp_f32_e32 v4, v7
	s_nop 0
	v_mul_f32_e32 v7, v8, v4
	v_lshlrev_b32_e32 v24, 16, v9
	v_and_b32_e32 v27, 0xffff0000, v9
	v_mul_f32_e32 v8, 0xbfb8aa3b, v24
	v_mul_f32_e32 v9, 0xbfb8aa3b, v27
	v_exp_f32_e32 v8, v8
	v_exp_f32_e32 v9, v9
	v_rcp_f32_e32 v4, v6
	s_nop 0
	v_mul_f32_e32 v6, v23, v4
	v_pk_fma_f32 v[6:7], v[12:13], v[6:7], 0 op_sel_hi:[1,1,0]
	s_nop 0
	v_cvt_pk_bf16_f32 v4, v6, v7
	v_pk_add_f32 v[6:7], v[8:9], 1.0 op_sel_hi:[1,0]
	v_lshlrev_b32_e32 v8, 16, v5
	v_and_b32_e32 v9, 0xffff0000, v5
	v_pk_mul_f32 v[8:9], v[22:23], v[8:9] op_sel_hi:[0,1]
	v_rcp_f32_e32 v5, v7
	s_nop 0
	v_mul_f32_e32 v7, v27, v5
	v_rcp_f32_e32 v5, v6
	s_nop 0
	v_mul_f32_e32 v6, v24, v5
	v_pk_fma_f32 v[6:7], v[8:9], v[6:7], 0 op_sel_hi:[1,1,0]
	s_nop 0
	v_cvt_pk_bf16_f32 v5, v6, v7
	v_lshl_add_u64 v[6:7], v[10:11], 0, v[14:15]
	global_store_dwordx4 v[6:7], v[2:5], off
	ds_read_b128 v[6:9], v26 offset:4352
	s_nop 0
	v_add_u32_e32 v2, 16, v25
	v_ashrrev_i32_e32 v2, 3, v2
	v_ashrrev_i32_e32 v3, 31, v2
	v_lshl_add_u64 v[2:3], s[80:81], 0, v[2:3]
	v_mad_u64_u32 v[4:5], s[0:1], v2, s76, v[16:17]
	v_mad_i32_i24 v5, v3, s76, v5
	v_lshl_add_u64 v[4:5], v[4:5], 0, v[0:1]
	v_lshl_add_u64 v[4:5], v[4:5], 0, v[14:15]
	global_load_dwordx4 v[10:13], v[4:5], off
	v_mad_u64_u32 v[4:5], s[0:1], v2, s77, v[18:19]
	v_mad_i32_i24 v5, v3, s77, v5
	v_lshl_add_u64 v[4:5], v[4:5], 0, v[20:21]
	global_load_dword v24, v[4:5], off
	v_lshlrev_b64 v[2:3], 13, v[2:3]
	v_lshl_add_u64 v[2:3], s[44:45], 0, v[2:3]
	v_lshl_add_u64 v[22:23], v[2:3], 0, v[0:1]
	s_waitcnt vmcnt(1)
	v_lshlrev_b32_e32 v27, 16, v10
	v_and_b32_e32 v10, 0xffff0000, v10
	v_mul_f32_e32 v4, 0xbfb8aa3b, v27
	v_mul_f32_e32 v5, 0xbfb8aa3b, v10
	v_exp_f32_e32 v4, v4
	v_exp_f32_e32 v5, v5
	s_nop 0
	v_pk_add_f32 v[28:29], v[4:5], 1.0 op_sel_hi:[1,0]
	s_nop 0
	ds_read_b128 v[2:5], v26 offset:5440
	s_waitcnt lgkmcnt(1)
	v_lshlrev_b32_e32 v30, 16, v6
	v_and_b32_e32 v31, 0xffff0000, v6
	v_rcp_f32_e32 v6, v29
	s_nop 0
	v_mul_f32_e32 v29, v10, v6
	s_waitcnt vmcnt(0)
	v_pk_mul_f32 v[30:31], v[24:25], v[30:31] op_sel_hi:[0,1]
	v_lshlrev_b32_e32 v32, 16, v11
	v_and_b32_e32 v33, 0xffff0000, v11
	v_mul_f32_e32 v10, 0xbfb8aa3b, v32
	v_mul_f32_e32 v11, 0xbfb8aa3b, v33
	v_exp_f32_e32 v10, v10
	v_exp_f32_e32 v11, v11
	v_rcp_f32_e32 v6, v28
	s_nop 0
	v_mul_f32_e32 v28, v27, v6
	v_pk_fma_f32 v[28:29], v[30:31], v[28:29], 0 op_sel_hi:[1,1,0]
	v_pk_add_f32 v[10:11], v[10:11], 1.0 op_sel_hi:[1,0]
	s_nop 0
	v_cvt_pk_bf16_f32 v6, v28, v29
	v_lshlrev_b32_e32 v28, 16, v7
	v_and_b32_e32 v29, 0xffff0000, v7
	v_rcp_f32_e32 v7, v11
	s_nop 0
	v_mul_f32_e32 v11, v33, v7
	v_pk_mul_f32 v[28:29], v[24:25], v[28:29] op_sel_hi:[0,1]
	v_lshlrev_b32_e32 v27, 16, v12
	v_and_b32_e32 v12, 0xffff0000, v12
	v_mul_f32_e32 v30, 0xbfb8aa3b, v27
	v_mul_f32_e32 v31, 0xbfb8aa3b, v12
	v_exp_f32_e32 v30, v30
	v_exp_f32_e32 v31, v31
	v_rcp_f32_e32 v7, v10
	s_nop 0
	v_mul_f32_e32 v10, v32, v7
	v_pk_fma_f32 v[10:11], v[28:29], v[10:11], 0 op_sel_hi:[1,1,0]
	v_lshlrev_b32_e32 v28, 16, v8
	v_cvt_pk_bf16_f32 v7, v10, v11
	v_pk_add_f32 v[10:11], v[30:31], 1.0 op_sel_hi:[1,0]
	v_and_b32_e32 v29, 0xffff0000, v8
	v_pk_mul_f32 v[28:29], v[24:25], v[28:29] op_sel_hi:[0,1]
	v_rcp_f32_e32 v8, v11
	s_nop 0
	v_mul_f32_e32 v11, v12, v8
	v_lshlrev_b32_e32 v30, 16, v13
	v_and_b32_e32 v31, 0xffff0000, v13
	v_mul_f32_e32 v12, 0xbfb8aa3b, v30
	v_mul_f32_e32 v13, 0xbfb8aa3b, v31
	v_exp_f32_e32 v12, v12
	v_exp_f32_e32 v13, v13
	v_rcp_f32_e32 v8, v10
	s_nop 0
	v_mul_f32_e32 v10, v27, v8
	v_pk_fma_f32 v[10:11], v[28:29], v[10:11], 0 op_sel_hi:[1,1,0]
	s_nop 0
	v_cvt_pk_bf16_f32 v8, v10, v11
	v_pk_add_f32 v[10:11], v[12:13], 1.0 op_sel_hi:[1,0]
	v_lshlrev_b32_e32 v12, 16, v9
	v_and_b32_e32 v13, 0xffff0000, v9
	v_pk_mul_f32 v[12:13], v[24:25], v[12:13] op_sel_hi:[0,1]
	v_rcp_f32_e32 v9, v11
	s_nop 0
	v_mul_f32_e32 v11, v31, v9
	v_rcp_f32_e32 v9, v10
	s_nop 0
	v_mul_f32_e32 v10, v30, v9
	v_pk_fma_f32 v[10:11], v[12:13], v[10:11], 0 op_sel_hi:[1,1,0]
	v_mov_b32_e32 v13, v1
	v_cvt_pk_bf16_f32 v9, v10, v11
	v_lshl_add_u64 v[10:11], v[22:23], 0, v[14:15]
	global_store_dwordx4 v[10:11], v[6:9], off
	v_mov_b32_e32 v29, v1
	s_nop 0
	v_add_u32_e32 v8, 20, v25
	v_ashrrev_i32_e32 v6, 3, v8
	v_ashrrev_i32_e32 v7, 31, v6
	v_lshl_add_u64 v[10:11], s[80:81], 0, v[6:7]
	v_and_or_b32 v24, v8, 7, s34
	v_mad_u64_u32 v[6:7], s[0:1], v10, s76, v[16:17]
	v_mad_i32_i24 v7, v11, s76, v7
	v_lshlrev_b32_e32 v12, 8, v24
	v_lshl_add_u64 v[6:7], v[6:7], 0, v[12:13]
	v_lshl_add_u64 v[6:7], v[6:7], 0, v[14:15]
	global_load_dwordx4 v[6:9], v[6:7], off
	v_mad_u64_u32 v[22:23], s[0:1], v10, s77, v[18:19]
	v_mad_i32_i24 v23, v11, s77, v23
	v_lshlrev_b32_e32 v28, 2, v24
	v_lshl_add_u64 v[22:23], v[22:23], 0, v[28:29]
	global_load_dword v22, v[22:23], off
	v_lshlrev_b64 v[10:11], 13, v[10:11]
	v_lshl_add_u64 v[10:11], s[44:45], 0, v[10:11]
	v_lshl_add_u64 v[10:11], v[10:11], 0, v[12:13]
	s_waitcnt vmcnt(1)
	v_lshlrev_b32_e32 v23, 16, v6
	v_and_b32_e32 v6, 0xffff0000, v6
	v_mul_f32_e32 v24, 0xbfb8aa3b, v23
	v_exp_f32_e32 v28, v24
	v_mul_f32_e32 v24, 0xbfb8aa3b, v6
	v_exp_f32_e32 v29, v24
	s_nop 0
	v_pk_add_f32 v[12:13], v[28:29], 1.0 op_sel_hi:[1,0]
	s_nop 0
	s_waitcnt lgkmcnt(0)
	v_lshlrev_b32_e32 v28, 16, v2
	v_and_b32_e32 v29, 0xffff0000, v2
	s_waitcnt vmcnt(0)
	v_pk_mul_f32 v[28:29], v[22:23], v[28:29] op_sel_hi:[0,1]
	v_rcp_f32_e32 v2, v13
	s_nop 0
	v_mul_f32_e32 v13, v6, v2
	v_lshlrev_b32_e32 v24, 16, v7
	v_and_b32_e32 v27, 0xffff0000, v7
	v_mul_f32_e32 v6, 0xbfb8aa3b, v24
	v_mul_f32_e32 v7, 0xbfb8aa3b, v27
	v_exp_f32_e32 v6, v6
	v_exp_f32_e32 v7, v7
	v_rcp_f32_e32 v2, v12
	s_nop 0
	v_mul_f32_e32 v12, v23, v2
	v_pk_fma_f32 v[12:13], v[28:29], v[12:13], 0 op_sel_hi:[1,1,0]
	v_pk_add_f32 v[6:7], v[6:7], 1.0 op_sel_hi:[1,0]
	s_nop 0
	v_cvt_pk_bf16_f32 v2, v12, v13
	v_lshlrev_b32_e32 v12, 16, v3
	v_and_b32_e32 v13, 0xffff0000, v3
	v_pk_mul_f32 v[12:13], v[22:23], v[12:13] op_sel_hi:[0,1]
	v_rcp_f32_e32 v3, v7
	s_nop 0
	v_mul_f32_e32 v7, v27, v3
	v_lshlrev_b32_e32 v23, 16, v8
	v_and_b32_e32 v8, 0xffff0000, v8
	v_mul_f32_e32 v27, 0xbfb8aa3b, v23
	v_exp_f32_e32 v28, v27
	v_mul_f32_e32 v27, 0xbfb8aa3b, v8
	v_exp_f32_e32 v29, v27
	v_rcp_f32_e32 v3, v6
	s_nop 0
	v_mul_f32_e32 v6, v24, v3
	v_pk_fma_f32 v[6:7], v[12:13], v[6:7], 0 op_sel_hi:[1,1,0]
	v_lshlrev_b32_e32 v12, 16, v4
	v_cvt_pk_bf16_f32 v3, v6, v7
	v_pk_add_f32 v[6:7], v[28:29], 1.0 op_sel_hi:[1,0]
	v_and_b32_e32 v13, 0xffff0000, v4
	v_pk_mul_f32 v[12:13], v[22:23], v[12:13] op_sel_hi:[0,1]
	v_rcp_f32_e32 v4, v7
	s_nop 0
	v_mul_f32_e32 v7, v8, v4
	v_lshlrev_b32_e32 v24, 16, v9
	v_and_b32_e32 v27, 0xffff0000, v9
	v_mul_f32_e32 v8, 0xbfb8aa3b, v24
	v_mul_f32_e32 v9, 0xbfb8aa3b, v27
	v_exp_f32_e32 v8, v8
	v_exp_f32_e32 v9, v9
	v_rcp_f32_e32 v4, v6
	s_nop 0
	v_mul_f32_e32 v6, v23, v4
	v_pk_fma_f32 v[6:7], v[12:13], v[6:7], 0 op_sel_hi:[1,1,0]
	s_nop 0
	v_cvt_pk_bf16_f32 v4, v6, v7
	v_pk_add_f32 v[6:7], v[8:9], 1.0 op_sel_hi:[1,0]
	v_lshlrev_b32_e32 v8, 16, v5
	v_and_b32_e32 v9, 0xffff0000, v5
	v_pk_mul_f32 v[8:9], v[22:23], v[8:9] op_sel_hi:[0,1]
	v_rcp_f32_e32 v5, v7
	s_nop 0
	v_mul_f32_e32 v7, v27, v5
	v_rcp_f32_e32 v5, v6
	s_nop 0
	v_mul_f32_e32 v6, v24, v5
	v_pk_fma_f32 v[6:7], v[8:9], v[6:7], 0 op_sel_hi:[1,1,0]
	s_nop 0
	v_cvt_pk_bf16_f32 v5, v6, v7
	v_lshl_add_u64 v[6:7], v[10:11], 0, v[14:15]
	global_store_dwordx4 v[6:7], v[2:5], off
	ds_read_b128 v[6:9], v26 offset:6528
	s_nop 0
	v_add_u32_e32 v2, 24, v25
	v_ashrrev_i32_e32 v2, 3, v2
	v_ashrrev_i32_e32 v3, 31, v2
	v_lshl_add_u64 v[2:3], s[80:81], 0, v[2:3]
	v_mad_u64_u32 v[4:5], s[0:1], v2, s76, v[16:17]
	v_mad_i32_i24 v5, v3, s76, v5
	v_lshl_add_u64 v[4:5], v[4:5], 0, v[0:1]
	v_lshl_add_u64 v[4:5], v[4:5], 0, v[14:15]
	global_load_dwordx4 v[10:13], v[4:5], off
	v_mad_u64_u32 v[4:5], s[0:1], v2, s77, v[18:19]
	v_mad_i32_i24 v5, v3, s77, v5
	v_lshl_add_u64 v[4:5], v[4:5], 0, v[20:21]
	global_load_dword v22, v[4:5], off
	v_lshlrev_b64 v[2:3], 13, v[2:3]
	v_lshl_add_u64 v[2:3], s[44:45], 0, v[2:3]
	v_lshl_add_u64 v[20:21], v[2:3], 0, v[0:1]
	s_waitcnt vmcnt(1)
	v_lshlrev_b32_e32 v23, 16, v10
	v_and_b32_e32 v10, 0xffff0000, v10
	v_mul_f32_e32 v4, 0xbfb8aa3b, v23
	v_mul_f32_e32 v5, 0xbfb8aa3b, v10
	v_exp_f32_e32 v4, v4
	v_exp_f32_e32 v5, v5
	s_nop 0
	v_pk_add_f32 v[28:29], v[4:5], 1.0 op_sel_hi:[1,0]
	s_nop 0
	ds_read_b128 v[2:5], v26 offset:7616
	s_waitcnt lgkmcnt(1)
	v_lshlrev_b32_e32 v26, 16, v6
	v_and_b32_e32 v27, 0xffff0000, v6
	v_rcp_f32_e32 v0, v29
	s_nop 0
	v_mul_f32_e32 v29, v10, v0
	v_and_b32_e32 v30, 0xffff0000, v11
	v_lshlrev_b32_e32 v24, 16, v11
	v_mul_f32_e32 v6, 0xbfb8aa3b, v24
	v_exp_f32_e32 v10, v6
	v_mul_f32_e32 v6, 0xbfb8aa3b, v30
	v_exp_f32_e32 v11, v6
	v_rcp_f32_e32 v0, v28
	s_nop 0
	v_mul_f32_e32 v28, v23, v0
	s_waitcnt vmcnt(0)
	v_pk_mul_f32 v[26:27], v[22:23], v[26:27] op_sel_hi:[0,1]
	v_pk_fma_f32 v[26:27], v[26:27], v[28:29], 0 op_sel_hi:[1,1,0]
	v_pk_add_f32 v[10:11], v[10:11], 1.0 op_sel_hi:[1,0]
	v_cvt_pk_bf16_f32 v6, v26, v27
	v_lshlrev_b32_e32 v26, 16, v7
	v_and_b32_e32 v27, 0xffff0000, v7
	v_pk_mul_f32 v[26:27], v[22:23], v[26:27] op_sel_hi:[0,1]
	v_rcp_f32_e32 v0, v11
	s_nop 0
	v_mul_f32_e32 v11, v30, v0
	v_lshlrev_b32_e32 v23, 16, v12
	v_and_b32_e32 v12, 0xffff0000, v12
	v_mul_f32_e32 v7, 0xbfb8aa3b, v23
	v_exp_f32_e32 v28, v7
	v_mul_f32_e32 v7, 0xbfb8aa3b, v12
	v_exp_f32_e32 v29, v7
	v_rcp_f32_e32 v0, v10
	s_nop 0
	v_mul_f32_e32 v10, v24, v0
	v_pk_fma_f32 v[10:11], v[26:27], v[10:11], 0 op_sel_hi:[1,1,0]
	v_lshlrev_b32_e32 v26, 16, v8
	v_cvt_pk_bf16_f32 v7, v10, v11
	v_pk_add_f32 v[10:11], v[28:29], 1.0 op_sel_hi:[1,0]
	v_and_b32_e32 v27, 0xffff0000, v8
	v_pk_mul_f32 v[26:27], v[22:23], v[26:27] op_sel_hi:[0,1]
	v_rcp_f32_e32 v0, v11
	s_nop 0
	v_mul_f32_e32 v11, v12, v0
	v_and_b32_e32 v28, 0xffff0000, v13
	v_lshlrev_b32_e32 v24, 16, v13
	v_mul_f32_e32 v8, 0xbfb8aa3b, v24
	v_exp_f32_e32 v12, v8
	v_mul_f32_e32 v8, 0xbfb8aa3b, v28
	v_exp_f32_e32 v13, v8
	v_rcp_f32_e32 v0, v10
	s_nop 0
	v_mul_f32_e32 v10, v23, v0
	v_pk_fma_f32 v[10:11], v[26:27], v[10:11], 0 op_sel_hi:[1,1,0]
	s_nop 0
	v_cvt_pk_bf16_f32 v8, v10, v11
	v_pk_add_f32 v[10:11], v[12:13], 1.0 op_sel_hi:[1,0]
	v_lshlrev_b32_e32 v12, 16, v9
	v_and_b32_e32 v13, 0xffff0000, v9
	v_pk_mul_f32 v[12:13], v[22:23], v[12:13] op_sel_hi:[0,1]
	v_rcp_f32_e32 v0, v11
	s_nop 0
	v_mul_f32_e32 v11, v28, v0
	v_rcp_f32_e32 v0, v10
	s_nop 0
	v_mul_f32_e32 v10, v24, v0
	v_pk_fma_f32 v[10:11], v[12:13], v[10:11], 0 op_sel_hi:[1,1,0]
	v_add_u32_e32 v0, 28, v25
	v_cvt_pk_bf16_f32 v9, v10, v11
	v_lshl_add_u64 v[10:11], v[20:21], 0, v[14:15]
	global_store_dwordx4 v[10:11], v[6:9], off
	v_and_or_b32 v20, v0, 7, s34
	s_nop 0
	v_ashrrev_i32_e32 v6, 3, v0
	v_ashrrev_i32_e32 v7, 31, v6
	v_lshl_add_u64 v[10:11], s[80:81], 0, v[6:7]
	v_mad_u64_u32 v[6:7], s[0:1], v10, s76, v[16:17]
	v_mad_i32_i24 v7, v11, s76, v7
	v_lshlrev_b32_e32 v0, 8, v20
	v_lshl_add_u64 v[6:7], v[6:7], 0, v[0:1]
	v_lshl_add_u64 v[6:7], v[6:7], 0, v[14:15]
	global_load_dwordx4 v[6:9], v[6:7], off
	v_mad_u64_u32 v[12:13], s[0:1], v10, s77, v[18:19]
	v_mad_i32_i24 v13, v11, s77, v13
	v_lshlrev_b32_e32 v16, 2, v20
	v_mov_b32_e32 v17, v1
	v_lshl_add_u64 v[12:13], v[12:13], 0, v[16:17]
	global_load_dword v12, v[12:13], off
	v_lshlrev_b64 v[10:11], 13, v[10:11]
	v_lshl_add_u64 v[10:11], s[44:45], 0, v[10:11]
	v_lshl_add_u64 v[10:11], v[10:11], 0, v[0:1]
	s_waitcnt lgkmcnt(0)
	v_lshlrev_b32_e32 v18, 16, v2
	v_and_b32_e32 v19, 0xffff0000, v2
	s_waitcnt vmcnt(1)
	v_lshlrev_b32_e32 v13, 16, v6
	v_and_b32_e32 v6, 0xffff0000, v6
	v_mul_f32_e32 v16, 0xbfb8aa3b, v13
	v_mul_f32_e32 v17, 0xbfb8aa3b, v6
	v_exp_f32_e32 v16, v16
	v_exp_f32_e32 v17, v17
	s_waitcnt vmcnt(0)
	v_pk_mul_f32 v[18:19], v[12:13], v[18:19] op_sel_hi:[0,1]
	v_pk_add_f32 v[16:17], v[16:17], 1.0 op_sel_hi:[1,0]
	s_nop 0
	s_nop 0
	v_rcp_f32_e32 v0, v17
	s_nop 0
	v_mul_f32_e32 v17, v6, v0
	v_and_b32_e32 v21, 0xffff0000, v7
	v_lshlrev_b32_e32 v20, 16, v7
	v_mul_f32_e32 v2, 0xbfb8aa3b, v20
	v_exp_f32_e32 v6, v2
	v_mul_f32_e32 v2, 0xbfb8aa3b, v21
	v_exp_f32_e32 v7, v2
	v_rcp_f32_e32 v0, v16
	s_nop 0
	v_mul_f32_e32 v16, v13, v0
	v_pk_fma_f32 v[16:17], v[18:19], v[16:17], 0 op_sel_hi:[1,1,0]
	v_pk_add_f32 v[6:7], v[6:7], 1.0 op_sel_hi:[1,0]
	s_nop 0
	v_cvt_pk_bf16_f32 v2, v16, v17
	v_lshlrev_b32_e32 v16, 16, v3
	v_and_b32_e32 v17, 0xffff0000, v3
	v_pk_mul_f32 v[16:17], v[12:13], v[16:17] op_sel_hi:[0,1]
	v_rcp_f32_e32 v0, v7
	s_nop 0
	v_mul_f32_e32 v7, v21, v0
	v_lshlrev_b32_e32 v13, 16, v8
	v_and_b32_e32 v8, 0xffff0000, v8
	v_mul_f32_e32 v3, 0xbfb8aa3b, v13
	v_exp_f32_e32 v18, v3
	v_mul_f32_e32 v3, 0xbfb8aa3b, v8
	v_exp_f32_e32 v19, v3
	v_rcp_f32_e32 v0, v6
	s_nop 0
	v_mul_f32_e32 v6, v20, v0
	v_pk_fma_f32 v[6:7], v[16:17], v[6:7], 0 op_sel_hi:[1,1,0]
	v_lshlrev_b32_e32 v16, 16, v4
	v_cvt_pk_bf16_f32 v3, v6, v7
	v_pk_add_f32 v[6:7], v[18:19], 1.0 op_sel_hi:[1,0]
	v_and_b32_e32 v17, 0xffff0000, v4
	v_pk_mul_f32 v[16:17], v[12:13], v[16:17] op_sel_hi:[0,1]
	v_rcp_f32_e32 v0, v7
	s_nop 0
	v_mul_f32_e32 v7, v8, v0
	v_and_b32_e32 v19, 0xffff0000, v9
	v_lshlrev_b32_e32 v18, 16, v9
	v_mul_f32_e32 v4, 0xbfb8aa3b, v18
	v_exp_f32_e32 v8, v4
	v_mul_f32_e32 v4, 0xbfb8aa3b, v19
	v_exp_f32_e32 v9, v4
	v_rcp_f32_e32 v0, v6
	s_nop 0
	v_mul_f32_e32 v6, v13, v0
	v_pk_fma_f32 v[6:7], v[16:17], v[6:7], 0 op_sel_hi:[1,1,0]
	s_nop 0
	v_cvt_pk_bf16_f32 v4, v6, v7
	v_pk_add_f32 v[6:7], v[8:9], 1.0 op_sel_hi:[1,0]
	v_lshlrev_b32_e32 v8, 16, v5
	v_and_b32_e32 v9, 0xffff0000, v5
	v_pk_mul_f32 v[8:9], v[12:13], v[8:9] op_sel_hi:[0,1]
	v_rcp_f32_e32 v0, v7
	s_nop 0
	v_mul_f32_e32 v7, v19, v0
	v_rcp_f32_e32 v0, v6
	s_nop 0
	v_mul_f32_e32 v6, v18, v0
	v_pk_fma_f32 v[6:7], v[8:9], v[6:7], 0 op_sel_hi:[1,1,0]
	v_add_u32_e32 v0, s67, v196
	v_cvt_pk_bf16_f32 v5, v6, v7
	v_lshl_add_u64 v[6:7], v[10:11], 0, v[14:15]
	global_store_dwordx4 v[6:7], v[2:5], off
	v_mov_b32_e32 v6, -1.0
	s_nop 0
	v_ashrrev_i32_e32 v3, 6, v0
	v_add_u32_e32 v2, -2, v3
	v_cmp_gt_i32_e32 vcc, v150, v3
	v_cmp_le_i32_e64 s[0:1], v150, v3
	v_mov_b32_e32 v0, -1.0
	s_barrier
	s_and_saveexec_b64 s[12:13], s[0:1]
	s_cbranch_execz .LBB0_1168
	v_readlane_b32 s14, v255, 29
	v_cmp_le_i32_e64 s[0:1], v150, v2
	v_readlane_b32 s15, v255, 30
	s_and_b64 s[14:15], s[14:15], s[0:1]
	v_mov_b32_e32 v6, 0x4e6e6b28
	s_and_saveexec_b64 s[0:1], s[14:15]
	s_cbranch_execz .LBB0_1167
	v_add_u32_e32 v4, -4, v197
	ds_read2_b32 v[4:5], v4 offset1:1
	s_waitcnt lgkmcnt(0)
	v_add_f32_e32 v6, v4, v5
	ds_read2_b32 v[4:5], v197 offset0:1 offset1:2
	s_waitcnt lgkmcnt(0)
	v_add_f32_e32 v4, v6, v4
	v_add_f32_e32 v4, v4, v5
	ds_read_b32 v5, v197 offset:12
	s_waitcnt lgkmcnt(0)
	v_add_f32_e32 v6, v4, v5

.LBB0_1210:
	s_bitcmp1_b32 s16, 0
	v_lshrrev_b64 v[10:11], v0, v[170:171]
	s_cselect_b32 s27, 0x8c00, 0
	v_and_b32_e32 v10, 1, v10
	v_add_u32_e32 v234, s27, v219
	v_cmp_eq_u32_e32 vcc, 1, v10
	v_cmp_ne_u32_e64 s[0:1], 0, v10
	ds_read_b128 v[82:85], v234
	ds_read_b128 v[142:145], v234 offset:32
	ds_read_b128 v[138:141], v234 offset:64
	ds_read_b128 v[10:13], v234 offset:96
	s_cmp_lg_u64 s[0:1], 0
	s_cselect_b64 s[22:23], -1, 0
	s_and_b64 s[16:17], s[12:13], vcc
	v_lshl_or_b32 v233, v0, 6, v188
	v_cndmask_b32_e64 v169, 0, v168, s[16:17]
	v_add_u32_e32 v81, s27, v220
	s_mov_b64 vcc, s[0:1]
	s_cbranch_vccz .LBB0_1214
	s_waitcnt lgkmcnt(3)
	v_mfma_f32_32x32x16_bf16 v[82:97], v[82:85], v[122:125], 0
	s_waitcnt lgkmcnt(2)
	v_mfma_f32_32x32x16_bf16 v[82:97], v[142:145], v[126:129], v[82:97]
	s_waitcnt lgkmcnt(1)
	v_mfma_f32_32x32x16_bf16 v[82:97], v[138:141], v[98:101], v[82:97]
	ds_read_b128 v[138:141], v234 offset:128
	ds_read_b128 v[142:145], v234 offset:160
	ds_read_b128 v[236:239], v234 offset:192
	ds_read_b128 v[240:243], v234 offset:224
	s_waitcnt lgkmcnt(4)
	v_mfma_f32_32x32x16_bf16 v[82:97], v[10:13], v[102:105], v[82:97]
	s_waitcnt lgkmcnt(3)
	v_mfma_f32_32x32x16_bf16 v[82:97], v[138:141], v[106:109], v[82:97]
	v_cndmask_b32_e64 v0, v230, v233, s[16:17]
	v_cmp_le_u32_e32 vcc, v0, v169
	v_or_b32_e32 v208, 10, v0
	v_or_b32_e32 v209, 11, v0
	v_or_b32_e32 v210, 16, v0
	v_or_b32_e32 v211, 17, v0
	ds_read_b128 v[138:141], v81 offset:17408
	ds_read_b128 v[10:13], v81 offset:22016
	s_waitcnt lgkmcnt(4)
	v_mfma_f32_32x32x16_bf16 v[82:97], v[142:145], v[110:113], v[82:97]
	v_or_b32_e32 v142, 2, v0
	v_or_b32_e32 v143, 3, v0
	v_or_b32_e32 v144, 8, v0
	v_or_b32_e32 v145, 9, v0
	s_waitcnt lgkmcnt(3)
	v_mfma_f32_32x32x16_bf16 v[82:97], v[236:239], v[114:117], v[82:97]
	s_waitcnt lgkmcnt(2)
	v_mfma_f32_32x32x16_bf16 v[82:97], v[240:243], v[118:121], v[82:97]
	s_cmp_eq_u64 s[14:15], 0
	s_nop 10
	s_cbranch_scc1 .Lself0
	v_cndmask_b32_e32 v237, v231, v82, vcc
	v_cmp_lt_u32_e32 vcc, v0, v169
	v_or_b32_e32 v82, 18, v0
	s_nop 0
	v_cndmask_b32_e32 v238, v231, v83, vcc
	v_cmp_le_u32_e32 vcc, v142, v169
	s_nop 1
	v_cndmask_b32_e32 v239, v231, v84, vcc
	v_cmp_le_u32_e32 vcc, v143, v169
	s_nop 1
	v_cndmask_b32_e32 v240, v231, v85, vcc
	v_cmp_le_u32_e32 vcc, v144, v169
	s_nop 1
	v_cndmask_b32_e32 v142, v231, v86, vcc
	v_cmp_le_u32_e32 vcc, v145, v169
	s_nop 1
	v_cndmask_b32_e32 v143, v231, v87, vcc
	v_cmp_le_u32_e32 vcc, v208, v169
	s_nop 1
	v_cndmask_b32_e32 v144, v231, v88, vcc
	v_cmp_le_u32_e32 vcc, v209, v169
	s_nop 1
	v_cndmask_b32_e32 v145, v231, v89, vcc
	v_cmp_le_u32_e32 vcc, v210, v169
	s_nop 1
	v_cndmask_b32_e32 v244, v231, v90, vcc
	v_cmp_le_u32_e32 vcc, v211, v169
	s_nop 1
	v_cndmask_b32_e32 v241, v231, v91, vcc
	v_cmp_le_u32_e32 vcc, v82, v169
	v_or_b32_e32 v82, 19, v0
	s_nop 0
	v_cndmask_b32_e32 v242, v231, v92, vcc
	v_cmp_le_u32_e32 vcc, v82, v169
	v_or_b32_e32 v82, 24, v0
	s_nop 0
	v_cndmask_b32_e32 v243, v231, v93, vcc
	v_cmp_le_u32_e32 vcc, v82, v169
	v_or_b32_e32 v82, 25, v0
	s_nop 0
	v_cndmask_b32_e32 v90, v231, v94, vcc
	v_cmp_le_u32_e32 vcc, v82, v169
	v_or_b32_e32 v82, 26, v0
	v_or_b32_e32 v0, 27, v0
	v_cndmask_b32_e32 v91, v231, v95, vcc
	v_cmp_le_u32_e32 vcc, v82, v169
	v_max_f32_e32 v82, v237, v237
	s_nop 0
	v_cndmask_b32_e32 v92, v231, v96, vcc
	v_cmp_le_u32_e32 vcc, v0, v169
	v_max_f32_e32 v0, v238, v238
	v_max_f32_e32 v0, v82, v0
	v_max3_f32 v0, v0, v239, v240
	v_max3_f32 v0, v0, v142, v143
	v_max3_f32 v0, v0, v144, v145
	v_max3_f32 v0, v0, v244, v241
	v_max3_f32 v0, v0, v242, v243
	v_cndmask_b32_e32 v93, v231, v97, vcc
	v_max3_f32 v0, v0, v90, v91
	v_max3_f32 v0, v0, v92, v93
.Lself0_join:
	v_mov_b32_e32 v82, v0
	s_nop 1
	v_permlane32_swap_b32_e32 v0, v82
	v_max_f32_e32 v82, v82, v82
	v_max_f32_e32 v0, v0, v0
	v_max_f32_e32 v0, v0, v82
	v_mul_f32_e32 v0, 0x3e0293ee, v0
	v_max_f32_e32 v82, v235, v235
	v_max_f32_e32 v236, v82, v0
	v_sub_f32_e32 v0, v235, v236
	v_exp_f32_e32 v0, v0
	ds_read_b128 v[86:89], v81 offset:26624
	ds_read_b128 v[82:85], v81 offset:31232
	v_cmp_eq_f32_e32 vcc, 1.0, v0
	s_cmp_eq_u64 vcc, exec
	s_cbranch_scc1 .LBB0_1213
	v_pk_mul_f32 v[78:79], v[78:79], v[0:1] op_sel_hi:[1,0]
	v_pk_mul_f32 v[76:77], v[76:77], v[0:1] op_sel_hi:[1,0]
	v_pk_mul_f32 v[74:75], v[74:75], v[0:1] op_sel_hi:[1,0]
	v_pk_mul_f32 v[72:73], v[72:73], v[0:1] op_sel_hi:[1,0]
	v_pk_mul_f32 v[70:71], v[70:71], v[0:1] op_sel_hi:[1,0]
	v_pk_mul_f32 v[68:69], v[68:69], v[0:1] op_sel_hi:[1,0]
	v_pk_mul_f32 v[66:67], v[66:67], v[0:1] op_sel_hi:[1,0]
	v_pk_mul_f32 v[64:65], v[64:65], v[0:1] op_sel_hi:[1,0]
	v_pk_mul_f32 v[62:63], v[62:63], v[0:1] op_sel_hi:[1,0]
	v_pk_mul_f32 v[60:61], v[60:61], v[0:1] op_sel_hi:[1,0]
	v_pk_mul_f32 v[58:59], v[58:59], v[0:1] op_sel_hi:[1,0]
	v_pk_mul_f32 v[56:57], v[56:57], v[0:1] op_sel_hi:[1,0]
	v_pk_mul_f32 v[54:55], v[54:55], v[0:1] op_sel_hi:[1,0]
	v_pk_mul_f32 v[52:53], v[52:53], v[0:1] op_sel_hi:[1,0]
	v_pk_mul_f32 v[50:51], v[50:51], v[0:1] op_sel_hi:[1,0]
	v_pk_mul_f32 v[48:49], v[48:49], v[0:1] op_sel_hi:[1,0]
	v_pk_mul_f32 v[46:47], v[46:47], v[0:1] op_sel_hi:[1,0]
	v_pk_mul_f32 v[44:45], v[44:45], v[0:1] op_sel_hi:[1,0]
	v_pk_mul_f32 v[42:43], v[42:43], v[0:1] op_sel_hi:[1,0]
	v_pk_mul_f32 v[40:41], v[40:41], v[0:1] op_sel_hi:[1,0]
	v_pk_mul_f32 v[38:39], v[38:39], v[0:1] op_sel_hi:[1,0]
	v_pk_mul_f32 v[36:37], v[36:37], v[0:1] op_sel_hi:[1,0]
	v_pk_mul_f32 v[34:35], v[34:35], v[0:1] op_sel_hi:[1,0]
	v_pk_mul_f32 v[32:33], v[32:33], v[0:1] op_sel_hi:[1,0]
	v_pk_mul_f32 v[30:31], v[30:31], v[0:1] op_sel_hi:[1,0]
	v_pk_mul_f32 v[28:29], v[28:29], v[0:1] op_sel_hi:[1,0]
	v_pk_mul_f32 v[26:27], v[26:27], v[0:1] op_sel_hi:[1,0]
	v_pk_mul_f32 v[24:25], v[24:25], v[0:1] op_sel_hi:[1,0]
	v_pk_mul_f32 v[22:23], v[22:23], v[0:1] op_sel_hi:[1,0]
	v_pk_mul_f32 v[20:21], v[20:21], v[0:1] op_sel_hi:[1,0]
	v_pk_mul_f32 v[18:19], v[18:19], v[0:1] op_sel_hi:[1,0]
	v_pk_mul_f32 v[16:17], v[16:17], v[0:1] op_sel_hi:[1,0]

.Lself0:
	v_cndmask_b32_e64 v237, v231, v82, s[16:17]
	v_cndmask_b32_e64 v238, v231, v83, s[16:17]
	v_cndmask_b32_e64 v239, v231, v84, s[16:17]
	v_cndmask_b32_e64 v240, v231, v85, s[16:17]
	v_cndmask_b32_e64 v142, v231, v86, s[16:17]
	v_cndmask_b32_e64 v143, v231, v87, s[16:17]
	v_cndmask_b32_e64 v144, v231, v88, s[16:17]
	v_cndmask_b32_e64 v145, v231, v89, s[16:17]
	v_cndmask_b32_e64 v244, v231, v90, s[16:17]
	v_cndmask_b32_e64 v241, v231, v91, s[16:17]
	v_cndmask_b32_e64 v242, v231, v92, s[16:17]
	v_cndmask_b32_e64 v243, v231, v93, s[16:17]
	v_cndmask_b32_e64 v90, v231, v94, s[16:17]
	v_cndmask_b32_e64 v91, v231, v95, s[16:17]
	v_max_f32_e32 v82, v237, v237
	v_cndmask_b32_e64 v92, v231, v96, s[16:17]
	v_max_f32_e32 v0, v238, v238
	v_max_f32_e32 v0, v82, v0
	v_max3_f32 v0, v0, v239, v240
	v_max3_f32 v0, v0, v142, v143
	v_max3_f32 v0, v0, v144, v145
	v_max3_f32 v0, v0, v244, v241
	v_max3_f32 v0, v0, v242, v243
	v_cndmask_b32_e64 v93, v231, v97, s[16:17]
	v_max3_f32 v0, v0, v90, v91
	v_max3_f32 v0, v0, v92, v93
	s_branch .Lself0_join
.Lself1:
	v_cndmask_b32_e64 v144, v231, v82, s[16:17]
	v_cndmask_b32_e64 v145, v231, v83, s[16:17]
	v_cndmask_b32_e64 v233, v231, v84, s[16:17]
	v_cndmask_b32_e64 v234, v231, v85, s[16:17]
	v_cndmask_b32_e64 v14, v231, v86, s[16:17]
	v_cndmask_b32_e64 v15, v231, v87, s[16:17]
	v_cndmask_b32_e64 v142, v231, v88, s[16:17]
	v_cndmask_b32_e64 v143, v231, v89, s[16:17]
	v_cndmask_b32_e64 v237, v231, v90, s[16:17]
	v_cndmask_b32_e64 v238, v231, v91, s[16:17]
	v_cndmask_b32_e64 v239, v231, v92, s[16:17]
	v_cndmask_b32_e64 v240, v231, v93, s[16:17]
	v_cndmask_b32_e64 v90, v231, v94, s[16:17]
	v_cndmask_b32_e64 v91, v231, v95, s[16:17]
	v_max_f32_e32 v82, v144, v144
	v_cndmask_b32_e64 v92, v231, v96, s[16:17]
	v_max_f32_e32 v0, v145, v145
	v_max_f32_e32 v0, v82, v0
	v_max3_f32 v0, v0, v233, v234
	v_max3_f32 v0, v0, v14, v15
	v_max3_f32 v0, v0, v142, v143
	v_max3_f32 v0, v0, v237, v238
	v_max3_f32 v0, v0, v239, v240
	v_cndmask_b32_e64 v93, v231, v97, s[16:17]
	v_max3_f32 v0, v0, v90, v91
	v_max3_f32 v0, v0, v92, v93
	s_branch .Lself1_join

.LBB0_1217:
	s_andn2_b64 vcc, exec, s[22:23]
	s_cbranch_vccnz .LBB0_1221
	s_waitcnt lgkmcnt(3)
	v_mfma_f32_32x32x16_bf16 v[82:97], v[82:85], v[122:125], 0
	s_waitcnt lgkmcnt(2)
	v_mfma_f32_32x32x16_bf16 v[82:97], v[142:145], v[126:129], v[82:97]
	s_waitcnt lgkmcnt(1)
	v_mfma_f32_32x32x16_bf16 v[82:97], v[138:141], v[98:101], v[82:97]
	ds_read_b128 v[138:141], v234 offset:8832
	ds_read_b128 v[142:145], v234 offset:8864
	ds_read_b128 v[238:241], v234 offset:8896
	ds_read_b128 v[242:245], v234 offset:8928
	s_waitcnt lgkmcnt(4)
	v_mfma_f32_32x32x16_bf16 v[82:97], v[10:13], v[102:105], v[82:97]
	s_waitcnt lgkmcnt(3)
	v_mfma_f32_32x32x16_bf16 v[82:97], v[138:141], v[106:109], v[82:97]
	v_or_b32_e32 v0, 32, v233
	v_cndmask_b32_e64 v0, v230, v0, s[16:17]
	v_cmp_le_u32_e32 vcc, v0, v169
	v_or_b32_e32 v14, 2, v0
	v_or_b32_e32 v15, 3, v0
	v_or_b32_e32 v208, 10, v0
	v_or_b32_e32 v209, 11, v0
	s_waitcnt lgkmcnt(2)
	v_mfma_f32_32x32x16_bf16 v[82:97], v[142:145], v[110:113], v[82:97]
	v_or_b32_e32 v142, 8, v0
	v_or_b32_e32 v143, 9, v0
	v_or_b32_e32 v210, 16, v0
	ds_read_b128 v[138:141], v81 offset:17472
	ds_read_b128 v[10:13], v81 offset:22080
	s_waitcnt lgkmcnt(3)
	v_mfma_f32_32x32x16_bf16 v[82:97], v[238:241], v[114:117], v[82:97]
	s_waitcnt lgkmcnt(2)
	v_mfma_f32_32x32x16_bf16 v[82:97], v[242:245], v[118:121], v[82:97]
	s_cmp_eq_u64 s[14:15], 0
	s_nop 10
	s_cbranch_scc1 .Lself1
	v_cndmask_b32_e32 v144, v231, v82, vcc
	v_cmp_lt_u32_e32 vcc, v0, v169
	v_or_b32_e32 v82, 17, v0
	s_nop 0
	v_cndmask_b32_e32 v145, v231, v83, vcc
	v_cmp_le_u32_e32 vcc, v14, v169
	s_nop 1
	v_cndmask_b32_e32 v233, v231, v84, vcc
	v_cmp_le_u32_e32 vcc, v15, v169
	s_nop 1
	v_cndmask_b32_e32 v234, v231, v85, vcc
	v_cmp_le_u32_e32 vcc, v142, v169
	s_nop 1
	v_cndmask_b32_e32 v14, v231, v86, vcc
	v_cmp_le_u32_e32 vcc, v143, v169
	s_nop 1
	v_cndmask_b32_e32 v15, v231, v87, vcc
	v_cmp_le_u32_e32 vcc, v208, v169
	s_nop 1
	v_cndmask_b32_e32 v142, v231, v88, vcc
	v_cmp_le_u32_e32 vcc, v209, v169
	s_nop 1
	v_cndmask_b32_e32 v143, v231, v89, vcc
	v_cmp_le_u32_e32 vcc, v210, v169
	s_nop 1
	v_cndmask_b32_e32 v237, v231, v90, vcc
	v_cmp_le_u32_e32 vcc, v82, v169
	v_or_b32_e32 v82, 18, v0
	s_nop 0
	v_cndmask_b32_e32 v238, v231, v91, vcc
	v_cmp_le_u32_e32 vcc, v82, v169
	v_or_b32_e32 v82, 19, v0
	s_nop 0
	v_cndmask_b32_e32 v239, v231, v92, vcc
	v_cmp_le_u32_e32 vcc, v82, v169
	v_or_b32_e32 v82, 24, v0
	s_nop 0
	v_cndmask_b32_e32 v240, v231, v93, vcc
	v_cmp_le_u32_e32 vcc, v82, v169
	v_or_b32_e32 v82, 25, v0
	s_nop 0
	v_cndmask_b32_e32 v90, v231, v94, vcc
	v_cmp_le_u32_e32 vcc, v82, v169
	v_or_b32_e32 v82, 26, v0
	v_or_b32_e32 v0, 27, v0
	v_cndmask_b32_e32 v91, v231, v95, vcc
	v_cmp_le_u32_e32 vcc, v82, v169
	v_max_f32_e32 v82, v144, v144
	s_nop 0
	v_cndmask_b32_e32 v92, v231, v96, vcc
	v_cmp_le_u32_e32 vcc, v0, v169
	v_max_f32_e32 v0, v145, v145
	v_max_f32_e32 v0, v82, v0
	v_max3_f32 v0, v0, v233, v234
	v_max3_f32 v0, v0, v14, v15
	v_max3_f32 v0, v0, v142, v143
	v_max3_f32 v0, v0, v237, v238
	v_max3_f32 v0, v0, v239, v240
	v_cndmask_b32_e32 v93, v231, v97, vcc
	v_max3_f32 v0, v0, v90, v91
	v_max3_f32 v0, v0, v92, v93
.Lself1_join:
	v_mov_b32_e32 v82, v0
	s_nop 1
	v_permlane32_swap_b32_e32 v0, v82
	v_max_f32_e32 v82, v82, v82
	v_max_f32_e32 v0, v0, v0
	v_max_f32_e32 v0, v0, v82
	v_mul_f32_e32 v0, 0x3e0293ee, v0
	v_max_f32_e32 v82, v236, v236
	v_max_f32_e32 v235, v82, v0
	v_sub_f32_e32 v0, v236, v235
	v_exp_f32_e32 v0, v0
	ds_read_b128 v[86:89], v81 offset:26688
	ds_read_b128 v[82:85], v81 offset:31296
	v_cmp_eq_f32_e32 vcc, 1.0, v0
	s_cmp_eq_u64 vcc, exec
	s_cbranch_scc1 .LBB0_1220
	v_pk_mul_f32 v[78:79], v[78:79], v[0:1] op_sel_hi:[1,0]
	v_pk_mul_f32 v[76:77], v[76:77], v[0:1] op_sel_hi:[1,0]
	v_pk_mul_f32 v[74:75], v[74:75], v[0:1] op_sel_hi:[1,0]
	v_pk_mul_f32 v[72:73], v[72:73], v[0:1] op_sel_hi:[1,0]
	v_pk_mul_f32 v[70:71], v[70:71], v[0:1] op_sel_hi:[1,0]
	v_pk_mul_f32 v[68:69], v[68:69], v[0:1] op_sel_hi:[1,0]
	v_pk_mul_f32 v[66:67], v[66:67], v[0:1] op_sel_hi:[1,0]
	v_pk_mul_f32 v[64:65], v[64:65], v[0:1] op_sel_hi:[1,0]
	v_pk_mul_f32 v[62:63], v[62:63], v[0:1] op_sel_hi:[1,0]
	v_pk_mul_f32 v[60:61], v[60:61], v[0:1] op_sel_hi:[1,0]
	v_pk_mul_f32 v[58:59], v[58:59], v[0:1] op_sel_hi:[1,0]
	v_pk_mul_f32 v[56:57], v[56:57], v[0:1] op_sel_hi:[1,0]
	v_pk_mul_f32 v[54:55], v[54:55], v[0:1] op_sel_hi:[1,0]
	v_pk_mul_f32 v[52:53], v[52:53], v[0:1] op_sel_hi:[1,0]
	v_pk_mul_f32 v[50:51], v[50:51], v[0:1] op_sel_hi:[1,0]
	v_pk_mul_f32 v[48:49], v[48:49], v[0:1] op_sel_hi:[1,0]
	v_pk_mul_f32 v[46:47], v[46:47], v[0:1] op_sel_hi:[1,0]
	v_pk_mul_f32 v[44:45], v[44:45], v[0:1] op_sel_hi:[1,0]
	v_pk_mul_f32 v[42:43], v[42:43], v[0:1] op_sel_hi:[1,0]
	v_pk_mul_f32 v[40:41], v[40:41], v[0:1] op_sel_hi:[1,0]
	v_pk_mul_f32 v[38:39], v[38:39], v[0:1] op_sel_hi:[1,0]
	v_pk_mul_f32 v[36:37], v[36:37], v[0:1] op_sel_hi:[1,0]
	v_pk_mul_f32 v[34:35], v[34:35], v[0:1] op_sel_hi:[1,0]
	v_pk_mul_f32 v[32:33], v[32:33], v[0:1] op_sel_hi:[1,0]
	v_pk_mul_f32 v[30:31], v[30:31], v[0:1] op_sel_hi:[1,0]
	v_pk_mul_f32 v[28:29], v[28:29], v[0:1] op_sel_hi:[1,0]
	v_pk_mul_f32 v[26:27], v[26:27], v[0:1] op_sel_hi:[1,0]
	v_pk_mul_f32 v[24:25], v[24:25], v[0:1] op_sel_hi:[1,0]
	v_pk_mul_f32 v[22:23], v[22:23], v[0:1] op_sel_hi:[1,0]
	v_pk_mul_f32 v[20:21], v[20:21], v[0:1] op_sel_hi:[1,0]
	v_pk_mul_f32 v[18:19], v[18:19], v[0:1] op_sel_hi:[1,0]
	v_pk_mul_f32 v[16:17], v[16:17], v[0:1] op_sel_hi:[1,0]

.LBB0_1229:
	ds_bpermute_b32 v0, v191, v80
	s_waitcnt vmcnt(0)
	v_mov_b32_e32 v8, v177
	s_waitcnt lgkmcnt(0)
	v_add_f32_e32 v0, v80, v0
	v_and_b32_e32 v4, 31, v8
	v_rcp_f32_e32 v2, v0
	s_nop 0
	v_mul_f32_e32 v2, 1.0, v2
	v_cmp_lt_f32_e32 vcc, 0, v0
	v_mul_u32_u24_e32 v6, 0x110, v4
	s_nop 0
	v_cndmask_b32_e32 v0, 0, v2, vcc
	v_pk_mul_f32 v[2:3], v[64:65], v[0:1] op_sel_hi:[1,0]
	v_pk_mul_f32 v[4:5], v[66:67], v[0:1] op_sel_hi:[1,0]
	v_cvt_pk_bf16_f32 v2, v2, v3
	v_cvt_pk_bf16_f32 v3, v4, v5
	v_ashrrev_i32_e32 v4, 2, v8
	v_and_b32_e32 v4, -8, v4
	v_add3_u32 v9, s95, v6, v4
	v_pk_mul_f32 v[4:5], v[68:69], v[0:1] op_sel_hi:[1,0]
	v_pk_mul_f32 v[6:7], v[70:71], v[0:1] op_sel_hi:[1,0]
	v_cvt_pk_bf16_f32 v4, v4, v5
	v_cvt_pk_bf16_f32 v5, v6, v7
	ds_write2_b64 v9, v[2:3], v[4:5] offset1:2
	v_pk_mul_f32 v[2:3], v[72:73], v[0:1] op_sel_hi:[1,0]
	v_pk_mul_f32 v[4:5], v[74:75], v[0:1] op_sel_hi:[1,0]
	v_cvt_pk_bf16_f32 v2, v2, v3
	v_cvt_pk_bf16_f32 v3, v4, v5
	v_pk_mul_f32 v[4:5], v[76:77], v[0:1] op_sel_hi:[1,0]
	v_pk_mul_f32 v[6:7], v[78:79], v[0:1] op_sel_hi:[1,0]
	v_cvt_pk_bf16_f32 v4, v4, v5
	v_cvt_pk_bf16_f32 v5, v6, v7
	ds_write2_b64 v9, v[2:3], v[4:5] offset0:4 offset1:6
	v_pk_mul_f32 v[2:3], v[48:49], v[0:1] op_sel_hi:[1,0]
	v_pk_mul_f32 v[4:5], v[50:51], v[0:1] op_sel_hi:[1,0]
	v_cvt_pk_bf16_f32 v2, v2, v3
	v_cvt_pk_bf16_f32 v3, v4, v5
	v_pk_mul_f32 v[4:5], v[52:53], v[0:1] op_sel_hi:[1,0]
	v_pk_mul_f32 v[6:7], v[54:55], v[0:1] op_sel_hi:[1,0]
	v_cvt_pk_bf16_f32 v4, v4, v5
	v_cvt_pk_bf16_f32 v5, v6, v7
	ds_write2_b64 v9, v[2:3], v[4:5] offset0:8 offset1:10
	v_pk_mul_f32 v[2:3], v[56:57], v[0:1] op_sel_hi:[1,0]
	v_pk_mul_f32 v[4:5], v[58:59], v[0:1] op_sel_hi:[1,0]
	v_cvt_pk_bf16_f32 v2, v2, v3
	v_cvt_pk_bf16_f32 v3, v4, v5
	v_pk_mul_f32 v[4:5], v[60:61], v[0:1] op_sel_hi:[1,0]
	v_pk_mul_f32 v[6:7], v[62:63], v[0:1] op_sel_hi:[1,0]
	v_cvt_pk_bf16_f32 v4, v4, v5
	v_cvt_pk_bf16_f32 v5, v6, v7
	ds_write2_b64 v9, v[2:3], v[4:5] offset0:12 offset1:14
	v_pk_mul_f32 v[2:3], v[32:33], v[0:1] op_sel_hi:[1,0]
	v_pk_mul_f32 v[4:5], v[34:35], v[0:1] op_sel_hi:[1,0]
	v_cvt_pk_bf16_f32 v2, v2, v3
	v_cvt_pk_bf16_f32 v3, v4, v5
	v_pk_mul_f32 v[4:5], v[36:37], v[0:1] op_sel_hi:[1,0]
	v_pk_mul_f32 v[6:7], v[38:39], v[0:1] op_sel_hi:[1,0]
	v_cvt_pk_bf16_f32 v4, v4, v5
	v_cvt_pk_bf16_f32 v5, v6, v7
	ds_write2_b64 v9, v[2:3], v[4:5] offset0:16 offset1:18
	v_pk_mul_f32 v[2:3], v[40:41], v[0:1] op_sel_hi:[1,0]
	v_pk_mul_f32 v[4:5], v[42:43], v[0:1] op_sel_hi:[1,0]
	v_cvt_pk_bf16_f32 v2, v2, v3
	v_cvt_pk_bf16_f32 v3, v4, v5
	v_pk_mul_f32 v[4:5], v[44:45], v[0:1] op_sel_hi:[1,0]
	v_pk_mul_f32 v[6:7], v[46:47], v[0:1] op_sel_hi:[1,0]
	v_cvt_pk_bf16_f32 v4, v4, v5
	v_cvt_pk_bf16_f32 v5, v6, v7
	ds_write2_b64 v9, v[2:3], v[4:5] offset0:20 offset1:22
	v_pk_mul_f32 v[2:3], v[16:17], v[0:1] op_sel_hi:[1,0]
	v_pk_mul_f32 v[4:5], v[18:19], v[0:1] op_sel_hi:[1,0]
	v_cvt_pk_bf16_f32 v2, v2, v3
	v_cvt_pk_bf16_f32 v3, v4, v5
	v_pk_mul_f32 v[4:5], v[20:21], v[0:1] op_sel_hi:[1,0]
	v_pk_mul_f32 v[6:7], v[22:23], v[0:1] op_sel_hi:[1,0]
	v_cvt_pk_bf16_f32 v4, v4, v5
	v_cvt_pk_bf16_f32 v5, v6, v7
	ds_write2_b64 v9, v[2:3], v[4:5] offset0:24 offset1:26
	v_pk_mul_f32 v[2:3], v[24:25], v[0:1] op_sel_hi:[1,0]
	v_pk_mul_f32 v[4:5], v[26:27], v[0:1] op_sel_hi:[1,0]
	v_cvt_pk_bf16_f32 v2, v2, v3
	v_cvt_pk_bf16_f32 v3, v4, v5
	v_pk_mul_f32 v[4:5], v[28:29], v[0:1] op_sel_hi:[1,0]
	v_pk_mul_f32 v[6:7], v[30:31], v[0:1] op_sel_hi:[1,0]
	v_cvt_pk_bf16_f32 v4, v4, v5
	v_cvt_pk_bf16_f32 v5, v6, v7
	ds_write2_b64 v9, v[2:3], v[4:5] offset0:28 offset1:30
	v_ashrrev_i32_e32 v2, 7, v8
	v_ashrrev_i32_e32 v3, 31, v2
	v_ashrrev_i32_e32 v29, 4, v8
	v_lshl_add_u64 v[2:3], s[80:81], 0, v[2:3]
	v_mov_b64_e32 v[20:21], s[48:49]
	v_lshlrev_b32_e32 v0, 4, v8
	v_and_or_b32 v6, v29, 7, s34
	v_mad_u64_u32 v[4:5], s[0:1], v2, s76, v[20:21]
	v_and_b32_e32 v18, 0xf0, v0
	v_mad_i32_i24 v5, v3, s76, v5
	v_lshlrev_b32_e32 v0, 8, v6
	v_lshl_add_u64 v[4:5], v[4:5], 0, v[0:1]
	v_mov_b32_e32 v19, v1
	v_lshl_add_u64 v[4:5], v[4:5], 0, v[18:19]
	v_add_co_u32_e32 v4, vcc, s35, v4
	s_waitcnt lgkmcnt(0)
	v_mov_b64_e32 v[22:23], s[50:51]
	s_nop 0
	v_addc_co_u32_e32 v5, vcc, 0, v5, vcc
	global_load_dwordx4 v[10:13], v[4:5], off
	global_load_dwordx4 v[40:43], v[4:5], off offset:1024
	v_add_co_u32_e32 v68, vcc, 0x6000, v4
	s_nop 1
	v_addc_co_u32_e32 v69, vcc, 0, v5, vcc
	global_load_dwordx4 v[44:47], v[68:69], off
	global_load_dwordx4 v[48:51], v[68:69], off offset:1024
	v_add_co_u32_e32 v68, vcc, 0xc000, v4
	s_nop 1
	v_addc_co_u32_e32 v69, vcc, 0, v5, vcc
	global_load_dwordx4 v[52:55], v[68:69], off
	global_load_dwordx4 v[56:59], v[68:69], off offset:1024
	v_add_co_u32_e32 v68, vcc, 0x12000, v4
	s_nop 1
	v_addc_co_u32_e32 v69, vcc, 0, v5, vcc
	global_load_dwordx4 v[60:63], v[68:69], off
	global_load_dwordx4 v[64:67], v[68:69], off offset:1024
	v_mad_u64_u32 v[4:5], s[0:1], v2, s77, v[22:23]
	v_mad_i32_i24 v5, v3, s77, v5
	v_lshlrev_b64 v[2:3], 13, v[2:3]
	v_lshl_add_u64 v[2:3], s[44:45], 0, v[2:3]
	v_lshlrev_b32_e32 v24, 2, v6
	v_mov_b32_e32 v25, v1
	v_lshl_add_u64 v[2:3], v[2:3], 0, v[0:1]
	v_lshl_add_u64 v[4:5], v[4:5], 0, v[24:25]
	v_lshl_add_u64 v[26:27], v[2:3], 0, v[18:19]
	global_load_dword v28, v[4:5], off offset:128
	global_load_dwordx4 v[6:9], v[26:27], off
	v_mul_lo_u32 v4, v29, s94
	v_add3_u32 v30, s95, v18, v4
	ds_read_b128 v[14:17], v30
	s_waitcnt vmcnt(2)
	v_lshlrev_b32_e32 v31, 16, v10
	v_and_b32_e32 v10, 0xffff0000, v10
	v_mul_f32_e32 v2, 0xbfb8aa3b, v31
	v_mul_f32_e32 v3, 0xbfb8aa3b, v10
	v_exp_f32_e32 v2, v2
	v_exp_f32_e32 v3, v3
	s_nop 0
	v_pk_add_f32 v[32:33], v[2:3], 1.0 op_sel_hi:[1,0]
	s_nop 0
	ds_read_b128 v[2:5], v30 offset:1088
	s_waitcnt lgkmcnt(1)
	v_lshlrev_b32_e32 v34, 16, v14
	v_and_b32_e32 v35, 0xffff0000, v14
	v_rcp_f32_e32 v14, v33
	s_nop 0
	v_mul_f32_e32 v33, v10, v14
	v_and_b32_e32 v38, 0xffff0000, v11
	v_rcp_f32_e32 v10, v32
	s_nop 0
	v_mul_f32_e32 v32, v31, v10
	v_lshlrev_b32_e32 v31, 16, v11
	v_mul_f32_e32 v11, 0xbfb8aa3b, v31
	v_exp_f32_e32 v36, v11
	v_mul_f32_e32 v11, 0xbfb8aa3b, v38
	v_exp_f32_e32 v37, v11
	s_waitcnt vmcnt(1)
	v_pk_mul_f32 v[34:35], v[28:29], v[34:35] op_sel_hi:[0,1]
	s_waitcnt vmcnt(0)
	v_lshlrev_b32_e32 v10, 16, v6
	v_and_b32_e32 v11, 0xffff0000, v6
	v_pk_fma_f32 v[10:11], v[34:35], v[32:33], v[10:11]
	v_lshlrev_b32_e32 v14, 16, v15
	v_cvt_pk_bf16_f32 v6, v10, v11
	v_pk_add_f32 v[10:11], v[36:37], 1.0 op_sel_hi:[1,0]
	v_and_b32_e32 v15, 0xffff0000, v15
	v_pk_mul_f32 v[14:15], v[28:29], v[14:15] op_sel_hi:[0,1]
	v_rcp_f32_e32 v32, v11
	s_nop 0
	v_mul_f32_e32 v11, v38, v32
	v_rcp_f32_e32 v32, v10
	s_nop 0
	v_mul_f32_e32 v10, v31, v32
	v_lshlrev_b32_e32 v31, 16, v12
	v_and_b32_e32 v12, 0xffff0000, v12
	v_mul_f32_e32 v33, 0xbfb8aa3b, v31
	v_exp_f32_e32 v34, v33
	v_mul_f32_e32 v33, 0xbfb8aa3b, v12
	v_exp_f32_e32 v35, v33
	v_lshlrev_b32_e32 v32, 16, v7
	v_and_b32_e32 v33, 0xffff0000, v7
	v_pk_fma_f32 v[10:11], v[14:15], v[10:11], v[32:33]
	v_lshlrev_b32_e32 v14, 16, v16
	v_cvt_pk_bf16_f32 v7, v10, v11
	v_pk_add_f32 v[10:11], v[34:35], 1.0 op_sel_hi:[1,0]
	v_and_b32_e32 v15, 0xffff0000, v16
	v_pk_mul_f32 v[14:15], v[28:29], v[14:15] op_sel_hi:[0,1]
	v_rcp_f32_e32 v16, v11
	s_nop 0
	v_mul_f32_e32 v11, v12, v16
	v_lshlrev_b32_e32 v16, 16, v13
	v_rcp_f32_e32 v12, v10
	s_nop 0
	v_mul_f32_e32 v10, v31, v12
	v_and_b32_e32 v31, 0xffff0000, v13
	v_mul_f32_e32 v13, 0xbfb8aa3b, v16
	v_exp_f32_e32 v32, v13
	v_mul_f32_e32 v13, 0xbfb8aa3b, v31
	v_exp_f32_e32 v33, v13
	v_lshlrev_b32_e32 v12, 16, v8
	v_and_b32_e32 v13, 0xffff0000, v8
	v_pk_fma_f32 v[10:11], v[14:15], v[10:11], v[12:13]
	v_lshlrev_b32_e32 v12, 16, v17
	v_cvt_pk_bf16_f32 v8, v10, v11
	v_pk_add_f32 v[10:11], v[32:33], 1.0 op_sel_hi:[1,0]
	v_and_b32_e32 v13, 0xffff0000, v17
	v_pk_mul_f32 v[12:13], v[28:29], v[12:13] op_sel_hi:[0,1]
	s_waitcnt lgkmcnt(0)
	v_and_b32_e32 v33, 0xffff0000, v2
	v_rcp_f32_e32 v14, v11
	s_nop 0
	v_mul_f32_e32 v11, v31, v14
	v_rcp_f32_e32 v14, v10
	s_nop 0
	v_mul_f32_e32 v10, v16, v14
	v_lshlrev_b32_e32 v14, 16, v9
	v_and_b32_e32 v15, 0xffff0000, v9
	v_pk_fma_f32 v[10:11], v[12:13], v[10:11], v[14:15]
	v_mov_b32_e32 v13, v1
	v_cvt_pk_bf16_f32 v9, v10, v11
	global_store_dwordx4 v[26:27], v[6:9], off
	v_mov_b32_e32 v17, v1
	v_lshlrev_b32_e32 v32, 16, v2
	v_add_u32_e32 v8, 4, v29
	v_ashrrev_i32_e32 v6, 3, v8
	v_ashrrev_i32_e32 v7, 31, v6
	v_lshl_add_u64 v[10:11], s[80:81], 0, v[6:7]
	v_and_or_b32 v16, v8, 7, s34
	v_mad_u64_u32 v[6:7], s[0:1], v10, s76, v[20:21]
	v_mad_i32_i24 v7, v11, s76, v7
	v_lshlrev_b32_e32 v12, 8, v16
	v_lshl_add_u64 v[6:7], v[6:7], 0, v[12:13]
	v_lshl_add_u64 v[6:7], v[6:7], 0, v[18:19]
	v_add_co_u32_e32 v6, vcc, s35, v6
	v_mad_u64_u32 v[14:15], s[0:1], v10, s77, v[22:23]
	s_nop 0
	v_addc_co_u32_e32 v7, vcc, 0, v7, vcc
	global_load_dwordx4 v[6:9], v[6:7], off
	v_mad_i32_i24 v15, v11, s77, v15
	v_lshlrev_b32_e32 v16, 2, v16
	v_lshl_add_u64 v[14:15], v[14:15], 0, v[16:17]
	global_load_dword v14, v[14:15], off offset:128
	v_lshlrev_b64 v[10:11], 13, v[10:11]
	v_lshl_add_u64 v[10:11], s[44:45], 0, v[10:11]
	v_lshl_add_u64 v[10:11], v[10:11], 0, v[12:13]
	v_lshl_add_u64 v[16:17], v[10:11], 0, v[18:19]
	global_load_dwordx4 v[10:13], v[16:17], off
	s_waitcnt vmcnt(2)
	v_lshlrev_b32_e32 v15, 16, v6
	v_and_b32_e32 v6, 0xffff0000, v6
	v_mul_f32_e32 v26, 0xbfb8aa3b, v15
	v_mul_f32_e32 v27, 0xbfb8aa3b, v6
	v_exp_f32_e32 v26, v26
	v_exp_f32_e32 v27, v27
	s_waitcnt vmcnt(1)
	v_pk_mul_f32 v[32:33], v[14:15], v[32:33] op_sel_hi:[0,1]
	v_pk_add_f32 v[26:27], v[26:27], 1.0 op_sel_hi:[1,0]
	s_nop 0
	s_nop 0
	v_rcp_f32_e32 v2, v27
	s_nop 0
	v_mul_f32_e32 v27, v6, v2
	v_rcp_f32_e32 v2, v26
	s_nop 0
	v_mul_f32_e32 v26, v15, v2
	v_lshlrev_b32_e32 v15, 16, v7
	v_and_b32_e32 v28, 0xffff0000, v7
	v_mul_f32_e32 v2, 0xbfb8aa3b, v15
	v_exp_f32_e32 v34, v2
	v_mul_f32_e32 v2, 0xbfb8aa3b, v28
	v_exp_f32_e32 v35, v2
	s_waitcnt vmcnt(0)
	v_lshlrev_b32_e32 v6, 16, v10
	v_and_b32_e32 v7, 0xffff0000, v10
	v_pk_fma_f32 v[6:7], v[32:33], v[26:27], v[6:7]
	v_lshlrev_b32_e32 v26, 16, v3
	v_cvt_pk_bf16_f32 v2, v6, v7
	v_pk_add_f32 v[6:7], v[34:35], 1.0 op_sel_hi:[1,0]
	v_and_b32_e32 v27, 0xffff0000, v3
	v_pk_mul_f32 v[26:27], v[14:15], v[26:27] op_sel_hi:[0,1]
	v_rcp_f32_e32 v3, v7
	s_nop 0
	v_mul_f32_e32 v7, v28, v3
	v_rcp_f32_e32 v3, v6
	s_nop 0
	v_mul_f32_e32 v6, v15, v3
	v_lshlrev_b32_e32 v15, 16, v8
	v_and_b32_e32 v8, 0xffff0000, v8
	v_mul_f32_e32 v3, 0xbfb8aa3b, v15
	v_exp_f32_e32 v32, v3
	v_mul_f32_e32 v3, 0xbfb8aa3b, v8
	v_exp_f32_e32 v33, v3
	v_lshlrev_b32_e32 v10, 16, v11
	v_and_b32_e32 v11, 0xffff0000, v11
	v_pk_fma_f32 v[6:7], v[26:27], v[6:7], v[10:11]
	v_lshlrev_b32_e32 v10, 16, v4
	v_cvt_pk_bf16_f32 v3, v6, v7
	v_pk_add_f32 v[6:7], v[32:33], 1.0 op_sel_hi:[1,0]
	v_and_b32_e32 v11, 0xffff0000, v4
	v_pk_mul_f32 v[10:11], v[14:15], v[10:11] op_sel_hi:[0,1]
	v_rcp_f32_e32 v4, v7
	s_nop 0
	v_mul_f32_e32 v7, v8, v4
	v_and_b32_e32 v28, 0xffff0000, v9
	v_rcp_f32_e32 v4, v6
	s_nop 0
	v_mul_f32_e32 v6, v15, v4
	v_lshlrev_b32_e32 v15, 16, v9
	v_mul_f32_e32 v4, 0xbfb8aa3b, v15
	v_exp_f32_e32 v26, v4
	v_mul_f32_e32 v4, 0xbfb8aa3b, v28
	v_exp_f32_e32 v27, v4
	v_lshlrev_b32_e32 v8, 16, v12
	v_and_b32_e32 v9, 0xffff0000, v12
	v_pk_fma_f32 v[6:7], v[10:11], v[6:7], v[8:9]
	v_lshlrev_b32_e32 v8, 16, v5
	v_cvt_pk_bf16_f32 v4, v6, v7
	v_pk_add_f32 v[6:7], v[26:27], 1.0 op_sel_hi:[1,0]
	v_and_b32_e32 v9, 0xffff0000, v5
	v_pk_mul_f32 v[8:9], v[14:15], v[8:9] op_sel_hi:[0,1]
	v_rcp_f32_e32 v5, v7
	s_nop 0
	v_mul_f32_e32 v7, v28, v5
	v_rcp_f32_e32 v5, v6
	s_nop 0
	v_mul_f32_e32 v6, v15, v5
	v_lshlrev_b32_e32 v10, 16, v13
	v_and_b32_e32 v11, 0xffff0000, v13
	v_pk_fma_f32 v[6:7], v[8:9], v[6:7], v[10:11]
	s_nop 0
	v_cvt_pk_bf16_f32 v5, v6, v7
	global_store_dwordx4 v[16:17], v[2:5], off
	ds_read_b128 v[14:17], v30 offset:2176
	s_nop 0
	v_add_u32_e32 v2, 8, v29
	v_ashrrev_i32_e32 v2, 3, v2
	v_ashrrev_i32_e32 v3, 31, v2
	v_lshl_add_u64 v[2:3], s[80:81], 0, v[2:3]
	v_mad_u64_u32 v[4:5], s[0:1], v2, s76, v[20:21]
	v_mad_i32_i24 v5, v3, s76, v5
	v_lshl_add_u64 v[4:5], v[4:5], 0, v[0:1]
	v_lshl_add_u64 v[4:5], v[4:5], 0, v[18:19]
	v_add_co_u32_e32 v4, vcc, s35, v4
	s_nop 1
	v_addc_co_u32_e32 v5, vcc, 0, v5, vcc
	global_load_dwordx4 v[10:13], v[4:5], off
	v_mad_u64_u32 v[4:5], s[0:1], v2, s77, v[22:23]
	v_mad_i32_i24 v5, v3, s77, v5
	v_lshlrev_b64 v[2:3], 13, v[2:3]
	v_lshl_add_u64 v[2:3], s[44:45], 0, v[2:3]
	v_lshl_add_u64 v[2:3], v[2:3], 0, v[0:1]
	v_lshl_add_u64 v[4:5], v[4:5], 0, v[24:25]
	v_lshl_add_u64 v[26:27], v[2:3], 0, v[18:19]
	global_load_dword v28, v[4:5], off offset:128
	global_load_dwordx4 v[6:9], v[26:27], off
	s_waitcnt vmcnt(2)
	v_lshlrev_b32_e32 v31, 16, v10
	v_and_b32_e32 v10, 0xffff0000, v10
	v_mul_f32_e32 v2, 0xbfb8aa3b, v31
	v_mul_f32_e32 v3, 0xbfb8aa3b, v10
	v_exp_f32_e32 v2, v2
	v_exp_f32_e32 v3, v3
	s_nop 0
	v_pk_add_f32 v[32:33], v[2:3], 1.0 op_sel_hi:[1,0]
	s_nop 0
	ds_read_b128 v[2:5], v30 offset:3264
	s_waitcnt lgkmcnt(1)
	v_lshlrev_b32_e32 v34, 16, v14
	v_and_b32_e32 v35, 0xffff0000, v14
	v_rcp_f32_e32 v14, v33
	s_nop 0
	v_mul_f32_e32 v33, v10, v14
	v_and_b32_e32 v38, 0xffff0000, v11
	v_rcp_f32_e32 v10, v32
	s_nop 0
	v_mul_f32_e32 v32, v31, v10
	v_lshlrev_b32_e32 v31, 16, v11
	v_mul_f32_e32 v11, 0xbfb8aa3b, v31
	v_exp_f32_e32 v36, v11
	v_mul_f32_e32 v11, 0xbfb8aa3b, v38
	v_exp_f32_e32 v37, v11
	s_waitcnt vmcnt(1)
	v_pk_mul_f32 v[34:35], v[28:29], v[34:35] op_sel_hi:[0,1]
	s_waitcnt vmcnt(0)
	v_lshlrev_b32_e32 v10, 16, v6
	v_and_b32_e32 v11, 0xffff0000, v6
	v_pk_fma_f32 v[10:11], v[34:35], v[32:33], v[10:11]
	v_lshlrev_b32_e32 v14, 16, v15
	v_cvt_pk_bf16_f32 v6, v10, v11
	v_pk_add_f32 v[10:11], v[36:37], 1.0 op_sel_hi:[1,0]
	v_and_b32_e32 v15, 0xffff0000, v15
	v_pk_mul_f32 v[14:15], v[28:29], v[14:15] op_sel_hi:[0,1]
	v_rcp_f32_e32 v32, v11
	s_nop 0
	v_mul_f32_e32 v11, v38, v32
	v_rcp_f32_e32 v32, v10
	s_nop 0
	v_mul_f32_e32 v10, v31, v32
	v_lshlrev_b32_e32 v31, 16, v12
	v_and_b32_e32 v12, 0xffff0000, v12
	v_mul_f32_e32 v33, 0xbfb8aa3b, v31
	v_exp_f32_e32 v34, v33
	v_mul_f32_e32 v33, 0xbfb8aa3b, v12
	v_exp_f32_e32 v35, v33
	v_lshlrev_b32_e32 v32, 16, v7
	v_and_b32_e32 v33, 0xffff0000, v7
	v_pk_fma_f32 v[10:11], v[14:15], v[10:11], v[32:33]
	v_lshlrev_b32_e32 v14, 16, v16
	v_cvt_pk_bf16_f32 v7, v10, v11
	v_pk_add_f32 v[10:11], v[34:35], 1.0 op_sel_hi:[1,0]
	v_and_b32_e32 v15, 0xffff0000, v16
	v_pk_mul_f32 v[14:15], v[28:29], v[14:15] op_sel_hi:[0,1]
	v_rcp_f32_e32 v16, v11
	s_nop 0
	v_mul_f32_e32 v11, v12, v16
	v_lshlrev_b32_e32 v16, 16, v13
	v_rcp_f32_e32 v12, v10
	s_nop 0
	v_mul_f32_e32 v10, v31, v12
	v_and_b32_e32 v31, 0xffff0000, v13
	v_mul_f32_e32 v13, 0xbfb8aa3b, v16
	v_exp_f32_e32 v32, v13
	v_mul_f32_e32 v13, 0xbfb8aa3b, v31
	v_exp_f32_e32 v33, v13
	v_lshlrev_b32_e32 v12, 16, v8
	v_and_b32_e32 v13, 0xffff0000, v8
	v_pk_fma_f32 v[10:11], v[14:15], v[10:11], v[12:13]
	v_lshlrev_b32_e32 v12, 16, v17
	v_cvt_pk_bf16_f32 v8, v10, v11
	v_pk_add_f32 v[10:11], v[32:33], 1.0 op_sel_hi:[1,0]
	v_and_b32_e32 v13, 0xffff0000, v17
	v_pk_mul_f32 v[12:13], v[28:29], v[12:13] op_sel_hi:[0,1]
	s_waitcnt lgkmcnt(0)
	v_and_b32_e32 v33, 0xffff0000, v2
	v_rcp_f32_e32 v14, v11
	s_nop 0
	v_mul_f32_e32 v11, v31, v14
	v_rcp_f32_e32 v14, v10
	s_nop 0
	v_mul_f32_e32 v10, v16, v14
	v_lshlrev_b32_e32 v14, 16, v9
	v_and_b32_e32 v15, 0xffff0000, v9
	v_pk_fma_f32 v[10:11], v[12:13], v[10:11], v[14:15]
	v_mov_b32_e32 v13, v1
	v_cvt_pk_bf16_f32 v9, v10, v11
	global_store_dwordx4 v[26:27], v[6:9], off
	v_mov_b32_e32 v17, v1
	v_lshlrev_b32_e32 v32, 16, v2
	v_add_u32_e32 v8, 12, v29
	v_ashrrev_i32_e32 v6, 3, v8
	v_ashrrev_i32_e32 v7, 31, v6
	v_lshl_add_u64 v[10:11], s[80:81], 0, v[6:7]
	v_and_or_b32 v16, v8, 7, s34
	v_mad_u64_u32 v[6:7], s[0:1], v10, s76, v[20:21]
	v_mad_i32_i24 v7, v11, s76, v7
	v_lshlrev_b32_e32 v12, 8, v16
	v_lshl_add_u64 v[6:7], v[6:7], 0, v[12:13]
	v_lshl_add_u64 v[6:7], v[6:7], 0, v[18:19]
	v_add_co_u32_e32 v6, vcc, s35, v6
	v_mad_u64_u32 v[14:15], s[0:1], v10, s77, v[22:23]
	s_nop 0
	v_addc_co_u32_e32 v7, vcc, 0, v7, vcc
	global_load_dwordx4 v[6:9], v[6:7], off
	v_mad_i32_i24 v15, v11, s77, v15
	v_lshlrev_b32_e32 v16, 2, v16
	v_lshl_add_u64 v[14:15], v[14:15], 0, v[16:17]
	global_load_dword v14, v[14:15], off offset:128
	v_lshlrev_b64 v[10:11], 13, v[10:11]
	v_lshl_add_u64 v[10:11], s[44:45], 0, v[10:11]
	v_lshl_add_u64 v[10:11], v[10:11], 0, v[12:13]
	v_lshl_add_u64 v[16:17], v[10:11], 0, v[18:19]
	global_load_dwordx4 v[10:13], v[16:17], off
	s_waitcnt vmcnt(2)
	v_lshlrev_b32_e32 v15, 16, v6
	v_and_b32_e32 v6, 0xffff0000, v6
	v_mul_f32_e32 v26, 0xbfb8aa3b, v15
	v_mul_f32_e32 v27, 0xbfb8aa3b, v6
	v_exp_f32_e32 v26, v26
	v_exp_f32_e32 v27, v27
	s_waitcnt vmcnt(1)
	v_pk_mul_f32 v[32:33], v[14:15], v[32:33] op_sel_hi:[0,1]
	v_pk_add_f32 v[26:27], v[26:27], 1.0 op_sel_hi:[1,0]
	s_nop 0
	s_nop 0
	v_rcp_f32_e32 v2, v27
	s_nop 0
	v_mul_f32_e32 v27, v6, v2
	v_rcp_f32_e32 v2, v26
	s_nop 0
	v_mul_f32_e32 v26, v15, v2
	v_lshlrev_b32_e32 v15, 16, v7
	v_and_b32_e32 v28, 0xffff0000, v7
	v_mul_f32_e32 v2, 0xbfb8aa3b, v15
	v_exp_f32_e32 v34, v2
	v_mul_f32_e32 v2, 0xbfb8aa3b, v28
	v_exp_f32_e32 v35, v2
	s_waitcnt vmcnt(0)
	v_lshlrev_b32_e32 v6, 16, v10
	v_and_b32_e32 v7, 0xffff0000, v10
	v_pk_fma_f32 v[6:7], v[32:33], v[26:27], v[6:7]
	v_lshlrev_b32_e32 v26, 16, v3
	v_cvt_pk_bf16_f32 v2, v6, v7
	v_pk_add_f32 v[6:7], v[34:35], 1.0 op_sel_hi:[1,0]
	v_and_b32_e32 v27, 0xffff0000, v3
	v_pk_mul_f32 v[26:27], v[14:15], v[26:27] op_sel_hi:[0,1]
	v_rcp_f32_e32 v3, v7
	s_nop 0
	v_mul_f32_e32 v7, v28, v3
	v_rcp_f32_e32 v3, v6
	s_nop 0
	v_mul_f32_e32 v6, v15, v3
	v_lshlrev_b32_e32 v15, 16, v8
	v_and_b32_e32 v8, 0xffff0000, v8
	v_mul_f32_e32 v3, 0xbfb8aa3b, v15
	v_exp_f32_e32 v32, v3
	v_mul_f32_e32 v3, 0xbfb8aa3b, v8
	v_exp_f32_e32 v33, v3
	v_lshlrev_b32_e32 v10, 16, v11
	v_and_b32_e32 v11, 0xffff0000, v11
	v_pk_fma_f32 v[6:7], v[26:27], v[6:7], v[10:11]
	v_lshlrev_b32_e32 v10, 16, v4
	v_cvt_pk_bf16_f32 v3, v6, v7
	v_pk_add_f32 v[6:7], v[32:33], 1.0 op_sel_hi:[1,0]
	v_and_b32_e32 v11, 0xffff0000, v4
	v_pk_mul_f32 v[10:11], v[14:15], v[10:11] op_sel_hi:[0,1]
	v_rcp_f32_e32 v4, v7
	s_nop 0
	v_mul_f32_e32 v7, v8, v4
	v_and_b32_e32 v28, 0xffff0000, v9
	v_rcp_f32_e32 v4, v6
	s_nop 0
	v_mul_f32_e32 v6, v15, v4
	v_lshlrev_b32_e32 v15, 16, v9
	v_mul_f32_e32 v4, 0xbfb8aa3b, v15
	v_exp_f32_e32 v26, v4
	v_mul_f32_e32 v4, 0xbfb8aa3b, v28
	v_exp_f32_e32 v27, v4
	v_lshlrev_b32_e32 v8, 16, v12
	v_and_b32_e32 v9, 0xffff0000, v12
	v_pk_fma_f32 v[6:7], v[10:11], v[6:7], v[8:9]
	v_lshlrev_b32_e32 v8, 16, v5
	v_cvt_pk_bf16_f32 v4, v6, v7
	v_pk_add_f32 v[6:7], v[26:27], 1.0 op_sel_hi:[1,0]
	v_and_b32_e32 v9, 0xffff0000, v5
	v_pk_mul_f32 v[8:9], v[14:15], v[8:9] op_sel_hi:[0,1]
	v_rcp_f32_e32 v5, v7
	s_nop 0
	v_mul_f32_e32 v7, v28, v5
	v_rcp_f32_e32 v5, v6
	s_nop 0
	v_mul_f32_e32 v6, v15, v5
	v_lshlrev_b32_e32 v10, 16, v13
	v_and_b32_e32 v11, 0xffff0000, v13
	v_pk_fma_f32 v[6:7], v[8:9], v[6:7], v[10:11]
	s_nop 0
	v_cvt_pk_bf16_f32 v5, v6, v7
	global_store_dwordx4 v[16:17], v[2:5], off
	ds_read_b128 v[14:17], v30 offset:4352
	s_nop 0
	v_add_u32_e32 v2, 16, v29
	v_ashrrev_i32_e32 v2, 3, v2
	v_ashrrev_i32_e32 v3, 31, v2
	v_lshl_add_u64 v[2:3], s[80:81], 0, v[2:3]
	v_mad_u64_u32 v[4:5], s[0:1], v2, s76, v[20:21]
	v_mad_i32_i24 v5, v3, s76, v5
	v_lshl_add_u64 v[4:5], v[4:5], 0, v[0:1]
	v_lshl_add_u64 v[4:5], v[4:5], 0, v[18:19]
	v_add_co_u32_e32 v4, vcc, s35, v4
	s_nop 1
	v_addc_co_u32_e32 v5, vcc, 0, v5, vcc
	global_load_dwordx4 v[10:13], v[4:5], off
	v_mad_u64_u32 v[4:5], s[0:1], v2, s77, v[22:23]
	v_mad_i32_i24 v5, v3, s77, v5
	v_lshlrev_b64 v[2:3], 13, v[2:3]
	v_lshl_add_u64 v[2:3], s[44:45], 0, v[2:3]
	v_lshl_add_u64 v[2:3], v[2:3], 0, v[0:1]
	v_lshl_add_u64 v[4:5], v[4:5], 0, v[24:25]
	v_lshl_add_u64 v[26:27], v[2:3], 0, v[18:19]
	global_load_dword v28, v[4:5], off offset:128
	global_load_dwordx4 v[6:9], v[26:27], off
	s_waitcnt vmcnt(2)
	v_lshlrev_b32_e32 v31, 16, v10
	v_and_b32_e32 v10, 0xffff0000, v10
	v_mul_f32_e32 v2, 0xbfb8aa3b, v31
	v_mul_f32_e32 v3, 0xbfb8aa3b, v10
	v_exp_f32_e32 v2, v2
	v_exp_f32_e32 v3, v3
	s_nop 0
	v_pk_add_f32 v[32:33], v[2:3], 1.0 op_sel_hi:[1,0]
	s_nop 0
	ds_read_b128 v[2:5], v30 offset:5440
	s_waitcnt lgkmcnt(1)
	v_lshlrev_b32_e32 v34, 16, v14
	v_and_b32_e32 v35, 0xffff0000, v14
	v_rcp_f32_e32 v14, v33
	s_nop 0
	v_mul_f32_e32 v33, v10, v14
	v_and_b32_e32 v38, 0xffff0000, v11
	v_rcp_f32_e32 v10, v32
	s_nop 0
	v_mul_f32_e32 v32, v31, v10
	v_lshlrev_b32_e32 v31, 16, v11
	v_mul_f32_e32 v11, 0xbfb8aa3b, v31
	v_exp_f32_e32 v36, v11
	v_mul_f32_e32 v11, 0xbfb8aa3b, v38
	v_exp_f32_e32 v37, v11
	s_waitcnt vmcnt(1)
	v_pk_mul_f32 v[34:35], v[28:29], v[34:35] op_sel_hi:[0,1]
	s_waitcnt vmcnt(0)
	v_lshlrev_b32_e32 v10, 16, v6
	v_and_b32_e32 v11, 0xffff0000, v6
	v_pk_fma_f32 v[10:11], v[34:35], v[32:33], v[10:11]
	v_lshlrev_b32_e32 v14, 16, v15
	v_cvt_pk_bf16_f32 v6, v10, v11
	v_pk_add_f32 v[10:11], v[36:37], 1.0 op_sel_hi:[1,0]
	v_and_b32_e32 v15, 0xffff0000, v15
	v_pk_mul_f32 v[14:15], v[28:29], v[14:15] op_sel_hi:[0,1]
	v_rcp_f32_e32 v32, v11
	s_nop 0
	v_mul_f32_e32 v11, v38, v32
	v_rcp_f32_e32 v32, v10
	s_nop 0
	v_mul_f32_e32 v10, v31, v32
	v_lshlrev_b32_e32 v31, 16, v12
	v_and_b32_e32 v12, 0xffff0000, v12
	v_mul_f32_e32 v33, 0xbfb8aa3b, v31
	v_exp_f32_e32 v34, v33
	v_mul_f32_e32 v33, 0xbfb8aa3b, v12
	v_exp_f32_e32 v35, v33
	v_lshlrev_b32_e32 v32, 16, v7
	v_and_b32_e32 v33, 0xffff0000, v7
	v_pk_fma_f32 v[10:11], v[14:15], v[10:11], v[32:33]
	v_lshlrev_b32_e32 v14, 16, v16
	v_cvt_pk_bf16_f32 v7, v10, v11
	v_pk_add_f32 v[10:11], v[34:35], 1.0 op_sel_hi:[1,0]
	v_and_b32_e32 v15, 0xffff0000, v16
	v_pk_mul_f32 v[14:15], v[28:29], v[14:15] op_sel_hi:[0,1]
	v_rcp_f32_e32 v16, v11
	s_nop 0
	v_mul_f32_e32 v11, v12, v16
	v_lshlrev_b32_e32 v16, 16, v13
	v_rcp_f32_e32 v12, v10
	s_nop 0
	v_mul_f32_e32 v10, v31, v12
	v_and_b32_e32 v31, 0xffff0000, v13
	v_mul_f32_e32 v13, 0xbfb8aa3b, v16
	v_exp_f32_e32 v32, v13
	v_mul_f32_e32 v13, 0xbfb8aa3b, v31
	v_exp_f32_e32 v33, v13
	v_lshlrev_b32_e32 v12, 16, v8
	v_and_b32_e32 v13, 0xffff0000, v8
	v_pk_fma_f32 v[10:11], v[14:15], v[10:11], v[12:13]
	v_lshlrev_b32_e32 v12, 16, v17
	v_cvt_pk_bf16_f32 v8, v10, v11
	v_pk_add_f32 v[10:11], v[32:33], 1.0 op_sel_hi:[1,0]
	v_and_b32_e32 v13, 0xffff0000, v17
	v_pk_mul_f32 v[12:13], v[28:29], v[12:13] op_sel_hi:[0,1]
	s_waitcnt lgkmcnt(0)
	v_and_b32_e32 v33, 0xffff0000, v2
	v_rcp_f32_e32 v14, v11
	s_nop 0
	v_mul_f32_e32 v11, v31, v14
	v_rcp_f32_e32 v14, v10
	s_nop 0
	v_mul_f32_e32 v10, v16, v14
	v_lshlrev_b32_e32 v14, 16, v9
	v_and_b32_e32 v15, 0xffff0000, v9
	v_pk_fma_f32 v[10:11], v[12:13], v[10:11], v[14:15]
	v_mov_b32_e32 v13, v1
	v_cvt_pk_bf16_f32 v9, v10, v11
	global_store_dwordx4 v[26:27], v[6:9], off
	v_mov_b32_e32 v17, v1
	v_lshlrev_b32_e32 v32, 16, v2
	v_add_u32_e32 v8, 20, v29
	v_ashrrev_i32_e32 v6, 3, v8
	v_ashrrev_i32_e32 v7, 31, v6
	v_lshl_add_u64 v[10:11], s[80:81], 0, v[6:7]
	v_and_or_b32 v16, v8, 7, s34
	v_mad_u64_u32 v[6:7], s[0:1], v10, s76, v[20:21]
	v_mad_i32_i24 v7, v11, s76, v7
	v_lshlrev_b32_e32 v12, 8, v16
	v_lshl_add_u64 v[6:7], v[6:7], 0, v[12:13]
	v_lshl_add_u64 v[6:7], v[6:7], 0, v[18:19]
	v_add_co_u32_e32 v6, vcc, s35, v6
	v_mad_u64_u32 v[14:15], s[0:1], v10, s77, v[22:23]
	s_nop 0
	v_addc_co_u32_e32 v7, vcc, 0, v7, vcc
	global_load_dwordx4 v[6:9], v[6:7], off
	v_mad_i32_i24 v15, v11, s77, v15
	v_lshlrev_b32_e32 v16, 2, v16
	v_lshl_add_u64 v[14:15], v[14:15], 0, v[16:17]
	global_load_dword v14, v[14:15], off offset:128
	v_lshlrev_b64 v[10:11], 13, v[10:11]
	v_lshl_add_u64 v[10:11], s[44:45], 0, v[10:11]
	v_lshl_add_u64 v[10:11], v[10:11], 0, v[12:13]
	v_lshl_add_u64 v[16:17], v[10:11], 0, v[18:19]
	global_load_dwordx4 v[10:13], v[16:17], off
	s_waitcnt vmcnt(2)
	v_lshlrev_b32_e32 v15, 16, v6
	v_and_b32_e32 v6, 0xffff0000, v6
	v_mul_f32_e32 v26, 0xbfb8aa3b, v15
	v_mul_f32_e32 v27, 0xbfb8aa3b, v6
	v_exp_f32_e32 v26, v26
	v_exp_f32_e32 v27, v27
	s_waitcnt vmcnt(1)
	v_pk_mul_f32 v[32:33], v[14:15], v[32:33] op_sel_hi:[0,1]
	v_pk_add_f32 v[26:27], v[26:27], 1.0 op_sel_hi:[1,0]
	s_nop 0
	s_nop 0
	v_rcp_f32_e32 v2, v27
	s_nop 0
	v_mul_f32_e32 v27, v6, v2
	v_rcp_f32_e32 v2, v26
	s_nop 0
	v_mul_f32_e32 v26, v15, v2
	v_lshlrev_b32_e32 v15, 16, v7
	v_and_b32_e32 v28, 0xffff0000, v7
	v_mul_f32_e32 v2, 0xbfb8aa3b, v15
	v_exp_f32_e32 v34, v2
	v_mul_f32_e32 v2, 0xbfb8aa3b, v28
	v_exp_f32_e32 v35, v2
	s_waitcnt vmcnt(0)
	v_lshlrev_b32_e32 v6, 16, v10
	v_and_b32_e32 v7, 0xffff0000, v10
	v_pk_fma_f32 v[6:7], v[32:33], v[26:27], v[6:7]
	v_lshlrev_b32_e32 v26, 16, v3
	v_cvt_pk_bf16_f32 v2, v6, v7
	v_pk_add_f32 v[6:7], v[34:35], 1.0 op_sel_hi:[1,0]
	v_and_b32_e32 v27, 0xffff0000, v3
	v_pk_mul_f32 v[26:27], v[14:15], v[26:27] op_sel_hi:[0,1]
	v_rcp_f32_e32 v3, v7
	s_nop 0
	v_mul_f32_e32 v7, v28, v3
	v_rcp_f32_e32 v3, v6
	s_nop 0
	v_mul_f32_e32 v6, v15, v3
	v_lshlrev_b32_e32 v15, 16, v8
	v_and_b32_e32 v8, 0xffff0000, v8
	v_mul_f32_e32 v3, 0xbfb8aa3b, v15
	v_exp_f32_e32 v32, v3
	v_mul_f32_e32 v3, 0xbfb8aa3b, v8
	v_exp_f32_e32 v33, v3
	v_lshlrev_b32_e32 v10, 16, v11
	v_and_b32_e32 v11, 0xffff0000, v11
	v_pk_fma_f32 v[6:7], v[26:27], v[6:7], v[10:11]
	v_lshlrev_b32_e32 v10, 16, v4
	v_cvt_pk_bf16_f32 v3, v6, v7
	v_pk_add_f32 v[6:7], v[32:33], 1.0 op_sel_hi:[1,0]
	v_and_b32_e32 v11, 0xffff0000, v4
	v_pk_mul_f32 v[10:11], v[14:15], v[10:11] op_sel_hi:[0,1]
	v_rcp_f32_e32 v4, v7
	s_nop 0
	v_mul_f32_e32 v7, v8, v4
	v_and_b32_e32 v28, 0xffff0000, v9
	v_rcp_f32_e32 v4, v6
	s_nop 0
	v_mul_f32_e32 v6, v15, v4
	v_lshlrev_b32_e32 v15, 16, v9
	v_mul_f32_e32 v4, 0xbfb8aa3b, v15
	v_exp_f32_e32 v26, v4
	v_mul_f32_e32 v4, 0xbfb8aa3b, v28
	v_exp_f32_e32 v27, v4
	v_lshlrev_b32_e32 v8, 16, v12
	v_and_b32_e32 v9, 0xffff0000, v12
	v_pk_fma_f32 v[6:7], v[10:11], v[6:7], v[8:9]
	v_lshlrev_b32_e32 v8, 16, v5
	v_cvt_pk_bf16_f32 v4, v6, v7
	v_pk_add_f32 v[6:7], v[26:27], 1.0 op_sel_hi:[1,0]
	v_and_b32_e32 v9, 0xffff0000, v5
	v_pk_mul_f32 v[8:9], v[14:15], v[8:9] op_sel_hi:[0,1]
	v_rcp_f32_e32 v5, v7
	s_nop 0
	v_mul_f32_e32 v7, v28, v5
	v_rcp_f32_e32 v5, v6
	s_nop 0
	v_mul_f32_e32 v6, v15, v5
	v_lshlrev_b32_e32 v10, 16, v13
	v_and_b32_e32 v11, 0xffff0000, v13
	v_pk_fma_f32 v[6:7], v[8:9], v[6:7], v[10:11]
	s_nop 0
	v_cvt_pk_bf16_f32 v5, v6, v7
	global_store_dwordx4 v[16:17], v[2:5], off
	ds_read_b128 v[14:17], v30 offset:6528
	s_nop 0
	v_add_u32_e32 v2, 24, v29
	v_ashrrev_i32_e32 v2, 3, v2
	v_ashrrev_i32_e32 v3, 31, v2
	v_lshl_add_u64 v[2:3], s[80:81], 0, v[2:3]
	v_mad_u64_u32 v[4:5], s[0:1], v2, s76, v[20:21]
	v_mad_i32_i24 v5, v3, s76, v5
	v_lshl_add_u64 v[4:5], v[4:5], 0, v[0:1]
	v_lshl_add_u64 v[4:5], v[4:5], 0, v[18:19]
	v_add_co_u32_e32 v4, vcc, s35, v4
	s_nop 1
	v_addc_co_u32_e32 v5, vcc, 0, v5, vcc
	global_load_dwordx4 v[10:13], v[4:5], off
	v_mad_u64_u32 v[4:5], s[0:1], v2, s77, v[22:23]
	v_mad_i32_i24 v5, v3, s77, v5
	v_lshl_add_u64 v[4:5], v[4:5], 0, v[24:25]
	global_load_dword v26, v[4:5], off offset:128
	v_lshlrev_b64 v[2:3], 13, v[2:3]
	v_lshl_add_u64 v[2:3], s[44:45], 0, v[2:3]
	v_lshl_add_u64 v[2:3], v[2:3], 0, v[0:1]
	v_lshl_add_u64 v[24:25], v[2:3], 0, v[18:19]
	global_load_dwordx4 v[6:9], v[24:25], off
	s_waitcnt vmcnt(2)
	v_lshlrev_b32_e32 v0, 16, v10
	v_and_b32_e32 v10, 0xffff0000, v10
	v_mul_f32_e32 v2, 0xbfb8aa3b, v0
	v_mul_f32_e32 v3, 0xbfb8aa3b, v10
	v_exp_f32_e32 v2, v2
	v_exp_f32_e32 v3, v3
	s_nop 0
	v_pk_add_f32 v[32:33], v[2:3], 1.0 op_sel_hi:[1,0]
	s_nop 0
	ds_read_b128 v[2:5], v30 offset:7616
	s_waitcnt lgkmcnt(1)
	v_lshlrev_b32_e32 v30, 16, v14
	v_and_b32_e32 v31, 0xffff0000, v14
	s_waitcnt vmcnt(1)
	v_pk_mul_f32 v[30:31], v[26:27], v[30:31] op_sel_hi:[0,1]
	v_rcp_f32_e32 v14, v33
	s_nop 0
	v_mul_f32_e32 v33, v10, v14
	v_rcp_f32_e32 v10, v32
	s_nop 0
	v_mul_f32_e32 v32, v0, v10
	v_lshlrev_b32_e32 v0, 16, v11
	v_and_b32_e32 v27, 0xffff0000, v11
	v_mul_f32_e32 v11, 0xbfb8aa3b, v0
	v_exp_f32_e32 v34, v11
	v_mul_f32_e32 v11, 0xbfb8aa3b, v27
	v_exp_f32_e32 v35, v11
	s_waitcnt vmcnt(0)
	v_lshlrev_b32_e32 v10, 16, v6
	v_and_b32_e32 v11, 0xffff0000, v6
	v_pk_fma_f32 v[10:11], v[30:31], v[32:33], v[10:11]
	v_lshlrev_b32_e32 v14, 16, v15
	v_cvt_pk_bf16_f32 v6, v10, v11
	v_pk_add_f32 v[10:11], v[34:35], 1.0 op_sel_hi:[1,0]
	v_and_b32_e32 v15, 0xffff0000, v15
	v_pk_mul_f32 v[14:15], v[26:27], v[14:15] op_sel_hi:[0,1]
	v_rcp_f32_e32 v28, v11
	s_nop 0
	v_mul_f32_e32 v11, v27, v28
	v_rcp_f32_e32 v27, v10
	s_nop 0
	v_mul_f32_e32 v10, v0, v27
	v_lshlrev_b32_e32 v0, 16, v12
	v_and_b32_e32 v12, 0xffff0000, v12
	v_mul_f32_e32 v27, 0xbfb8aa3b, v0
	v_exp_f32_e32 v32, v27
	v_mul_f32_e32 v27, 0xbfb8aa3b, v12
	v_exp_f32_e32 v33, v27
	v_lshlrev_b32_e32 v30, 16, v7
	v_and_b32_e32 v31, 0xffff0000, v7
	v_pk_fma_f32 v[10:11], v[14:15], v[10:11], v[30:31]
	v_lshlrev_b32_e32 v14, 16, v16
	v_cvt_pk_bf16_f32 v7, v10, v11
	v_pk_add_f32 v[10:11], v[32:33], 1.0 op_sel_hi:[1,0]
	v_and_b32_e32 v15, 0xffff0000, v16
	v_pk_mul_f32 v[14:15], v[26:27], v[14:15] op_sel_hi:[0,1]
	v_rcp_f32_e32 v16, v11
	s_nop 0
	v_mul_f32_e32 v11, v12, v16
	v_rcp_f32_e32 v12, v10
	s_nop 0
	v_mul_f32_e32 v10, v0, v12
	v_lshlrev_b32_e32 v0, 16, v13
	v_and_b32_e32 v16, 0xffff0000, v13
	v_mul_f32_e32 v13, 0xbfb8aa3b, v0
	v_exp_f32_e32 v30, v13
	v_mul_f32_e32 v13, 0xbfb8aa3b, v16
	v_exp_f32_e32 v31, v13
	v_lshlrev_b32_e32 v12, 16, v8
	v_and_b32_e32 v13, 0xffff0000, v8
	v_pk_fma_f32 v[10:11], v[14:15], v[10:11], v[12:13]
	v_lshlrev_b32_e32 v12, 16, v17
	v_cvt_pk_bf16_f32 v8, v10, v11
	v_pk_add_f32 v[10:11], v[30:31], 1.0 op_sel_hi:[1,0]
	v_and_b32_e32 v13, 0xffff0000, v17
	v_pk_mul_f32 v[12:13], v[26:27], v[12:13] op_sel_hi:[0,1]
	v_rcp_f32_e32 v14, v11
	s_nop 0
	v_mul_f32_e32 v11, v16, v14
	v_rcp_f32_e32 v14, v10
	s_nop 0
	v_mul_f32_e32 v10, v0, v14
	v_lshlrev_b32_e32 v14, 16, v9
	v_and_b32_e32 v15, 0xffff0000, v9
	v_pk_fma_f32 v[10:11], v[12:13], v[10:11], v[14:15]
	v_add_u32_e32 v0, 28, v29
	v_cvt_pk_bf16_f32 v9, v10, v11
	global_store_dwordx4 v[24:25], v[6:9], off
	v_and_or_b32 v14, v0, 7, s34
	v_mov_b32_e32 v15, v1
	v_ashrrev_i32_e32 v6, 3, v0
	v_ashrrev_i32_e32 v7, 31, v6
	v_lshl_add_u64 v[10:11], s[80:81], 0, v[6:7]
	v_mad_u64_u32 v[6:7], s[0:1], v10, s76, v[20:21]
	v_mad_i32_i24 v7, v11, s76, v7
	v_lshlrev_b32_e32 v0, 8, v14
	v_lshl_add_u64 v[6:7], v[6:7], 0, v[0:1]
	v_lshl_add_u64 v[6:7], v[6:7], 0, v[18:19]
	v_add_co_u32_e32 v6, vcc, s35, v6
	v_mad_u64_u32 v[12:13], s[0:1], v10, s77, v[22:23]
	s_nop 0
	v_addc_co_u32_e32 v7, vcc, 0, v7, vcc
	global_load_dwordx4 v[6:9], v[6:7], off
	v_mad_i32_i24 v13, v11, s77, v13
	v_lshlrev_b32_e32 v14, 2, v14
	v_lshl_add_u64 v[12:13], v[12:13], 0, v[14:15]
	global_load_dword v14, v[12:13], off offset:128
	v_lshlrev_b64 v[10:11], 13, v[10:11]
	v_lshl_add_u64 v[10:11], s[44:45], 0, v[10:11]
	v_lshl_add_u64 v[10:11], v[10:11], 0, v[0:1]
	v_lshl_add_u64 v[16:17], v[10:11], 0, v[18:19]
	global_load_dwordx4 v[10:13], v[16:17], off
	s_waitcnt lgkmcnt(0)
	v_lshlrev_b32_e32 v20, 16, v2
	v_and_b32_e32 v21, 0xffff0000, v2
	s_waitcnt vmcnt(2)
	v_lshlrev_b32_e32 v0, 16, v6
	v_and_b32_e32 v6, 0xffff0000, v6
	v_mul_f32_e32 v15, 0xbfb8aa3b, v0
	v_exp_f32_e32 v18, v15
	v_mul_f32_e32 v15, 0xbfb8aa3b, v6
	v_exp_f32_e32 v19, v15
	s_nop 0
	v_pk_add_f32 v[18:19], v[18:19], 1.0 op_sel_hi:[1,0]
	s_nop 0
	s_waitcnt vmcnt(1)
	v_pk_mul_f32 v[20:21], v[14:15], v[20:21] op_sel_hi:[0,1]
	v_rcp_f32_e32 v2, v19
	s_nop 0
	v_mul_f32_e32 v19, v6, v2
	v_rcp_f32_e32 v2, v18
	s_nop 0
	v_mul_f32_e32 v18, v0, v2
	v_lshlrev_b32_e32 v0, 16, v7
	v_and_b32_e32 v15, 0xffff0000, v7
	v_mul_f32_e32 v2, 0xbfb8aa3b, v0
	v_exp_f32_e32 v22, v2
	v_mul_f32_e32 v2, 0xbfb8aa3b, v15
	v_exp_f32_e32 v23, v2
	s_waitcnt vmcnt(0)
	v_lshlrev_b32_e32 v6, 16, v10
	v_and_b32_e32 v7, 0xffff0000, v10
	v_pk_fma_f32 v[6:7], v[20:21], v[18:19], v[6:7]
	v_lshlrev_b32_e32 v18, 16, v3
	v_cvt_pk_bf16_f32 v2, v6, v7
	v_pk_add_f32 v[6:7], v[22:23], 1.0 op_sel_hi:[1,0]
	v_and_b32_e32 v19, 0xffff0000, v3
	v_pk_mul_f32 v[18:19], v[14:15], v[18:19] op_sel_hi:[0,1]
	v_rcp_f32_e32 v3, v7
	s_nop 0
	v_mul_f32_e32 v7, v15, v3
	v_rcp_f32_e32 v3, v6
	s_nop 0
	v_mul_f32_e32 v6, v0, v3
	v_lshlrev_b32_e32 v0, 16, v8
	v_and_b32_e32 v8, 0xffff0000, v8
	v_mul_f32_e32 v3, 0xbfb8aa3b, v0
	v_exp_f32_e32 v20, v3
	v_mul_f32_e32 v3, 0xbfb8aa3b, v8
	v_exp_f32_e32 v21, v3
	v_lshlrev_b32_e32 v10, 16, v11
	v_and_b32_e32 v11, 0xffff0000, v11
	v_pk_fma_f32 v[6:7], v[18:19], v[6:7], v[10:11]
	v_lshlrev_b32_e32 v10, 16, v4
	v_cvt_pk_bf16_f32 v3, v6, v7
	v_pk_add_f32 v[6:7], v[20:21], 1.0 op_sel_hi:[1,0]
	v_and_b32_e32 v11, 0xffff0000, v4
	v_pk_mul_f32 v[10:11], v[14:15], v[10:11] op_sel_hi:[0,1]
	v_rcp_f32_e32 v4, v7
	s_nop 0
	v_mul_f32_e32 v7, v8, v4
	v_rcp_f32_e32 v4, v6
	s_nop 0
	v_mul_f32_e32 v6, v0, v4
	v_lshlrev_b32_e32 v0, 16, v9
	v_and_b32_e32 v15, 0xffff0000, v9
	v_mul_f32_e32 v4, 0xbfb8aa3b, v0
	v_exp_f32_e32 v18, v4
	v_mul_f32_e32 v4, 0xbfb8aa3b, v15
	v_exp_f32_e32 v19, v4
	v_lshlrev_b32_e32 v8, 16, v12
	v_and_b32_e32 v9, 0xffff0000, v12
	v_pk_fma_f32 v[6:7], v[10:11], v[6:7], v[8:9]
	v_lshlrev_b32_e32 v8, 16, v5
	v_cvt_pk_bf16_f32 v4, v6, v7
	v_pk_add_f32 v[6:7], v[18:19], 1.0 op_sel_hi:[1,0]
	v_and_b32_e32 v9, 0xffff0000, v5
	v_pk_mul_f32 v[8:9], v[14:15], v[8:9] op_sel_hi:[0,1]
	v_rcp_f32_e32 v5, v7
	s_nop 0
	v_mul_f32_e32 v7, v15, v5
	s_max_i32 s0, s67, 0x1ff
	s_addk_i32 s0, 0xfe01
	v_rcp_f32_e32 v5, v6
	s_nop 0
	v_mul_f32_e32 v6, v0, v5
	v_lshlrev_b32_e32 v10, 16, v13
	v_and_b32_e32 v11, 0xffff0000, v13
	s_lshr_b32 s12, s0, 6
	s_ashr_i32 s0, s31, 1
	v_pk_fma_f32 v[6:7], v[8:9], v[6:7], v[10:11]
	s_sub_i32 s14, s0, s12
	v_cvt_pk_bf16_f32 v5, v6, v7
	v_cmp_ge_i32_e32 vcc, s14, v176
	global_store_dwordx4 v[16:17], v[2:5], off
	s_barrier
	s_and_saveexec_b64 s[0:1], vcc
	v_add_u32_e32 v0, s12, v176
	ds_write_b32 v179, v0
	s_or_b64 exec, exec, s[0:1]
	v_mov_b32_e32 v79, 0
	s_cmp_lt_i32 s14, 0
	v_mov_b32_e32 v78, 0
	v_mov_b32_e32 v77, 0
	v_mov_b32_e32 v76, 0
	v_mov_b32_e32 v75, 0
	v_mov_b32_e32 v74, 0
	v_mov_b32_e32 v73, 0
	v_mov_b32_e32 v72, 0
	v_mov_b32_e32 v71, 0
	v_mov_b32_e32 v70, 0
	v_mov_b32_e32 v69, 0
	v_mov_b32_e32 v68, 0
	v_mov_b32_e32 v67, 0
	v_mov_b32_e32 v66, 0
	v_mov_b32_e32 v65, 0
	v_mov_b32_e32 v64, 0
	v_mov_b32_e32 v63, 0
	v_mov_b32_e32 v62, 0
	v_mov_b32_e32 v61, 0
	v_mov_b32_e32 v60, 0
	v_mov_b32_e32 v59, 0
	v_mov_b32_e32 v58, 0
	v_mov_b32_e32 v57, 0
	v_mov_b32_e32 v56, 0
	v_mov_b32_e32 v55, 0
	v_mov_b32_e32 v54, 0
	v_mov_b32_e32 v53, 0
	v_mov_b32_e32 v52, 0
	v_mov_b32_e32 v51, 0
	v_mov_b32_e32 v50, 0
	v_mov_b32_e32 v49, 0
	v_mov_b32_e32 v48, 0
	v_mov_b32_e32 v47, 0
	v_mov_b32_e32 v46, 0
	v_mov_b32_e32 v45, 0
	v_mov_b32_e32 v44, 0
	v_mov_b32_e32 v43, 0
	v_mov_b32_e32 v42, 0
	v_mov_b32_e32 v41, 0
	v_mov_b32_e32 v40, 0
	v_mov_b32_e32 v39, 0
	v_mov_b32_e32 v38, 0
	v_mov_b32_e32 v37, 0
	v_mov_b32_e32 v36, 0
	v_mov_b32_e32 v35, 0
	v_mov_b32_e32 v34, 0
	v_mov_b32_e32 v33, 0
	v_mov_b32_e32 v32, 0
	v_mov_b32_e32 v31, 0
	v_mov_b32_e32 v30, 0
	v_mov_b32_e32 v29, 0
	v_mov_b32_e32 v28, 0
	v_mov_b32_e32 v27, 0
	v_mov_b32_e32 v26, 0
	v_mov_b32_e32 v25, 0
	v_mov_b32_e32 v24, 0
	v_mov_b32_e32 v23, 0
	v_mov_b32_e32 v22, 0
	v_mov_b32_e32 v21, 0
	v_mov_b32_e32 v20, 0
	v_mov_b32_e32 v19, 0
	v_mov_b32_e32 v18, 0
	v_mov_b32_e32 v17, 0
	v_mov_b32_e32 v16, 0
	v_mov_b32_e32 v170, 0
	s_waitcnt lgkmcnt(0)
	s_barrier
	s_cbranch_scc1 .LBB0_1058
	v_mov_b32_e32 v0, s92
	ds_read_b32 v2, v0
	s_lshl_b64 s[0:1], s[20:21], 1
	v_readlane_b32 s12, v255, 24
	s_add_u32 s12, s12, s0
	v_readlane_b32 s13, v255, 25
	s_addc_u32 s13, s13, s1
	v_readlane_b32 s15, v255, 26
	s_add_u32 s0, s15, s0
	v_readlane_b32 s15, v255, 27
	s_waitcnt lgkmcnt(0)
	v_ashrrev_i32_e32 v3, 31, v2
	s_addc_u32 s1, s15, s1
	v_lshlrev_b64 v[4:5], 14, v[2:3]
	v_lshl_add_u64 v[4:5], s[0:1], 0, v[4:5]
	v_lshl_add_u64 v[4:5], v[4:5], 0, v[146:147]
	v_lshlrev_b64 v[2:3], 7, v[2:3]
	v_add_co_u32_e32 v6, vcc, s35, v4
	v_lshl_add_u64 v[2:3], s[12:13], 0, v[2:3]
	s_nop 0
	v_addc_co_u32_e32 v7, vcc, 0, v5, vcc
	v_lshl_add_u64 v[2:3], v[2:3], 0, v[162:163]
	s_mov_b32 s15, 0x80000
	global_load_dwordx4 v[64:67], v[4:5], off
	global_load_dwordx4 v[68:71], v[6:7], off
	v_add_co_u32_e32 v4, vcc, s15, v2
	v_mov_b32_e32 v14, v1
	s_nop 0
	v_addc_co_u32_e32 v5, vcc, 0, v3, vcc
	global_load_dwordx4 v[72:75], v[2:3], off
	global_load_dwordx4 v[76:79], v[4:5], off
	v_mov_b32_e32 v15, v1
	v_mov_b32_e32 v0, v1
	v_mov_b32_e32 v2, v1
	v_mov_b32_e32 v3, v1
	v_mov_b32_e32 v4, v1
	v_mov_b32_e32 v5, v1
	v_mov_b32_e32 v6, v1
	v_mov_b32_e32 v7, v1
	v_mov_b32_e32 v8, v1
	v_mov_b32_e32 v9, v1
	v_mov_b32_e32 v10, v1
	v_mov_b32_e32 v11, v1
	v_mov_b32_e32 v12, v1
	v_mov_b32_e32 v13, v1
	v_mov_b64_e32 v[30:31], v[14:15]
	v_mov_b64_e32 v[46:47], v[14:15]
	v_mov_b64_e32 v[62:63], v[14:15]
	s_mov_b32 s15, 0
	v_sub_u32_e32 v171, v221, v168
	v_mov_b32_e32 v170, 0
	v_mov_b32_e32 v142, 0xf149f2ca
	v_mov_b32_e32 v130, 0
	v_mov_b32_e32 v131, 0
	v_mov_b32_e32 v132, 0
	v_mov_b32_e32 v133, 0
	v_mov_b32_e32 v134, 0
	v_mov_b32_e32 v135, 0
	v_mov_b32_e32 v136, 0
	v_mov_b32_e32 v137, 0
	v_mov_b64_e32 v[28:29], v[12:13]
	v_mov_b64_e32 v[26:27], v[10:11]
	v_mov_b64_e32 v[24:25], v[8:9]
	v_mov_b64_e32 v[22:23], v[6:7]
	v_mov_b64_e32 v[20:21], v[4:5]
	v_mov_b64_e32 v[18:19], v[2:3]
	v_mov_b64_e32 v[16:17], v[0:1]
	v_mov_b64_e32 v[44:45], v[12:13]
	v_mov_b64_e32 v[42:43], v[10:11]
	v_mov_b64_e32 v[40:41], v[8:9]
	v_mov_b64_e32 v[38:39], v[6:7]
	v_mov_b64_e32 v[36:37], v[4:5]
	v_mov_b64_e32 v[34:35], v[2:3]
	v_mov_b64_e32 v[32:33], v[0:1]
	v_mov_b64_e32 v[60:61], v[12:13]
	v_mov_b64_e32 v[58:59], v[10:11]
	v_mov_b64_e32 v[56:57], v[8:9]
	v_mov_b64_e32 v[54:55], v[6:7]
	v_mov_b64_e32 v[52:53], v[4:5]
	v_mov_b64_e32 v[50:51], v[2:3]
	v_mov_b64_e32 v[48:49], v[0:1]
	v_lshl_add_u64 v[96:97], s[12:13], 0, v[162:163]
	s_add_i32 s16, 0, 0x1bb04
	s_add_i32 s17, s14, 1
	v_lshl_add_u64 v[168:169], s[0:1], 0, v[146:147]
	s_waitcnt vmcnt(3)
	ds_write_b128 v225, v[64:67]
	s_waitcnt vmcnt(2)
	ds_write_b128 v225, v[68:71] offset:8704
	s_waitcnt vmcnt(1)
	ds_write2_b64 v167, v[72:73], v[74:75] offset0:128 offset1:130
	s_waitcnt vmcnt(0)
	ds_write2_b64 v232, v[76:77], v[78:79] offset1:2
	v_mov_b64_e32 v[78:79], v[14:15]
	v_mov_b64_e32 v[76:77], v[12:13]
	v_mov_b64_e32 v[74:75], v[10:11]
	v_mov_b64_e32 v[72:73], v[8:9]
	v_mov_b64_e32 v[70:71], v[6:7]
	v_mov_b64_e32 v[68:69], v[4:5]
	v_mov_b64_e32 v[66:67], v[2:3]
	v_mov_b64_e32 v[64:65], v[0:1]
	s_waitcnt lgkmcnt(0)
	s_barrier
	s_branch .LBB0_1234

.LBB0_1238:
	s_bitcmp1_b32 s15, 0
	s_cselect_b32 s0, 0x8c00, 0
	v_add_u32_e32 v245, s0, v219
	ds_read_b128 v[10:13], v245
	ds_read_b128 v[138:141], v245 offset:32
	v_add_u32_e32 v167, s0, v220
	v_lshl_add_u32 v172, v0, 6, v171
	s_waitcnt lgkmcnt(1)
	v_mfma_f32_32x32x16_bf16 v[80:95], v[10:13], v[122:125], 0
	s_waitcnt lgkmcnt(0)
	v_mfma_f32_32x32x16_bf16 v[80:95], v[138:141], v[126:129], v[80:95]
	ds_read_b128 v[10:13], v245 offset:64
	ds_read_b128 v[138:141], v245 offset:96
	s_waitcnt lgkmcnt(1)
	v_mfma_f32_32x32x16_bf16 v[80:95], v[10:13], v[98:101], v[80:95]
	ds_read_b128 v[10:13], v245 offset:128
	ds_read_b128 v[232:235], v245 offset:160
	ds_read_b128 v[236:239], v245 offset:192
	ds_read_b128 v[240:243], v245 offset:224
	s_waitcnt lgkmcnt(4)
	v_mfma_f32_32x32x16_bf16 v[80:95], v[138:141], v[102:105], v[80:95]
	s_waitcnt lgkmcnt(3)
	v_mfma_f32_32x32x16_bf16 v[80:95], v[10:13], v[106:109], v[80:95]
	s_movk_i32 s0, 0x200
	v_add_u32_e32 v0, 0xfffffe01, v172
	v_cmp_gt_u32_e32 vcc, s0, v172
	v_add_u32_e32 v145, 0xfffffe02, v172
	v_add_u32_e32 v173, 0xfffffe03, v172
	v_add_u32_e32 v174, 0xfffffe08, v172
	v_add_u32_e32 v175, 0xfffffe09, v172
	s_waitcnt lgkmcnt(2)
	v_mfma_f32_32x32x16_bf16 v[80:95], v[232:235], v[110:113], v[80:95]
	v_add_u32_e32 v208, 0xfffffe0a, v172
	v_add_u32_e32 v209, 0xfffffe0b, v172
	v_add_u32_e32 v210, 0xfffffe10, v172
	v_add_u32_e32 v211, 0xfffffe11, v172
	ds_read_b128 v[138:141], v167 offset:17408
	ds_read_b128 v[10:13], v167 offset:22016
	s_waitcnt lgkmcnt(3)
	v_mfma_f32_32x32x16_bf16 v[80:95], v[236:239], v[114:117], v[80:95]
	s_waitcnt lgkmcnt(2)
	v_mfma_f32_32x32x16_bf16 v[80:95], v[240:243], v[118:121], v[80:95]
	s_cmp_eq_u64 s[12:13], 0
	s_cselect_b32 s98, s15, 0
	s_cmp_lg_u32 s98, 0
	s_nop 8
	s_cbranch_scc1 .Lwinf0
	v_cndmask_b32_e32 v143, v231, v80, vcc
	v_cmp_lt_u32_e32 vcc, s87, v0
	v_add_u32_e32 v0, 0xfffffe12, v172
	v_max_f32_e32 v80, v143, v143
	v_cndmask_b32_e32 v144, v231, v81, vcc
	v_cmp_lt_u32_e32 vcc, s87, v145
	s_nop 1
	v_cndmask_b32_e32 v145, v231, v82, vcc
	v_cmp_lt_u32_e32 vcc, s87, v173
	s_nop 1
	v_cndmask_b32_e32 v232, v231, v83, vcc
	v_cmp_lt_u32_e32 vcc, s87, v174
	s_nop 1
	v_cndmask_b32_e32 v233, v231, v84, vcc
	v_cmp_lt_u32_e32 vcc, s87, v175
	s_nop 1
	v_cndmask_b32_e32 v234, v231, v85, vcc
	v_cmp_lt_u32_e32 vcc, s87, v208
	s_nop 1
	v_cndmask_b32_e32 v235, v231, v86, vcc
	v_cmp_lt_u32_e32 vcc, s87, v209
	s_nop 1
	v_cndmask_b32_e32 v236, v231, v87, vcc
	v_cmp_lt_u32_e32 vcc, s87, v210
	s_nop 1
	v_cndmask_b32_e32 v88, v231, v88, vcc
	v_cmp_lt_u32_e32 vcc, s87, v211
	s_nop 1
	v_cndmask_b32_e32 v89, v231, v89, vcc
	v_cmp_lt_u32_e32 vcc, s87, v0
	v_add_u32_e32 v0, 0xfffffe13, v172
	s_nop 0
	v_cndmask_b32_e32 v90, v231, v90, vcc
	v_cmp_lt_u32_e32 vcc, s87, v0
	v_add_u32_e32 v0, 0xfffffe18, v172
	s_nop 0
	v_cndmask_b32_e32 v91, v231, v91, vcc
	v_cmp_lt_u32_e32 vcc, s87, v0
	v_add_u32_e32 v0, 0xfffffe19, v172
	s_nop 0
	v_cndmask_b32_e32 v92, v231, v92, vcc
	v_cmp_lt_u32_e32 vcc, s87, v0
	v_add_u32_e32 v0, 0xfffffe1a, v172
	s_nop 0
	v_cndmask_b32_e32 v93, v231, v93, vcc
	v_cmp_lt_u32_e32 vcc, s87, v0
	v_add_u32_e32 v0, 0xfffffe1b, v172
	s_nop 0
	v_cndmask_b32_e32 v94, v231, v94, vcc
	v_cmp_lt_u32_e32 vcc, s87, v0
	v_max_f32_e32 v0, v144, v144
	v_max_f32_e32 v0, v80, v0
	v_max3_f32 v0, v0, v145, v232
	v_max3_f32 v0, v0, v233, v234
	v_max3_f32 v0, v0, v235, v236
	v_max3_f32 v0, v0, v88, v89
	v_max3_f32 v0, v0, v90, v91
	v_cndmask_b32_e32 v95, v231, v95, vcc
	v_max3_f32 v0, v0, v92, v93
	v_max3_f32 v0, v0, v94, v95
.Lwinf0_join:
	v_mov_b32_e32 v80, v0
	s_nop 1
	v_permlane32_swap_b32_e32 v0, v80
	v_max_f32_e32 v80, v80, v80
	v_max_f32_e32 v0, v0, v0
	v_max_f32_e32 v0, v0, v80
	v_mul_f32_e32 v0, 0x3e0293ee, v0
	v_max_f32_e32 v80, v142, v142
	v_max_f32_e32 v246, v80, v0
	v_sub_f32_e32 v0, v142, v246
	v_exp_f32_e32 v0, v0
	ds_read_b128 v[84:87], v167 offset:26624
	ds_read_b128 v[80:83], v167 offset:31232
	v_cmp_eq_f32_e32 vcc, 1.0, v0
	s_cmp_eq_u64 vcc, exec
	s_cbranch_scc1 .LBB0_1240
	v_pk_mul_f32 v[78:79], v[78:79], v[0:1] op_sel_hi:[1,0]
	v_pk_mul_f32 v[76:77], v[76:77], v[0:1] op_sel_hi:[1,0]
	v_pk_mul_f32 v[74:75], v[74:75], v[0:1] op_sel_hi:[1,0]
	v_pk_mul_f32 v[72:73], v[72:73], v[0:1] op_sel_hi:[1,0]
	v_pk_mul_f32 v[70:71], v[70:71], v[0:1] op_sel_hi:[1,0]
	v_pk_mul_f32 v[68:69], v[68:69], v[0:1] op_sel_hi:[1,0]
	v_pk_mul_f32 v[66:67], v[66:67], v[0:1] op_sel_hi:[1,0]
	v_pk_mul_f32 v[64:65], v[64:65], v[0:1] op_sel_hi:[1,0]
	v_pk_mul_f32 v[62:63], v[62:63], v[0:1] op_sel_hi:[1,0]
	v_pk_mul_f32 v[60:61], v[60:61], v[0:1] op_sel_hi:[1,0]
	v_pk_mul_f32 v[58:59], v[58:59], v[0:1] op_sel_hi:[1,0]
	v_pk_mul_f32 v[56:57], v[56:57], v[0:1] op_sel_hi:[1,0]
	v_pk_mul_f32 v[54:55], v[54:55], v[0:1] op_sel_hi:[1,0]
	v_pk_mul_f32 v[52:53], v[52:53], v[0:1] op_sel_hi:[1,0]
	v_pk_mul_f32 v[50:51], v[50:51], v[0:1] op_sel_hi:[1,0]
	v_pk_mul_f32 v[48:49], v[48:49], v[0:1] op_sel_hi:[1,0]
	v_pk_mul_f32 v[46:47], v[46:47], v[0:1] op_sel_hi:[1,0]
	v_pk_mul_f32 v[44:45], v[44:45], v[0:1] op_sel_hi:[1,0]
	v_pk_mul_f32 v[42:43], v[42:43], v[0:1] op_sel_hi:[1,0]
	v_pk_mul_f32 v[40:41], v[40:41], v[0:1] op_sel_hi:[1,0]
	v_pk_mul_f32 v[38:39], v[38:39], v[0:1] op_sel_hi:[1,0]
	v_pk_mul_f32 v[36:37], v[36:37], v[0:1] op_sel_hi:[1,0]
	v_pk_mul_f32 v[34:35], v[34:35], v[0:1] op_sel_hi:[1,0]
	v_pk_mul_f32 v[32:33], v[32:33], v[0:1] op_sel_hi:[1,0]
	v_pk_mul_f32 v[30:31], v[30:31], v[0:1] op_sel_hi:[1,0]
	v_pk_mul_f32 v[28:29], v[28:29], v[0:1] op_sel_hi:[1,0]
	v_pk_mul_f32 v[26:27], v[26:27], v[0:1] op_sel_hi:[1,0]
	v_pk_mul_f32 v[24:25], v[24:25], v[0:1] op_sel_hi:[1,0]
	v_pk_mul_f32 v[22:23], v[22:23], v[0:1] op_sel_hi:[1,0]
	v_pk_mul_f32 v[20:21], v[20:21], v[0:1] op_sel_hi:[1,0]
	v_pk_mul_f32 v[18:19], v[18:19], v[0:1] op_sel_hi:[1,0]
	v_pk_mul_f32 v[16:17], v[16:17], v[0:1] op_sel_hi:[1,0]

.LBB0_1242:
	s_waitcnt lgkmcnt(3)
	v_mfma_f32_32x32x16_bf16 v[80:95], v[80:83], v[122:125], 0
	s_waitcnt lgkmcnt(2)
	v_mfma_f32_32x32x16_bf16 v[80:95], v[142:145], v[126:129], v[80:95]
	s_waitcnt lgkmcnt(1)
	v_mfma_f32_32x32x16_bf16 v[80:95], v[138:141], v[98:101], v[80:95]
	ds_read_b128 v[138:141], v245 offset:8832
	ds_read_b128 v[142:145], v245 offset:8864
	ds_read_b128 v[248:251], v245 offset:8896
	ds_read_b128 v[208:211], v245 offset:8928
	s_waitcnt lgkmcnt(4)
	v_mfma_f32_32x32x16_bf16 v[80:95], v[10:13], v[102:105], v[80:95]
	s_waitcnt lgkmcnt(3)
	v_mfma_f32_32x32x16_bf16 v[80:95], v[138:141], v[106:109], v[80:95]
	v_add_u32_e32 v14, 0xfffffe20, v172
	v_cmp_lt_u32_e32 vcc, s87, v14
	v_add_u32_e32 v245, 0xfffffe28, v172
	v_add_u32_e32 v247, 0xfffffe29, v172
	v_add_u32_e32 v14, 0xfffffe31, v172
	ds_read_b128 v[138:141], v167 offset:17472
	ds_read_b128 v[10:13], v167 offset:22080
	s_waitcnt lgkmcnt(4)
	v_mfma_f32_32x32x16_bf16 v[80:95], v[142:145], v[110:113], v[80:95]
	v_add_u32_e32 v142, 0xfffffe21, v172
	v_add_u32_e32 v144, 0xfffffe22, v172
	v_add_u32_e32 v145, 0xfffffe23, v172
	s_waitcnt lgkmcnt(3)
	v_mfma_f32_32x32x16_bf16 v[80:95], v[248:251], v[114:117], v[80:95]
	v_add_u32_e32 v248, 0xfffffe2a, v172
	v_add_u32_e32 v249, 0xfffffe2b, v172
	v_add_u32_e32 v250, 0xfffffe30, v172
	s_waitcnt lgkmcnt(2)
	v_mfma_f32_32x32x16_bf16 v[80:95], v[208:211], v[118:121], v[80:95]
	s_cmp_eq_u64 s[12:13], 0
	s_cselect_b32 s98, s15, 1
	s_cmp_lg_u32 s98, 1
	s_nop 8
	s_cbranch_scc1 .Lwinf1
	v_cndmask_b32_e32 v15, v231, v80, vcc
	v_cmp_lt_u32_e32 vcc, s87, v142
	v_max_f32_e32 v80, v15, v15
	s_nop 0
	v_cndmask_b32_e32 v143, v231, v81, vcc
	v_cmp_lt_u32_e32 vcc, s87, v144
	s_nop 1
	v_cndmask_b32_e32 v144, v231, v82, vcc
	v_cmp_lt_u32_e32 vcc, s87, v145
	s_nop 1
	v_cndmask_b32_e32 v145, v231, v83, vcc
	v_cmp_lt_u32_e32 vcc, s87, v245
	s_nop 1
	v_cndmask_b32_e32 v245, v231, v84, vcc
	v_cmp_lt_u32_e32 vcc, s87, v247
	s_nop 1
	v_cndmask_b32_e32 v247, v231, v85, vcc
	v_cmp_lt_u32_e32 vcc, s87, v248
	s_nop 1
	v_cndmask_b32_e32 v248, v231, v86, vcc
	v_cmp_lt_u32_e32 vcc, s87, v249
	s_nop 1
	v_cndmask_b32_e32 v249, v231, v87, vcc
	v_cmp_lt_u32_e32 vcc, s87, v250
	s_nop 1
	v_cndmask_b32_e32 v88, v231, v88, vcc
	v_cmp_lt_u32_e32 vcc, s87, v14
	v_add_u32_e32 v14, 0xfffffe32, v172
	s_nop 0
	v_cndmask_b32_e32 v89, v231, v89, vcc
	v_cmp_lt_u32_e32 vcc, s87, v14
	v_add_u32_e32 v14, 0xfffffe33, v172
	s_nop 0
	v_cndmask_b32_e32 v90, v231, v90, vcc
	v_cmp_lt_u32_e32 vcc, s87, v14
	v_add_u32_e32 v14, 0xfffffe38, v172
	s_nop 0
	v_cndmask_b32_e32 v91, v231, v91, vcc
	v_cmp_lt_u32_e32 vcc, s87, v14
	v_add_u32_e32 v14, 0xfffffe39, v172
	s_nop 0
	v_cndmask_b32_e32 v92, v231, v92, vcc
	v_cmp_lt_u32_e32 vcc, s87, v14
	v_add_u32_e32 v14, 0xfffffe3a, v172
	s_nop 0
	v_cndmask_b32_e32 v93, v231, v93, vcc
	v_cmp_lt_u32_e32 vcc, s87, v14
	v_add_u32_e32 v14, 0xfffffe3b, v172
	s_nop 0
	v_cndmask_b32_e32 v94, v231, v94, vcc
	v_cmp_lt_u32_e32 vcc, s87, v14
	v_max_f32_e32 v14, v143, v143
	v_max_f32_e32 v14, v80, v14
	v_max3_f32 v14, v14, v144, v145
	v_max3_f32 v14, v14, v245, v247
	v_max3_f32 v14, v14, v248, v249
	v_max3_f32 v14, v14, v88, v89
	v_max3_f32 v14, v14, v90, v91
	v_cndmask_b32_e32 v95, v231, v95, vcc
	v_max3_f32 v14, v14, v92, v93
	v_max3_f32 v14, v14, v94, v95
.Lwinf1_join:
	v_mov_b32_e32 v80, v14
	s_nop 1
	v_permlane32_swap_b32_e32 v14, v80
	v_max_f32_e32 v80, v80, v80
	v_max_f32_e32 v14, v14, v14
	v_max_f32_e32 v14, v14, v80
	v_mul_f32_e32 v14, 0x3e0293ee, v14
	v_max_f32_e32 v80, v246, v246
	v_max_f32_e32 v142, v80, v14
	v_sub_f32_e32 v14, v246, v142
	v_exp_f32_e32 v14, v14
	ds_read_b128 v[84:87], v167 offset:26688
	ds_read_b128 v[80:83], v167 offset:31296
	v_cmp_eq_f32_e32 vcc, 1.0, v14
	s_cmp_eq_u64 vcc, exec
	s_cbranch_scc1 .LBB0_1244
	v_pk_mul_f32 v[78:79], v[78:79], v[14:15] op_sel_hi:[1,0]
	v_pk_mul_f32 v[76:77], v[76:77], v[14:15] op_sel_hi:[1,0]
	v_pk_mul_f32 v[74:75], v[74:75], v[14:15] op_sel_hi:[1,0]
	v_pk_mul_f32 v[72:73], v[72:73], v[14:15] op_sel_hi:[1,0]
	v_pk_mul_f32 v[70:71], v[70:71], v[14:15] op_sel_hi:[1,0]
	v_pk_mul_f32 v[68:69], v[68:69], v[14:15] op_sel_hi:[1,0]
	v_pk_mul_f32 v[66:67], v[66:67], v[14:15] op_sel_hi:[1,0]
	v_pk_mul_f32 v[64:65], v[64:65], v[14:15] op_sel_hi:[1,0]
	v_pk_mul_f32 v[62:63], v[62:63], v[14:15] op_sel_hi:[1,0]
	v_pk_mul_f32 v[60:61], v[60:61], v[14:15] op_sel_hi:[1,0]
	v_pk_mul_f32 v[58:59], v[58:59], v[14:15] op_sel_hi:[1,0]
	v_pk_mul_f32 v[56:57], v[56:57], v[14:15] op_sel_hi:[1,0]
	v_pk_mul_f32 v[54:55], v[54:55], v[14:15] op_sel_hi:[1,0]
	v_pk_mul_f32 v[52:53], v[52:53], v[14:15] op_sel_hi:[1,0]
	v_pk_mul_f32 v[50:51], v[50:51], v[14:15] op_sel_hi:[1,0]
	v_pk_mul_f32 v[48:49], v[48:49], v[14:15] op_sel_hi:[1,0]
	v_pk_mul_f32 v[46:47], v[46:47], v[14:15] op_sel_hi:[1,0]
	v_pk_mul_f32 v[44:45], v[44:45], v[14:15] op_sel_hi:[1,0]
	v_pk_mul_f32 v[42:43], v[42:43], v[14:15] op_sel_hi:[1,0]
	v_pk_mul_f32 v[40:41], v[40:41], v[14:15] op_sel_hi:[1,0]
	v_pk_mul_f32 v[38:39], v[38:39], v[14:15] op_sel_hi:[1,0]
	v_pk_mul_f32 v[36:37], v[36:37], v[14:15] op_sel_hi:[1,0]
	v_pk_mul_f32 v[34:35], v[34:35], v[14:15] op_sel_hi:[1,0]
	v_pk_mul_f32 v[32:33], v[32:33], v[14:15] op_sel_hi:[1,0]
	v_pk_mul_f32 v[30:31], v[30:31], v[14:15] op_sel_hi:[1,0]
	v_pk_mul_f32 v[28:29], v[28:29], v[14:15] op_sel_hi:[1,0]
	v_pk_mul_f32 v[26:27], v[26:27], v[14:15] op_sel_hi:[1,0]
	v_pk_mul_f32 v[24:25], v[24:25], v[14:15] op_sel_hi:[1,0]
	v_pk_mul_f32 v[22:23], v[22:23], v[14:15] op_sel_hi:[1,0]
	v_pk_mul_f32 v[20:21], v[20:21], v[14:15] op_sel_hi:[1,0]
	v_pk_mul_f32 v[18:19], v[18:19], v[14:15] op_sel_hi:[1,0]
	v_pk_mul_f32 v[16:17], v[16:17], v[14:15] op_sel_hi:[1,0]

.Lwinf0:
	v_mov_b32_e32 v143, v80
	v_max_f32_e32 v80, v143, v143
	v_mov_b32_e32 v144, v81
	v_mov_b32_e32 v145, v82
	v_mov_b32_e32 v232, v83
	v_mov_b32_e32 v233, v84
	v_mov_b32_e32 v234, v85
	v_mov_b32_e32 v235, v86
	v_mov_b32_e32 v236, v87
	v_max_f32_e32 v0, v144, v144
	v_max_f32_e32 v0, v80, v0
	v_max3_f32 v0, v0, v145, v232
	v_max3_f32 v0, v0, v233, v234
	v_max3_f32 v0, v0, v235, v236
	v_max3_f32 v0, v0, v88, v89
	v_max3_f32 v0, v0, v90, v91
	v_max3_f32 v0, v0, v92, v93
	v_max3_f32 v0, v0, v94, v95
	s_branch .Lwinf0_join
.Lwinf1:
	v_mov_b32_e32 v15, v80
	v_max_f32_e32 v80, v15, v15
	v_mov_b32_e32 v143, v81
	v_mov_b32_e32 v144, v82
	v_mov_b32_e32 v145, v83
	v_mov_b32_e32 v245, v84
	v_mov_b32_e32 v247, v85
	v_mov_b32_e32 v248, v86
	v_mov_b32_e32 v249, v87
	v_max_f32_e32 v14, v143, v143
	v_max_f32_e32 v14, v80, v14
	v_max3_f32 v14, v14, v144, v145
	v_max3_f32 v14, v14, v245, v247
	v_max3_f32 v14, v14, v248, v249
	v_max3_f32 v14, v14, v88, v89
	v_max3_f32 v14, v14, v90, v91
	v_max3_f32 v14, v14, v92, v93
	v_max3_f32 v14, v14, v94, v95
	s_branch .Lwinf1_join

.LBB0_1376:
	v_cvt_f32_i32_e32 v124, v124
	v_cvt_f32_i32_e32 v125, v125
	v_cvt_f32_i32_e32 v126, v126
	v_cvt_f32_i32_e32 v127, v127
	v_cvt_f32_i32_e32 v120, v120
	v_cvt_f32_i32_e32 v121, v121
	v_cvt_f32_i32_e32 v122, v122
	v_cvt_f32_i32_e32 v123, v123
	v_cvt_f32_i32_e32 v108, v108
	v_cvt_f32_i32_e32 v109, v109
	v_cvt_f32_i32_e32 v110, v110
	v_cvt_f32_i32_e32 v111, v111
	v_cvt_f32_i32_e32 v104, v104
	v_cvt_f32_i32_e32 v105, v105
	v_cvt_f32_i32_e32 v106, v106
	v_cvt_f32_i32_e32 v107, v107
	v_cvt_f32_i32_e32 v92, v92
	v_cvt_f32_i32_e32 v93, v93
	v_cvt_f32_i32_e32 v94, v94
	v_cvt_f32_i32_e32 v95, v95
	v_cvt_f32_i32_e32 v88, v88
	v_cvt_f32_i32_e32 v89, v89
	v_cvt_f32_i32_e32 v90, v90
	v_cvt_f32_i32_e32 v91, v91
	v_cvt_f32_i32_e32 v76, v76
	v_cvt_f32_i32_e32 v77, v77
	v_cvt_f32_i32_e32 v78, v78
	v_cvt_f32_i32_e32 v79, v79
	v_cvt_f32_i32_e32 v72, v72
	v_cvt_f32_i32_e32 v73, v73
	v_cvt_f32_i32_e32 v74, v74
	v_cvt_f32_i32_e32 v75, v75
	v_cvt_f32_i32_e32 v116, v116
	v_cvt_f32_i32_e32 v117, v117
	v_cvt_f32_i32_e32 v118, v118
	v_cvt_f32_i32_e32 v119, v119
	v_cvt_f32_i32_e32 v112, v112
	v_cvt_f32_i32_e32 v113, v113
	v_cvt_f32_i32_e32 v114, v114
	v_cvt_f32_i32_e32 v115, v115
	v_cvt_f32_i32_e32 v100, v100
	v_cvt_f32_i32_e32 v101, v101
	v_cvt_f32_i32_e32 v102, v102
	v_cvt_f32_i32_e32 v103, v103
	v_cvt_f32_i32_e32 v96, v96
	v_cvt_f32_i32_e32 v97, v97
	v_cvt_f32_i32_e32 v98, v98
	v_cvt_f32_i32_e32 v99, v99
	v_cvt_f32_i32_e32 v84, v84
	v_cvt_f32_i32_e32 v85, v85
	v_cvt_f32_i32_e32 v86, v86
	v_cvt_f32_i32_e32 v87, v87
	v_cvt_f32_i32_e32 v80, v80
	v_cvt_f32_i32_e32 v81, v81
	v_cvt_f32_i32_e32 v82, v82
	v_cvt_f32_i32_e32 v83, v83
	v_cvt_f32_i32_e32 v68, v68
	v_cvt_f32_i32_e32 v69, v69
	v_cvt_f32_i32_e32 v70, v70
	v_cvt_f32_i32_e32 v71, v71
	v_cvt_f32_i32_e32 v64, v64
	v_cvt_f32_i32_e32 v65, v65
	v_cvt_f32_i32_e32 v66, v66
	v_cvt_f32_i32_e32 v67, v67
	v_cvt_f32_i32_e32 v60, v60
	v_cvt_f32_i32_e32 v61, v61
	v_cvt_f32_i32_e32 v62, v62
	v_cvt_f32_i32_e32 v63, v63
	v_cvt_f32_i32_e32 v56, v56
	v_cvt_f32_i32_e32 v57, v57
	v_cvt_f32_i32_e32 v58, v58
	v_cvt_f32_i32_e32 v59, v59
	v_cvt_f32_i32_e32 v44, v44
	v_cvt_f32_i32_e32 v45, v45
	v_cvt_f32_i32_e32 v46, v46
	v_cvt_f32_i32_e32 v47, v47
	v_cvt_f32_i32_e32 v40, v40
	v_cvt_f32_i32_e32 v41, v41
	v_cvt_f32_i32_e32 v42, v42
	v_cvt_f32_i32_e32 v43, v43
	v_cvt_f32_i32_e32 v28, v28
	v_cvt_f32_i32_e32 v29, v29
	v_cvt_f32_i32_e32 v30, v30
	v_cvt_f32_i32_e32 v31, v31
	v_cvt_f32_i32_e32 v24, v24
	v_cvt_f32_i32_e32 v25, v25
	v_cvt_f32_i32_e32 v26, v26
	v_cvt_f32_i32_e32 v27, v27
	v_cvt_f32_i32_e32 v12, v12
	v_cvt_f32_i32_e32 v13, v13
	v_cvt_f32_i32_e32 v14, v14
	v_cvt_f32_i32_e32 v15, v15
	v_cvt_f32_i32_e32 v8, v8
	v_cvt_f32_i32_e32 v9, v9
	v_cvt_f32_i32_e32 v10, v10
	v_cvt_f32_i32_e32 v11, v11
	v_cvt_f32_i32_e32 v52, v52
	v_cvt_f32_i32_e32 v53, v53
	v_cvt_f32_i32_e32 v54, v54
	v_cvt_f32_i32_e32 v55, v55
	v_cvt_f32_i32_e32 v48, v48
	v_cvt_f32_i32_e32 v49, v49
	v_cvt_f32_i32_e32 v50, v50
	v_cvt_f32_i32_e32 v51, v51
	v_cvt_f32_i32_e32 v36, v36
	v_cvt_f32_i32_e32 v37, v37
	v_cvt_f32_i32_e32 v38, v38
	v_cvt_f32_i32_e32 v39, v39
	v_cvt_f32_i32_e32 v32, v32
	v_cvt_f32_i32_e32 v33, v33
	v_cvt_f32_i32_e32 v34, v34
	v_cvt_f32_i32_e32 v35, v35
	v_cvt_f32_i32_e32 v20, v20
	v_cvt_f32_i32_e32 v21, v21
	v_cvt_f32_i32_e32 v22, v22
	v_cvt_f32_i32_e32 v23, v23
	v_cvt_f32_i32_e32 v16, v16
	v_cvt_f32_i32_e32 v17, v17
	v_cvt_f32_i32_e32 v18, v18
	v_cvt_f32_i32_e32 v19, v19
	v_cvt_f32_i32_e32 v4, v4
	v_cvt_f32_i32_e32 v5, v5
	v_cvt_f32_i32_e32 v6, v6
	v_cvt_f32_i32_e32 v7, v7
	v_cvt_f32_i32_e32 v0, v0
	v_cvt_f32_i32_e32 v1, v1
	v_cvt_f32_i32_e32 v2, v2
	v_cvt_f32_i32_e32 v3, v3
	s_andn2_b64 vcc, exec, s[20:21]
	v_lshl_add_u32 v215, s50, 8, v146
	v_lshlrev_b32_e32 v217, 2, v215
	s_cbranch_vccnz .Lp4e_nors1
	global_load_dword v214, v217, s[14:15]
	global_load_dword v216, v217, s[14:15] offset:64
	global_load_dword v218, v217, s[14:15] offset:128
	global_load_dword v220, v217, s[14:15] offset:192
	global_load_dword v142, v217, s[14:15] offset:512
	global_load_dword v144, v217, s[14:15] offset:576
	global_load_dword v198, v217, s[14:15] offset:640
	global_load_dword v132, v217, s[14:15] offset:704
.Lp4e_nors1:
	v_lshl_or_b32 v219, s66, 8, v148
	v_lshlrev_b32_e32 v217, 2, v219
	global_load_dwordx4 v[150:153], v217, s[10:11]
	global_load_dwordx4 v[154:157], v217, s[10:11] offset:64
	global_load_dwordx4 v[158:161], v217, s[10:11] offset:512
	global_load_dwordx4 v[162:165], v217, s[10:11] offset:576
	v_lshl_add_u32 v219, v215, 12, v219
	v_lshlrev_b32_e32 v219, 2, v219
	v_mov_b32_e32 v221, v219
	global_load_dwordx4 v[166:169], v219, s[36:37]
	global_load_dwordx4 v[170:173], v219, s[36:37] offset:64
	global_load_dwordx4 v[174:177], v219, s[36:37] offset:512
	global_load_dwordx4 v[178:181], v219, s[36:37] offset:576
	v_add_u32_e32 v219, 0x40000, v219
	global_load_dwordx4 v[182:185], v219, s[36:37]
	global_load_dwordx4 v[186:189], v219, s[36:37] offset:64
	global_load_dwordx4 v[190:193], v219, s[36:37] offset:512
	global_load_dwordx4 v[194:197], v219, s[36:37] offset:576
	v_add_u32_e32 v219, 0x40000, v219
	global_load_dwordx4 v[202:205], v219, s[36:37]
	global_load_dwordx4 v[206:209], v219, s[36:37] offset:64
	global_load_dwordx4 v[210:213], v219, s[36:37] offset:512
	s_cbranch_vccnz .Lp4e_nors2
	s_waitcnt vmcnt(15)
	v_pk_mul_f32 v[126:127], v[126:127], v[214:215] op_sel_hi:[1,0]
	v_pk_mul_f32 v[124:125], v[124:125], v[214:215] op_sel_hi:[1,0]
	v_pk_mul_f32 v[122:123], v[122:123], v[214:215] op_sel_hi:[1,0]
	v_pk_mul_f32 v[120:121], v[120:121], v[214:215] op_sel_hi:[1,0]
	v_pk_mul_f32 v[118:119], v[118:119], v[214:215] op_sel_hi:[1,0]
	v_pk_mul_f32 v[116:117], v[116:117], v[214:215] op_sel_hi:[1,0]
	v_pk_mul_f32 v[114:115], v[114:115], v[214:215] op_sel_hi:[1,0]
	v_pk_mul_f32 v[112:113], v[112:113], v[214:215] op_sel_hi:[1,0]
	v_pk_mul_f32 v[110:111], v[110:111], v[216:217] op_sel_hi:[1,0]
	v_pk_mul_f32 v[108:109], v[108:109], v[216:217] op_sel_hi:[1,0]
	v_pk_mul_f32 v[106:107], v[106:107], v[216:217] op_sel_hi:[1,0]
	v_pk_mul_f32 v[104:105], v[104:105], v[216:217] op_sel_hi:[1,0]
	v_pk_mul_f32 v[102:103], v[102:103], v[216:217] op_sel_hi:[1,0]
	v_pk_mul_f32 v[100:101], v[100:101], v[216:217] op_sel_hi:[1,0]
	v_pk_mul_f32 v[98:99], v[98:99], v[216:217] op_sel_hi:[1,0]
	v_pk_mul_f32 v[96:97], v[96:97], v[216:217] op_sel_hi:[1,0]
	v_pk_mul_f32 v[94:95], v[94:95], v[218:219] op_sel_hi:[1,0]
	v_pk_mul_f32 v[92:93], v[92:93], v[218:219] op_sel_hi:[1,0]
	v_pk_mul_f32 v[90:91], v[90:91], v[218:219] op_sel_hi:[1,0]
	v_pk_mul_f32 v[88:89], v[88:89], v[218:219] op_sel_hi:[1,0]
	v_pk_mul_f32 v[86:87], v[86:87], v[218:219] op_sel_hi:[1,0]
	v_pk_mul_f32 v[84:85], v[84:85], v[218:219] op_sel_hi:[1,0]
	v_pk_mul_f32 v[82:83], v[82:83], v[218:219] op_sel_hi:[1,0]
	v_pk_mul_f32 v[80:81], v[80:81], v[218:219] op_sel_hi:[1,0]
	v_pk_mul_f32 v[78:79], v[78:79], v[220:221] op_sel_hi:[1,0]
	v_pk_mul_f32 v[76:77], v[76:77], v[220:221] op_sel_hi:[1,0]
	v_pk_mul_f32 v[74:75], v[74:75], v[220:221] op_sel_hi:[1,0]
	v_pk_mul_f32 v[72:73], v[72:73], v[220:221] op_sel_hi:[1,0]
	v_pk_mul_f32 v[70:71], v[70:71], v[220:221] op_sel_hi:[1,0]
	v_pk_mul_f32 v[68:69], v[68:69], v[220:221] op_sel_hi:[1,0]
	v_pk_mul_f32 v[66:67], v[66:67], v[220:221] op_sel_hi:[1,0]
	v_pk_mul_f32 v[64:65], v[64:65], v[220:221] op_sel_hi:[1,0]
	v_pk_mul_f32 v[62:63], v[62:63], v[142:143] op_sel_hi:[1,0]
	v_pk_mul_f32 v[60:61], v[60:61], v[142:143] op_sel_hi:[1,0]
	v_pk_mul_f32 v[58:59], v[58:59], v[142:143] op_sel_hi:[1,0]
	v_pk_mul_f32 v[56:57], v[56:57], v[142:143] op_sel_hi:[1,0]
	v_pk_mul_f32 v[54:55], v[54:55], v[142:143] op_sel_hi:[1,0]
	v_pk_mul_f32 v[52:53], v[52:53], v[142:143] op_sel_hi:[1,0]
	v_pk_mul_f32 v[50:51], v[50:51], v[142:143] op_sel_hi:[1,0]
	v_pk_mul_f32 v[48:49], v[48:49], v[142:143] op_sel_hi:[1,0]
	v_pk_mul_f32 v[46:47], v[46:47], v[144:145] op_sel_hi:[1,0]
	v_pk_mul_f32 v[44:45], v[44:45], v[144:145] op_sel_hi:[1,0]
	v_pk_mul_f32 v[42:43], v[42:43], v[144:145] op_sel_hi:[1,0]
	v_pk_mul_f32 v[40:41], v[40:41], v[144:145] op_sel_hi:[1,0]
	v_pk_mul_f32 v[38:39], v[38:39], v[144:145] op_sel_hi:[1,0]
	v_pk_mul_f32 v[36:37], v[36:37], v[144:145] op_sel_hi:[1,0]
	v_pk_mul_f32 v[34:35], v[34:35], v[144:145] op_sel_hi:[1,0]
	v_pk_mul_f32 v[32:33], v[32:33], v[144:145] op_sel_hi:[1,0]
	v_pk_mul_f32 v[30:31], v[30:31], v[198:199] op_sel_hi:[1,0]
	v_pk_mul_f32 v[28:29], v[28:29], v[198:199] op_sel_hi:[1,0]
	v_pk_mul_f32 v[26:27], v[26:27], v[198:199] op_sel_hi:[1,0]
	v_pk_mul_f32 v[24:25], v[24:25], v[198:199] op_sel_hi:[1,0]
	v_pk_mul_f32 v[22:23], v[22:23], v[198:199] op_sel_hi:[1,0]
	v_pk_mul_f32 v[20:21], v[20:21], v[198:199] op_sel_hi:[1,0]
	v_pk_mul_f32 v[18:19], v[18:19], v[198:199] op_sel_hi:[1,0]
	v_pk_mul_f32 v[16:17], v[16:17], v[198:199] op_sel_hi:[1,0]
	v_pk_mul_f32 v[14:15], v[14:15], v[132:133] op_sel_hi:[1,0]
	v_pk_mul_f32 v[12:13], v[12:13], v[132:133] op_sel_hi:[1,0]
	v_pk_mul_f32 v[10:11], v[10:11], v[132:133] op_sel_hi:[1,0]
	v_pk_mul_f32 v[8:9], v[8:9], v[132:133] op_sel_hi:[1,0]
	v_pk_mul_f32 v[6:7], v[6:7], v[132:133] op_sel_hi:[1,0]
	v_pk_mul_f32 v[4:5], v[4:5], v[132:133] op_sel_hi:[1,0]
	v_pk_mul_f32 v[2:3], v[2:3], v[132:133] op_sel_hi:[1,0]
	v_pk_mul_f32 v[0:1], v[0:1], v[132:133] op_sel_hi:[1,0]
.Lp4e_nors2:
	s_waitcnt vmcnt(11)
	v_pk_mul_f32 v[152:153], v[152:153], s[22:23] op_sel_hi:[1,0]
	v_pk_mul_f32 v[150:151], v[150:151], s[22:23] op_sel_hi:[1,0]
	v_pk_mul_f32 v[156:157], v[156:157], s[22:23] op_sel_hi:[1,0]
	v_pk_mul_f32 v[154:155], v[154:155], s[22:23] op_sel_hi:[1,0]
	v_pk_mul_f32 v[160:161], v[160:161], s[22:23] op_sel_hi:[1,0]
	v_pk_mul_f32 v[158:159], v[158:159], s[22:23] op_sel_hi:[1,0]
	v_pk_mul_f32 v[164:165], v[164:165], s[22:23] op_sel_hi:[1,0]
	v_pk_mul_f32 v[162:163], v[162:163], s[22:23] op_sel_hi:[1,0]
	s_waitcnt vmcnt(10)
	v_pk_fma_f32 v[126:127], v[126:127], v[152:153], v[168:169]
	v_pk_fma_f32 v[124:125], v[124:125], v[150:151], v[166:167]
	global_load_dwordx4 v[166:169], v219, s[36:37] offset:576
	v_add_u32_e32 v219, 0x40000, v219
	global_store_dwordx4 v221, v[124:127], s[70:71]
	s_waitcnt vmcnt(11)
	v_pk_fma_f32 v[122:123], v[122:123], v[156:157], v[172:173]
	v_pk_fma_f32 v[120:121], v[120:121], v[154:155], v[170:171]
	global_load_dwordx4 v[170:173], v219, s[36:37]
	global_store_dwordx4 v221, v[120:123], s[70:71] offset:64
	s_waitcnt vmcnt(12)
	v_pk_fma_f32 v[118:119], v[118:119], v[160:161], v[176:177]
	v_pk_fma_f32 v[116:117], v[116:117], v[158:159], v[174:175]
	global_load_dwordx4 v[174:177], v219, s[36:37] offset:64
	global_store_dwordx4 v221, v[116:119], s[70:71] offset:512
	s_waitcnt vmcnt(13)
	v_pk_fma_f32 v[114:115], v[114:115], v[164:165], v[180:181]
	v_pk_fma_f32 v[112:113], v[112:113], v[162:163], v[178:179]
	global_load_dwordx4 v[178:181], v219, s[36:37] offset:512
	global_store_dwordx4 v221, v[112:115], s[70:71] offset:576
	v_add_u32_e32 v221, 0x40000, v221
	s_waitcnt vmcnt(14)
	v_pk_fma_f32 v[110:111], v[110:111], v[152:153], v[184:185]
	v_pk_fma_f32 v[108:109], v[108:109], v[150:151], v[182:183]
	global_load_dwordx4 v[182:185], v219, s[36:37] offset:576
	v_add_u32_e32 v219, 0x140000, v219
	global_store_dwordx4 v221, v[108:111], s[70:71]
	s_waitcnt vmcnt(15)
	v_pk_fma_f32 v[106:107], v[106:107], v[156:157], v[188:189]
	v_pk_fma_f32 v[104:105], v[104:105], v[154:155], v[186:187]
	global_load_dwordx4 v[186:189], v219, s[36:37]
	global_store_dwordx4 v221, v[104:107], s[70:71] offset:64
	s_waitcnt vmcnt(16)
	v_pk_fma_f32 v[102:103], v[102:103], v[160:161], v[192:193]
	v_pk_fma_f32 v[100:101], v[100:101], v[158:159], v[190:191]
	global_load_dwordx4 v[190:193], v219, s[36:37] offset:64
	global_store_dwordx4 v221, v[100:103], s[70:71] offset:512
	s_waitcnt vmcnt(17)
	v_pk_fma_f32 v[98:99], v[98:99], v[164:165], v[196:197]
	v_pk_fma_f32 v[96:97], v[96:97], v[162:163], v[194:195]
	global_load_dwordx4 v[194:197], v219, s[36:37] offset:512
	global_store_dwordx4 v221, v[96:99], s[70:71] offset:576
	v_add_u32_e32 v221, 0x40000, v221
	s_waitcnt vmcnt(18)
	v_pk_fma_f32 v[94:95], v[94:95], v[152:153], v[204:205]
	v_pk_fma_f32 v[92:93], v[92:93], v[150:151], v[202:203]
	global_load_dwordx4 v[202:205], v219, s[36:37] offset:576
	v_add_u32_e32 v219, 0x40000, v219
	global_store_dwordx4 v221, v[92:95], s[70:71]
	s_waitcnt vmcnt(19)
	v_pk_fma_f32 v[90:91], v[90:91], v[156:157], v[208:209]
	v_pk_fma_f32 v[88:89], v[88:89], v[154:155], v[206:207]
	global_load_dwordx4 v[206:209], v219, s[36:37]
	global_store_dwordx4 v221, v[88:91], s[70:71] offset:64
	s_waitcnt vmcnt(20)
	v_pk_fma_f32 v[86:87], v[86:87], v[160:161], v[212:213]
	v_pk_fma_f32 v[84:85], v[84:85], v[158:159], v[210:211]
	global_load_dwordx4 v[210:213], v219, s[36:37] offset:64
	global_store_dwordx4 v221, v[84:87], s[70:71] offset:512
	s_waitcnt vmcnt(21)
	v_pk_fma_f32 v[82:83], v[82:83], v[164:165], v[168:169]
	v_pk_fma_f32 v[80:81], v[80:81], v[162:163], v[166:167]
	global_load_dwordx4 v[166:169], v219, s[36:37] offset:512
	global_store_dwordx4 v221, v[80:83], s[70:71] offset:576
	v_add_u32_e32 v221, 0x40000, v221
	s_waitcnt vmcnt(21)
	v_pk_fma_f32 v[78:79], v[78:79], v[152:153], v[172:173]
	v_pk_fma_f32 v[76:77], v[76:77], v[150:151], v[170:171]
	global_load_dwordx4 v[170:173], v219, s[36:37] offset:576
	v_add_u32_e32 v219, 0x40000, v219
	global_store_dwordx4 v221, v[76:79], s[70:71]
	s_waitcnt vmcnt(21)
	v_pk_fma_f32 v[74:75], v[74:75], v[156:157], v[176:177]
	v_pk_fma_f32 v[72:73], v[72:73], v[154:155], v[174:175]
	global_load_dwordx4 v[174:177], v219, s[36:37]
	global_store_dwordx4 v221, v[72:75], s[70:71] offset:64
	s_waitcnt vmcnt(21)
	v_pk_fma_f32 v[70:71], v[70:71], v[160:161], v[180:181]
	v_pk_fma_f32 v[68:69], v[68:69], v[158:159], v[178:179]
	global_load_dwordx4 v[178:181], v219, s[36:37] offset:64
	global_store_dwordx4 v221, v[68:71], s[70:71] offset:512
	s_waitcnt vmcnt(21)
	v_pk_fma_f32 v[66:67], v[66:67], v[164:165], v[184:185]
	v_pk_fma_f32 v[64:65], v[64:65], v[162:163], v[182:183]
	global_load_dwordx4 v[182:185], v219, s[36:37] offset:512
	global_store_dwordx4 v221, v[64:67], s[70:71] offset:576
	v_add_u32_e32 v221, 0x140000, v221
	s_waitcnt vmcnt(21)
	v_pk_fma_f32 v[62:63], v[62:63], v[152:153], v[188:189]
	v_pk_fma_f32 v[60:61], v[60:61], v[150:151], v[186:187]
	global_load_dwordx4 v[186:189], v219, s[36:37] offset:576
	v_add_u32_e32 v219, 0x40000, v219
	global_store_dwordx4 v221, v[60:63], s[70:71]
	s_waitcnt vmcnt(21)
	v_pk_fma_f32 v[58:59], v[58:59], v[156:157], v[192:193]
	v_pk_fma_f32 v[56:57], v[56:57], v[154:155], v[190:191]
	global_load_dwordx4 v[190:193], v219, s[36:37]
	global_store_dwordx4 v221, v[56:59], s[70:71] offset:64
	s_waitcnt vmcnt(21)
	v_pk_fma_f32 v[54:55], v[54:55], v[160:161], v[196:197]
	v_pk_fma_f32 v[52:53], v[52:53], v[158:159], v[194:195]
	global_load_dwordx4 v[194:197], v219, s[36:37] offset:64
	global_store_dwordx4 v221, v[52:55], s[70:71] offset:512
	s_waitcnt vmcnt(21)
	v_pk_fma_f32 v[50:51], v[50:51], v[164:165], v[204:205]
	v_pk_fma_f32 v[48:49], v[48:49], v[162:163], v[202:203]
	global_load_dwordx4 v[202:205], v219, s[36:37] offset:512
	global_store_dwordx4 v221, v[48:51], s[70:71] offset:576
	v_add_u32_e32 v221, 0x40000, v221
	s_waitcnt vmcnt(21)
	v_pk_fma_f32 v[46:47], v[46:47], v[152:153], v[208:209]
	v_pk_fma_f32 v[44:45], v[44:45], v[150:151], v[206:207]
	global_load_dwordx4 v[206:209], v219, s[36:37] offset:576
	global_store_dwordx4 v221, v[44:47], s[70:71]
	s_waitcnt vmcnt(21)
	v_pk_fma_f32 v[42:43], v[42:43], v[156:157], v[212:213]
	v_pk_fma_f32 v[40:41], v[40:41], v[154:155], v[210:211]
	global_store_dwordx4 v221, v[40:43], s[70:71] offset:64
	s_waitcnt vmcnt(20)
	v_pk_fma_f32 v[38:39], v[38:39], v[160:161], v[168:169]
	v_pk_fma_f32 v[36:37], v[36:37], v[158:159], v[166:167]
	global_store_dwordx4 v221, v[36:39], s[70:71] offset:512
	s_waitcnt vmcnt(19)
	v_pk_fma_f32 v[34:35], v[34:35], v[164:165], v[172:173]
	v_pk_fma_f32 v[32:33], v[32:33], v[162:163], v[170:171]
	global_store_dwordx4 v221, v[32:35], s[70:71] offset:576
	v_add_u32_e32 v221, 0x40000, v221
	s_waitcnt vmcnt(18)
	v_pk_fma_f32 v[30:31], v[30:31], v[152:153], v[176:177]
	v_pk_fma_f32 v[28:29], v[28:29], v[150:151], v[174:175]
	global_store_dwordx4 v221, v[28:31], s[70:71]
	s_waitcnt vmcnt(17)
	v_pk_fma_f32 v[26:27], v[26:27], v[156:157], v[180:181]
	v_pk_fma_f32 v[24:25], v[24:25], v[154:155], v[178:179]
	global_store_dwordx4 v221, v[24:27], s[70:71] offset:64
	s_waitcnt vmcnt(16)
	v_pk_fma_f32 v[22:23], v[22:23], v[160:161], v[184:185]
	v_pk_fma_f32 v[20:21], v[20:21], v[158:159], v[182:183]
	global_store_dwordx4 v221, v[20:23], s[70:71] offset:512
	s_waitcnt vmcnt(15)
	v_pk_fma_f32 v[18:19], v[18:19], v[164:165], v[188:189]
	v_pk_fma_f32 v[16:17], v[16:17], v[162:163], v[186:187]
	global_store_dwordx4 v221, v[16:19], s[70:71] offset:576
	v_add_u32_e32 v221, 0x40000, v221
	s_waitcnt vmcnt(14)
	v_pk_fma_f32 v[14:15], v[14:15], v[152:153], v[192:193]
	v_pk_fma_f32 v[12:13], v[12:13], v[150:151], v[190:191]
	global_store_dwordx4 v221, v[12:15], s[70:71]
	s_waitcnt vmcnt(13)
	v_pk_fma_f32 v[10:11], v[10:11], v[156:157], v[196:197]
	v_pk_fma_f32 v[8:9], v[8:9], v[154:155], v[194:195]
	global_store_dwordx4 v221, v[8:11], s[70:71] offset:64
	s_waitcnt vmcnt(12)
	v_pk_fma_f32 v[6:7], v[6:7], v[160:161], v[204:205]
	v_pk_fma_f32 v[4:5], v[4:5], v[158:159], v[202:203]
	global_store_dwordx4 v221, v[4:7], s[70:71] offset:512
	s_waitcnt vmcnt(11)
	v_pk_fma_f32 v[2:3], v[2:3], v[164:165], v[208:209]
	v_pk_fma_f32 v[0:1], v[0:1], v[162:163], v[206:207]
	global_store_dwordx4 v221, v[0:3], s[70:71] offset:576
	s_andn2_b64 vcc, exec, s[6:7]
	s_mov_b64 s[6:7], -1
	s_waitcnt vmcnt(0)
	s_cbranch_vccnz .LBB0_1364
	s_andn2_b64 vcc, exec, s[0:1]
	s_cbranch_vccnz .LBB0_1363
	s_barrier
	s_branch .LBB0_1363

.LBB0_1513:
	v_lshl_or_b32 v134, s1, 8, v159
	v_ashrrev_i32_e32 v135, 31, v134
	v_lshl_add_u32 v132, s0, 8, v157
	v_lshl_add_u64 v[170:171], v[134:135], 2, s[20:21]
	global_load_dwordx4 v[128:131], v[170:171], off
	v_ashrrev_i32_e32 v133, 31, v132
	v_lshl_add_u32 v140, v132, 12, v134
	v_lshl_add_u64 v[150:151], v[132:133], 2, s[40:41]
	v_lshl_add_u64 v[154:155], v[140:141], 1, s[54:55]
	global_load_dword v156, v[150:151], off
	global_load_dwordx2 v[174:175], v[154:155], off
	v_lshl_add_u64 v[152:153], v[140:141], 2, s[70:71]
	global_load_dwordx4 v[162:165], v[152:153], off
	v_cvt_f32_i32_e32 v176, v124
	v_cvt_f32_i32_e32 v177, v125
	v_cvt_f32_i32_e32 v178, v126
	v_cvt_f32_i32_e32 v179, v127
	global_load_dwordx4 v[166:169], v[170:171], off offset:64
	global_load_dwordx4 v[132:135], v[170:171], off offset:512
	global_load_dwordx4 v[124:127], v[170:171], off offset:576
	s_nop 0
	global_load_dwordx4 v[170:173], v[152:153], off offset:64
	v_add_u32_e32 v140, 0x10000, v140
	v_cvt_f32_i32_e32 v108, v108
	v_cvt_f32_i32_e32 v109, v109
	v_cvt_f32_i32_e32 v110, v110
	v_cvt_f32_i32_e32 v111, v111
	v_cvt_f32_i32_e32 v104, v104
	v_cvt_f32_i32_e32 v105, v105
	v_cvt_f32_i32_e32 v106, v106
	v_cvt_f32_i32_e32 v107, v107
	v_cvt_f32_i32_e32 v100, v100
	v_cvt_f32_i32_e32 v101, v101
	v_cvt_f32_i32_e32 v96, v96
	v_cvt_f32_i32_e32 v97, v97
	v_cvt_f32_i32_e32 v98, v98
	v_cvt_f32_i32_e32 v99, v99
	v_cvt_f32_i32_e32 v92, v92
	v_cvt_f32_i32_e32 v93, v93
	v_cvt_f32_i32_e32 v94, v94
	v_cvt_f32_i32_e32 v95, v95
	v_cvt_f32_i32_e32 v88, v88
	v_cvt_f32_i32_e32 v89, v89
	v_cvt_f32_i32_e32 v90, v90
	v_cvt_f32_i32_e32 v91, v91
	v_cvt_f32_i32_e32 v84, v84
	v_cvt_f32_i32_e32 v85, v85
	v_cvt_f32_i32_e32 v80, v80
	v_cvt_f32_i32_e32 v81, v81
	v_cvt_f32_i32_e32 v82, v82
	v_cvt_f32_i32_e32 v83, v83
	v_cvt_f32_i32_e32 v76, v76
	v_cvt_f32_i32_e32 v77, v77
	v_cvt_f32_i32_e32 v78, v78
	v_cvt_f32_i32_e32 v79, v79
	v_cvt_f32_i32_e32 v72, v72
	v_cvt_f32_i32_e32 v73, v73
	v_cvt_f32_i32_e32 v74, v74
	v_cvt_f32_i32_e32 v75, v75
	v_cvt_f32_i32_e32 v68, v68
	v_cvt_f32_i32_e32 v69, v69
	v_cvt_f32_i32_e32 v64, v64
	v_cvt_f32_i32_e32 v65, v65
	v_cvt_f32_i32_e32 v66, v66
	v_cvt_f32_i32_e32 v67, v67
	v_cvt_f32_i32_e32 v60, v60
	v_cvt_f32_i32_e32 v61, v61
	v_cvt_f32_i32_e32 v62, v62
	v_cvt_f32_i32_e32 v63, v63
	v_cvt_f32_i32_e32 v56, v56
	v_cvt_f32_i32_e32 v57, v57
	v_cvt_f32_i32_e32 v58, v58
	v_cvt_f32_i32_e32 v59, v59
	v_cvt_f32_i32_e32 v52, v52
	v_cvt_f32_i32_e32 v53, v53
	v_cvt_f32_i32_e32 v48, v48
	v_cvt_f32_i32_e32 v49, v49
	v_cvt_f32_i32_e32 v50, v50
	v_cvt_f32_i32_e32 v51, v51
	v_cvt_f32_i32_e32 v44, v44
	v_cvt_f32_i32_e32 v45, v45
	v_cvt_f32_i32_e32 v46, v46
	v_cvt_f32_i32_e32 v47, v47
	v_cvt_f32_i32_e32 v40, v40
	v_cvt_f32_i32_e32 v41, v41
	v_cvt_f32_i32_e32 v42, v42
	v_cvt_f32_i32_e32 v43, v43
	v_cvt_f32_i32_e32 v36, v36
	s_waitcnt vmcnt(0)
	v_pk_mul_f32 v[128:129], v[128:129], s[26:27] op_sel_hi:[1,0]
	v_pk_mul_f32 v[130:131], v[130:131], s[26:27] op_sel_hi:[1,0]
	v_pk_mul_f32 v[176:177], v[176:177], v[128:129]
	v_pk_mul_f32 v[178:179], v[178:179], v[130:131]
	v_cvt_f32_i32_e32 v37, v37
	v_pk_mul_f32 v[176:177], v[176:177], v[156:157] op_sel_hi:[1,0]
	v_lshlrev_b32_e32 v180, 16, v174
	v_and_b32_e32 v181, 0xffff0000, v174
	v_mul_f32_e32 v161, 0xbfb8aa3b, v176
	v_mul_f32_e32 v174, 0xbfb8aa3b, v177
	v_pk_mul_f32 v[178:179], v[178:179], v[156:157] op_sel_hi:[1,0]
	v_exp_f32_e32 v176, v161
	v_exp_f32_e32 v177, v174
	v_mul_f32_e32 v178, 0xbfb8aa3b, v178
	v_mul_f32_e32 v179, 0xbfb8aa3b, v179
	v_exp_f32_e32 v178, v178
	v_exp_f32_e32 v179, v179
	v_pk_add_f32 v[176:177], v[176:177], 1.0 op_sel_hi:[1,0]
	v_lshlrev_b32_e32 v174, 16, v175
	v_pk_add_f32 v[178:179], v[178:179], 1.0 op_sel_hi:[1,0]
	s_mov_b64 vcc, s[0:1]
	v_rcp_f32_e32 v161, v177
	s_nop 0
	v_mul_f32_e32 v177, 1.0, v161
	s_mov_b64 vcc, s[10:11]
	v_rcp_f32_e32 v161, v176
	s_nop 0
	v_mul_f32_e32 v176, 1.0, v161
	s_mov_b64 vcc, s[12:13]
	v_pk_fma_f32 v[162:163], v[176:177], v[180:181], v[162:163]
	v_rcp_f32_e32 v161, v179
	s_nop 0
	v_mul_f32_e32 v177, 1.0, v161
	v_and_b32_e32 v175, 0xffff0000, v175
	v_rcp_f32_e32 v161, v178
	s_nop 0
	v_mul_f32_e32 v176, 1.0, v161
	v_pk_fma_f32 v[164:165], v[176:177], v[174:175], v[164:165]
	global_store_dwordx4 v[152:153], v[162:165], off
	global_load_dwordx2 v[162:163], v[154:155], off offset:32
	v_cvt_f32_i32_e32 v174, v122
	v_cvt_f32_i32_e32 v164, v120
	v_cvt_f32_i32_e32 v165, v121
	v_cvt_f32_i32_e32 v175, v123
	v_pk_mul_f32 v[122:123], v[166:167], s[26:27] op_sel_hi:[1,0]
	v_pk_mul_f32 v[120:121], v[168:169], s[26:27] op_sel_hi:[1,0]
	v_pk_mul_f32 v[164:165], v[164:165], v[122:123]
	v_pk_mul_f32 v[166:167], v[174:175], v[120:121]
	v_pk_mul_f32 v[164:165], v[164:165], v[156:157] op_sel_hi:[1,0]
	v_pk_mul_f32 v[166:167], v[166:167], v[156:157] op_sel_hi:[1,0]
	v_mul_f32_e32 v161, 0xbfb8aa3b, v164
	v_mul_f32_e32 v165, 0xbfb8aa3b, v165
	v_exp_f32_e32 v164, v161
	v_exp_f32_e32 v165, v165
	v_mul_f32_e32 v166, 0xbfb8aa3b, v166
	v_mul_f32_e32 v167, 0xbfb8aa3b, v167
	v_exp_f32_e32 v166, v166
	v_exp_f32_e32 v167, v167
	v_pk_add_f32 v[164:165], v[164:165], 1.0 op_sel_hi:[1,0]
	v_pk_mul_f32 v[104:105], v[104:105], v[122:123]
	v_pk_add_f32 v[166:167], v[166:167], 1.0 op_sel_hi:[1,0]
	s_mov_b64 vcc, s[0:1]
	v_rcp_f32_e32 v161, v165
	s_nop 0
	v_mul_f32_e32 v165, 1.0, v161
	s_mov_b64 vcc, s[10:11]
	v_rcp_f32_e32 v161, v164
	s_nop 0
	v_mul_f32_e32 v164, 1.0, v161
	s_mov_b64 vcc, s[12:13]
	v_rcp_f32_e32 v161, v167
	s_nop 0
	v_mul_f32_e32 v167, 1.0, v161
	v_rcp_f32_e32 v161, v166
	s_nop 0
	v_mul_f32_e32 v166, 1.0, v161
	v_pk_mul_f32 v[106:107], v[106:107], v[120:121]
	v_pk_mul_f32 v[88:89], v[88:89], v[122:123]
	v_pk_mul_f32 v[90:91], v[90:91], v[120:121]
	s_waitcnt vmcnt(0)
	v_lshlrev_b32_e32 v168, 16, v162
	v_and_b32_e32 v169, 0xffff0000, v162
	v_lshlrev_b32_e32 v174, 16, v163
	v_and_b32_e32 v175, 0xffff0000, v163
	v_pk_fma_f32 v[162:163], v[164:165], v[168:169], v[170:171]
	v_pk_fma_f32 v[164:165], v[166:167], v[174:175], v[172:173]
	global_store_dwordx4 v[152:153], v[162:165], off offset:64
	global_load_dwordx2 v[166:167], v[154:155], off offset:256
	v_cvt_f32_i32_e32 v168, v116
	global_load_dwordx4 v[162:165], v[152:153], off offset:512
	v_cvt_f32_i32_e32 v169, v117
	v_cvt_f32_i32_e32 v170, v118
	v_cvt_f32_i32_e32 v171, v119
	v_pk_mul_f32 v[118:119], v[132:133], s[26:27] op_sel_hi:[1,0]
	v_pk_mul_f32 v[116:117], v[134:135], s[26:27] op_sel_hi:[1,0]
	v_pk_mul_f32 v[134:135], v[168:169], v[118:119]
	v_pk_mul_f32 v[132:133], v[170:171], v[116:117]
	v_pk_mul_f32 v[134:135], v[134:135], v[156:157] op_sel_hi:[1,0]
	v_pk_mul_f32 v[132:133], v[132:133], v[156:157] op_sel_hi:[1,0]
	v_mul_f32_e32 v134, 0xbfb8aa3b, v134
	v_mul_f32_e32 v135, 0xbfb8aa3b, v135
	v_exp_f32_e32 v168, v134
	v_exp_f32_e32 v169, v135
	v_mul_f32_e32 v132, 0xbfb8aa3b, v132
	v_mul_f32_e32 v133, 0xbfb8aa3b, v133
	v_exp_f32_e32 v170, v132
	v_exp_f32_e32 v171, v133
	v_pk_add_f32 v[168:169], v[168:169], 1.0 op_sel_hi:[1,0]
	global_load_dwordx4 v[132:135], v[152:153], off offset:576
	v_pk_add_f32 v[170:171], v[170:171], 1.0 op_sel_hi:[1,0]
	s_mov_b64 vcc, s[0:1]
	v_rcp_f32_e32 v161, v169
	s_nop 0
	v_mul_f32_e32 v169, 1.0, v161
	s_mov_b64 vcc, s[10:11]
	v_rcp_f32_e32 v161, v168
	s_nop 0
	v_mul_f32_e32 v168, 1.0, v161
	s_mov_b64 vcc, s[12:13]
	v_rcp_f32_e32 v161, v171
	s_nop 0
	v_mul_f32_e32 v171, 1.0, v161
	v_rcp_f32_e32 v161, v170
	s_nop 0
	v_mul_f32_e32 v170, 1.0, v161
	v_pk_mul_f32 v[100:101], v[100:101], v[118:119]
	v_pk_mul_f32 v[84:85], v[84:85], v[118:119]
	s_waitcnt vmcnt(0)
	v_lshlrev_b32_e32 v172, 16, v166
	v_and_b32_e32 v173, 0xffff0000, v166
	v_lshlrev_b32_e32 v166, 16, v167
	v_and_b32_e32 v167, 0xffff0000, v167
	v_pk_fma_f32 v[162:163], v[168:169], v[172:173], v[162:163]
	v_pk_fma_f32 v[164:165], v[170:171], v[166:167], v[164:165]
	global_store_dwordx4 v[152:153], v[162:165], off offset:512
	global_load_dwordx2 v[154:155], v[154:155], off offset:288
	v_pk_mul_f32 v[72:73], v[72:73], v[122:123]
	v_cvt_f32_i32_e32 v162, v112
	v_cvt_f32_i32_e32 v163, v113
	v_cvt_f32_i32_e32 v164, v114
	v_cvt_f32_i32_e32 v165, v115
	v_pk_mul_f32 v[114:115], v[124:125], s[26:27] op_sel_hi:[1,0]
	v_pk_mul_f32 v[112:113], v[126:127], s[26:27] op_sel_hi:[1,0]
	v_pk_mul_f32 v[126:127], v[162:163], v[114:115]
	v_pk_mul_f32 v[124:125], v[164:165], v[112:113]
	v_pk_mul_f32 v[126:127], v[126:127], v[156:157] op_sel_hi:[1,0]
	v_pk_mul_f32 v[124:125], v[124:125], v[156:157] op_sel_hi:[1,0]
	v_mul_f32_e32 v126, 0xbfb8aa3b, v126
	v_mul_f32_e32 v127, 0xbfb8aa3b, v127
	v_mul_f32_e32 v156, 0xbfb8aa3b, v124
	v_mul_f32_e32 v161, 0xbfb8aa3b, v125
	v_exp_f32_e32 v124, v126
	v_exp_f32_e32 v125, v127
	v_exp_f32_e32 v126, v156
	v_exp_f32_e32 v127, v161
	v_pk_mul_f32 v[96:97], v[96:97], v[114:115]
	v_pk_add_f32 v[124:125], v[124:125], 1.0 op_sel_hi:[1,0]
	v_pk_mul_f32 v[98:99], v[98:99], v[112:113]
	v_pk_add_f32 v[126:127], v[126:127], 1.0 op_sel_hi:[1,0]
	s_mov_b64 vcc, s[0:1]
	v_rcp_f32_e32 v156, v125
	s_nop 0
	v_mul_f32_e32 v125, 1.0, v156
	s_mov_b64 vcc, s[10:11]
	v_rcp_f32_e32 v156, v124
	s_nop 0
	v_mul_f32_e32 v124, 1.0, v156
	s_mov_b64 vcc, s[12:13]
	v_rcp_f32_e32 v156, v127
	s_nop 0
	v_mul_f32_e32 v127, 1.0, v156
	v_rcp_f32_e32 v156, v126
	s_nop 0
	v_mul_f32_e32 v126, 1.0, v156
	v_pk_mul_f32 v[164:165], v[108:109], v[128:129]
	s_waitcnt vmcnt(0)
	v_lshlrev_b32_e32 v162, 16, v154
	v_and_b32_e32 v163, 0xffff0000, v154
	v_lshlrev_b32_e32 v154, 16, v155
	v_and_b32_e32 v155, 0xffff0000, v155
	v_pk_fma_f32 v[124:125], v[124:125], v[162:163], v[132:133]
	v_pk_fma_f32 v[126:127], v[126:127], v[154:155], v[134:135]
	global_store_dwordx4 v[152:153], v[124:127], off offset:576
	global_load_dword v126, v[150:151], off offset:64
	v_lshl_add_u64 v[132:133], v[140:141], 1, s[54:55]
	global_load_dwordx2 v[134:135], v[132:133], off
	v_lshl_add_u64 v[124:125], v[140:141], 2, s[70:71]
	global_load_dwordx4 v[152:155], v[124:125], off
	v_pk_mul_f32 v[162:163], v[110:111], v[130:131]
	global_load_dwordx4 v[108:111], v[124:125], off offset:64
	v_add_u32_e32 v140, 0x10000, v140
	v_pk_mul_f32 v[80:81], v[80:81], v[114:115]
	v_pk_mul_f32 v[82:83], v[82:83], v[112:113]
	v_pk_mul_f32 v[74:75], v[74:75], v[120:121]
	v_pk_mul_f32 v[68:69], v[68:69], v[118:119]
	v_pk_mul_f32 v[64:65], v[64:65], v[114:115]
	v_pk_mul_f32 v[66:67], v[66:67], v[112:113]
	v_pk_mul_f32 v[56:57], v[56:57], v[122:123]
	v_pk_mul_f32 v[58:59], v[58:59], v[120:121]
	v_pk_mul_f32 v[52:53], v[52:53], v[118:119]
	v_pk_mul_f32 v[48:49], v[48:49], v[114:115]
	v_pk_mul_f32 v[50:51], v[50:51], v[112:113]
	v_pk_mul_f32 v[40:41], v[40:41], v[122:123]
	v_pk_mul_f32 v[42:43], v[42:43], v[120:121]
	v_pk_mul_f32 v[36:37], v[36:37], v[118:119]
	v_cvt_f32_i32_e32 v32, v32
	v_cvt_f32_i32_e32 v33, v33
	v_cvt_f32_i32_e32 v34, v34
	v_cvt_f32_i32_e32 v35, v35
	v_cvt_f32_i32_e32 v28, v28
	v_pk_mul_f32 v[32:33], v[32:33], v[114:115]
	v_cvt_f32_i32_e32 v29, v29
	v_pk_mul_f32 v[34:35], v[34:35], v[112:113]
	v_cvt_f32_i32_e32 v30, v30
	v_cvt_f32_i32_e32 v31, v31
	v_cvt_f32_i32_e32 v24, v24
	v_cvt_f32_i32_e32 v25, v25
	v_cvt_f32_i32_e32 v26, v26
	v_cvt_f32_i32_e32 v27, v27
	v_cvt_f32_i32_e32 v20, v20
	v_pk_mul_f32 v[24:25], v[24:25], v[122:123]
	v_cvt_f32_i32_e32 v21, v21
	v_pk_mul_f32 v[26:27], v[26:27], v[120:121]
	v_cvt_f32_i32_e32 v16, v16
	v_cvt_f32_i32_e32 v17, v17
	v_pk_mul_f32 v[20:21], v[20:21], v[118:119]
	v_cvt_f32_i32_e32 v18, v18
	v_cvt_f32_i32_e32 v19, v19
	v_pk_mul_f32 v[16:17], v[16:17], v[114:115]
	v_cvt_f32_i32_e32 v12, v12
	v_cvt_f32_i32_e32 v13, v13
	v_pk_mul_f32 v[18:19], v[18:19], v[112:113]
	v_cvt_f32_i32_e32 v14, v14
	v_cvt_f32_i32_e32 v15, v15
	v_cvt_f32_i32_e32 v8, v8
	v_cvt_f32_i32_e32 v9, v9
	v_cvt_f32_i32_e32 v10, v10
	v_cvt_f32_i32_e32 v11, v11
	v_cvt_f32_i32_e32 v4, v4
	v_pk_mul_f32 v[8:9], v[8:9], v[122:123]
	v_cvt_f32_i32_e32 v5, v5
	v_pk_mul_f32 v[10:11], v[10:11], v[120:121]
	v_cvt_f32_i32_e32 v0, v0
	v_cvt_f32_i32_e32 v1, v1
	v_pk_mul_f32 v[4:5], v[4:5], v[118:119]
	v_cvt_f32_i32_e32 v2, v2
	v_cvt_f32_i32_e32 v3, v3
	v_pk_mul_f32 v[0:1], v[0:1], v[114:115]
	v_pk_mul_f32 v[2:3], v[2:3], v[112:113]
	s_waitcnt vmcnt(0)
	v_pk_mul_f32 v[164:165], v[164:165], v[126:127] op_sel_hi:[1,0]
	v_pk_mul_f32 v[162:163], v[162:163], v[126:127] op_sel_hi:[1,0]
	v_mul_f32_e32 v127, 0xbfb8aa3b, v164
	v_mul_f32_e32 v156, 0xbfb8aa3b, v165
	v_mul_f32_e32 v161, 0xbfb8aa3b, v162
	v_mul_f32_e32 v165, 0xbfb8aa3b, v163
	v_exp_f32_e32 v162, v127
	v_exp_f32_e32 v163, v156
	v_exp_f32_e32 v164, v161
	v_exp_f32_e32 v165, v165
	v_lshlrev_b32_e32 v166, 16, v134
	v_pk_add_f32 v[162:163], v[162:163], 1.0 op_sel_hi:[1,0]
	v_and_b32_e32 v167, 0xffff0000, v134
	v_pk_add_f32 v[164:165], v[164:165], 1.0 op_sel_hi:[1,0]
	s_mov_b64 vcc, s[0:1]
	v_rcp_f32_e32 v127, v163
	s_nop 0
	v_mul_f32_e32 v163, 1.0, v127
	s_mov_b64 vcc, s[10:11]
	v_rcp_f32_e32 v127, v162
	s_nop 0
	v_mul_f32_e32 v162, 1.0, v127
	s_mov_b64 vcc, s[12:13]
	v_pk_fma_f32 v[152:153], v[162:163], v[166:167], v[152:153]
	v_rcp_f32_e32 v127, v165
	s_nop 0
	v_mul_f32_e32 v163, 1.0, v127
	v_lshlrev_b32_e32 v134, 16, v135
	v_and_b32_e32 v135, 0xffff0000, v135
	v_rcp_f32_e32 v127, v164
	s_nop 0
	v_mul_f32_e32 v162, 1.0, v127
	v_pk_fma_f32 v[154:155], v[162:163], v[134:135], v[154:155]
	global_store_dwordx4 v[124:125], v[152:155], off
	global_load_dwordx2 v[134:135], v[132:133], off offset:32
	v_pk_mul_f32 v[104:105], v[104:105], v[126:127] op_sel_hi:[1,0]
	v_pk_mul_f32 v[106:107], v[106:107], v[126:127] op_sel_hi:[1,0]
	v_mul_f32_e32 v104, 0xbfb8aa3b, v104
	v_mul_f32_e32 v105, 0xbfb8aa3b, v105
	v_exp_f32_e32 v104, v104
	v_exp_f32_e32 v105, v105
	v_mul_f32_e32 v106, 0xbfb8aa3b, v106
	v_mul_f32_e32 v107, 0xbfb8aa3b, v107
	v_exp_f32_e32 v106, v106
	v_exp_f32_e32 v107, v107
	v_pk_add_f32 v[104:105], v[104:105], 1.0 op_sel_hi:[1,0]
	v_pk_add_f32 v[106:107], v[106:107], 1.0 op_sel_hi:[1,0]
	s_mov_b64 vcc, s[0:1]
	v_rcp_f32_e32 v127, v105
	s_nop 0
	v_mul_f32_e32 v105, 1.0, v127
	s_mov_b64 vcc, s[10:11]
	v_rcp_f32_e32 v127, v104
	s_nop 0
	v_mul_f32_e32 v104, 1.0, v127
	s_mov_b64 vcc, s[12:13]
	v_rcp_f32_e32 v127, v107
	s_nop 0
	v_mul_f32_e32 v107, 1.0, v127
	v_rcp_f32_e32 v127, v106
	s_nop 0
	v_mul_f32_e32 v106, 1.0, v127
	v_pk_mul_f32 v[100:101], v[100:101], v[126:127] op_sel_hi:[1,0]
	s_waitcnt vmcnt(0)
	v_lshlrev_b32_e32 v152, 16, v134
	v_and_b32_e32 v153, 0xffff0000, v134
	v_lshlrev_b32_e32 v134, 16, v135
	v_and_b32_e32 v135, 0xffff0000, v135
	v_pk_fma_f32 v[104:105], v[104:105], v[152:153], v[108:109]
	v_pk_fma_f32 v[106:107], v[106:107], v[134:135], v[110:111]
	global_store_dwordx4 v[124:125], v[104:107], off offset:64
	global_load_dwordx2 v[110:111], v[132:133], off offset:256
	v_mul_f32_e32 v100, 0xbfb8aa3b, v100
	v_cvt_f32_i32_e32 v106, v102
	v_cvt_f32_i32_e32 v107, v103
	global_load_dwordx4 v[102:105], v[124:125], off offset:512
	v_mul_f32_e32 v101, 0xbfb8aa3b, v101
	v_exp_f32_e32 v100, v100
	v_pk_mul_f32 v[106:107], v[106:107], v[116:117]
	v_exp_f32_e32 v101, v101
	v_pk_mul_f32 v[106:107], v[106:107], v[126:127] op_sel_hi:[1,0]
	v_pk_add_f32 v[100:101], v[100:101], 1.0 op_sel_hi:[1,0]
	v_mul_f32_e32 v106, 0xbfb8aa3b, v106
	v_mul_f32_e32 v107, 0xbfb8aa3b, v107
	v_exp_f32_e32 v134, v106
	v_exp_f32_e32 v135, v107
	s_nop 0
	v_pk_add_f32 v[134:135], v[134:135], 1.0 op_sel_hi:[1,0]
	s_mov_b64 vcc, s[0:1]
	v_rcp_f32_e32 v127, v101
	s_nop 0
	v_mul_f32_e32 v101, 1.0, v127
	s_mov_b64 vcc, s[10:11]
	v_rcp_f32_e32 v127, v100
	s_nop 0
	v_mul_f32_e32 v100, 1.0, v127
	s_mov_b64 vcc, s[12:13]
	v_rcp_f32_e32 v127, v135
	s_nop 0
	v_mul_f32_e32 v135, 1.0, v127
	v_rcp_f32_e32 v127, v134
	s_nop 0
	v_mul_f32_e32 v134, 1.0, v127
	global_load_dwordx4 v[106:109], v[124:125], off offset:576
	v_pk_mul_f32 v[96:97], v[96:97], v[126:127] op_sel_hi:[1,0]
	v_pk_mul_f32 v[98:99], v[98:99], v[126:127] op_sel_hi:[1,0]
	v_mul_f32_e32 v96, 0xbfb8aa3b, v96
	v_mul_f32_e32 v97, 0xbfb8aa3b, v97
	v_exp_f32_e32 v96, v96
	v_exp_f32_e32 v97, v97
	s_waitcnt vmcnt(0)
	v_lshlrev_b32_e32 v152, 16, v110
	v_and_b32_e32 v153, 0xffff0000, v110
	v_lshlrev_b32_e32 v110, 16, v111
	v_and_b32_e32 v111, 0xffff0000, v111
	v_pk_fma_f32 v[100:101], v[100:101], v[152:153], v[102:103]
	v_pk_fma_f32 v[102:103], v[134:135], v[110:111], v[104:105]
	global_store_dwordx4 v[124:125], v[100:103], off offset:512
	global_load_dwordx2 v[100:101], v[132:133], off offset:288
	v_mul_f32_e32 v98, 0xbfb8aa3b, v98
	v_mul_f32_e32 v99, 0xbfb8aa3b, v99
	v_exp_f32_e32 v98, v98
	v_exp_f32_e32 v99, v99
	v_pk_add_f32 v[96:97], v[96:97], 1.0 op_sel_hi:[1,0]
	v_pk_add_f32 v[98:99], v[98:99], 1.0 op_sel_hi:[1,0]
	s_mov_b64 vcc, s[0:1]
	v_rcp_f32_e32 v102, v97
	s_nop 0
	v_mul_f32_e32 v97, 1.0, v102
	s_mov_b64 vcc, s[10:11]
	v_rcp_f32_e32 v102, v96
	s_nop 0
	v_mul_f32_e32 v96, 1.0, v102
	s_mov_b64 vcc, s[12:13]
	v_rcp_f32_e32 v102, v99
	s_nop 0
	v_mul_f32_e32 v99, 1.0, v102
	v_rcp_f32_e32 v102, v98
	s_nop 0
	v_mul_f32_e32 v98, 1.0, v102
	v_pk_mul_f32 v[110:111], v[92:93], v[128:129]
	s_waitcnt vmcnt(0)
	v_lshlrev_b32_e32 v102, 16, v100
	v_and_b32_e32 v103, 0xffff0000, v100
	v_lshlrev_b32_e32 v100, 16, v101
	v_and_b32_e32 v101, 0xffff0000, v101
	v_pk_fma_f32 v[96:97], v[96:97], v[102:103], v[106:107]
	v_pk_fma_f32 v[98:99], v[98:99], v[100:101], v[108:109]
	global_store_dwordx4 v[124:125], v[96:99], off offset:576
	global_load_dword v98, v[150:151], off offset:128
	v_lshl_add_u64 v[100:101], v[140:141], 1, s[54:55]
	global_load_dwordx2 v[106:107], v[100:101], off
	v_lshl_add_u64 v[96:97], v[140:141], 2, s[70:71]
	global_load_dwordx4 v[102:105], v[96:97], off
	v_pk_mul_f32 v[108:109], v[94:95], v[130:131]
	global_load_dwordx4 v[92:95], v[96:97], off offset:64
	v_add_u32_e32 v140, 0x10000, v140
	s_waitcnt vmcnt(0)
	v_pk_mul_f32 v[110:111], v[110:111], v[98:99] op_sel_hi:[1,0]
	v_pk_mul_f32 v[108:109], v[108:109], v[98:99] op_sel_hi:[1,0]
	v_mul_f32_e32 v99, 0xbfb8aa3b, v110
	v_mul_f32_e32 v110, 0xbfb8aa3b, v111
	v_mul_f32_e32 v111, 0xbfb8aa3b, v108
	v_mul_f32_e32 v124, 0xbfb8aa3b, v109
	v_exp_f32_e32 v108, v99
	v_exp_f32_e32 v109, v110
	v_exp_f32_e32 v110, v111
	v_exp_f32_e32 v111, v124
	v_lshlrev_b32_e32 v124, 16, v106
	v_pk_add_f32 v[108:109], v[108:109], 1.0 op_sel_hi:[1,0]
	v_and_b32_e32 v125, 0xffff0000, v106
	v_pk_add_f32 v[110:111], v[110:111], 1.0 op_sel_hi:[1,0]
	s_mov_b64 vcc, s[0:1]
	v_rcp_f32_e32 v99, v109
	s_nop 0
	v_mul_f32_e32 v109, 1.0, v99
	s_mov_b64 vcc, s[10:11]
	v_rcp_f32_e32 v99, v108
	s_nop 0
	v_mul_f32_e32 v108, 1.0, v99
	s_mov_b64 vcc, s[12:13]
	v_pk_fma_f32 v[102:103], v[108:109], v[124:125], v[102:103]
	v_rcp_f32_e32 v99, v111
	s_nop 0
	v_mul_f32_e32 v109, 1.0, v99
	v_lshlrev_b32_e32 v106, 16, v107
	v_and_b32_e32 v107, 0xffff0000, v107
	v_rcp_f32_e32 v99, v110
	s_nop 0
	v_mul_f32_e32 v108, 1.0, v99
	v_pk_fma_f32 v[104:105], v[108:109], v[106:107], v[104:105]
	global_store_dwordx4 v[96:97], v[102:105], off
	global_load_dwordx2 v[102:103], v[100:101], off offset:32
	v_pk_mul_f32 v[88:89], v[88:89], v[98:99] op_sel_hi:[1,0]
	v_pk_mul_f32 v[90:91], v[90:91], v[98:99] op_sel_hi:[1,0]
	v_mul_f32_e32 v88, 0xbfb8aa3b, v88
	v_mul_f32_e32 v89, 0xbfb8aa3b, v89
	v_exp_f32_e32 v88, v88
	v_exp_f32_e32 v89, v89
	v_mul_f32_e32 v90, 0xbfb8aa3b, v90
	v_mul_f32_e32 v91, 0xbfb8aa3b, v91
	v_exp_f32_e32 v90, v90
	v_exp_f32_e32 v91, v91
	v_pk_add_f32 v[88:89], v[88:89], 1.0 op_sel_hi:[1,0]
	v_pk_add_f32 v[90:91], v[90:91], 1.0 op_sel_hi:[1,0]
	s_mov_b64 vcc, s[0:1]
	v_rcp_f32_e32 v99, v89
	s_nop 0
	v_mul_f32_e32 v89, 1.0, v99
	s_mov_b64 vcc, s[10:11]
	v_rcp_f32_e32 v99, v88
	s_nop 0
	v_mul_f32_e32 v88, 1.0, v99
	s_mov_b64 vcc, s[12:13]
	v_rcp_f32_e32 v99, v91
	s_nop 0
	v_mul_f32_e32 v91, 1.0, v99
	v_rcp_f32_e32 v99, v90
	s_nop 0
	v_mul_f32_e32 v90, 1.0, v99
	v_pk_mul_f32 v[84:85], v[84:85], v[98:99] op_sel_hi:[1,0]
	s_waitcnt vmcnt(0)
	v_lshlrev_b32_e32 v104, 16, v102
	v_and_b32_e32 v105, 0xffff0000, v102
	v_lshlrev_b32_e32 v102, 16, v103
	v_and_b32_e32 v103, 0xffff0000, v103
	v_pk_fma_f32 v[88:89], v[88:89], v[104:105], v[92:93]
	v_pk_fma_f32 v[90:91], v[90:91], v[102:103], v[94:95]
	global_store_dwordx4 v[96:97], v[88:91], off offset:64
	global_load_dwordx2 v[94:95], v[100:101], off offset:256
	v_mul_f32_e32 v84, 0xbfb8aa3b, v84
	v_cvt_f32_i32_e32 v90, v86
	v_cvt_f32_i32_e32 v91, v87
	global_load_dwordx4 v[86:89], v[96:97], off offset:512
	v_mul_f32_e32 v85, 0xbfb8aa3b, v85
	v_exp_f32_e32 v84, v84
	v_pk_mul_f32 v[90:91], v[90:91], v[116:117]
	v_exp_f32_e32 v85, v85
	v_pk_mul_f32 v[90:91], v[90:91], v[98:99] op_sel_hi:[1,0]
	v_pk_add_f32 v[84:85], v[84:85], 1.0 op_sel_hi:[1,0]
	v_mul_f32_e32 v90, 0xbfb8aa3b, v90
	v_mul_f32_e32 v91, 0xbfb8aa3b, v91
	v_exp_f32_e32 v102, v90
	v_exp_f32_e32 v103, v91
	s_nop 0
	v_pk_add_f32 v[102:103], v[102:103], 1.0 op_sel_hi:[1,0]
	s_mov_b64 vcc, s[0:1]
	v_rcp_f32_e32 v99, v85
	s_nop 0
	v_mul_f32_e32 v85, 1.0, v99
	s_mov_b64 vcc, s[10:11]
	v_rcp_f32_e32 v99, v84
	s_nop 0
	v_mul_f32_e32 v84, 1.0, v99
	s_mov_b64 vcc, s[12:13]
	v_rcp_f32_e32 v99, v103
	s_nop 0
	v_mul_f32_e32 v103, 1.0, v99
	v_rcp_f32_e32 v99, v102
	s_nop 0
	v_mul_f32_e32 v102, 1.0, v99
	global_load_dwordx4 v[90:93], v[96:97], off offset:576
	v_pk_mul_f32 v[80:81], v[80:81], v[98:99] op_sel_hi:[1,0]
	v_pk_mul_f32 v[82:83], v[82:83], v[98:99] op_sel_hi:[1,0]
	v_mul_f32_e32 v80, 0xbfb8aa3b, v80
	v_mul_f32_e32 v81, 0xbfb8aa3b, v81
	v_exp_f32_e32 v80, v80
	v_exp_f32_e32 v81, v81
	s_waitcnt vmcnt(0)
	v_lshlrev_b32_e32 v104, 16, v94
	v_and_b32_e32 v105, 0xffff0000, v94
	v_lshlrev_b32_e32 v94, 16, v95
	v_and_b32_e32 v95, 0xffff0000, v95
	v_pk_fma_f32 v[84:85], v[84:85], v[104:105], v[86:87]
	v_pk_fma_f32 v[86:87], v[102:103], v[94:95], v[88:89]
	global_store_dwordx4 v[96:97], v[84:87], off offset:512
	global_load_dwordx2 v[84:85], v[100:101], off offset:288
	v_mul_f32_e32 v82, 0xbfb8aa3b, v82
	v_mul_f32_e32 v83, 0xbfb8aa3b, v83
	v_exp_f32_e32 v82, v82
	v_exp_f32_e32 v83, v83
	v_pk_add_f32 v[80:81], v[80:81], 1.0 op_sel_hi:[1,0]
	v_pk_add_f32 v[82:83], v[82:83], 1.0 op_sel_hi:[1,0]
	s_mov_b64 vcc, s[0:1]
	v_rcp_f32_e32 v86, v81
	s_nop 0
	v_mul_f32_e32 v81, 1.0, v86
	s_mov_b64 vcc, s[10:11]
	v_rcp_f32_e32 v86, v80
	s_nop 0
	v_mul_f32_e32 v80, 1.0, v86
	s_mov_b64 vcc, s[12:13]
	v_rcp_f32_e32 v86, v83
	s_nop 0
	v_mul_f32_e32 v83, 1.0, v86
	v_rcp_f32_e32 v86, v82
	s_nop 0
	v_mul_f32_e32 v82, 1.0, v86
	v_pk_mul_f32 v[94:95], v[76:77], v[128:129]
	s_waitcnt vmcnt(0)
	v_lshlrev_b32_e32 v86, 16, v84
	v_and_b32_e32 v87, 0xffff0000, v84
	v_lshlrev_b32_e32 v84, 16, v85
	v_and_b32_e32 v85, 0xffff0000, v85
	v_pk_fma_f32 v[80:81], v[80:81], v[86:87], v[90:91]
	v_pk_fma_f32 v[82:83], v[82:83], v[84:85], v[92:93]
	global_store_dwordx4 v[96:97], v[80:83], off offset:576
	global_load_dword v82, v[150:151], off offset:192
	v_lshl_add_u64 v[84:85], v[140:141], 1, s[54:55]
	global_load_dwordx2 v[90:91], v[84:85], off
	v_lshl_add_u64 v[80:81], v[140:141], 2, s[70:71]
	global_load_dwordx4 v[86:89], v[80:81], off
	v_pk_mul_f32 v[92:93], v[78:79], v[130:131]
	global_load_dwordx4 v[76:79], v[80:81], off offset:64
	s_waitcnt vmcnt(0)
	v_pk_mul_f32 v[94:95], v[94:95], v[82:83] op_sel_hi:[1,0]
	v_pk_mul_f32 v[92:93], v[92:93], v[82:83] op_sel_hi:[1,0]
	v_mul_f32_e32 v83, 0xbfb8aa3b, v94
	v_mul_f32_e32 v94, 0xbfb8aa3b, v95
	v_mul_f32_e32 v95, 0xbfb8aa3b, v92
	v_mul_f32_e32 v96, 0xbfb8aa3b, v93
	v_exp_f32_e32 v92, v83
	v_exp_f32_e32 v93, v94
	v_exp_f32_e32 v94, v95
	v_exp_f32_e32 v95, v96
	v_lshlrev_b32_e32 v96, 16, v90
	v_pk_add_f32 v[92:93], v[92:93], 1.0 op_sel_hi:[1,0]
	v_and_b32_e32 v97, 0xffff0000, v90
	v_pk_add_f32 v[94:95], v[94:95], 1.0 op_sel_hi:[1,0]
	s_mov_b64 vcc, s[0:1]
	v_rcp_f32_e32 v83, v93
	s_nop 0
	v_mul_f32_e32 v93, 1.0, v83
	s_mov_b64 vcc, s[10:11]
	v_rcp_f32_e32 v83, v92
	s_nop 0
	v_mul_f32_e32 v92, 1.0, v83
	s_mov_b64 vcc, s[12:13]
	v_pk_fma_f32 v[86:87], v[92:93], v[96:97], v[86:87]
	v_rcp_f32_e32 v83, v95
	s_nop 0
	v_mul_f32_e32 v93, 1.0, v83
	v_lshlrev_b32_e32 v90, 16, v91
	v_and_b32_e32 v91, 0xffff0000, v91
	v_rcp_f32_e32 v83, v94
	s_nop 0
	v_mul_f32_e32 v92, 1.0, v83
	v_pk_fma_f32 v[88:89], v[92:93], v[90:91], v[88:89]
	global_store_dwordx4 v[80:81], v[86:89], off
	global_load_dwordx2 v[86:87], v[84:85], off offset:32
	v_pk_mul_f32 v[72:73], v[72:73], v[82:83] op_sel_hi:[1,0]
	v_pk_mul_f32 v[74:75], v[74:75], v[82:83] op_sel_hi:[1,0]
	v_mul_f32_e32 v72, 0xbfb8aa3b, v72
	v_mul_f32_e32 v73, 0xbfb8aa3b, v73
	v_exp_f32_e32 v72, v72
	v_exp_f32_e32 v73, v73
	v_mul_f32_e32 v74, 0xbfb8aa3b, v74
	v_mul_f32_e32 v75, 0xbfb8aa3b, v75
	v_exp_f32_e32 v74, v74
	v_exp_f32_e32 v75, v75
	v_pk_add_f32 v[72:73], v[72:73], 1.0 op_sel_hi:[1,0]
	v_pk_add_f32 v[74:75], v[74:75], 1.0 op_sel_hi:[1,0]
	s_mov_b64 vcc, s[0:1]
	v_rcp_f32_e32 v83, v73
	s_nop 0
	v_mul_f32_e32 v73, 1.0, v83
	s_mov_b64 vcc, s[10:11]
	v_rcp_f32_e32 v83, v72
	s_nop 0
	v_mul_f32_e32 v72, 1.0, v83
	s_mov_b64 vcc, s[12:13]
	v_rcp_f32_e32 v83, v75
	s_nop 0
	v_mul_f32_e32 v75, 1.0, v83
	v_rcp_f32_e32 v83, v74
	s_nop 0
	v_mul_f32_e32 v74, 1.0, v83
	v_pk_mul_f32 v[68:69], v[68:69], v[82:83] op_sel_hi:[1,0]
	s_waitcnt vmcnt(0)
	v_lshlrev_b32_e32 v88, 16, v86
	v_and_b32_e32 v89, 0xffff0000, v86
	v_lshlrev_b32_e32 v86, 16, v87
	v_and_b32_e32 v87, 0xffff0000, v87
	v_pk_fma_f32 v[72:73], v[72:73], v[88:89], v[76:77]
	v_pk_fma_f32 v[74:75], v[74:75], v[86:87], v[78:79]
	global_store_dwordx4 v[80:81], v[72:75], off offset:64
	global_load_dwordx2 v[78:79], v[84:85], off offset:256
	v_mul_f32_e32 v68, 0xbfb8aa3b, v68
	v_cvt_f32_i32_e32 v74, v70
	v_cvt_f32_i32_e32 v75, v71
	global_load_dwordx4 v[70:73], v[80:81], off offset:512
	v_mul_f32_e32 v69, 0xbfb8aa3b, v69
	v_exp_f32_e32 v68, v68
	v_pk_mul_f32 v[74:75], v[74:75], v[116:117]
	v_exp_f32_e32 v69, v69
	v_pk_mul_f32 v[74:75], v[74:75], v[82:83] op_sel_hi:[1,0]
	v_pk_add_f32 v[68:69], v[68:69], 1.0 op_sel_hi:[1,0]
	v_mul_f32_e32 v74, 0xbfb8aa3b, v74
	v_mul_f32_e32 v75, 0xbfb8aa3b, v75
	v_exp_f32_e32 v86, v74
	v_exp_f32_e32 v87, v75
	s_nop 0
	v_pk_add_f32 v[86:87], v[86:87], 1.0 op_sel_hi:[1,0]
	s_mov_b64 vcc, s[0:1]
	v_rcp_f32_e32 v83, v69
	s_nop 0
	v_mul_f32_e32 v69, 1.0, v83
	s_mov_b64 vcc, s[10:11]
	v_rcp_f32_e32 v83, v68
	s_nop 0
	v_mul_f32_e32 v68, 1.0, v83
	s_mov_b64 vcc, s[12:13]
	v_rcp_f32_e32 v83, v87
	s_nop 0
	v_mul_f32_e32 v87, 1.0, v83
	v_rcp_f32_e32 v83, v86
	s_nop 0
	v_mul_f32_e32 v86, 1.0, v83
	global_load_dwordx4 v[74:77], v[80:81], off offset:576
	v_pk_mul_f32 v[64:65], v[64:65], v[82:83] op_sel_hi:[1,0]
	v_pk_mul_f32 v[66:67], v[66:67], v[82:83] op_sel_hi:[1,0]
	v_mul_f32_e32 v64, 0xbfb8aa3b, v64
	v_mul_f32_e32 v65, 0xbfb8aa3b, v65
	v_exp_f32_e32 v64, v64
	v_exp_f32_e32 v65, v65
	s_waitcnt vmcnt(0)
	v_lshlrev_b32_e32 v88, 16, v78
	v_and_b32_e32 v89, 0xffff0000, v78
	v_lshlrev_b32_e32 v78, 16, v79
	v_and_b32_e32 v79, 0xffff0000, v79
	v_pk_fma_f32 v[68:69], v[68:69], v[88:89], v[70:71]
	v_pk_fma_f32 v[70:71], v[86:87], v[78:79], v[72:73]
	global_store_dwordx4 v[80:81], v[68:71], off offset:512
	global_load_dwordx2 v[68:69], v[84:85], off offset:288
	v_mul_f32_e32 v66, 0xbfb8aa3b, v66
	v_mul_f32_e32 v67, 0xbfb8aa3b, v67
	v_exp_f32_e32 v70, v66
	v_exp_f32_e32 v71, v67
	v_pk_add_f32 v[64:65], v[64:65], 1.0 op_sel_hi:[1,0]
	v_add_u32_e32 v67, 0x10000, v140
	v_pk_add_f32 v[70:71], v[70:71], 1.0 op_sel_hi:[1,0]
	s_mov_b64 vcc, s[0:1]
	v_rcp_f32_e32 v66, v65
	s_nop 0
	v_mul_f32_e32 v65, 1.0, v66
	s_mov_b64 vcc, s[10:11]
	v_rcp_f32_e32 v66, v64
	s_nop 0
	v_mul_f32_e32 v64, 1.0, v66
	s_mov_b64 vcc, s[12:13]
	v_rcp_f32_e32 v66, v71
	s_nop 0
	v_mul_f32_e32 v71, 1.0, v66
	v_rcp_f32_e32 v66, v70
	s_nop 0
	v_mul_f32_e32 v70, 1.0, v66
	s_waitcnt vmcnt(0)
	v_lshlrev_b32_e32 v72, 16, v68
	v_and_b32_e32 v73, 0xffff0000, v68
	v_lshlrev_b32_e32 v78, 16, v69
	v_and_b32_e32 v79, 0xffff0000, v69
	v_pk_fma_f32 v[68:69], v[64:65], v[72:73], v[74:75]
	v_pk_fma_f32 v[70:71], v[70:71], v[78:79], v[76:77]
	global_store_dwordx4 v[80:81], v[68:71], off offset:576
	global_load_dword v66, v[150:151], off offset:512
	v_add_u32_e32 v140, 0x40000, v67
	v_lshl_add_u64 v[68:69], v[140:141], 1, s[54:55]
	global_load_dwordx2 v[74:75], v[68:69], off
	v_lshl_add_u64 v[64:65], v[140:141], 2, s[70:71]
	global_load_dwordx4 v[70:73], v[64:65], off
	v_pk_mul_f32 v[78:79], v[60:61], v[128:129]
	v_pk_mul_f32 v[76:77], v[62:63], v[130:131]
	global_load_dwordx4 v[60:63], v[64:65], off offset:64
	v_add_u32_e32 v140, 0x50000, v67
	s_waitcnt vmcnt(0)
	v_pk_mul_f32 v[78:79], v[78:79], v[66:67] op_sel_hi:[1,0]
	v_pk_mul_f32 v[76:77], v[76:77], v[66:67] op_sel_hi:[1,0]
	v_mul_f32_e32 v78, 0xbfb8aa3b, v78
	v_mul_f32_e32 v79, 0xbfb8aa3b, v79
	v_mul_f32_e32 v80, 0xbfb8aa3b, v76
	v_mul_f32_e32 v81, 0xbfb8aa3b, v77
	v_exp_f32_e32 v76, v78
	v_exp_f32_e32 v77, v79
	v_exp_f32_e32 v78, v80
	v_exp_f32_e32 v79, v81
	v_lshlrev_b32_e32 v80, 16, v74
	v_pk_add_f32 v[76:77], v[76:77], 1.0 op_sel_hi:[1,0]
	v_and_b32_e32 v81, 0xffff0000, v74
	v_pk_add_f32 v[78:79], v[78:79], 1.0 op_sel_hi:[1,0]
	s_mov_b64 vcc, s[0:1]
	v_rcp_f32_e32 v82, v77
	s_nop 0
	v_mul_f32_e32 v77, 1.0, v82
	s_mov_b64 vcc, s[10:11]
	v_rcp_f32_e32 v82, v76
	s_nop 0
	v_mul_f32_e32 v76, 1.0, v82
	s_mov_b64 vcc, s[12:13]
	v_pk_fma_f32 v[70:71], v[76:77], v[80:81], v[70:71]
	v_lshlrev_b32_e32 v74, 16, v75
	v_and_b32_e32 v75, 0xffff0000, v75
	v_rcp_f32_e32 v82, v79
	s_nop 0
	v_mul_f32_e32 v77, 1.0, v82
	v_rcp_f32_e32 v76, v78
	s_nop 0
	v_mul_f32_e32 v76, 1.0, v76
	v_pk_fma_f32 v[72:73], v[76:77], v[74:75], v[72:73]
	global_store_dwordx4 v[64:65], v[70:73], off
	global_load_dwordx2 v[70:71], v[68:69], off offset:32
	v_pk_mul_f32 v[56:57], v[56:57], v[66:67] op_sel_hi:[1,0]
	v_pk_mul_f32 v[58:59], v[58:59], v[66:67] op_sel_hi:[1,0]
	v_mul_f32_e32 v56, 0xbfb8aa3b, v56
	v_mul_f32_e32 v57, 0xbfb8aa3b, v57
	v_exp_f32_e32 v56, v56
	v_exp_f32_e32 v57, v57
	v_mul_f32_e32 v58, 0xbfb8aa3b, v58
	v_mul_f32_e32 v59, 0xbfb8aa3b, v59
	v_exp_f32_e32 v58, v58
	v_exp_f32_e32 v59, v59
	v_pk_add_f32 v[56:57], v[56:57], 1.0 op_sel_hi:[1,0]
	v_pk_mul_f32 v[52:53], v[52:53], v[66:67] op_sel_hi:[1,0]
	v_pk_add_f32 v[58:59], v[58:59], 1.0 op_sel_hi:[1,0]
	s_mov_b64 vcc, s[0:1]
	v_rcp_f32_e32 v72, v57
	s_nop 0
	v_mul_f32_e32 v57, 1.0, v72
	s_mov_b64 vcc, s[10:11]
	v_rcp_f32_e32 v72, v56
	s_nop 0
	v_mul_f32_e32 v56, 1.0, v72
	s_mov_b64 vcc, s[12:13]
	v_rcp_f32_e32 v72, v59
	s_nop 0
	v_mul_f32_e32 v59, 1.0, v72
	v_rcp_f32_e32 v72, v58
	s_nop 0
	v_mul_f32_e32 v58, 1.0, v72
	v_mul_f32_e32 v52, 0xbfb8aa3b, v52
	v_mul_f32_e32 v53, 0xbfb8aa3b, v53
	v_exp_f32_e32 v52, v52
	v_exp_f32_e32 v53, v53
	v_pk_mul_f32 v[48:49], v[48:49], v[66:67] op_sel_hi:[1,0]
	v_pk_mul_f32 v[50:51], v[50:51], v[66:67] op_sel_hi:[1,0]
	v_mul_f32_e32 v48, 0xbfb8aa3b, v48
	v_pk_add_f32 v[52:53], v[52:53], 1.0 op_sel_hi:[1,0]
	v_mul_f32_e32 v49, 0xbfb8aa3b, v49
	s_waitcnt vmcnt(0)
	v_lshlrev_b32_e32 v72, 16, v70
	v_and_b32_e32 v73, 0xffff0000, v70
	v_lshlrev_b32_e32 v70, 16, v71
	v_and_b32_e32 v71, 0xffff0000, v71
	v_pk_fma_f32 v[56:57], v[56:57], v[72:73], v[60:61]
	v_pk_fma_f32 v[58:59], v[58:59], v[70:71], v[62:63]
	global_store_dwordx4 v[64:65], v[56:59], off offset:64
	global_load_dwordx2 v[62:63], v[68:69], off offset:256
	s_nop 1
	v_cvt_f32_i32_e32 v58, v54
	v_cvt_f32_i32_e32 v59, v55
	global_load_dwordx4 v[54:57], v[64:65], off offset:512
	v_pk_mul_f32 v[58:59], v[58:59], v[116:117]
	v_pk_mul_f32 v[58:59], v[58:59], v[66:67] op_sel_hi:[1,0]
	v_mul_f32_e32 v58, 0xbfb8aa3b, v58
	v_mul_f32_e32 v59, 0xbfb8aa3b, v59
	v_exp_f32_e32 v70, v58
	v_exp_f32_e32 v71, v59
	s_nop 0
	v_pk_add_f32 v[70:71], v[70:71], 1.0 op_sel_hi:[1,0]
	s_mov_b64 vcc, s[0:1]
	v_rcp_f32_e32 v72, v53
	s_nop 0
	v_mul_f32_e32 v53, 1.0, v72
	s_mov_b64 vcc, s[10:11]
	v_rcp_f32_e32 v72, v52
	s_nop 0
	v_mul_f32_e32 v52, 1.0, v72
	s_mov_b64 vcc, s[12:13]
	v_rcp_f32_e32 v72, v71
	s_nop 0
	v_mul_f32_e32 v71, 1.0, v72
	v_rcp_f32_e32 v72, v70
	s_nop 0
	v_mul_f32_e32 v70, 1.0, v72
	global_load_dwordx4 v[58:61], v[64:65], off offset:576
	v_exp_f32_e32 v48, v48
	v_exp_f32_e32 v49, v49
	v_mul_f32_e32 v50, 0xbfb8aa3b, v50
	v_mul_f32_e32 v51, 0xbfb8aa3b, v51
	v_exp_f32_e32 v50, v50
	v_exp_f32_e32 v51, v51
	v_pk_add_f32 v[48:49], v[48:49], 1.0 op_sel_hi:[1,0]
	v_pk_add_f32 v[50:51], v[50:51], 1.0 op_sel_hi:[1,0]
	s_nop 0
	s_waitcnt vmcnt(0)
	v_lshlrev_b32_e32 v72, 16, v62
	v_and_b32_e32 v73, 0xffff0000, v62
	v_lshlrev_b32_e32 v62, 16, v63
	v_and_b32_e32 v63, 0xffff0000, v63
	v_pk_fma_f32 v[52:53], v[52:53], v[72:73], v[54:55]
	v_pk_fma_f32 v[54:55], v[70:71], v[62:63], v[56:57]
	global_store_dwordx4 v[64:65], v[52:55], off offset:512
	global_load_dwordx2 v[52:53], v[68:69], off offset:288
	s_mov_b64 vcc, s[0:1]
	v_rcp_f32_e32 v54, v49
	s_nop 0
	v_mul_f32_e32 v49, 1.0, v54
	s_mov_b64 vcc, s[10:11]
	v_rcp_f32_e32 v54, v48
	s_nop 0
	v_mul_f32_e32 v48, 1.0, v54
	s_mov_b64 vcc, s[12:13]
	v_rcp_f32_e32 v54, v51
	s_nop 0
	v_mul_f32_e32 v51, 1.0, v54
	v_rcp_f32_e32 v54, v50
	s_nop 0
	v_mul_f32_e32 v50, 1.0, v54
	v_pk_mul_f32 v[62:63], v[44:45], v[128:129]
	s_waitcnt vmcnt(0)
	v_lshlrev_b32_e32 v54, 16, v52
	v_and_b32_e32 v55, 0xffff0000, v52
	v_lshlrev_b32_e32 v52, 16, v53
	v_and_b32_e32 v53, 0xffff0000, v53
	v_pk_fma_f32 v[48:49], v[48:49], v[54:55], v[58:59]
	v_pk_fma_f32 v[50:51], v[50:51], v[52:53], v[60:61]
	global_store_dwordx4 v[64:65], v[48:51], off offset:576
	global_load_dword v50, v[150:151], off offset:576
	v_lshl_add_u64 v[52:53], v[140:141], 1, s[54:55]
	global_load_dwordx2 v[58:59], v[52:53], off
	v_lshl_add_u64 v[48:49], v[140:141], 2, s[70:71]
	global_load_dwordx4 v[54:57], v[48:49], off
	v_pk_mul_f32 v[60:61], v[46:47], v[130:131]
	global_load_dwordx4 v[44:47], v[48:49], off offset:64
	v_add_u32_e32 v140, 0x10000, v140
	s_waitcnt vmcnt(0)
	v_pk_mul_f32 v[62:63], v[62:63], v[50:51] op_sel_hi:[1,0]
	v_pk_mul_f32 v[60:61], v[60:61], v[50:51] op_sel_hi:[1,0]
	v_mul_f32_e32 v51, 0xbfb8aa3b, v62
	v_mul_f32_e32 v62, 0xbfb8aa3b, v63
	v_mul_f32_e32 v63, 0xbfb8aa3b, v60
	v_mul_f32_e32 v64, 0xbfb8aa3b, v61
	v_exp_f32_e32 v60, v51
	v_exp_f32_e32 v61, v62
	v_exp_f32_e32 v62, v63
	v_exp_f32_e32 v63, v64
	v_lshlrev_b32_e32 v64, 16, v58
	v_pk_add_f32 v[60:61], v[60:61], 1.0 op_sel_hi:[1,0]
	v_and_b32_e32 v65, 0xffff0000, v58
	v_pk_add_f32 v[62:63], v[62:63], 1.0 op_sel_hi:[1,0]
	s_mov_b64 vcc, s[0:1]
	v_rcp_f32_e32 v51, v61
	s_nop 0
	v_mul_f32_e32 v61, 1.0, v51
	s_mov_b64 vcc, s[10:11]
	v_rcp_f32_e32 v51, v60
	s_nop 0
	v_mul_f32_e32 v60, 1.0, v51
	s_mov_b64 vcc, s[12:13]
	v_pk_fma_f32 v[54:55], v[60:61], v[64:65], v[54:55]
	v_rcp_f32_e32 v51, v63
	s_nop 0
	v_mul_f32_e32 v61, 1.0, v51
	v_lshlrev_b32_e32 v58, 16, v59
	v_and_b32_e32 v59, 0xffff0000, v59
	v_rcp_f32_e32 v51, v62
	s_nop 0
	v_mul_f32_e32 v60, 1.0, v51
	v_pk_fma_f32 v[56:57], v[60:61], v[58:59], v[56:57]
	global_store_dwordx4 v[48:49], v[54:57], off
	global_load_dwordx2 v[54:55], v[52:53], off offset:32
	v_pk_mul_f32 v[40:41], v[40:41], v[50:51] op_sel_hi:[1,0]
	v_pk_mul_f32 v[42:43], v[42:43], v[50:51] op_sel_hi:[1,0]
	v_mul_f32_e32 v40, 0xbfb8aa3b, v40
	v_mul_f32_e32 v41, 0xbfb8aa3b, v41
	v_exp_f32_e32 v40, v40
	v_exp_f32_e32 v41, v41
	v_mul_f32_e32 v42, 0xbfb8aa3b, v42
	v_mul_f32_e32 v43, 0xbfb8aa3b, v43
	v_exp_f32_e32 v42, v42
	v_exp_f32_e32 v43, v43
	v_pk_add_f32 v[40:41], v[40:41], 1.0 op_sel_hi:[1,0]
	v_pk_add_f32 v[42:43], v[42:43], 1.0 op_sel_hi:[1,0]
	s_mov_b64 vcc, s[0:1]
	v_rcp_f32_e32 v51, v41
	s_nop 0
	v_mul_f32_e32 v41, 1.0, v51
	s_mov_b64 vcc, s[10:11]
	v_rcp_f32_e32 v51, v40
	s_nop 0
	v_mul_f32_e32 v40, 1.0, v51
	s_mov_b64 vcc, s[12:13]
	v_rcp_f32_e32 v51, v43
	s_nop 0
	v_mul_f32_e32 v43, 1.0, v51
	v_rcp_f32_e32 v51, v42
	s_nop 0
	v_mul_f32_e32 v42, 1.0, v51
	v_pk_mul_f32 v[36:37], v[36:37], v[50:51] op_sel_hi:[1,0]
	s_waitcnt vmcnt(0)
	v_lshlrev_b32_e32 v56, 16, v54
	v_and_b32_e32 v57, 0xffff0000, v54
	v_lshlrev_b32_e32 v54, 16, v55
	v_and_b32_e32 v55, 0xffff0000, v55
	v_pk_fma_f32 v[40:41], v[40:41], v[56:57], v[44:45]
	v_pk_fma_f32 v[42:43], v[42:43], v[54:55], v[46:47]
	global_store_dwordx4 v[48:49], v[40:43], off offset:64
	global_load_dwordx2 v[46:47], v[52:53], off offset:256
	v_mul_f32_e32 v36, 0xbfb8aa3b, v36
	v_cvt_f32_i32_e32 v42, v38
	v_cvt_f32_i32_e32 v43, v39
	global_load_dwordx4 v[38:41], v[48:49], off offset:512
	v_mul_f32_e32 v37, 0xbfb8aa3b, v37
	v_exp_f32_e32 v36, v36
	v_pk_mul_f32 v[42:43], v[42:43], v[116:117]
	v_exp_f32_e32 v37, v37
	v_pk_mul_f32 v[42:43], v[42:43], v[50:51] op_sel_hi:[1,0]
	v_pk_add_f32 v[36:37], v[36:37], 1.0 op_sel_hi:[1,0]
	v_mul_f32_e32 v42, 0xbfb8aa3b, v42
	v_mul_f32_e32 v43, 0xbfb8aa3b, v43
	v_exp_f32_e32 v54, v42
	v_exp_f32_e32 v55, v43
	s_nop 0
	v_pk_add_f32 v[54:55], v[54:55], 1.0 op_sel_hi:[1,0]
	s_mov_b64 vcc, s[0:1]
	v_rcp_f32_e32 v51, v37
	s_nop 0
	v_mul_f32_e32 v37, 1.0, v51
	s_mov_b64 vcc, s[10:11]
	v_rcp_f32_e32 v51, v36
	s_nop 0
	v_mul_f32_e32 v36, 1.0, v51
	s_mov_b64 vcc, s[12:13]
	v_rcp_f32_e32 v51, v55
	s_nop 0
	v_mul_f32_e32 v55, 1.0, v51
	v_rcp_f32_e32 v51, v54
	s_nop 0
	v_mul_f32_e32 v54, 1.0, v51
	global_load_dwordx4 v[42:45], v[48:49], off offset:576
	v_pk_mul_f32 v[32:33], v[32:33], v[50:51] op_sel_hi:[1,0]
	v_pk_mul_f32 v[34:35], v[34:35], v[50:51] op_sel_hi:[1,0]
	v_mul_f32_e32 v32, 0xbfb8aa3b, v32
	v_mul_f32_e32 v33, 0xbfb8aa3b, v33
	v_exp_f32_e32 v32, v32
	v_exp_f32_e32 v33, v33
	s_waitcnt vmcnt(0)
	v_lshlrev_b32_e32 v56, 16, v46
	v_and_b32_e32 v57, 0xffff0000, v46
	v_lshlrev_b32_e32 v46, 16, v47
	v_and_b32_e32 v47, 0xffff0000, v47
	v_pk_fma_f32 v[36:37], v[36:37], v[56:57], v[38:39]
	v_pk_fma_f32 v[38:39], v[54:55], v[46:47], v[40:41]
	global_store_dwordx4 v[48:49], v[36:39], off offset:512
	global_load_dwordx2 v[36:37], v[52:53], off offset:288
	v_mul_f32_e32 v34, 0xbfb8aa3b, v34
	v_mul_f32_e32 v35, 0xbfb8aa3b, v35
	v_exp_f32_e32 v34, v34
	v_exp_f32_e32 v35, v35
	v_pk_add_f32 v[32:33], v[32:33], 1.0 op_sel_hi:[1,0]
	v_pk_add_f32 v[34:35], v[34:35], 1.0 op_sel_hi:[1,0]
	s_mov_b64 vcc, s[0:1]
	v_rcp_f32_e32 v38, v33
	s_nop 0
	v_mul_f32_e32 v33, 1.0, v38
	s_mov_b64 vcc, s[10:11]
	v_rcp_f32_e32 v38, v32
	s_nop 0
	v_mul_f32_e32 v32, 1.0, v38
	s_mov_b64 vcc, s[12:13]
	v_rcp_f32_e32 v38, v35
	s_nop 0
	v_mul_f32_e32 v35, 1.0, v38
	v_rcp_f32_e32 v38, v34
	s_nop 0
	v_mul_f32_e32 v34, 1.0, v38
	v_pk_mul_f32 v[46:47], v[28:29], v[128:129]
	s_waitcnt vmcnt(0)
	v_lshlrev_b32_e32 v38, 16, v36
	v_and_b32_e32 v39, 0xffff0000, v36
	v_lshlrev_b32_e32 v36, 16, v37
	v_and_b32_e32 v37, 0xffff0000, v37
	v_pk_fma_f32 v[32:33], v[32:33], v[38:39], v[42:43]
	v_pk_fma_f32 v[34:35], v[34:35], v[36:37], v[44:45]
	global_store_dwordx4 v[48:49], v[32:35], off offset:576
	global_load_dword v34, v[150:151], off offset:640
	v_lshl_add_u64 v[36:37], v[140:141], 1, s[54:55]
	global_load_dwordx2 v[42:43], v[36:37], off
	v_lshl_add_u64 v[32:33], v[140:141], 2, s[70:71]
	global_load_dwordx4 v[38:41], v[32:33], off
	v_pk_mul_f32 v[44:45], v[30:31], v[130:131]
	global_load_dwordx4 v[28:31], v[32:33], off offset:64
	v_add_u32_e32 v140, 0x10000, v140
	s_waitcnt vmcnt(0)
	v_pk_mul_f32 v[46:47], v[46:47], v[34:35] op_sel_hi:[1,0]
	v_pk_mul_f32 v[44:45], v[44:45], v[34:35] op_sel_hi:[1,0]
	v_mul_f32_e32 v35, 0xbfb8aa3b, v46
	v_mul_f32_e32 v46, 0xbfb8aa3b, v47
	v_mul_f32_e32 v47, 0xbfb8aa3b, v44
	v_mul_f32_e32 v48, 0xbfb8aa3b, v45
	v_exp_f32_e32 v44, v35
	v_exp_f32_e32 v45, v46
	v_exp_f32_e32 v46, v47
	v_exp_f32_e32 v47, v48
	v_lshlrev_b32_e32 v48, 16, v42
	v_pk_add_f32 v[44:45], v[44:45], 1.0 op_sel_hi:[1,0]
	v_and_b32_e32 v49, 0xffff0000, v42
	v_pk_add_f32 v[46:47], v[46:47], 1.0 op_sel_hi:[1,0]
	s_mov_b64 vcc, s[0:1]
	v_rcp_f32_e32 v35, v45
	s_nop 0
	v_mul_f32_e32 v45, 1.0, v35
	s_mov_b64 vcc, s[10:11]
	v_rcp_f32_e32 v35, v44
	s_nop 0
	v_mul_f32_e32 v44, 1.0, v35
	s_mov_b64 vcc, s[12:13]
	v_pk_fma_f32 v[38:39], v[44:45], v[48:49], v[38:39]
	v_rcp_f32_e32 v35, v47
	s_nop 0
	v_mul_f32_e32 v45, 1.0, v35
	v_lshlrev_b32_e32 v42, 16, v43
	v_and_b32_e32 v43, 0xffff0000, v43
	v_rcp_f32_e32 v35, v46
	s_nop 0
	v_mul_f32_e32 v44, 1.0, v35
	v_pk_fma_f32 v[40:41], v[44:45], v[42:43], v[40:41]
	global_store_dwordx4 v[32:33], v[38:41], off
	global_load_dwordx2 v[38:39], v[36:37], off offset:32
	v_pk_mul_f32 v[24:25], v[24:25], v[34:35] op_sel_hi:[1,0]
	v_pk_mul_f32 v[26:27], v[26:27], v[34:35] op_sel_hi:[1,0]
	v_mul_f32_e32 v24, 0xbfb8aa3b, v24
	v_mul_f32_e32 v25, 0xbfb8aa3b, v25
	v_exp_f32_e32 v24, v24
	v_exp_f32_e32 v25, v25
	v_mul_f32_e32 v26, 0xbfb8aa3b, v26
	v_mul_f32_e32 v27, 0xbfb8aa3b, v27
	v_exp_f32_e32 v26, v26
	v_exp_f32_e32 v27, v27
	v_pk_add_f32 v[24:25], v[24:25], 1.0 op_sel_hi:[1,0]
	v_pk_add_f32 v[26:27], v[26:27], 1.0 op_sel_hi:[1,0]
	s_mov_b64 vcc, s[0:1]
	v_rcp_f32_e32 v35, v25
	s_nop 0
	v_mul_f32_e32 v25, 1.0, v35
	s_mov_b64 vcc, s[10:11]
	v_rcp_f32_e32 v35, v24
	s_nop 0
	v_mul_f32_e32 v24, 1.0, v35
	s_mov_b64 vcc, s[12:13]
	v_rcp_f32_e32 v35, v27
	s_nop 0
	v_mul_f32_e32 v27, 1.0, v35
	v_rcp_f32_e32 v35, v26
	s_nop 0
	v_mul_f32_e32 v26, 1.0, v35
	v_pk_mul_f32 v[20:21], v[20:21], v[34:35] op_sel_hi:[1,0]
	s_waitcnt vmcnt(0)
	v_lshlrev_b32_e32 v40, 16, v38
	v_and_b32_e32 v41, 0xffff0000, v38
	v_lshlrev_b32_e32 v38, 16, v39
	v_and_b32_e32 v39, 0xffff0000, v39
	v_pk_fma_f32 v[24:25], v[24:25], v[40:41], v[28:29]
	v_pk_fma_f32 v[26:27], v[26:27], v[38:39], v[30:31]
	global_store_dwordx4 v[32:33], v[24:27], off offset:64
	global_load_dwordx2 v[30:31], v[36:37], off offset:256
	v_mul_f32_e32 v20, 0xbfb8aa3b, v20
	v_cvt_f32_i32_e32 v26, v22
	v_cvt_f32_i32_e32 v27, v23
	global_load_dwordx4 v[22:25], v[32:33], off offset:512
	v_mul_f32_e32 v21, 0xbfb8aa3b, v21
	v_exp_f32_e32 v20, v20
	v_pk_mul_f32 v[26:27], v[26:27], v[116:117]
	v_exp_f32_e32 v21, v21
	v_pk_mul_f32 v[26:27], v[26:27], v[34:35] op_sel_hi:[1,0]
	v_pk_add_f32 v[20:21], v[20:21], 1.0 op_sel_hi:[1,0]
	v_mul_f32_e32 v26, 0xbfb8aa3b, v26
	v_mul_f32_e32 v27, 0xbfb8aa3b, v27
	v_exp_f32_e32 v38, v26
	v_exp_f32_e32 v39, v27
	s_nop 0
	v_pk_add_f32 v[38:39], v[38:39], 1.0 op_sel_hi:[1,0]
	s_mov_b64 vcc, s[0:1]
	v_rcp_f32_e32 v35, v21
	s_nop 0
	v_mul_f32_e32 v21, 1.0, v35
	s_mov_b64 vcc, s[10:11]
	v_rcp_f32_e32 v35, v20
	s_nop 0
	v_mul_f32_e32 v20, 1.0, v35
	s_mov_b64 vcc, s[12:13]
	v_rcp_f32_e32 v35, v39
	s_nop 0
	v_mul_f32_e32 v39, 1.0, v35
	v_rcp_f32_e32 v35, v38
	s_nop 0
	v_mul_f32_e32 v38, 1.0, v35
	global_load_dwordx4 v[26:29], v[32:33], off offset:576
	v_pk_mul_f32 v[16:17], v[16:17], v[34:35] op_sel_hi:[1,0]
	v_pk_mul_f32 v[18:19], v[18:19], v[34:35] op_sel_hi:[1,0]
	v_mul_f32_e32 v16, 0xbfb8aa3b, v16
	v_mul_f32_e32 v17, 0xbfb8aa3b, v17
	v_exp_f32_e32 v16, v16
	v_exp_f32_e32 v17, v17
	s_waitcnt vmcnt(0)
	v_lshlrev_b32_e32 v40, 16, v30
	v_and_b32_e32 v41, 0xffff0000, v30
	v_lshlrev_b32_e32 v30, 16, v31
	v_and_b32_e32 v31, 0xffff0000, v31
	v_pk_fma_f32 v[20:21], v[20:21], v[40:41], v[22:23]
	v_pk_fma_f32 v[22:23], v[38:39], v[30:31], v[24:25]
	global_store_dwordx4 v[32:33], v[20:23], off offset:512
	global_load_dwordx2 v[20:21], v[36:37], off offset:288
	v_mul_f32_e32 v18, 0xbfb8aa3b, v18
	v_mul_f32_e32 v19, 0xbfb8aa3b, v19
	v_exp_f32_e32 v18, v18
	v_exp_f32_e32 v19, v19
	v_pk_add_f32 v[16:17], v[16:17], 1.0 op_sel_hi:[1,0]
	v_pk_add_f32 v[18:19], v[18:19], 1.0 op_sel_hi:[1,0]
	s_mov_b64 vcc, s[0:1]
	v_rcp_f32_e32 v22, v17
	s_nop 0
	v_mul_f32_e32 v17, 1.0, v22
	s_mov_b64 vcc, s[10:11]
	v_rcp_f32_e32 v22, v16
	s_nop 0
	v_mul_f32_e32 v16, 1.0, v22
	s_mov_b64 vcc, s[12:13]
	v_rcp_f32_e32 v22, v19
	s_nop 0
	v_mul_f32_e32 v19, 1.0, v22
	v_rcp_f32_e32 v22, v18
	s_nop 0
	v_mul_f32_e32 v18, 1.0, v22
	v_pk_mul_f32 v[30:31], v[12:13], v[128:129]
	s_waitcnt vmcnt(0)
	v_lshlrev_b32_e32 v22, 16, v20
	v_and_b32_e32 v23, 0xffff0000, v20
	v_lshlrev_b32_e32 v20, 16, v21
	v_and_b32_e32 v21, 0xffff0000, v21
	v_pk_fma_f32 v[16:17], v[16:17], v[22:23], v[26:27]
	v_pk_fma_f32 v[18:19], v[18:19], v[20:21], v[28:29]
	global_store_dwordx4 v[32:33], v[16:19], off offset:576
	global_load_dword v18, v[150:151], off offset:704
	v_lshl_add_u64 v[20:21], v[140:141], 1, s[54:55]
	global_load_dwordx2 v[26:27], v[20:21], off
	v_lshl_add_u64 v[16:17], v[140:141], 2, s[70:71]
	global_load_dwordx4 v[22:25], v[16:17], off
	v_pk_mul_f32 v[28:29], v[14:15], v[130:131]
	global_load_dwordx4 v[12:15], v[16:17], off offset:64
	s_waitcnt vmcnt(0)
	v_pk_mul_f32 v[30:31], v[30:31], v[18:19] op_sel_hi:[1,0]
	v_pk_mul_f32 v[28:29], v[28:29], v[18:19] op_sel_hi:[1,0]
	v_mul_f32_e32 v19, 0xbfb8aa3b, v30
	v_mul_f32_e32 v30, 0xbfb8aa3b, v31
	v_mul_f32_e32 v31, 0xbfb8aa3b, v28
	v_mul_f32_e32 v32, 0xbfb8aa3b, v29
	v_exp_f32_e32 v28, v19
	v_exp_f32_e32 v29, v30
	v_exp_f32_e32 v30, v31
	v_exp_f32_e32 v31, v32
	v_lshlrev_b32_e32 v32, 16, v26
	v_pk_add_f32 v[28:29], v[28:29], 1.0 op_sel_hi:[1,0]
	v_and_b32_e32 v33, 0xffff0000, v26
	v_pk_add_f32 v[30:31], v[30:31], 1.0 op_sel_hi:[1,0]
	s_mov_b64 vcc, s[0:1]
	v_rcp_f32_e32 v19, v29
	s_nop 0
	v_mul_f32_e32 v29, 1.0, v19
	s_mov_b64 vcc, s[10:11]
	v_rcp_f32_e32 v19, v28
	s_nop 0
	v_mul_f32_e32 v28, 1.0, v19
	s_mov_b64 vcc, s[12:13]
	v_pk_fma_f32 v[22:23], v[28:29], v[32:33], v[22:23]
	v_rcp_f32_e32 v19, v31
	s_nop 0
	v_mul_f32_e32 v29, 1.0, v19
	v_lshlrev_b32_e32 v26, 16, v27
	v_and_b32_e32 v27, 0xffff0000, v27
	v_rcp_f32_e32 v19, v30
	s_nop 0
	v_mul_f32_e32 v28, 1.0, v19
	v_pk_fma_f32 v[24:25], v[28:29], v[26:27], v[24:25]
	global_store_dwordx4 v[16:17], v[22:25], off
	global_load_dwordx2 v[22:23], v[20:21], off offset:32
	v_pk_mul_f32 v[8:9], v[8:9], v[18:19] op_sel_hi:[1,0]
	v_pk_mul_f32 v[10:11], v[10:11], v[18:19] op_sel_hi:[1,0]
	v_mul_f32_e32 v8, 0xbfb8aa3b, v8
	v_mul_f32_e32 v9, 0xbfb8aa3b, v9
	v_exp_f32_e32 v8, v8
	v_exp_f32_e32 v9, v9
	v_mul_f32_e32 v10, 0xbfb8aa3b, v10
	v_mul_f32_e32 v11, 0xbfb8aa3b, v11
	v_exp_f32_e32 v10, v10
	v_exp_f32_e32 v11, v11
	v_pk_add_f32 v[8:9], v[8:9], 1.0 op_sel_hi:[1,0]
	v_pk_add_f32 v[10:11], v[10:11], 1.0 op_sel_hi:[1,0]
	s_mov_b64 vcc, s[0:1]
	v_rcp_f32_e32 v19, v9
	s_nop 0
	v_mul_f32_e32 v9, 1.0, v19
	s_mov_b64 vcc, s[10:11]
	v_rcp_f32_e32 v19, v8
	s_nop 0
	v_mul_f32_e32 v8, 1.0, v19
	s_mov_b64 vcc, s[12:13]
	v_rcp_f32_e32 v19, v11
	s_nop 0
	v_mul_f32_e32 v11, 1.0, v19
	v_rcp_f32_e32 v19, v10
	s_nop 0
	v_mul_f32_e32 v10, 1.0, v19
	v_pk_mul_f32 v[4:5], v[4:5], v[18:19] op_sel_hi:[1,0]
	s_waitcnt vmcnt(0)
	v_lshlrev_b32_e32 v24, 16, v22
	v_and_b32_e32 v25, 0xffff0000, v22
	v_lshlrev_b32_e32 v22, 16, v23
	v_and_b32_e32 v23, 0xffff0000, v23
	v_pk_fma_f32 v[8:9], v[8:9], v[24:25], v[12:13]
	v_pk_fma_f32 v[10:11], v[10:11], v[22:23], v[14:15]
	global_store_dwordx4 v[16:17], v[8:11], off offset:64
	global_load_dwordx2 v[14:15], v[20:21], off offset:256
	v_mul_f32_e32 v4, 0xbfb8aa3b, v4
	v_cvt_f32_i32_e32 v10, v6
	v_cvt_f32_i32_e32 v11, v7
	global_load_dwordx4 v[6:9], v[16:17], off offset:512
	v_mul_f32_e32 v5, 0xbfb8aa3b, v5
	v_exp_f32_e32 v4, v4
	v_pk_mul_f32 v[10:11], v[10:11], v[116:117]
	v_exp_f32_e32 v5, v5
	v_pk_mul_f32 v[10:11], v[10:11], v[18:19] op_sel_hi:[1,0]
	v_pk_add_f32 v[4:5], v[4:5], 1.0 op_sel_hi:[1,0]
	v_mul_f32_e32 v10, 0xbfb8aa3b, v10
	v_mul_f32_e32 v11, 0xbfb8aa3b, v11
	v_exp_f32_e32 v22, v10
	v_exp_f32_e32 v23, v11
	s_nop 0
	v_pk_add_f32 v[22:23], v[22:23], 1.0 op_sel_hi:[1,0]
	s_mov_b64 vcc, s[0:1]
	v_rcp_f32_e32 v19, v5
	s_nop 0
	v_mul_f32_e32 v5, 1.0, v19
	s_mov_b64 vcc, s[10:11]
	v_rcp_f32_e32 v19, v4
	s_nop 0
	v_mul_f32_e32 v4, 1.0, v19
	s_mov_b64 vcc, s[12:13]
	v_rcp_f32_e32 v19, v23
	s_nop 0
	v_mul_f32_e32 v23, 1.0, v19
	v_rcp_f32_e32 v19, v22
	s_nop 0
	v_mul_f32_e32 v22, 1.0, v19
	global_load_dwordx4 v[10:13], v[16:17], off offset:576
	v_pk_mul_f32 v[0:1], v[0:1], v[18:19] op_sel_hi:[1,0]
	v_pk_mul_f32 v[2:3], v[2:3], v[18:19] op_sel_hi:[1,0]
	v_mul_f32_e32 v0, 0xbfb8aa3b, v0
	v_mul_f32_e32 v1, 0xbfb8aa3b, v1
	v_exp_f32_e32 v0, v0
	v_exp_f32_e32 v1, v1
	s_waitcnt vmcnt(0)
	v_lshlrev_b32_e32 v24, 16, v14
	v_and_b32_e32 v25, 0xffff0000, v14
	v_lshlrev_b32_e32 v14, 16, v15
	v_and_b32_e32 v15, 0xffff0000, v15
	v_pk_fma_f32 v[4:5], v[4:5], v[24:25], v[6:7]
	v_pk_fma_f32 v[6:7], v[22:23], v[14:15], v[8:9]
	global_store_dwordx4 v[16:17], v[4:7], off offset:512
	global_load_dwordx2 v[4:5], v[20:21], off offset:288
	v_mul_f32_e32 v2, 0xbfb8aa3b, v2
	v_mul_f32_e32 v3, 0xbfb8aa3b, v3
	v_exp_f32_e32 v2, v2
	v_exp_f32_e32 v3, v3
	v_pk_add_f32 v[0:1], v[0:1], 1.0 op_sel_hi:[1,0]
	v_add_u32_e32 v8, 0x10000, v140
	v_pk_add_f32 v[2:3], v[2:3], 1.0 op_sel_hi:[1,0]
	s_mov_b64 vcc, s[0:1]
	v_rcp_f32_e32 v6, v1
	s_nop 0
	v_mul_f32_e32 v1, 1.0, v6
	s_mov_b64 vcc, s[10:11]
	v_rcp_f32_e32 v6, v0
	s_nop 0
	v_mul_f32_e32 v0, 1.0, v6
	s_mov_b64 vcc, s[12:13]
	v_rcp_f32_e32 v6, v3
	s_nop 0
	v_mul_f32_e32 v3, 1.0, v6
	v_rcp_f32_e32 v6, v2
	s_nop 0
	v_mul_f32_e32 v2, 1.0, v6
	s_andn2_b64 vcc, exec, s[8:9]
	s_mov_b64 s[0:1], -1
	s_waitcnt vmcnt(0)
	v_lshlrev_b32_e32 v6, 16, v4
	v_and_b32_e32 v7, 0xffff0000, v4
	v_lshlrev_b32_e32 v4, 16, v5
	v_and_b32_e32 v5, 0xffff0000, v5
	v_pk_fma_f32 v[0:1], v[0:1], v[6:7], v[10:11]
	v_pk_fma_f32 v[2:3], v[2:3], v[4:5], v[12:13]
	global_store_dwordx4 v[16:17], v[0:3], off offset:576
	s_waitcnt vmcnt(0)
	s_cbranch_vccnz .LBB0_1501
	s_andn2_b64 vcc, exec, s[16:17]
	s_cbranch_vccnz .LBB0_1500
	s_barrier
	s_branch .LBB0_1500

.LBB0_2219:
	ds_bpermute_b32 v33, v169, v183
	v_mov_b32_e32 v32, v167
	s_waitcnt lgkmcnt(0)
	v_add_f32_e32 v33, v183, v33
	v_and_b32_e32 v36, 31, v32
	v_rcp_f32_e32 v34, v33
	s_nop 0
	v_mul_f32_e32 v34, 1.0, v34
	v_pk_mul_f32 v[0:1], v[0:1], v[34:35] op_sel_hi:[1,0]
	v_pk_mul_f32 v[2:3], v[2:3], v[34:35] op_sel_hi:[1,0]
	v_cvt_pk_bf16_f32 v0, v0, v1
	v_cvt_pk_bf16_f32 v1, v2, v3
	v_ashrrev_i32_e32 v2, 2, v32
	v_mul_u32_u24_e32 v33, 0x90, v36
	v_and_b32_e32 v2, -8, v2
	v_add3_u32 v33, s25, v33, v2
	v_pk_mul_f32 v[2:3], v[4:5], v[34:35] op_sel_hi:[1,0]
	v_pk_mul_f32 v[4:5], v[6:7], v[34:35] op_sel_hi:[1,0]
	v_cvt_pk_bf16_f32 v2, v2, v3
	v_cvt_pk_bf16_f32 v3, v4, v5
	ds_write2_b64 v33, v[0:1], v[2:3] offset1:2
	v_pk_mul_f32 v[0:1], v[8:9], v[34:35] op_sel_hi:[1,0]
	v_pk_mul_f32 v[2:3], v[10:11], v[34:35] op_sel_hi:[1,0]
	v_cvt_pk_bf16_f32 v0, v0, v1
	v_cvt_pk_bf16_f32 v1, v2, v3
	v_pk_mul_f32 v[2:3], v[12:13], v[34:35] op_sel_hi:[1,0]
	v_pk_mul_f32 v[4:5], v[14:15], v[34:35] op_sel_hi:[1,0]
	v_cvt_pk_bf16_f32 v2, v2, v3
	v_cvt_pk_bf16_f32 v3, v4, v5
	ds_write2_b64 v33, v[0:1], v[2:3] offset0:4 offset1:6
	v_pk_mul_f32 v[0:1], v[16:17], v[34:35] op_sel_hi:[1,0]
	v_pk_mul_f32 v[2:3], v[18:19], v[34:35] op_sel_hi:[1,0]
	v_cvt_pk_bf16_f32 v0, v0, v1
	v_cvt_pk_bf16_f32 v1, v2, v3
	v_pk_mul_f32 v[2:3], v[20:21], v[34:35] op_sel_hi:[1,0]
	v_pk_mul_f32 v[4:5], v[22:23], v[34:35] op_sel_hi:[1,0]
	v_cvt_pk_bf16_f32 v2, v2, v3
	v_cvt_pk_bf16_f32 v3, v4, v5
	ds_write2_b64 v33, v[0:1], v[2:3] offset0:8 offset1:10
	v_pk_mul_f32 v[0:1], v[24:25], v[34:35] op_sel_hi:[1,0]
	v_pk_mul_f32 v[2:3], v[26:27], v[34:35] op_sel_hi:[1,0]
	v_cvt_pk_bf16_f32 v0, v0, v1
	v_cvt_pk_bf16_f32 v1, v2, v3
	v_pk_mul_f32 v[2:3], v[28:29], v[34:35] op_sel_hi:[1,0]
	v_pk_mul_f32 v[4:5], v[30:31], v[34:35] op_sel_hi:[1,0]
	s_ashr_i32 s0, s33, 31
	v_cvt_pk_bf16_f32 v2, v2, v3
	v_cvt_pk_bf16_f32 v3, v4, v5
	s_add_u32 s8, s10, s33
	v_ashrrev_i32_e32 v6, 3, v32
	ds_write2_b64 v33, v[0:1], v[2:3] offset0:12 offset1:14
	s_addc_u32 s9, 0, s0
	v_lshlrev_b32_e32 v0, 4, v32
	v_ashrrev_i32_e32 v7, 31, v6
	s_waitcnt vmcnt(0)
	v_and_b32_e32 v64, 0x70, v0
	v_lshl_add_u64 v[0:1], s[8:9], 0, v[6:7]
	v_lshlrev_b64 v[10:11], 13, v[0:1]
	v_lshl_add_u64 v[0:1], s[42:43], 0, v[10:11]
	v_lshl_add_u64 v[0:1], v[0:1], 0, s[22:23]
	s_waitcnt lgkmcnt(0)
	v_lshl_add_u64 v[0:1], v[0:1], 0, v[64:65]
	global_load_dwordx4 v[2:5], v[0:1], off
	v_add_u32_e32 v0, s25, v64
	v_mad_u64_u32 v[6:7], s[0:1], v6, s24, v[0:1]
	ds_read_b128 v[6:9], v6
	s_waitcnt lgkmcnt(0)
	v_lshlrev_b32_e32 v14, 16, v6
	v_and_b32_e32 v15, 0xffff0000, v6
	s_waitcnt vmcnt(0)
	v_lshlrev_b32_e32 v1, 16, v2
	v_and_b32_e32 v16, 0xffff0000, v2
	v_lshlrev_b32_e32 v17, 16, v3
	v_and_b32_e32 v18, 0xffff0000, v3
	v_mul_f32_e32 v2, 0xbfb8aa3b, v1
	v_mul_f32_e32 v3, 0xbfb8aa3b, v16
	v_exp_f32_e32 v2, v2
	v_exp_f32_e32 v3, v3
	v_mul_f32_e32 v12, 0xbfb8aa3b, v17
	v_mul_f32_e32 v13, 0xbfb8aa3b, v18
	v_exp_f32_e32 v12, v12
	v_pk_add_f32 v[2:3], v[2:3], 1.0 op_sel_hi:[1,0]
	v_exp_f32_e32 v13, v13
	s_nop 0
	v_pk_add_f32 v[12:13], v[12:13], 1.0 op_sel_hi:[1,0]
	s_mov_b64 vcc, s[0:1]
	v_rcp_f32_e32 v6, v3
	s_nop 0
	v_mul_f32_e32 v3, v16, v6
	v_rcp_f32_e32 v6, v2
	s_nop 0
	v_mul_f32_e32 v2, v1, v6
	v_pk_mul_f32 v[2:3], v[2:3], v[14:15]
	v_cvt_pk_bf16_f32 v2, v2, v3
	v_rcp_f32_e32 v1, v13
	s_nop 0
	v_mul_f32_e32 v13, v18, v1
	v_lshlrev_b32_e32 v18, 16, v4
	v_and_b32_e32 v4, 0xffff0000, v4
	v_mul_f32_e32 v14, 0xbfb8aa3b, v18
	v_mul_f32_e32 v15, 0xbfb8aa3b, v4
	v_exp_f32_e32 v14, v14
	v_exp_f32_e32 v15, v15
	v_lshlrev_b32_e32 v6, 16, v7
	v_and_b32_e32 v7, 0xffff0000, v7
	v_rcp_f32_e32 v1, v12
	s_nop 0
	v_mul_f32_e32 v12, v17, v1
	v_pk_mul_f32 v[6:7], v[12:13], v[6:7]
	v_pk_add_f32 v[12:13], v[14:15], 1.0 op_sel_hi:[1,0]
	v_cvt_pk_bf16_f32 v3, v6, v7
	v_lshlrev_b32_e32 v6, 16, v8
	v_and_b32_e32 v7, 0xffff0000, v8
	v_rcp_f32_e32 v1, v13
	s_nop 0
	v_mul_f32_e32 v13, v4, v1
	v_and_b32_e32 v15, 0xffff0000, v5
	v_lshlrev_b32_e32 v8, 16, v5
	v_mul_f32_e32 v4, 0xbfb8aa3b, v8
	v_mul_f32_e32 v5, 0xbfb8aa3b, v15
	v_exp_f32_e32 v4, v4
	v_exp_f32_e32 v5, v5
	v_rcp_f32_e32 v1, v12
	s_nop 0
	v_mul_f32_e32 v12, v18, v1
	v_pk_mul_f32 v[6:7], v[12:13], v[6:7]
	v_pk_add_f32 v[12:13], v[4:5], 1.0 op_sel_hi:[1,0]
	v_cvt_pk_bf16_f32 v4, v6, v7
	v_lshlrev_b32_e32 v6, 16, v9
	v_and_b32_e32 v7, 0xffff0000, v9
	v_rcp_f32_e32 v1, v13
	s_nop 0
	v_mul_f32_e32 v9, v15, v1
	v_rcp_f32_e32 v1, v12
	s_nop 0
	v_mul_f32_e32 v8, v8, v1
	v_pk_mul_f32 v[6:7], v[8:9], v[6:7]
	v_add_u32_e32 v1, 64, v32
	v_cvt_pk_bf16_f32 v5, v6, v7
	v_lshl_add_u64 v[6:7], s[44:45], 0, v[10:11]
	v_lshl_add_u64 v[6:7], v[6:7], 0, s[22:23]
	v_lshl_add_u64 v[6:7], v[6:7], 0, v[64:65]
	global_store_dwordx4 v[6:7], v[2:5], off
	v_ashrrev_i32_e32 v6, 3, v1
	v_ashrrev_i32_e32 v7, 31, v6
	v_lshl_add_u64 v[2:3], s[8:9], 0, v[6:7]
	v_lshlrev_b64 v[10:11], 13, v[2:3]
	v_lshl_add_u64 v[2:3], s[42:43], 0, v[10:11]
	v_lshl_add_u64 v[2:3], v[2:3], 0, s[22:23]
	v_lshl_add_u64 v[2:3], v[2:3], 0, v[64:65]
	global_load_dwordx4 v[2:5], v[2:3], off
	s_waitcnt vmcnt(0)
	v_lshlrev_b32_e32 v1, 16, v2
	v_and_b32_e32 v2, 0xffff0000, v2
	v_mul_f32_e32 v7, 0xbfb8aa3b, v1
	v_exp_f32_e32 v12, v7
	v_mul_f32_e32 v7, 0xbfb8aa3b, v2
	v_exp_f32_e32 v13, v7
	v_mad_u64_u32 v[6:7], s[0:1], v6, s24, v[0:1]
	ds_read_b128 v[6:9], v6
	v_pk_add_f32 v[12:13], v[12:13], 1.0 op_sel_hi:[1,0]
	s_waitcnt lgkmcnt(0)
	v_lshlrev_b32_e32 v14, 16, v6
	v_and_b32_e32 v15, 0xffff0000, v6
	v_rcp_f32_e32 v6, v13
	s_nop 0
	v_mul_f32_e32 v13, v2, v6
	v_lshlrev_b32_e32 v18, 16, v3
	v_and_b32_e32 v17, 0xffff0000, v3
	v_mul_f32_e32 v2, 0xbfb8aa3b, v18
	v_mul_f32_e32 v3, 0xbfb8aa3b, v17
	v_exp_f32_e32 v2, v2
	v_exp_f32_e32 v3, v3
	v_rcp_f32_e32 v6, v12
	s_nop 0
	v_mul_f32_e32 v12, v1, v6
	v_pk_mul_f32 v[12:13], v[12:13], v[14:15]
	v_pk_add_f32 v[14:15], v[2:3], 1.0 op_sel_hi:[1,0]
	v_cvt_pk_bf16_f32 v2, v12, v13
	v_lshlrev_b32_e32 v6, 16, v7
	v_and_b32_e32 v7, 0xffff0000, v7
	v_rcp_f32_e32 v1, v15
	s_nop 0
	v_mul_f32_e32 v13, v17, v1
	v_lshlrev_b32_e32 v15, 16, v4
	v_and_b32_e32 v4, 0xffff0000, v4
	v_mul_f32_e32 v12, 0xbfb8aa3b, v15
	v_exp_f32_e32 v16, v12
	v_mul_f32_e32 v12, 0xbfb8aa3b, v4
	v_exp_f32_e32 v17, v12
	v_rcp_f32_e32 v1, v14
	s_nop 0
	v_mul_f32_e32 v12, v18, v1
	v_pk_mul_f32 v[6:7], v[12:13], v[6:7]
	v_pk_add_f32 v[12:13], v[16:17], 1.0 op_sel_hi:[1,0]
	v_cvt_pk_bf16_f32 v3, v6, v7
	v_lshlrev_b32_e32 v6, 16, v8
	v_and_b32_e32 v7, 0xffff0000, v8
	v_rcp_f32_e32 v1, v13
	s_nop 0
	v_mul_f32_e32 v13, v4, v1
	v_and_b32_e32 v16, 0xffff0000, v5
	v_lshlrev_b32_e32 v8, 16, v5
	v_mul_f32_e32 v4, 0xbfb8aa3b, v8
	v_mul_f32_e32 v5, 0xbfb8aa3b, v16
	v_exp_f32_e32 v4, v4
	v_exp_f32_e32 v5, v5
	v_rcp_f32_e32 v1, v12
	s_nop 0
	v_mul_f32_e32 v12, v15, v1
	v_pk_mul_f32 v[6:7], v[12:13], v[6:7]
	v_pk_add_f32 v[12:13], v[4:5], 1.0 op_sel_hi:[1,0]
	v_cvt_pk_bf16_f32 v4, v6, v7
	v_lshlrev_b32_e32 v6, 16, v9
	v_and_b32_e32 v7, 0xffff0000, v9
	v_rcp_f32_e32 v1, v13
	s_nop 0
	v_mul_f32_e32 v9, v16, v1
	v_rcp_f32_e32 v1, v12
	s_nop 0
	v_mul_f32_e32 v8, v8, v1
	v_pk_mul_f32 v[6:7], v[8:9], v[6:7]
	v_add_u32_e32 v1, 0x80, v32
	v_cvt_pk_bf16_f32 v5, v6, v7
	v_lshl_add_u64 v[6:7], s[44:45], 0, v[10:11]
	v_lshl_add_u64 v[6:7], v[6:7], 0, s[22:23]
	v_lshl_add_u64 v[6:7], v[6:7], 0, v[64:65]
	global_store_dwordx4 v[6:7], v[2:5], off
	v_ashrrev_i32_e32 v6, 3, v1
	v_ashrrev_i32_e32 v7, 31, v6
	v_lshl_add_u64 v[2:3], s[8:9], 0, v[6:7]
	v_lshlrev_b64 v[10:11], 13, v[2:3]
	v_lshl_add_u64 v[2:3], s[42:43], 0, v[10:11]
	v_lshl_add_u64 v[2:3], v[2:3], 0, s[22:23]
	v_lshl_add_u64 v[2:3], v[2:3], 0, v[64:65]
	global_load_dwordx4 v[2:5], v[2:3], off
	s_waitcnt vmcnt(0)
	v_lshlrev_b32_e32 v1, 16, v2
	v_and_b32_e32 v2, 0xffff0000, v2
	v_mul_f32_e32 v7, 0xbfb8aa3b, v1
	v_exp_f32_e32 v12, v7
	v_mul_f32_e32 v7, 0xbfb8aa3b, v2
	v_exp_f32_e32 v13, v7
	v_mad_u64_u32 v[6:7], s[0:1], v6, s24, v[0:1]
	ds_read_b128 v[6:9], v6
	v_pk_add_f32 v[12:13], v[12:13], 1.0 op_sel_hi:[1,0]
	s_waitcnt lgkmcnt(0)
	v_lshlrev_b32_e32 v14, 16, v6
	v_and_b32_e32 v15, 0xffff0000, v6
	v_rcp_f32_e32 v6, v13
	s_nop 0
	v_mul_f32_e32 v13, v2, v6
	v_lshlrev_b32_e32 v18, 16, v3
	v_and_b32_e32 v17, 0xffff0000, v3
	v_mul_f32_e32 v2, 0xbfb8aa3b, v18
	v_mul_f32_e32 v3, 0xbfb8aa3b, v17
	v_exp_f32_e32 v2, v2
	v_exp_f32_e32 v3, v3
	v_rcp_f32_e32 v6, v12
	s_nop 0
	v_mul_f32_e32 v12, v1, v6
	v_pk_mul_f32 v[12:13], v[12:13], v[14:15]
	v_pk_add_f32 v[14:15], v[2:3], 1.0 op_sel_hi:[1,0]
	v_cvt_pk_bf16_f32 v2, v12, v13
	v_lshlrev_b32_e32 v6, 16, v7
	v_and_b32_e32 v7, 0xffff0000, v7
	v_rcp_f32_e32 v1, v15
	s_nop 0
	v_mul_f32_e32 v13, v17, v1
	v_lshlrev_b32_e32 v15, 16, v4
	v_and_b32_e32 v4, 0xffff0000, v4
	v_mul_f32_e32 v12, 0xbfb8aa3b, v15
	v_exp_f32_e32 v16, v12
	v_mul_f32_e32 v12, 0xbfb8aa3b, v4
	v_exp_f32_e32 v17, v12
	v_rcp_f32_e32 v1, v14
	s_nop 0
	v_mul_f32_e32 v12, v18, v1
	v_pk_mul_f32 v[6:7], v[12:13], v[6:7]
	v_pk_add_f32 v[12:13], v[16:17], 1.0 op_sel_hi:[1,0]
	v_cvt_pk_bf16_f32 v3, v6, v7
	v_lshlrev_b32_e32 v6, 16, v8
	v_and_b32_e32 v7, 0xffff0000, v8
	v_rcp_f32_e32 v1, v13
	s_nop 0
	v_mul_f32_e32 v13, v4, v1
	v_and_b32_e32 v16, 0xffff0000, v5
	v_lshlrev_b32_e32 v8, 16, v5
	v_mul_f32_e32 v4, 0xbfb8aa3b, v8
	v_mul_f32_e32 v5, 0xbfb8aa3b, v16
	v_exp_f32_e32 v4, v4
	v_exp_f32_e32 v5, v5
	v_rcp_f32_e32 v1, v12
	s_nop 0
	v_mul_f32_e32 v12, v15, v1
	v_pk_mul_f32 v[6:7], v[12:13], v[6:7]
	v_pk_add_f32 v[12:13], v[4:5], 1.0 op_sel_hi:[1,0]
	v_cvt_pk_bf16_f32 v4, v6, v7
	v_lshlrev_b32_e32 v6, 16, v9
	v_and_b32_e32 v7, 0xffff0000, v9
	v_rcp_f32_e32 v1, v13
	s_nop 0
	v_mul_f32_e32 v9, v16, v1
	v_rcp_f32_e32 v1, v12
	s_nop 0
	v_mul_f32_e32 v8, v8, v1
	v_pk_mul_f32 v[6:7], v[8:9], v[6:7]
	v_add_u32_e32 v1, 0xc0, v32
	v_cvt_pk_bf16_f32 v5, v6, v7
	v_lshl_add_u64 v[6:7], s[44:45], 0, v[10:11]
	v_lshl_add_u64 v[6:7], v[6:7], 0, s[22:23]
	v_lshl_add_u64 v[6:7], v[6:7], 0, v[64:65]
	global_store_dwordx4 v[6:7], v[2:5], off
	v_ashrrev_i32_e32 v6, 3, v1
	v_ashrrev_i32_e32 v7, 31, v6
	v_lshl_add_u64 v[2:3], s[8:9], 0, v[6:7]
	v_lshlrev_b64 v[10:11], 13, v[2:3]
	v_lshl_add_u64 v[2:3], s[42:43], 0, v[10:11]
	v_lshl_add_u64 v[2:3], v[2:3], 0, s[22:23]
	v_lshl_add_u64 v[2:3], v[2:3], 0, v[64:65]
	global_load_dwordx4 v[2:5], v[2:3], off
	s_waitcnt vmcnt(0)
	v_lshlrev_b32_e32 v14, 16, v2
	v_and_b32_e32 v2, 0xffff0000, v2
	v_mul_f32_e32 v1, 0xbfb8aa3b, v14
	v_exp_f32_e32 v12, v1
	v_mul_f32_e32 v1, 0xbfb8aa3b, v2
	v_exp_f32_e32 v13, v1
	v_mad_u64_u32 v[0:1], s[0:1], v6, s24, v[0:1]
	ds_read_b128 v[6:9], v0
	v_pk_add_f32 v[0:1], v[12:13], 1.0 op_sel_hi:[1,0]
	s_waitcnt lgkmcnt(0)
	v_lshlrev_b32_e32 v12, 16, v6
	v_and_b32_e32 v13, 0xffff0000, v6
	v_rcp_f32_e32 v6, v1
	s_nop 0
	v_mul_f32_e32 v1, v2, v6
	v_and_b32_e32 v17, 0xffff0000, v3
	v_lshlrev_b32_e32 v16, 16, v3
	v_mul_f32_e32 v2, 0xbfb8aa3b, v16
	v_mul_f32_e32 v3, 0xbfb8aa3b, v17
	v_exp_f32_e32 v2, v2
	v_exp_f32_e32 v3, v3
	v_rcp_f32_e32 v6, v0
	s_nop 0
	v_mul_f32_e32 v0, v14, v6
	v_pk_mul_f32 v[0:1], v[0:1], v[12:13]
	v_pk_add_f32 v[2:3], v[2:3], 1.0 op_sel_hi:[1,0]
	v_cvt_pk_bf16_f32 v0, v0, v1
	v_lshlrev_b32_e32 v6, 16, v7
	v_and_b32_e32 v7, 0xffff0000, v7
	v_rcp_f32_e32 v1, v3
	s_nop 0
	v_mul_f32_e32 v3, v17, v1
	v_lshlrev_b32_e32 v17, 16, v4
	v_and_b32_e32 v4, 0xffff0000, v4
	v_mul_f32_e32 v12, 0xbfb8aa3b, v17
	v_mul_f32_e32 v13, 0xbfb8aa3b, v4
	v_exp_f32_e32 v12, v12
	v_exp_f32_e32 v13, v13
	v_rcp_f32_e32 v1, v2
	s_nop 0
	v_mul_f32_e32 v2, v16, v1
	v_pk_mul_f32 v[2:3], v[2:3], v[6:7]
	v_pk_add_f32 v[6:7], v[12:13], 1.0 op_sel_hi:[1,0]
	v_cvt_pk_bf16_f32 v1, v2, v3
	v_lshlrev_b32_e32 v2, 16, v8
	v_and_b32_e32 v3, 0xffff0000, v8
	v_rcp_f32_e32 v8, v7
	s_nop 0
	v_mul_f32_e32 v7, v4, v8
	v_and_b32_e32 v14, 0xffff0000, v5
	v_lshlrev_b32_e32 v13, 16, v5
	v_mul_f32_e32 v4, 0xbfb8aa3b, v13
	v_mul_f32_e32 v5, 0xbfb8aa3b, v14
	v_exp_f32_e32 v4, v4
	v_exp_f32_e32 v5, v5
	v_rcp_f32_e32 v8, v6
	s_nop 0
	v_mul_f32_e32 v6, v17, v8
	v_pk_mul_f32 v[2:3], v[6:7], v[2:3]
	v_pk_add_f32 v[4:5], v[4:5], 1.0 op_sel_hi:[1,0]
	v_cvt_pk_bf16_f32 v2, v2, v3
	v_lshlrev_b32_e32 v6, 16, v9
	v_and_b32_e32 v7, 0xffff0000, v9
	v_rcp_f32_e32 v3, v5
	s_nop 0
	v_mul_f32_e32 v5, v14, v3
	v_rcp_f32_e32 v3, v4
	s_nop 0
	v_mul_f32_e32 v4, v13, v3
	v_pk_mul_f32 v[4:5], v[4:5], v[6:7]
	ds_bpermute_b32 v6, v169, v182
	v_cvt_pk_bf16_f32 v3, v4, v5
	v_lshl_add_u64 v[4:5], s[44:45], 0, v[10:11]
	v_lshl_add_u64 v[4:5], v[4:5], 0, s[22:23]
	v_lshl_add_u64 v[4:5], v[4:5], 0, v[64:65]
	s_waitcnt lgkmcnt(0)
	v_add_f32_e32 v6, v182, v6
	global_store_dwordx4 v[4:5], v[0:3], off
	s_waitcnt lgkmcnt(0)
	s_or_b32 s0, s33, 32
	s_ashr_i32 s1, s0, 31
	v_mov_b32_e32 v1, v167
	v_rcp_f32_e32 v0, v6
	s_nop 0
	v_mul_f32_e32 v0, 1.0, v0
	s_add_u32 s0, s0, s10
	v_and_b32_e32 v2, 31, v1
	v_mul_u32_u24_e32 v6, 0x90, v2
	v_pk_mul_f32 v[2:3], v[82:83], v[0:1] op_sel_hi:[1,0]
	v_pk_mul_f32 v[4:5], v[84:85], v[0:1] op_sel_hi:[1,0]
	v_cvt_pk_bf16_f32 v2, v2, v3
	v_cvt_pk_bf16_f32 v3, v4, v5
	v_ashrrev_i32_e32 v4, 2, v1
	v_and_b32_e32 v4, -8, v4
	v_add3_u32 v8, s25, v6, v4
	v_pk_mul_f32 v[4:5], v[86:87], v[0:1] op_sel_hi:[1,0]
	v_pk_mul_f32 v[6:7], v[88:89], v[0:1] op_sel_hi:[1,0]
	v_cvt_pk_bf16_f32 v4, v4, v5
	v_cvt_pk_bf16_f32 v5, v6, v7
	ds_write2_b64 v8, v[2:3], v[4:5] offset1:2
	v_pk_mul_f32 v[2:3], v[90:91], v[0:1] op_sel_hi:[1,0]
	v_pk_mul_f32 v[4:5], v[92:93], v[0:1] op_sel_hi:[1,0]
	v_cvt_pk_bf16_f32 v2, v2, v3
	v_cvt_pk_bf16_f32 v3, v4, v5
	v_pk_mul_f32 v[4:5], v[94:95], v[0:1] op_sel_hi:[1,0]
	v_pk_mul_f32 v[6:7], v[96:97], v[0:1] op_sel_hi:[1,0]
	v_cvt_pk_bf16_f32 v4, v4, v5
	v_cvt_pk_bf16_f32 v5, v6, v7
	ds_write2_b64 v8, v[2:3], v[4:5] offset0:4 offset1:6
	v_pk_mul_f32 v[2:3], v[66:67], v[0:1] op_sel_hi:[1,0]
	v_pk_mul_f32 v[4:5], v[68:69], v[0:1] op_sel_hi:[1,0]
	v_cvt_pk_bf16_f32 v2, v2, v3
	v_cvt_pk_bf16_f32 v3, v4, v5
	v_pk_mul_f32 v[4:5], v[70:71], v[0:1] op_sel_hi:[1,0]
	v_pk_mul_f32 v[6:7], v[72:73], v[0:1] op_sel_hi:[1,0]
	v_cvt_pk_bf16_f32 v4, v4, v5
	v_cvt_pk_bf16_f32 v5, v6, v7
	ds_write2_b64 v8, v[2:3], v[4:5] offset0:8 offset1:10
	v_pk_mul_f32 v[2:3], v[74:75], v[0:1] op_sel_hi:[1,0]
	v_pk_mul_f32 v[4:5], v[76:77], v[0:1] op_sel_hi:[1,0]
	v_cvt_pk_bf16_f32 v2, v2, v3
	v_cvt_pk_bf16_f32 v3, v4, v5
	v_pk_mul_f32 v[4:5], v[78:79], v[0:1] op_sel_hi:[1,0]
	v_pk_mul_f32 v[6:7], v[80:81], v[0:1] op_sel_hi:[1,0]
	v_cvt_pk_bf16_f32 v4, v4, v5
	v_cvt_pk_bf16_f32 v5, v6, v7
	v_ashrrev_i32_e32 v6, 3, v1
	s_addc_u32 s1, s1, 0
	v_ashrrev_i32_e32 v7, 31, v6
	ds_write2_b64 v8, v[2:3], v[4:5] offset0:12 offset1:14
	v_lshl_add_u64 v[2:3], s[0:1], 0, v[6:7]
	v_lshlrev_b64 v[10:11], 13, v[2:3]
	v_lshlrev_b32_e32 v0, 4, v1
	v_lshl_add_u64 v[2:3], s[42:43], 0, v[10:11]
	v_and_b32_e32 v64, 0x70, v0
	v_lshl_add_u64 v[2:3], v[2:3], 0, s[22:23]
	s_waitcnt lgkmcnt(0)
	v_lshl_add_u64 v[2:3], v[2:3], 0, v[64:65]
	global_load_dwordx4 v[2:5], v[2:3], off
	v_add_u32_e32 v0, s25, v64
	s_add_i32 s31, s31, s74
	s_cmpk_gt_i32 s31, 0x7ff
	s_waitcnt vmcnt(0)
	v_lshlrev_b32_e32 v16, 16, v2
	v_and_b32_e32 v2, 0xffff0000, v2
	v_mul_f32_e32 v7, 0xbfb8aa3b, v16
	v_exp_f32_e32 v12, v7
	v_mul_f32_e32 v7, 0xbfb8aa3b, v2
	v_exp_f32_e32 v13, v7
	v_mad_u64_u32 v[6:7], s[8:9], v6, s24, v[0:1]
	ds_read_b128 v[6:9], v6
	v_pk_add_f32 v[12:13], v[12:13], 1.0 op_sel_hi:[1,0]
	s_waitcnt lgkmcnt(0)
	v_lshlrev_b32_e32 v14, 16, v6
	v_and_b32_e32 v15, 0xffff0000, v6
	v_rcp_f32_e32 v6, v13
	s_nop 0
	v_mul_f32_e32 v13, v2, v6
	v_and_b32_e32 v19, 0xffff0000, v3
	v_lshlrev_b32_e32 v18, 16, v3
	v_mul_f32_e32 v2, 0xbfb8aa3b, v18
	v_mul_f32_e32 v3, 0xbfb8aa3b, v19
	v_exp_f32_e32 v2, v2
	v_exp_f32_e32 v3, v3
	v_rcp_f32_e32 v6, v12
	s_nop 0
	v_mul_f32_e32 v12, v16, v6
	v_pk_mul_f32 v[12:13], v[12:13], v[14:15]
	v_pk_add_f32 v[14:15], v[2:3], 1.0 op_sel_hi:[1,0]
	v_cvt_pk_bf16_f32 v2, v12, v13
	v_lshlrev_b32_e32 v6, 16, v7
	v_and_b32_e32 v7, 0xffff0000, v7
	v_rcp_f32_e32 v3, v15
	s_nop 0
	v_mul_f32_e32 v13, v19, v3
	v_lshlrev_b32_e32 v19, 16, v4
	v_and_b32_e32 v4, 0xffff0000, v4
	v_mul_f32_e32 v12, 0xbfb8aa3b, v19
	v_exp_f32_e32 v16, v12
	v_mul_f32_e32 v12, 0xbfb8aa3b, v4
	v_exp_f32_e32 v17, v12
	v_rcp_f32_e32 v3, v14
	s_nop 0
	v_mul_f32_e32 v12, v18, v3
	v_pk_mul_f32 v[6:7], v[12:13], v[6:7]
	v_pk_add_f32 v[12:13], v[16:17], 1.0 op_sel_hi:[1,0]
	v_cvt_pk_bf16_f32 v3, v6, v7
	v_lshlrev_b32_e32 v6, 16, v8
	v_and_b32_e32 v7, 0xffff0000, v8
	v_rcp_f32_e32 v8, v13
	s_nop 0
	v_mul_f32_e32 v13, v4, v8
	v_and_b32_e32 v16, 0xffff0000, v5
	v_lshlrev_b32_e32 v15, 16, v5
	v_mul_f32_e32 v4, 0xbfb8aa3b, v15
	v_mul_f32_e32 v5, 0xbfb8aa3b, v16
	v_exp_f32_e32 v4, v4
	v_exp_f32_e32 v5, v5
	v_rcp_f32_e32 v8, v12
	s_nop 0
	v_mul_f32_e32 v12, v19, v8
	v_pk_mul_f32 v[6:7], v[12:13], v[6:7]
	v_pk_add_f32 v[12:13], v[4:5], 1.0 op_sel_hi:[1,0]
	v_cvt_pk_bf16_f32 v4, v6, v7
	v_lshlrev_b32_e32 v6, 16, v9
	v_and_b32_e32 v7, 0xffff0000, v9
	v_rcp_f32_e32 v5, v13
	s_nop 0
	v_mul_f32_e32 v9, v16, v5
	v_rcp_f32_e32 v5, v12
	s_nop 0
	v_mul_f32_e32 v8, v15, v5
	v_pk_mul_f32 v[6:7], v[8:9], v[6:7]
	s_nop 0
	v_cvt_pk_bf16_f32 v5, v6, v7
	v_lshl_add_u64 v[6:7], s[44:45], 0, v[10:11]
	v_lshl_add_u64 v[6:7], v[6:7], 0, s[22:23]
	v_lshl_add_u64 v[6:7], v[6:7], 0, v[64:65]
	global_store_dwordx4 v[6:7], v[2:5], off
	s_nop 1
	v_add_u32_e32 v2, 64, v1
	v_ashrrev_i32_e32 v6, 3, v2
	v_ashrrev_i32_e32 v7, 31, v6
	v_lshl_add_u64 v[2:3], s[0:1], 0, v[6:7]
	v_lshlrev_b64 v[10:11], 13, v[2:3]
	v_lshl_add_u64 v[2:3], s[42:43], 0, v[10:11]
	v_lshl_add_u64 v[2:3], v[2:3], 0, s[22:23]
	v_lshl_add_u64 v[2:3], v[2:3], 0, v[64:65]
	global_load_dwordx4 v[2:5], v[2:3], off
	s_waitcnt vmcnt(0)
	v_lshlrev_b32_e32 v16, 16, v2
	v_and_b32_e32 v2, 0xffff0000, v2
	v_mul_f32_e32 v7, 0xbfb8aa3b, v16
	v_exp_f32_e32 v12, v7
	v_mul_f32_e32 v7, 0xbfb8aa3b, v2
	v_exp_f32_e32 v13, v7
	v_mad_u64_u32 v[6:7], s[8:9], v6, s24, v[0:1]
	ds_read_b128 v[6:9], v6
	v_pk_add_f32 v[12:13], v[12:13], 1.0 op_sel_hi:[1,0]
	s_waitcnt lgkmcnt(0)
	v_lshlrev_b32_e32 v14, 16, v6
	v_and_b32_e32 v15, 0xffff0000, v6
	v_rcp_f32_e32 v6, v13
	s_nop 0
	v_mul_f32_e32 v13, v2, v6
	v_and_b32_e32 v19, 0xffff0000, v3
	v_lshlrev_b32_e32 v18, 16, v3
	v_mul_f32_e32 v2, 0xbfb8aa3b, v18
	v_mul_f32_e32 v3, 0xbfb8aa3b, v19
	v_exp_f32_e32 v2, v2
	v_exp_f32_e32 v3, v3
	v_rcp_f32_e32 v6, v12
	s_nop 0
	v_mul_f32_e32 v12, v16, v6
	v_pk_mul_f32 v[12:13], v[12:13], v[14:15]
	v_pk_add_f32 v[14:15], v[2:3], 1.0 op_sel_hi:[1,0]
	v_cvt_pk_bf16_f32 v2, v12, v13
	v_lshlrev_b32_e32 v6, 16, v7
	v_and_b32_e32 v7, 0xffff0000, v7
	v_rcp_f32_e32 v3, v15
	s_nop 0
	v_mul_f32_e32 v13, v19, v3
	v_lshlrev_b32_e32 v19, 16, v4
	v_and_b32_e32 v4, 0xffff0000, v4
	v_mul_f32_e32 v12, 0xbfb8aa3b, v19
	v_exp_f32_e32 v16, v12
	v_mul_f32_e32 v12, 0xbfb8aa3b, v4
	v_exp_f32_e32 v17, v12
	v_rcp_f32_e32 v3, v14
	s_nop 0
	v_mul_f32_e32 v12, v18, v3
	v_pk_mul_f32 v[6:7], v[12:13], v[6:7]
	v_pk_add_f32 v[12:13], v[16:17], 1.0 op_sel_hi:[1,0]
	v_cvt_pk_bf16_f32 v3, v6, v7
	v_lshlrev_b32_e32 v6, 16, v8
	v_and_b32_e32 v7, 0xffff0000, v8
	v_rcp_f32_e32 v8, v13
	s_nop 0
	v_mul_f32_e32 v13, v4, v8
	v_and_b32_e32 v16, 0xffff0000, v5
	v_lshlrev_b32_e32 v15, 16, v5
	v_mul_f32_e32 v4, 0xbfb8aa3b, v15
	v_mul_f32_e32 v5, 0xbfb8aa3b, v16
	v_exp_f32_e32 v4, v4
	v_exp_f32_e32 v5, v5
	v_rcp_f32_e32 v8, v12
	s_nop 0
	v_mul_f32_e32 v12, v19, v8
	v_pk_mul_f32 v[6:7], v[12:13], v[6:7]
	v_pk_add_f32 v[12:13], v[4:5], 1.0 op_sel_hi:[1,0]
	v_cvt_pk_bf16_f32 v4, v6, v7
	v_lshlrev_b32_e32 v6, 16, v9
	v_and_b32_e32 v7, 0xffff0000, v9
	v_rcp_f32_e32 v5, v13
	s_nop 0
	v_mul_f32_e32 v9, v16, v5
	v_rcp_f32_e32 v5, v12
	s_nop 0
	v_mul_f32_e32 v8, v15, v5
	v_pk_mul_f32 v[6:7], v[8:9], v[6:7]
	s_nop 0
	v_cvt_pk_bf16_f32 v5, v6, v7
	v_lshl_add_u64 v[6:7], s[44:45], 0, v[10:11]
	v_lshl_add_u64 v[6:7], v[6:7], 0, s[22:23]
	v_lshl_add_u64 v[6:7], v[6:7], 0, v[64:65]
	global_store_dwordx4 v[6:7], v[2:5], off
	s_nop 1
	v_add_u32_e32 v2, 0x80, v1
	v_ashrrev_i32_e32 v6, 3, v2
	v_ashrrev_i32_e32 v7, 31, v6
	v_lshl_add_u64 v[2:3], s[0:1], 0, v[6:7]
	v_lshlrev_b64 v[10:11], 13, v[2:3]
	v_lshl_add_u64 v[2:3], s[42:43], 0, v[10:11]
	v_lshl_add_u64 v[2:3], v[2:3], 0, s[22:23]
	v_lshl_add_u64 v[2:3], v[2:3], 0, v[64:65]
	global_load_dwordx4 v[2:5], v[2:3], off
	s_waitcnt vmcnt(0)
	v_lshlrev_b32_e32 v16, 16, v2
	v_and_b32_e32 v2, 0xffff0000, v2
	v_mul_f32_e32 v7, 0xbfb8aa3b, v16
	v_exp_f32_e32 v12, v7
	v_mul_f32_e32 v7, 0xbfb8aa3b, v2
	v_exp_f32_e32 v13, v7
	v_mad_u64_u32 v[6:7], s[8:9], v6, s24, v[0:1]
	ds_read_b128 v[6:9], v6
	v_pk_add_f32 v[12:13], v[12:13], 1.0 op_sel_hi:[1,0]
	v_add_u32_e32 v1, 0xc0, v1
	s_waitcnt lgkmcnt(0)
	v_lshlrev_b32_e32 v14, 16, v6
	v_and_b32_e32 v15, 0xffff0000, v6
	v_rcp_f32_e32 v6, v13
	s_nop 0
	v_mul_f32_e32 v13, v2, v6
	v_and_b32_e32 v19, 0xffff0000, v3
	v_lshlrev_b32_e32 v18, 16, v3
	v_mul_f32_e32 v2, 0xbfb8aa3b, v18
	v_mul_f32_e32 v3, 0xbfb8aa3b, v19
	v_exp_f32_e32 v2, v2
	v_exp_f32_e32 v3, v3
	v_rcp_f32_e32 v6, v12
	s_nop 0
	v_mul_f32_e32 v12, v16, v6
	v_pk_mul_f32 v[12:13], v[12:13], v[14:15]
	v_pk_add_f32 v[14:15], v[2:3], 1.0 op_sel_hi:[1,0]
	v_cvt_pk_bf16_f32 v2, v12, v13
	v_lshlrev_b32_e32 v6, 16, v7
	v_and_b32_e32 v7, 0xffff0000, v7
	v_rcp_f32_e32 v3, v15
	s_nop 0
	v_mul_f32_e32 v13, v19, v3
	v_lshlrev_b32_e32 v19, 16, v4
	v_and_b32_e32 v4, 0xffff0000, v4
	v_mul_f32_e32 v12, 0xbfb8aa3b, v19
	v_exp_f32_e32 v16, v12
	v_mul_f32_e32 v12, 0xbfb8aa3b, v4
	v_exp_f32_e32 v17, v12
	v_rcp_f32_e32 v3, v14
	s_nop 0
	v_mul_f32_e32 v12, v18, v3
	v_pk_mul_f32 v[6:7], v[12:13], v[6:7]
	v_pk_add_f32 v[12:13], v[16:17], 1.0 op_sel_hi:[1,0]
	v_cvt_pk_bf16_f32 v3, v6, v7
	v_lshlrev_b32_e32 v6, 16, v8
	v_and_b32_e32 v7, 0xffff0000, v8
	v_rcp_f32_e32 v8, v13
	s_nop 0
	v_mul_f32_e32 v13, v4, v8
	v_and_b32_e32 v16, 0xffff0000, v5
	v_lshlrev_b32_e32 v15, 16, v5
	v_mul_f32_e32 v4, 0xbfb8aa3b, v15
	v_mul_f32_e32 v5, 0xbfb8aa3b, v16
	v_exp_f32_e32 v4, v4
	v_exp_f32_e32 v5, v5
	v_rcp_f32_e32 v8, v12
	s_nop 0
	v_mul_f32_e32 v12, v19, v8
	v_pk_mul_f32 v[6:7], v[12:13], v[6:7]
	v_pk_add_f32 v[12:13], v[4:5], 1.0 op_sel_hi:[1,0]
	v_cvt_pk_bf16_f32 v4, v6, v7
	v_lshlrev_b32_e32 v6, 16, v9
	v_and_b32_e32 v7, 0xffff0000, v9
	v_rcp_f32_e32 v5, v13
	s_nop 0
	v_mul_f32_e32 v9, v16, v5
	v_rcp_f32_e32 v5, v12
	s_nop 0
	v_mul_f32_e32 v8, v15, v5
	v_pk_mul_f32 v[6:7], v[8:9], v[6:7]
	s_nop 0
	v_cvt_pk_bf16_f32 v5, v6, v7
	v_lshl_add_u64 v[6:7], s[44:45], 0, v[10:11]
	v_lshl_add_u64 v[6:7], v[6:7], 0, s[22:23]
	v_lshl_add_u64 v[6:7], v[6:7], 0, v[64:65]
	global_store_dwordx4 v[6:7], v[2:5], off
	v_ashrrev_i32_e32 v6, 3, v1
	v_ashrrev_i32_e32 v7, 31, v6
	v_lshl_add_u64 v[2:3], s[0:1], 0, v[6:7]
	v_lshlrev_b64 v[10:11], 13, v[2:3]
	v_lshl_add_u64 v[2:3], s[42:43], 0, v[10:11]
	v_lshl_add_u64 v[2:3], v[2:3], 0, s[22:23]
	v_lshl_add_u64 v[2:3], v[2:3], 0, v[64:65]
	global_load_dwordx4 v[2:5], v[2:3], off
	s_waitcnt vmcnt(0)
	v_lshlrev_b32_e32 v14, 16, v2
	v_and_b32_e32 v2, 0xffff0000, v2
	v_mul_f32_e32 v1, 0xbfb8aa3b, v14
	v_exp_f32_e32 v12, v1
	v_mul_f32_e32 v1, 0xbfb8aa3b, v2
	v_exp_f32_e32 v13, v1
	v_mad_u64_u32 v[0:1], s[0:1], v6, s24, v[0:1]
	ds_read_b128 v[6:9], v0
	v_pk_add_f32 v[0:1], v[12:13], 1.0 op_sel_hi:[1,0]
	s_waitcnt lgkmcnt(0)
	v_lshlrev_b32_e32 v12, 16, v6
	v_and_b32_e32 v13, 0xffff0000, v6
	v_rcp_f32_e32 v6, v1
	s_nop 0
	v_mul_f32_e32 v1, v2, v6
	v_and_b32_e32 v17, 0xffff0000, v3
	v_lshlrev_b32_e32 v16, 16, v3
	v_mul_f32_e32 v2, 0xbfb8aa3b, v16
	v_mul_f32_e32 v3, 0xbfb8aa3b, v17
	v_exp_f32_e32 v2, v2
	v_exp_f32_e32 v3, v3
	v_rcp_f32_e32 v6, v0
	s_nop 0
	v_mul_f32_e32 v0, v14, v6
	v_pk_mul_f32 v[0:1], v[0:1], v[12:13]
	v_pk_add_f32 v[2:3], v[2:3], 1.0 op_sel_hi:[1,0]
	v_cvt_pk_bf16_f32 v0, v0, v1
	v_lshlrev_b32_e32 v6, 16, v7
	v_and_b32_e32 v7, 0xffff0000, v7
	v_rcp_f32_e32 v1, v3
	s_nop 0
	v_mul_f32_e32 v3, v17, v1
	v_lshlrev_b32_e32 v17, 16, v4
	v_and_b32_e32 v4, 0xffff0000, v4
	v_mul_f32_e32 v12, 0xbfb8aa3b, v17
	v_mul_f32_e32 v13, 0xbfb8aa3b, v4
	v_exp_f32_e32 v12, v12
	v_exp_f32_e32 v13, v13
	v_rcp_f32_e32 v1, v2
	s_nop 0
	v_mul_f32_e32 v2, v16, v1
	v_pk_mul_f32 v[2:3], v[2:3], v[6:7]
	v_pk_add_f32 v[6:7], v[12:13], 1.0 op_sel_hi:[1,0]
	v_cvt_pk_bf16_f32 v1, v2, v3
	v_lshlrev_b32_e32 v2, 16, v8
	v_and_b32_e32 v3, 0xffff0000, v8
	v_rcp_f32_e32 v8, v7
	s_nop 0
	v_mul_f32_e32 v7, v4, v8
	v_and_b32_e32 v14, 0xffff0000, v5
	v_lshlrev_b32_e32 v13, 16, v5
	v_mul_f32_e32 v4, 0xbfb8aa3b, v13
	v_mul_f32_e32 v5, 0xbfb8aa3b, v14
	v_exp_f32_e32 v4, v4
	v_exp_f32_e32 v5, v5
	v_rcp_f32_e32 v8, v6
	s_nop 0
	v_mul_f32_e32 v6, v17, v8
	v_pk_mul_f32 v[2:3], v[6:7], v[2:3]
	v_pk_add_f32 v[4:5], v[4:5], 1.0 op_sel_hi:[1,0]
	v_cvt_pk_bf16_f32 v2, v2, v3
	v_lshlrev_b32_e32 v6, 16, v9
	v_and_b32_e32 v7, 0xffff0000, v9
	v_rcp_f32_e32 v3, v5
	s_nop 0
	v_mul_f32_e32 v5, v14, v3
	v_rcp_f32_e32 v3, v4
	s_nop 0
	v_mul_f32_e32 v4, v13, v3
	v_pk_mul_f32 v[4:5], v[4:5], v[6:7]
	s_nop 0
	v_cvt_pk_bf16_f32 v3, v4, v5
	v_lshl_add_u64 v[4:5], s[44:45], 0, v[10:11]
	v_lshl_add_u64 v[4:5], v[4:5], 0, s[22:23]
	v_lshl_add_u64 v[4:5], v[4:5], 0, v[64:65]
	global_store_dwordx4 v[4:5], v[0:3], off
	s_waitcnt lgkmcnt(0)
	s_cbranch_scc1 .LBB0_2242

.LBB0_2372:
	v_cvt_f32_i32_e32 v124, v124
	v_cvt_f32_i32_e32 v125, v125
	v_cvt_f32_i32_e32 v126, v126
	v_cvt_f32_i32_e32 v127, v127
	v_cvt_f32_i32_e32 v120, v120
	v_cvt_f32_i32_e32 v121, v121
	v_cvt_f32_i32_e32 v122, v122
	v_cvt_f32_i32_e32 v123, v123
	v_cvt_f32_i32_e32 v108, v108
	v_cvt_f32_i32_e32 v109, v109
	v_cvt_f32_i32_e32 v110, v110
	v_cvt_f32_i32_e32 v111, v111
	v_cvt_f32_i32_e32 v104, v104
	v_cvt_f32_i32_e32 v105, v105
	v_cvt_f32_i32_e32 v106, v106
	v_cvt_f32_i32_e32 v107, v107
	v_cvt_f32_i32_e32 v92, v92
	v_cvt_f32_i32_e32 v93, v93
	v_cvt_f32_i32_e32 v94, v94
	v_cvt_f32_i32_e32 v95, v95
	v_cvt_f32_i32_e32 v88, v88
	v_cvt_f32_i32_e32 v89, v89
	v_cvt_f32_i32_e32 v90, v90
	v_cvt_f32_i32_e32 v91, v91
	v_cvt_f32_i32_e32 v76, v76
	v_cvt_f32_i32_e32 v77, v77
	v_cvt_f32_i32_e32 v78, v78
	v_cvt_f32_i32_e32 v79, v79
	v_cvt_f32_i32_e32 v72, v72
	v_cvt_f32_i32_e32 v73, v73
	v_cvt_f32_i32_e32 v74, v74
	v_cvt_f32_i32_e32 v75, v75
	v_cvt_f32_i32_e32 v116, v116
	v_cvt_f32_i32_e32 v117, v117
	v_cvt_f32_i32_e32 v118, v118
	v_cvt_f32_i32_e32 v119, v119
	v_cvt_f32_i32_e32 v112, v112
	v_cvt_f32_i32_e32 v113, v113
	v_cvt_f32_i32_e32 v114, v114
	v_cvt_f32_i32_e32 v115, v115
	v_cvt_f32_i32_e32 v100, v100
	v_cvt_f32_i32_e32 v101, v101
	v_cvt_f32_i32_e32 v102, v102
	v_cvt_f32_i32_e32 v103, v103
	v_cvt_f32_i32_e32 v96, v96
	v_cvt_f32_i32_e32 v97, v97
	v_cvt_f32_i32_e32 v98, v98
	v_cvt_f32_i32_e32 v99, v99
	v_cvt_f32_i32_e32 v84, v84
	v_cvt_f32_i32_e32 v85, v85
	v_cvt_f32_i32_e32 v86, v86
	v_cvt_f32_i32_e32 v87, v87
	v_cvt_f32_i32_e32 v80, v80
	v_cvt_f32_i32_e32 v81, v81
	v_cvt_f32_i32_e32 v82, v82
	v_cvt_f32_i32_e32 v83, v83
	v_cvt_f32_i32_e32 v68, v68
	v_cvt_f32_i32_e32 v69, v69
	v_cvt_f32_i32_e32 v70, v70
	v_cvt_f32_i32_e32 v71, v71
	v_cvt_f32_i32_e32 v64, v64
	v_cvt_f32_i32_e32 v65, v65
	v_cvt_f32_i32_e32 v66, v66
	v_cvt_f32_i32_e32 v67, v67
	v_cvt_f32_i32_e32 v60, v60
	v_cvt_f32_i32_e32 v61, v61
	v_cvt_f32_i32_e32 v62, v62
	v_cvt_f32_i32_e32 v63, v63
	v_cvt_f32_i32_e32 v56, v56
	v_cvt_f32_i32_e32 v57, v57
	v_cvt_f32_i32_e32 v58, v58
	v_cvt_f32_i32_e32 v59, v59
	v_cvt_f32_i32_e32 v44, v44
	v_cvt_f32_i32_e32 v45, v45
	v_cvt_f32_i32_e32 v46, v46
	v_cvt_f32_i32_e32 v47, v47
	v_cvt_f32_i32_e32 v40, v40
	v_cvt_f32_i32_e32 v41, v41
	v_cvt_f32_i32_e32 v42, v42
	v_cvt_f32_i32_e32 v43, v43
	v_cvt_f32_i32_e32 v28, v28
	v_cvt_f32_i32_e32 v29, v29
	v_cvt_f32_i32_e32 v30, v30
	v_cvt_f32_i32_e32 v31, v31
	v_cvt_f32_i32_e32 v24, v24
	v_cvt_f32_i32_e32 v25, v25
	v_cvt_f32_i32_e32 v26, v26
	v_cvt_f32_i32_e32 v27, v27
	v_cvt_f32_i32_e32 v12, v12
	v_cvt_f32_i32_e32 v13, v13
	v_cvt_f32_i32_e32 v14, v14
	v_cvt_f32_i32_e32 v15, v15
	v_cvt_f32_i32_e32 v8, v8
	v_cvt_f32_i32_e32 v9, v9
	v_cvt_f32_i32_e32 v10, v10
	v_cvt_f32_i32_e32 v11, v11
	v_cvt_f32_i32_e32 v52, v52
	v_cvt_f32_i32_e32 v53, v53
	v_cvt_f32_i32_e32 v54, v54
	v_cvt_f32_i32_e32 v55, v55
	v_cvt_f32_i32_e32 v48, v48
	v_cvt_f32_i32_e32 v49, v49
	v_cvt_f32_i32_e32 v50, v50
	v_cvt_f32_i32_e32 v51, v51
	v_cvt_f32_i32_e32 v36, v36
	v_cvt_f32_i32_e32 v37, v37
	v_cvt_f32_i32_e32 v38, v38
	v_cvt_f32_i32_e32 v39, v39
	v_cvt_f32_i32_e32 v32, v32
	v_cvt_f32_i32_e32 v33, v33
	v_cvt_f32_i32_e32 v34, v34
	v_cvt_f32_i32_e32 v35, v35
	v_cvt_f32_i32_e32 v20, v20
	v_cvt_f32_i32_e32 v21, v21
	v_cvt_f32_i32_e32 v22, v22
	v_cvt_f32_i32_e32 v23, v23
	v_cvt_f32_i32_e32 v16, v16
	v_cvt_f32_i32_e32 v17, v17
	v_cvt_f32_i32_e32 v18, v18
	v_cvt_f32_i32_e32 v19, v19
	v_cvt_f32_i32_e32 v4, v4
	v_cvt_f32_i32_e32 v5, v5
	v_cvt_f32_i32_e32 v6, v6
	v_cvt_f32_i32_e32 v7, v7
	v_cvt_f32_i32_e32 v0, v0
	v_cvt_f32_i32_e32 v1, v1
	v_cvt_f32_i32_e32 v2, v2
	v_cvt_f32_i32_e32 v3, v3
	s_andn2_b64 vcc, exec, s[20:21]
	v_lshl_add_u32 v215, s44, 8, v158
	v_lshlrev_b32_e32 v217, 2, v215
	s_cbranch_vccnz .Lp10e_nors1
	global_load_dword v214, v217, s[14:15]
	global_load_dword v216, v217, s[14:15] offset:64
	global_load_dword v218, v217, s[14:15] offset:128
	global_load_dword v220, v217, s[14:15] offset:192
	global_load_dword v210, v217, s[14:15] offset:512
	global_load_dword v212, v217, s[14:15] offset:576
	global_load_dword v198, v217, s[14:15] offset:640
	global_load_dword v132, v217, s[14:15] offset:704
.Lp10e_nors1:
	v_lshl_or_b32 v219, s60, 8, v160
	v_lshlrev_b32_e32 v217, 2, v219
	global_load_dwordx4 v[142:145], v217, s[10:11]
	global_load_dwordx4 v[146:149], v217, s[10:11] offset:64
	global_load_dwordx4 v[150:153], v217, s[10:11] offset:512
	global_load_dwordx4 v[154:157], v217, s[10:11] offset:576
	v_lshl_add_u32 v219, v215, 12, v219
	v_lshlrev_b32_e32 v219, 2, v219
	v_mov_b32_e32 v221, v219
	global_load_dwordx4 v[162:165], v219, s[70:71]
	global_load_dwordx4 v[166:169], v219, s[70:71] offset:64
	global_load_dwordx4 v[170:173], v219, s[70:71] offset:512
	global_load_dwordx4 v[174:177], v219, s[70:71] offset:576
	v_add_u32_e32 v219, 0x40000, v219
	global_load_dwordx4 v[178:181], v219, s[70:71]
	global_load_dwordx4 v[182:185], v219, s[70:71] offset:64
	global_load_dwordx4 v[186:189], v219, s[70:71] offset:512
	global_load_dwordx4 v[190:193], v219, s[70:71] offset:576
	v_add_u32_e32 v219, 0x40000, v219
	global_load_dwordx4 v[194:197], v219, s[70:71]
	global_load_dwordx4 v[202:205], v219, s[70:71] offset:64
	global_load_dwordx4 v[206:209], v219, s[70:71] offset:512
	s_cbranch_vccnz .Lp10e_nors2
	s_waitcnt vmcnt(15)
	v_pk_mul_f32 v[126:127], v[126:127], v[214:215] op_sel_hi:[1,0]
	v_pk_mul_f32 v[124:125], v[124:125], v[214:215] op_sel_hi:[1,0]
	v_pk_mul_f32 v[122:123], v[122:123], v[214:215] op_sel_hi:[1,0]
	v_pk_mul_f32 v[120:121], v[120:121], v[214:215] op_sel_hi:[1,0]
	v_pk_mul_f32 v[118:119], v[118:119], v[214:215] op_sel_hi:[1,0]
	v_pk_mul_f32 v[116:117], v[116:117], v[214:215] op_sel_hi:[1,0]
	v_pk_mul_f32 v[114:115], v[114:115], v[214:215] op_sel_hi:[1,0]
	v_pk_mul_f32 v[112:113], v[112:113], v[214:215] op_sel_hi:[1,0]
	v_pk_mul_f32 v[110:111], v[110:111], v[216:217] op_sel_hi:[1,0]
	v_pk_mul_f32 v[108:109], v[108:109], v[216:217] op_sel_hi:[1,0]
	v_pk_mul_f32 v[106:107], v[106:107], v[216:217] op_sel_hi:[1,0]
	v_pk_mul_f32 v[104:105], v[104:105], v[216:217] op_sel_hi:[1,0]
	v_pk_mul_f32 v[102:103], v[102:103], v[216:217] op_sel_hi:[1,0]
	v_pk_mul_f32 v[100:101], v[100:101], v[216:217] op_sel_hi:[1,0]
	v_pk_mul_f32 v[98:99], v[98:99], v[216:217] op_sel_hi:[1,0]
	v_pk_mul_f32 v[96:97], v[96:97], v[216:217] op_sel_hi:[1,0]
	v_pk_mul_f32 v[94:95], v[94:95], v[218:219] op_sel_hi:[1,0]
	v_pk_mul_f32 v[92:93], v[92:93], v[218:219] op_sel_hi:[1,0]
	v_pk_mul_f32 v[90:91], v[90:91], v[218:219] op_sel_hi:[1,0]
	v_pk_mul_f32 v[88:89], v[88:89], v[218:219] op_sel_hi:[1,0]
	v_pk_mul_f32 v[86:87], v[86:87], v[218:219] op_sel_hi:[1,0]
	v_pk_mul_f32 v[84:85], v[84:85], v[218:219] op_sel_hi:[1,0]
	v_pk_mul_f32 v[82:83], v[82:83], v[218:219] op_sel_hi:[1,0]
	v_pk_mul_f32 v[80:81], v[80:81], v[218:219] op_sel_hi:[1,0]
	v_pk_mul_f32 v[78:79], v[78:79], v[220:221] op_sel_hi:[1,0]
	v_pk_mul_f32 v[76:77], v[76:77], v[220:221] op_sel_hi:[1,0]
	v_pk_mul_f32 v[74:75], v[74:75], v[220:221] op_sel_hi:[1,0]
	v_pk_mul_f32 v[72:73], v[72:73], v[220:221] op_sel_hi:[1,0]
	v_pk_mul_f32 v[70:71], v[70:71], v[220:221] op_sel_hi:[1,0]
	v_pk_mul_f32 v[68:69], v[68:69], v[220:221] op_sel_hi:[1,0]
	v_pk_mul_f32 v[66:67], v[66:67], v[220:221] op_sel_hi:[1,0]
	v_pk_mul_f32 v[64:65], v[64:65], v[220:221] op_sel_hi:[1,0]
	v_pk_mul_f32 v[62:63], v[62:63], v[210:211] op_sel_hi:[1,0]
	v_pk_mul_f32 v[60:61], v[60:61], v[210:211] op_sel_hi:[1,0]
	v_pk_mul_f32 v[58:59], v[58:59], v[210:211] op_sel_hi:[1,0]
	v_pk_mul_f32 v[56:57], v[56:57], v[210:211] op_sel_hi:[1,0]
	v_pk_mul_f32 v[54:55], v[54:55], v[210:211] op_sel_hi:[1,0]
	v_pk_mul_f32 v[52:53], v[52:53], v[210:211] op_sel_hi:[1,0]
	v_pk_mul_f32 v[50:51], v[50:51], v[210:211] op_sel_hi:[1,0]
	v_pk_mul_f32 v[48:49], v[48:49], v[210:211] op_sel_hi:[1,0]
	v_pk_mul_f32 v[46:47], v[46:47], v[212:213] op_sel_hi:[1,0]
	v_pk_mul_f32 v[44:45], v[44:45], v[212:213] op_sel_hi:[1,0]
	v_pk_mul_f32 v[42:43], v[42:43], v[212:213] op_sel_hi:[1,0]
	v_pk_mul_f32 v[40:41], v[40:41], v[212:213] op_sel_hi:[1,0]
	v_pk_mul_f32 v[38:39], v[38:39], v[212:213] op_sel_hi:[1,0]
	v_pk_mul_f32 v[36:37], v[36:37], v[212:213] op_sel_hi:[1,0]
	v_pk_mul_f32 v[34:35], v[34:35], v[212:213] op_sel_hi:[1,0]
	v_pk_mul_f32 v[32:33], v[32:33], v[212:213] op_sel_hi:[1,0]
	v_pk_mul_f32 v[30:31], v[30:31], v[198:199] op_sel_hi:[1,0]
	v_pk_mul_f32 v[28:29], v[28:29], v[198:199] op_sel_hi:[1,0]
	v_pk_mul_f32 v[26:27], v[26:27], v[198:199] op_sel_hi:[1,0]
	v_pk_mul_f32 v[24:25], v[24:25], v[198:199] op_sel_hi:[1,0]
	v_pk_mul_f32 v[22:23], v[22:23], v[198:199] op_sel_hi:[1,0]
	v_pk_mul_f32 v[20:21], v[20:21], v[198:199] op_sel_hi:[1,0]
	v_pk_mul_f32 v[18:19], v[18:19], v[198:199] op_sel_hi:[1,0]
	v_pk_mul_f32 v[16:17], v[16:17], v[198:199] op_sel_hi:[1,0]
	v_pk_mul_f32 v[14:15], v[14:15], v[132:133] op_sel_hi:[1,0]
	v_pk_mul_f32 v[12:13], v[12:13], v[132:133] op_sel_hi:[1,0]
	v_pk_mul_f32 v[10:11], v[10:11], v[132:133] op_sel_hi:[1,0]
	v_pk_mul_f32 v[8:9], v[8:9], v[132:133] op_sel_hi:[1,0]
	v_pk_mul_f32 v[6:7], v[6:7], v[132:133] op_sel_hi:[1,0]
	v_pk_mul_f32 v[4:5], v[4:5], v[132:133] op_sel_hi:[1,0]
	v_pk_mul_f32 v[2:3], v[2:3], v[132:133] op_sel_hi:[1,0]
	v_pk_mul_f32 v[0:1], v[0:1], v[132:133] op_sel_hi:[1,0]
.Lp10e_nors2:
	s_waitcnt vmcnt(11)
	v_pk_mul_f32 v[144:145], v[144:145], s[22:23] op_sel_hi:[1,0]
	v_pk_mul_f32 v[142:143], v[142:143], s[22:23] op_sel_hi:[1,0]
	v_pk_mul_f32 v[148:149], v[148:149], s[22:23] op_sel_hi:[1,0]
	v_pk_mul_f32 v[146:147], v[146:147], s[22:23] op_sel_hi:[1,0]
	v_pk_mul_f32 v[152:153], v[152:153], s[22:23] op_sel_hi:[1,0]
	v_pk_mul_f32 v[150:151], v[150:151], s[22:23] op_sel_hi:[1,0]
	v_pk_mul_f32 v[156:157], v[156:157], s[22:23] op_sel_hi:[1,0]
	v_pk_mul_f32 v[154:155], v[154:155], s[22:23] op_sel_hi:[1,0]
	s_waitcnt vmcnt(10)
	v_pk_fma_f32 v[126:127], v[126:127], v[144:145], v[164:165]
	v_pk_fma_f32 v[124:125], v[124:125], v[142:143], v[162:163]
	global_load_dwordx4 v[162:165], v219, s[70:71] offset:576
	v_add_u32_e32 v219, 0x40000, v219
	global_store_dwordx4 v221, v[124:127], s[70:71]
	s_waitcnt vmcnt(11)
	v_pk_fma_f32 v[122:123], v[122:123], v[148:149], v[168:169]
	v_pk_fma_f32 v[120:121], v[120:121], v[146:147], v[166:167]
	global_load_dwordx4 v[166:169], v219, s[70:71]
	global_store_dwordx4 v221, v[120:123], s[70:71] offset:64
	s_waitcnt vmcnt(12)
	v_pk_fma_f32 v[118:119], v[118:119], v[152:153], v[172:173]
	v_pk_fma_f32 v[116:117], v[116:117], v[150:151], v[170:171]
	global_load_dwordx4 v[170:173], v219, s[70:71] offset:64
	global_store_dwordx4 v221, v[116:119], s[70:71] offset:512
	s_waitcnt vmcnt(13)
	v_pk_fma_f32 v[114:115], v[114:115], v[156:157], v[176:177]
	v_pk_fma_f32 v[112:113], v[112:113], v[154:155], v[174:175]
	global_load_dwordx4 v[174:177], v219, s[70:71] offset:512
	global_store_dwordx4 v221, v[112:115], s[70:71] offset:576
	v_add_u32_e32 v221, 0x40000, v221
	s_waitcnt vmcnt(14)
	v_pk_fma_f32 v[110:111], v[110:111], v[144:145], v[180:181]
	v_pk_fma_f32 v[108:109], v[108:109], v[142:143], v[178:179]
	global_load_dwordx4 v[178:181], v219, s[70:71] offset:576
	v_add_u32_e32 v219, 0x140000, v219
	global_store_dwordx4 v221, v[108:111], s[70:71]
	s_waitcnt vmcnt(15)
	v_pk_fma_f32 v[106:107], v[106:107], v[148:149], v[184:185]
	v_pk_fma_f32 v[104:105], v[104:105], v[146:147], v[182:183]
	global_load_dwordx4 v[182:185], v219, s[70:71]
	global_store_dwordx4 v221, v[104:107], s[70:71] offset:64
	s_waitcnt vmcnt(16)
	v_pk_fma_f32 v[102:103], v[102:103], v[152:153], v[188:189]
	v_pk_fma_f32 v[100:101], v[100:101], v[150:151], v[186:187]
	global_load_dwordx4 v[186:189], v219, s[70:71] offset:64
	global_store_dwordx4 v221, v[100:103], s[70:71] offset:512
	s_waitcnt vmcnt(17)
	v_pk_fma_f32 v[98:99], v[98:99], v[156:157], v[192:193]
	v_pk_fma_f32 v[96:97], v[96:97], v[154:155], v[190:191]
	global_load_dwordx4 v[190:193], v219, s[70:71] offset:512
	global_store_dwordx4 v221, v[96:99], s[70:71] offset:576
	v_add_u32_e32 v221, 0x40000, v221
	s_waitcnt vmcnt(18)
	v_pk_fma_f32 v[94:95], v[94:95], v[144:145], v[196:197]
	v_pk_fma_f32 v[92:93], v[92:93], v[142:143], v[194:195]
	global_load_dwordx4 v[194:197], v219, s[70:71] offset:576
	v_add_u32_e32 v219, 0x40000, v219
	global_store_dwordx4 v221, v[92:95], s[70:71]
	s_waitcnt vmcnt(19)
	v_pk_fma_f32 v[90:91], v[90:91], v[148:149], v[204:205]
	v_pk_fma_f32 v[88:89], v[88:89], v[146:147], v[202:203]
	global_load_dwordx4 v[202:205], v219, s[70:71]
	global_store_dwordx4 v221, v[88:91], s[70:71] offset:64
	s_waitcnt vmcnt(20)
	v_pk_fma_f32 v[86:87], v[86:87], v[152:153], v[208:209]
	v_pk_fma_f32 v[84:85], v[84:85], v[150:151], v[206:207]
	global_load_dwordx4 v[206:209], v219, s[70:71] offset:64
	global_store_dwordx4 v221, v[84:87], s[70:71] offset:512
	s_waitcnt vmcnt(21)
	v_pk_fma_f32 v[82:83], v[82:83], v[156:157], v[164:165]
	v_pk_fma_f32 v[80:81], v[80:81], v[154:155], v[162:163]
	global_load_dwordx4 v[162:165], v219, s[70:71] offset:512
	global_store_dwordx4 v221, v[80:83], s[70:71] offset:576
	v_add_u32_e32 v221, 0x40000, v221
	s_waitcnt vmcnt(21)
	v_pk_fma_f32 v[78:79], v[78:79], v[144:145], v[168:169]
	v_pk_fma_f32 v[76:77], v[76:77], v[142:143], v[166:167]
	global_load_dwordx4 v[166:169], v219, s[70:71] offset:576
	v_add_u32_e32 v219, 0x40000, v219
	global_store_dwordx4 v221, v[76:79], s[70:71]
	s_waitcnt vmcnt(21)
	v_pk_fma_f32 v[74:75], v[74:75], v[148:149], v[172:173]
	v_pk_fma_f32 v[72:73], v[72:73], v[146:147], v[170:171]
	global_load_dwordx4 v[170:173], v219, s[70:71]
	global_store_dwordx4 v221, v[72:75], s[70:71] offset:64
	s_waitcnt vmcnt(21)
	v_pk_fma_f32 v[70:71], v[70:71], v[152:153], v[176:177]
	v_pk_fma_f32 v[68:69], v[68:69], v[150:151], v[174:175]
	global_load_dwordx4 v[174:177], v219, s[70:71] offset:64
	global_store_dwordx4 v221, v[68:71], s[70:71] offset:512
	s_waitcnt vmcnt(21)
	v_pk_fma_f32 v[66:67], v[66:67], v[156:157], v[180:181]
	v_pk_fma_f32 v[64:65], v[64:65], v[154:155], v[178:179]
	global_load_dwordx4 v[178:181], v219, s[70:71] offset:512
	global_store_dwordx4 v221, v[64:67], s[70:71] offset:576
	v_add_u32_e32 v221, 0x140000, v221
	s_waitcnt vmcnt(21)
	v_pk_fma_f32 v[62:63], v[62:63], v[144:145], v[184:185]
	v_pk_fma_f32 v[60:61], v[60:61], v[142:143], v[182:183]
	global_load_dwordx4 v[182:185], v219, s[70:71] offset:576
	v_add_u32_e32 v219, 0x40000, v219
	global_store_dwordx4 v221, v[60:63], s[70:71]
	s_waitcnt vmcnt(21)
	v_pk_fma_f32 v[58:59], v[58:59], v[148:149], v[188:189]
	v_pk_fma_f32 v[56:57], v[56:57], v[146:147], v[186:187]
	global_load_dwordx4 v[186:189], v219, s[70:71]
	global_store_dwordx4 v221, v[56:59], s[70:71] offset:64
	s_waitcnt vmcnt(21)
	v_pk_fma_f32 v[54:55], v[54:55], v[152:153], v[192:193]
	v_pk_fma_f32 v[52:53], v[52:53], v[150:151], v[190:191]
	global_load_dwordx4 v[190:193], v219, s[70:71] offset:64
	global_store_dwordx4 v221, v[52:55], s[70:71] offset:512
	s_waitcnt vmcnt(21)
	v_pk_fma_f32 v[50:51], v[50:51], v[156:157], v[196:197]
	v_pk_fma_f32 v[48:49], v[48:49], v[154:155], v[194:195]
	global_load_dwordx4 v[194:197], v219, s[70:71] offset:512
	global_store_dwordx4 v221, v[48:51], s[70:71] offset:576
	v_add_u32_e32 v221, 0x40000, v221
	s_waitcnt vmcnt(21)
	v_pk_fma_f32 v[46:47], v[46:47], v[144:145], v[204:205]
	v_pk_fma_f32 v[44:45], v[44:45], v[142:143], v[202:203]
	global_load_dwordx4 v[202:205], v219, s[70:71] offset:576
	global_store_dwordx4 v221, v[44:47], s[70:71]
	s_waitcnt vmcnt(21)
	v_pk_fma_f32 v[42:43], v[42:43], v[148:149], v[208:209]
	v_pk_fma_f32 v[40:41], v[40:41], v[146:147], v[206:207]
	global_store_dwordx4 v221, v[40:43], s[70:71] offset:64
	s_waitcnt vmcnt(20)
	v_pk_fma_f32 v[38:39], v[38:39], v[152:153], v[164:165]
	v_pk_fma_f32 v[36:37], v[36:37], v[150:151], v[162:163]
	global_store_dwordx4 v221, v[36:39], s[70:71] offset:512
	s_waitcnt vmcnt(19)
	v_pk_fma_f32 v[34:35], v[34:35], v[156:157], v[168:169]
	v_pk_fma_f32 v[32:33], v[32:33], v[154:155], v[166:167]
	global_store_dwordx4 v221, v[32:35], s[70:71] offset:576
	v_add_u32_e32 v221, 0x40000, v221
	s_waitcnt vmcnt(18)
	v_pk_fma_f32 v[30:31], v[30:31], v[144:145], v[172:173]
	v_pk_fma_f32 v[28:29], v[28:29], v[142:143], v[170:171]
	global_store_dwordx4 v221, v[28:31], s[70:71]
	s_waitcnt vmcnt(17)
	v_pk_fma_f32 v[26:27], v[26:27], v[148:149], v[176:177]
	v_pk_fma_f32 v[24:25], v[24:25], v[146:147], v[174:175]
	global_store_dwordx4 v221, v[24:27], s[70:71] offset:64
	s_waitcnt vmcnt(16)
	v_pk_fma_f32 v[22:23], v[22:23], v[152:153], v[180:181]
	v_pk_fma_f32 v[20:21], v[20:21], v[150:151], v[178:179]
	global_store_dwordx4 v221, v[20:23], s[70:71] offset:512
	s_waitcnt vmcnt(15)
	v_pk_fma_f32 v[18:19], v[18:19], v[156:157], v[184:185]
	v_pk_fma_f32 v[16:17], v[16:17], v[154:155], v[182:183]
	global_store_dwordx4 v221, v[16:19], s[70:71] offset:576
	v_add_u32_e32 v221, 0x40000, v221
	s_waitcnt vmcnt(14)
	v_pk_fma_f32 v[14:15], v[14:15], v[144:145], v[188:189]
	v_pk_fma_f32 v[12:13], v[12:13], v[142:143], v[186:187]
	global_store_dwordx4 v221, v[12:15], s[70:71]
	s_waitcnt vmcnt(13)
	v_pk_fma_f32 v[10:11], v[10:11], v[148:149], v[192:193]
	v_pk_fma_f32 v[8:9], v[8:9], v[146:147], v[190:191]
	global_store_dwordx4 v221, v[8:11], s[70:71] offset:64
	s_waitcnt vmcnt(12)
	v_pk_fma_f32 v[6:7], v[6:7], v[152:153], v[196:197]
	v_pk_fma_f32 v[4:5], v[4:5], v[150:151], v[194:195]
	global_store_dwordx4 v221, v[4:7], s[70:71] offset:512
	s_waitcnt vmcnt(11)
	v_pk_fma_f32 v[2:3], v[2:3], v[156:157], v[204:205]
	v_pk_fma_f32 v[0:1], v[0:1], v[154:155], v[202:203]
	global_store_dwordx4 v221, v[0:3], s[70:71] offset:576
	s_andn2_b64 vcc, exec, s[8:9]
	s_mov_b64 s[8:9], -1
	s_waitcnt vmcnt(0)
	s_cbranch_vccnz .LBB0_2360
	s_andn2_b64 vcc, exec, s[0:1]
	s_cbranch_vccnz .LBB0_2359
	s_barrier
	s_branch .LBB0_2359

.LBB0_2509:
	v_lshl_or_b32 v134, s1, 8, v159
	v_ashrrev_i32_e32 v135, 31, v134
	v_lshl_add_u32 v132, s0, 8, v157
	v_lshl_add_u64 v[170:171], v[134:135], 2, s[14:15]
	global_load_dwordx4 v[128:131], v[170:171], off
	v_ashrrev_i32_e32 v133, 31, v132
	v_lshl_add_u32 v140, v132, 12, v134
	v_lshl_add_u64 v[150:151], v[132:133], 2, s[40:41]
	v_lshl_add_u64 v[154:155], v[140:141], 1, s[46:47]
	global_load_dword v156, v[150:151], off
	global_load_dwordx2 v[174:175], v[154:155], off
	v_lshl_add_u64 v[152:153], v[140:141], 2, s[70:71]
	global_load_dwordx4 v[162:165], v[152:153], off
	v_cvt_f32_i32_e32 v176, v124
	v_cvt_f32_i32_e32 v177, v125
	v_cvt_f32_i32_e32 v178, v126
	v_cvt_f32_i32_e32 v179, v127
	global_load_dwordx4 v[166:169], v[170:171], off offset:64
	global_load_dwordx4 v[132:135], v[170:171], off offset:512
	global_load_dwordx4 v[124:127], v[170:171], off offset:576
	s_nop 0
	global_load_dwordx4 v[170:173], v[152:153], off offset:64
	v_add_u32_e32 v140, 0x10000, v140
	v_cvt_f32_i32_e32 v108, v108
	v_cvt_f32_i32_e32 v109, v109
	v_cvt_f32_i32_e32 v110, v110
	v_cvt_f32_i32_e32 v111, v111
	v_cvt_f32_i32_e32 v104, v104
	v_cvt_f32_i32_e32 v105, v105
	v_cvt_f32_i32_e32 v106, v106
	v_cvt_f32_i32_e32 v107, v107
	v_cvt_f32_i32_e32 v100, v100
	v_cvt_f32_i32_e32 v101, v101
	v_cvt_f32_i32_e32 v96, v96
	v_cvt_f32_i32_e32 v97, v97
	v_cvt_f32_i32_e32 v98, v98
	v_cvt_f32_i32_e32 v99, v99
	v_cvt_f32_i32_e32 v92, v92
	v_cvt_f32_i32_e32 v93, v93
	v_cvt_f32_i32_e32 v94, v94
	v_cvt_f32_i32_e32 v95, v95
	v_cvt_f32_i32_e32 v88, v88
	v_cvt_f32_i32_e32 v89, v89
	v_cvt_f32_i32_e32 v90, v90
	v_cvt_f32_i32_e32 v91, v91
	v_cvt_f32_i32_e32 v84, v84
	v_cvt_f32_i32_e32 v85, v85
	v_cvt_f32_i32_e32 v80, v80
	v_cvt_f32_i32_e32 v81, v81
	v_cvt_f32_i32_e32 v82, v82
	v_cvt_f32_i32_e32 v83, v83
	v_cvt_f32_i32_e32 v76, v76
	v_cvt_f32_i32_e32 v77, v77
	v_cvt_f32_i32_e32 v78, v78
	v_cvt_f32_i32_e32 v79, v79
	v_cvt_f32_i32_e32 v72, v72
	v_cvt_f32_i32_e32 v73, v73
	v_cvt_f32_i32_e32 v74, v74
	v_cvt_f32_i32_e32 v75, v75
	v_cvt_f32_i32_e32 v68, v68
	v_cvt_f32_i32_e32 v69, v69
	v_cvt_f32_i32_e32 v64, v64
	v_cvt_f32_i32_e32 v65, v65
	v_cvt_f32_i32_e32 v66, v66
	v_cvt_f32_i32_e32 v67, v67
	v_cvt_f32_i32_e32 v60, v60
	v_cvt_f32_i32_e32 v61, v61
	v_cvt_f32_i32_e32 v62, v62
	v_cvt_f32_i32_e32 v63, v63
	v_cvt_f32_i32_e32 v56, v56
	v_cvt_f32_i32_e32 v57, v57
	v_cvt_f32_i32_e32 v58, v58
	v_cvt_f32_i32_e32 v59, v59
	v_cvt_f32_i32_e32 v52, v52
	v_cvt_f32_i32_e32 v53, v53
	v_cvt_f32_i32_e32 v48, v48
	v_cvt_f32_i32_e32 v49, v49
	v_cvt_f32_i32_e32 v50, v50
	v_cvt_f32_i32_e32 v51, v51
	v_cvt_f32_i32_e32 v44, v44
	v_cvt_f32_i32_e32 v45, v45
	v_cvt_f32_i32_e32 v46, v46
	v_cvt_f32_i32_e32 v47, v47
	v_cvt_f32_i32_e32 v40, v40
	v_cvt_f32_i32_e32 v41, v41
	v_cvt_f32_i32_e32 v42, v42
	v_cvt_f32_i32_e32 v43, v43
	v_cvt_f32_i32_e32 v36, v36
	s_waitcnt vmcnt(0)
	v_pk_mul_f32 v[128:129], v[128:129], s[22:23] op_sel_hi:[1,0]
	v_pk_mul_f32 v[130:131], v[130:131], s[22:23] op_sel_hi:[1,0]
	v_pk_mul_f32 v[176:177], v[176:177], v[128:129]
	v_pk_mul_f32 v[178:179], v[178:179], v[130:131]
	v_cvt_f32_i32_e32 v37, v37
	v_pk_mul_f32 v[176:177], v[176:177], v[156:157] op_sel_hi:[1,0]
	v_lshlrev_b32_e32 v180, 16, v174
	v_and_b32_e32 v181, 0xffff0000, v174
	v_mul_f32_e32 v161, 0xbfb8aa3b, v176
	v_mul_f32_e32 v174, 0xbfb8aa3b, v177
	v_pk_mul_f32 v[178:179], v[178:179], v[156:157] op_sel_hi:[1,0]
	v_exp_f32_e32 v176, v161
	v_exp_f32_e32 v177, v174
	v_mul_f32_e32 v178, 0xbfb8aa3b, v178
	v_mul_f32_e32 v179, 0xbfb8aa3b, v179
	v_exp_f32_e32 v178, v178
	v_exp_f32_e32 v179, v179
	v_pk_add_f32 v[176:177], v[176:177], 1.0 op_sel_hi:[1,0]
	v_lshlrev_b32_e32 v174, 16, v175
	v_pk_add_f32 v[178:179], v[178:179], 1.0 op_sel_hi:[1,0]
	s_mov_b64 vcc, s[0:1]
	v_rcp_f32_e32 v161, v177
	s_nop 0
	v_mul_f32_e32 v177, 1.0, v161
	s_mov_b64 vcc, s[8:9]
	v_rcp_f32_e32 v161, v176
	s_nop 0
	v_mul_f32_e32 v176, 1.0, v161
	s_mov_b64 vcc, s[10:11]
	v_pk_fma_f32 v[162:163], v[176:177], v[180:181], v[162:163]
	v_rcp_f32_e32 v161, v179
	s_nop 0
	v_mul_f32_e32 v177, 1.0, v161
	v_and_b32_e32 v175, 0xffff0000, v175
	v_rcp_f32_e32 v161, v178
	s_nop 0
	v_mul_f32_e32 v176, 1.0, v161
	v_pk_fma_f32 v[164:165], v[176:177], v[174:175], v[164:165]
	global_store_dwordx4 v[152:153], v[162:165], off
	global_load_dwordx2 v[162:163], v[154:155], off offset:32
	v_cvt_f32_i32_e32 v174, v122
	v_cvt_f32_i32_e32 v164, v120
	v_cvt_f32_i32_e32 v165, v121
	v_cvt_f32_i32_e32 v175, v123
	v_pk_mul_f32 v[122:123], v[166:167], s[22:23] op_sel_hi:[1,0]
	v_pk_mul_f32 v[120:121], v[168:169], s[22:23] op_sel_hi:[1,0]
	v_pk_mul_f32 v[164:165], v[164:165], v[122:123]
	v_pk_mul_f32 v[166:167], v[174:175], v[120:121]
	v_pk_mul_f32 v[164:165], v[164:165], v[156:157] op_sel_hi:[1,0]
	v_pk_mul_f32 v[166:167], v[166:167], v[156:157] op_sel_hi:[1,0]
	v_mul_f32_e32 v161, 0xbfb8aa3b, v164
	v_mul_f32_e32 v165, 0xbfb8aa3b, v165
	v_exp_f32_e32 v164, v161
	v_exp_f32_e32 v165, v165
	v_mul_f32_e32 v166, 0xbfb8aa3b, v166
	v_mul_f32_e32 v167, 0xbfb8aa3b, v167
	v_exp_f32_e32 v166, v166
	v_exp_f32_e32 v167, v167
	v_pk_add_f32 v[164:165], v[164:165], 1.0 op_sel_hi:[1,0]
	v_pk_mul_f32 v[104:105], v[104:105], v[122:123]
	v_pk_add_f32 v[166:167], v[166:167], 1.0 op_sel_hi:[1,0]
	s_mov_b64 vcc, s[0:1]
	v_rcp_f32_e32 v161, v165
	s_nop 0
	v_mul_f32_e32 v165, 1.0, v161
	s_mov_b64 vcc, s[8:9]
	v_rcp_f32_e32 v161, v164
	s_nop 0
	v_mul_f32_e32 v164, 1.0, v161
	s_mov_b64 vcc, s[10:11]
	v_rcp_f32_e32 v161, v167
	s_nop 0
	v_mul_f32_e32 v167, 1.0, v161
	v_rcp_f32_e32 v161, v166
	s_nop 0
	v_mul_f32_e32 v166, 1.0, v161
	v_pk_mul_f32 v[106:107], v[106:107], v[120:121]
	v_pk_mul_f32 v[88:89], v[88:89], v[122:123]
	v_pk_mul_f32 v[90:91], v[90:91], v[120:121]
	s_waitcnt vmcnt(0)
	v_lshlrev_b32_e32 v168, 16, v162
	v_and_b32_e32 v169, 0xffff0000, v162
	v_lshlrev_b32_e32 v174, 16, v163
	v_and_b32_e32 v175, 0xffff0000, v163
	v_pk_fma_f32 v[162:163], v[164:165], v[168:169], v[170:171]
	v_pk_fma_f32 v[164:165], v[166:167], v[174:175], v[172:173]
	global_store_dwordx4 v[152:153], v[162:165], off offset:64
	global_load_dwordx2 v[166:167], v[154:155], off offset:256
	v_cvt_f32_i32_e32 v168, v116
	global_load_dwordx4 v[162:165], v[152:153], off offset:512
	v_cvt_f32_i32_e32 v169, v117
	v_cvt_f32_i32_e32 v170, v118
	v_cvt_f32_i32_e32 v171, v119
	v_pk_mul_f32 v[118:119], v[132:133], s[22:23] op_sel_hi:[1,0]
	v_pk_mul_f32 v[116:117], v[134:135], s[22:23] op_sel_hi:[1,0]
	v_pk_mul_f32 v[134:135], v[168:169], v[118:119]
	v_pk_mul_f32 v[132:133], v[170:171], v[116:117]
	v_pk_mul_f32 v[134:135], v[134:135], v[156:157] op_sel_hi:[1,0]
	v_pk_mul_f32 v[132:133], v[132:133], v[156:157] op_sel_hi:[1,0]
	v_mul_f32_e32 v134, 0xbfb8aa3b, v134
	v_mul_f32_e32 v135, 0xbfb8aa3b, v135
	v_exp_f32_e32 v168, v134
	v_exp_f32_e32 v169, v135
	v_mul_f32_e32 v132, 0xbfb8aa3b, v132
	v_mul_f32_e32 v133, 0xbfb8aa3b, v133
	v_exp_f32_e32 v170, v132
	v_exp_f32_e32 v171, v133
	v_pk_add_f32 v[168:169], v[168:169], 1.0 op_sel_hi:[1,0]
	global_load_dwordx4 v[132:135], v[152:153], off offset:576
	v_pk_add_f32 v[170:171], v[170:171], 1.0 op_sel_hi:[1,0]
	s_mov_b64 vcc, s[0:1]
	v_rcp_f32_e32 v161, v169
	s_nop 0
	v_mul_f32_e32 v169, 1.0, v161
	s_mov_b64 vcc, s[8:9]
	v_rcp_f32_e32 v161, v168
	s_nop 0
	v_mul_f32_e32 v168, 1.0, v161
	s_mov_b64 vcc, s[10:11]
	v_rcp_f32_e32 v161, v171
	s_nop 0
	v_mul_f32_e32 v171, 1.0, v161
	v_rcp_f32_e32 v161, v170
	s_nop 0
	v_mul_f32_e32 v170, 1.0, v161
	v_pk_mul_f32 v[100:101], v[100:101], v[118:119]
	v_pk_mul_f32 v[84:85], v[84:85], v[118:119]
	s_waitcnt vmcnt(0)
	v_lshlrev_b32_e32 v172, 16, v166
	v_and_b32_e32 v173, 0xffff0000, v166
	v_lshlrev_b32_e32 v166, 16, v167
	v_and_b32_e32 v167, 0xffff0000, v167
	v_pk_fma_f32 v[162:163], v[168:169], v[172:173], v[162:163]
	v_pk_fma_f32 v[164:165], v[170:171], v[166:167], v[164:165]
	global_store_dwordx4 v[152:153], v[162:165], off offset:512
	global_load_dwordx2 v[154:155], v[154:155], off offset:288
	v_pk_mul_f32 v[72:73], v[72:73], v[122:123]
	v_cvt_f32_i32_e32 v162, v112
	v_cvt_f32_i32_e32 v163, v113
	v_cvt_f32_i32_e32 v164, v114
	v_cvt_f32_i32_e32 v165, v115
	v_pk_mul_f32 v[114:115], v[124:125], s[22:23] op_sel_hi:[1,0]
	v_pk_mul_f32 v[112:113], v[126:127], s[22:23] op_sel_hi:[1,0]
	v_pk_mul_f32 v[126:127], v[162:163], v[114:115]
	v_pk_mul_f32 v[124:125], v[164:165], v[112:113]
	v_pk_mul_f32 v[126:127], v[126:127], v[156:157] op_sel_hi:[1,0]
	v_pk_mul_f32 v[124:125], v[124:125], v[156:157] op_sel_hi:[1,0]
	v_mul_f32_e32 v126, 0xbfb8aa3b, v126
	v_mul_f32_e32 v127, 0xbfb8aa3b, v127
	v_mul_f32_e32 v156, 0xbfb8aa3b, v124
	v_mul_f32_e32 v161, 0xbfb8aa3b, v125
	v_exp_f32_e32 v124, v126
	v_exp_f32_e32 v125, v127
	v_exp_f32_e32 v126, v156
	v_exp_f32_e32 v127, v161
	v_pk_mul_f32 v[96:97], v[96:97], v[114:115]
	v_pk_add_f32 v[124:125], v[124:125], 1.0 op_sel_hi:[1,0]
	v_pk_mul_f32 v[98:99], v[98:99], v[112:113]
	v_pk_add_f32 v[126:127], v[126:127], 1.0 op_sel_hi:[1,0]
	s_mov_b64 vcc, s[0:1]
	v_rcp_f32_e32 v156, v125
	s_nop 0
	v_mul_f32_e32 v125, 1.0, v156
	s_mov_b64 vcc, s[8:9]
	v_rcp_f32_e32 v156, v124
	s_nop 0
	v_mul_f32_e32 v124, 1.0, v156
	s_mov_b64 vcc, s[10:11]
	v_rcp_f32_e32 v156, v127
	s_nop 0
	v_mul_f32_e32 v127, 1.0, v156
	v_rcp_f32_e32 v156, v126
	s_nop 0
	v_mul_f32_e32 v126, 1.0, v156
	v_pk_mul_f32 v[164:165], v[108:109], v[128:129]
	s_waitcnt vmcnt(0)
	v_lshlrev_b32_e32 v162, 16, v154
	v_and_b32_e32 v163, 0xffff0000, v154
	v_lshlrev_b32_e32 v154, 16, v155
	v_and_b32_e32 v155, 0xffff0000, v155
	v_pk_fma_f32 v[124:125], v[124:125], v[162:163], v[132:133]
	v_pk_fma_f32 v[126:127], v[126:127], v[154:155], v[134:135]
	global_store_dwordx4 v[152:153], v[124:127], off offset:576
	global_load_dword v126, v[150:151], off offset:64
	v_lshl_add_u64 v[132:133], v[140:141], 1, s[46:47]
	global_load_dwordx2 v[134:135], v[132:133], off
	v_lshl_add_u64 v[124:125], v[140:141], 2, s[70:71]
	global_load_dwordx4 v[152:155], v[124:125], off
	v_pk_mul_f32 v[162:163], v[110:111], v[130:131]
	global_load_dwordx4 v[108:111], v[124:125], off offset:64
	v_add_u32_e32 v140, 0x10000, v140
	v_pk_mul_f32 v[80:81], v[80:81], v[114:115]
	v_pk_mul_f32 v[82:83], v[82:83], v[112:113]
	v_pk_mul_f32 v[74:75], v[74:75], v[120:121]
	v_pk_mul_f32 v[68:69], v[68:69], v[118:119]
	v_pk_mul_f32 v[64:65], v[64:65], v[114:115]
	v_pk_mul_f32 v[66:67], v[66:67], v[112:113]
	v_pk_mul_f32 v[56:57], v[56:57], v[122:123]
	v_pk_mul_f32 v[58:59], v[58:59], v[120:121]
	v_pk_mul_f32 v[52:53], v[52:53], v[118:119]
	v_pk_mul_f32 v[48:49], v[48:49], v[114:115]
	v_pk_mul_f32 v[50:51], v[50:51], v[112:113]
	v_pk_mul_f32 v[40:41], v[40:41], v[122:123]
	v_pk_mul_f32 v[42:43], v[42:43], v[120:121]
	v_pk_mul_f32 v[36:37], v[36:37], v[118:119]
	v_cvt_f32_i32_e32 v32, v32
	v_cvt_f32_i32_e32 v33, v33
	v_cvt_f32_i32_e32 v34, v34
	v_cvt_f32_i32_e32 v35, v35
	v_cvt_f32_i32_e32 v28, v28
	v_pk_mul_f32 v[32:33], v[32:33], v[114:115]
	v_cvt_f32_i32_e32 v29, v29
	v_pk_mul_f32 v[34:35], v[34:35], v[112:113]
	v_cvt_f32_i32_e32 v30, v30
	v_cvt_f32_i32_e32 v31, v31
	v_cvt_f32_i32_e32 v24, v24
	v_cvt_f32_i32_e32 v25, v25
	v_cvt_f32_i32_e32 v26, v26
	v_cvt_f32_i32_e32 v27, v27
	v_cvt_f32_i32_e32 v20, v20
	v_pk_mul_f32 v[24:25], v[24:25], v[122:123]
	v_cvt_f32_i32_e32 v21, v21
	v_pk_mul_f32 v[26:27], v[26:27], v[120:121]
	v_cvt_f32_i32_e32 v16, v16
	v_cvt_f32_i32_e32 v17, v17
	v_pk_mul_f32 v[20:21], v[20:21], v[118:119]
	v_cvt_f32_i32_e32 v18, v18
	v_cvt_f32_i32_e32 v19, v19
	v_pk_mul_f32 v[16:17], v[16:17], v[114:115]
	v_cvt_f32_i32_e32 v12, v12
	v_cvt_f32_i32_e32 v13, v13
	v_pk_mul_f32 v[18:19], v[18:19], v[112:113]
	v_cvt_f32_i32_e32 v14, v14
	v_cvt_f32_i32_e32 v15, v15
	v_cvt_f32_i32_e32 v8, v8
	v_cvt_f32_i32_e32 v9, v9
	v_cvt_f32_i32_e32 v10, v10
	v_cvt_f32_i32_e32 v11, v11
	v_cvt_f32_i32_e32 v4, v4
	v_pk_mul_f32 v[8:9], v[8:9], v[122:123]
	v_cvt_f32_i32_e32 v5, v5
	v_pk_mul_f32 v[10:11], v[10:11], v[120:121]
	v_cvt_f32_i32_e32 v0, v0
	v_cvt_f32_i32_e32 v1, v1
	v_pk_mul_f32 v[4:5], v[4:5], v[118:119]
	v_cvt_f32_i32_e32 v2, v2
	v_cvt_f32_i32_e32 v3, v3
	v_pk_mul_f32 v[0:1], v[0:1], v[114:115]
	v_pk_mul_f32 v[2:3], v[2:3], v[112:113]
	s_waitcnt vmcnt(0)
	v_pk_mul_f32 v[164:165], v[164:165], v[126:127] op_sel_hi:[1,0]
	v_pk_mul_f32 v[162:163], v[162:163], v[126:127] op_sel_hi:[1,0]
	v_mul_f32_e32 v127, 0xbfb8aa3b, v164
	v_mul_f32_e32 v156, 0xbfb8aa3b, v165
	v_mul_f32_e32 v161, 0xbfb8aa3b, v162
	v_mul_f32_e32 v165, 0xbfb8aa3b, v163
	v_exp_f32_e32 v162, v127
	v_exp_f32_e32 v163, v156
	v_exp_f32_e32 v164, v161
	v_exp_f32_e32 v165, v165
	v_lshlrev_b32_e32 v166, 16, v134
	v_pk_add_f32 v[162:163], v[162:163], 1.0 op_sel_hi:[1,0]
	v_and_b32_e32 v167, 0xffff0000, v134
	v_pk_add_f32 v[164:165], v[164:165], 1.0 op_sel_hi:[1,0]
	s_mov_b64 vcc, s[0:1]
	v_rcp_f32_e32 v127, v163
	s_nop 0
	v_mul_f32_e32 v163, 1.0, v127
	s_mov_b64 vcc, s[8:9]
	v_rcp_f32_e32 v127, v162
	s_nop 0
	v_mul_f32_e32 v162, 1.0, v127
	s_mov_b64 vcc, s[10:11]
	v_pk_fma_f32 v[152:153], v[162:163], v[166:167], v[152:153]
	v_rcp_f32_e32 v127, v165
	s_nop 0
	v_mul_f32_e32 v163, 1.0, v127
	v_lshlrev_b32_e32 v134, 16, v135
	v_and_b32_e32 v135, 0xffff0000, v135
	v_rcp_f32_e32 v127, v164
	s_nop 0
	v_mul_f32_e32 v162, 1.0, v127
	v_pk_fma_f32 v[154:155], v[162:163], v[134:135], v[154:155]
	global_store_dwordx4 v[124:125], v[152:155], off
	global_load_dwordx2 v[134:135], v[132:133], off offset:32
	v_pk_mul_f32 v[104:105], v[104:105], v[126:127] op_sel_hi:[1,0]
	v_pk_mul_f32 v[106:107], v[106:107], v[126:127] op_sel_hi:[1,0]
	v_mul_f32_e32 v104, 0xbfb8aa3b, v104
	v_mul_f32_e32 v105, 0xbfb8aa3b, v105
	v_exp_f32_e32 v104, v104
	v_exp_f32_e32 v105, v105
	v_mul_f32_e32 v106, 0xbfb8aa3b, v106
	v_mul_f32_e32 v107, 0xbfb8aa3b, v107
	v_exp_f32_e32 v106, v106
	v_exp_f32_e32 v107, v107
	v_pk_add_f32 v[104:105], v[104:105], 1.0 op_sel_hi:[1,0]
	v_pk_add_f32 v[106:107], v[106:107], 1.0 op_sel_hi:[1,0]
	s_mov_b64 vcc, s[0:1]
	v_rcp_f32_e32 v127, v105
	s_nop 0
	v_mul_f32_e32 v105, 1.0, v127
	s_mov_b64 vcc, s[8:9]
	v_rcp_f32_e32 v127, v104
	s_nop 0
	v_mul_f32_e32 v104, 1.0, v127
	s_mov_b64 vcc, s[10:11]
	v_rcp_f32_e32 v127, v107
	s_nop 0
	v_mul_f32_e32 v107, 1.0, v127
	v_rcp_f32_e32 v127, v106
	s_nop 0
	v_mul_f32_e32 v106, 1.0, v127
	v_pk_mul_f32 v[100:101], v[100:101], v[126:127] op_sel_hi:[1,0]
	s_waitcnt vmcnt(0)
	v_lshlrev_b32_e32 v152, 16, v134
	v_and_b32_e32 v153, 0xffff0000, v134
	v_lshlrev_b32_e32 v134, 16, v135
	v_and_b32_e32 v135, 0xffff0000, v135
	v_pk_fma_f32 v[104:105], v[104:105], v[152:153], v[108:109]
	v_pk_fma_f32 v[106:107], v[106:107], v[134:135], v[110:111]
	global_store_dwordx4 v[124:125], v[104:107], off offset:64
	global_load_dwordx2 v[110:111], v[132:133], off offset:256
	v_mul_f32_e32 v100, 0xbfb8aa3b, v100
	v_cvt_f32_i32_e32 v106, v102
	v_cvt_f32_i32_e32 v107, v103
	global_load_dwordx4 v[102:105], v[124:125], off offset:512
	v_mul_f32_e32 v101, 0xbfb8aa3b, v101
	v_exp_f32_e32 v100, v100
	v_pk_mul_f32 v[106:107], v[106:107], v[116:117]
	v_exp_f32_e32 v101, v101
	v_pk_mul_f32 v[106:107], v[106:107], v[126:127] op_sel_hi:[1,0]
	v_pk_add_f32 v[100:101], v[100:101], 1.0 op_sel_hi:[1,0]
	v_mul_f32_e32 v106, 0xbfb8aa3b, v106
	v_mul_f32_e32 v107, 0xbfb8aa3b, v107
	v_exp_f32_e32 v134, v106
	v_exp_f32_e32 v135, v107
	s_nop 0
	v_pk_add_f32 v[134:135], v[134:135], 1.0 op_sel_hi:[1,0]
	s_mov_b64 vcc, s[0:1]
	v_rcp_f32_e32 v127, v101
	s_nop 0
	v_mul_f32_e32 v101, 1.0, v127
	s_mov_b64 vcc, s[8:9]
	v_rcp_f32_e32 v127, v100
	s_nop 0
	v_mul_f32_e32 v100, 1.0, v127
	s_mov_b64 vcc, s[10:11]
	v_rcp_f32_e32 v127, v135
	s_nop 0
	v_mul_f32_e32 v135, 1.0, v127
	v_rcp_f32_e32 v127, v134
	s_nop 0
	v_mul_f32_e32 v134, 1.0, v127
	global_load_dwordx4 v[106:109], v[124:125], off offset:576
	v_pk_mul_f32 v[96:97], v[96:97], v[126:127] op_sel_hi:[1,0]
	v_pk_mul_f32 v[98:99], v[98:99], v[126:127] op_sel_hi:[1,0]
	v_mul_f32_e32 v96, 0xbfb8aa3b, v96
	v_mul_f32_e32 v97, 0xbfb8aa3b, v97
	v_exp_f32_e32 v96, v96
	v_exp_f32_e32 v97, v97
	s_waitcnt vmcnt(0)
	v_lshlrev_b32_e32 v152, 16, v110
	v_and_b32_e32 v153, 0xffff0000, v110
	v_lshlrev_b32_e32 v110, 16, v111
	v_and_b32_e32 v111, 0xffff0000, v111
	v_pk_fma_f32 v[100:101], v[100:101], v[152:153], v[102:103]
	v_pk_fma_f32 v[102:103], v[134:135], v[110:111], v[104:105]
	global_store_dwordx4 v[124:125], v[100:103], off offset:512
	global_load_dwordx2 v[100:101], v[132:133], off offset:288
	v_mul_f32_e32 v98, 0xbfb8aa3b, v98
	v_mul_f32_e32 v99, 0xbfb8aa3b, v99
	v_exp_f32_e32 v98, v98
	v_exp_f32_e32 v99, v99
	v_pk_add_f32 v[96:97], v[96:97], 1.0 op_sel_hi:[1,0]
	v_pk_add_f32 v[98:99], v[98:99], 1.0 op_sel_hi:[1,0]
	s_mov_b64 vcc, s[0:1]
	v_rcp_f32_e32 v102, v97
	s_nop 0
	v_mul_f32_e32 v97, 1.0, v102
	s_mov_b64 vcc, s[8:9]
	v_rcp_f32_e32 v102, v96
	s_nop 0
	v_mul_f32_e32 v96, 1.0, v102
	s_mov_b64 vcc, s[10:11]
	v_rcp_f32_e32 v102, v99
	s_nop 0
	v_mul_f32_e32 v99, 1.0, v102
	v_rcp_f32_e32 v102, v98
	s_nop 0
	v_mul_f32_e32 v98, 1.0, v102
	v_pk_mul_f32 v[110:111], v[92:93], v[128:129]
	s_waitcnt vmcnt(0)
	v_lshlrev_b32_e32 v102, 16, v100
	v_and_b32_e32 v103, 0xffff0000, v100
	v_lshlrev_b32_e32 v100, 16, v101
	v_and_b32_e32 v101, 0xffff0000, v101
	v_pk_fma_f32 v[96:97], v[96:97], v[102:103], v[106:107]
	v_pk_fma_f32 v[98:99], v[98:99], v[100:101], v[108:109]
	global_store_dwordx4 v[124:125], v[96:99], off offset:576
	global_load_dword v98, v[150:151], off offset:128
	v_lshl_add_u64 v[100:101], v[140:141], 1, s[46:47]
	global_load_dwordx2 v[106:107], v[100:101], off
	v_lshl_add_u64 v[96:97], v[140:141], 2, s[70:71]
	global_load_dwordx4 v[102:105], v[96:97], off
	v_pk_mul_f32 v[108:109], v[94:95], v[130:131]
	global_load_dwordx4 v[92:95], v[96:97], off offset:64
	v_add_u32_e32 v140, 0x10000, v140
	s_waitcnt vmcnt(0)
	v_pk_mul_f32 v[110:111], v[110:111], v[98:99] op_sel_hi:[1,0]
	v_pk_mul_f32 v[108:109], v[108:109], v[98:99] op_sel_hi:[1,0]
	v_mul_f32_e32 v99, 0xbfb8aa3b, v110
	v_mul_f32_e32 v110, 0xbfb8aa3b, v111
	v_mul_f32_e32 v111, 0xbfb8aa3b, v108
	v_mul_f32_e32 v124, 0xbfb8aa3b, v109
	v_exp_f32_e32 v108, v99
	v_exp_f32_e32 v109, v110
	v_exp_f32_e32 v110, v111
	v_exp_f32_e32 v111, v124
	v_lshlrev_b32_e32 v124, 16, v106
	v_pk_add_f32 v[108:109], v[108:109], 1.0 op_sel_hi:[1,0]
	v_and_b32_e32 v125, 0xffff0000, v106
	v_pk_add_f32 v[110:111], v[110:111], 1.0 op_sel_hi:[1,0]
	s_mov_b64 vcc, s[0:1]
	v_rcp_f32_e32 v99, v109
	s_nop 0
	v_mul_f32_e32 v109, 1.0, v99
	s_mov_b64 vcc, s[8:9]
	v_rcp_f32_e32 v99, v108
	s_nop 0
	v_mul_f32_e32 v108, 1.0, v99
	s_mov_b64 vcc, s[10:11]
	v_pk_fma_f32 v[102:103], v[108:109], v[124:125], v[102:103]
	v_rcp_f32_e32 v99, v111
	s_nop 0
	v_mul_f32_e32 v109, 1.0, v99
	v_lshlrev_b32_e32 v106, 16, v107
	v_and_b32_e32 v107, 0xffff0000, v107
	v_rcp_f32_e32 v99, v110
	s_nop 0
	v_mul_f32_e32 v108, 1.0, v99
	v_pk_fma_f32 v[104:105], v[108:109], v[106:107], v[104:105]
	global_store_dwordx4 v[96:97], v[102:105], off
	global_load_dwordx2 v[102:103], v[100:101], off offset:32
	v_pk_mul_f32 v[88:89], v[88:89], v[98:99] op_sel_hi:[1,0]
	v_pk_mul_f32 v[90:91], v[90:91], v[98:99] op_sel_hi:[1,0]
	v_mul_f32_e32 v88, 0xbfb8aa3b, v88
	v_mul_f32_e32 v89, 0xbfb8aa3b, v89
	v_exp_f32_e32 v88, v88
	v_exp_f32_e32 v89, v89
	v_mul_f32_e32 v90, 0xbfb8aa3b, v90
	v_mul_f32_e32 v91, 0xbfb8aa3b, v91
	v_exp_f32_e32 v90, v90
	v_exp_f32_e32 v91, v91
	v_pk_add_f32 v[88:89], v[88:89], 1.0 op_sel_hi:[1,0]
	v_pk_add_f32 v[90:91], v[90:91], 1.0 op_sel_hi:[1,0]
	s_mov_b64 vcc, s[0:1]
	v_rcp_f32_e32 v99, v89
	s_nop 0
	v_mul_f32_e32 v89, 1.0, v99
	s_mov_b64 vcc, s[8:9]
	v_rcp_f32_e32 v99, v88
	s_nop 0
	v_mul_f32_e32 v88, 1.0, v99
	s_mov_b64 vcc, s[10:11]
	v_rcp_f32_e32 v99, v91
	s_nop 0
	v_mul_f32_e32 v91, 1.0, v99
	v_rcp_f32_e32 v99, v90
	s_nop 0
	v_mul_f32_e32 v90, 1.0, v99
	v_pk_mul_f32 v[84:85], v[84:85], v[98:99] op_sel_hi:[1,0]
	s_waitcnt vmcnt(0)
	v_lshlrev_b32_e32 v104, 16, v102
	v_and_b32_e32 v105, 0xffff0000, v102
	v_lshlrev_b32_e32 v102, 16, v103
	v_and_b32_e32 v103, 0xffff0000, v103
	v_pk_fma_f32 v[88:89], v[88:89], v[104:105], v[92:93]
	v_pk_fma_f32 v[90:91], v[90:91], v[102:103], v[94:95]
	global_store_dwordx4 v[96:97], v[88:91], off offset:64
	global_load_dwordx2 v[94:95], v[100:101], off offset:256
	v_mul_f32_e32 v84, 0xbfb8aa3b, v84
	v_cvt_f32_i32_e32 v90, v86
	v_cvt_f32_i32_e32 v91, v87
	global_load_dwordx4 v[86:89], v[96:97], off offset:512
	v_mul_f32_e32 v85, 0xbfb8aa3b, v85
	v_exp_f32_e32 v84, v84
	v_pk_mul_f32 v[90:91], v[90:91], v[116:117]
	v_exp_f32_e32 v85, v85
	v_pk_mul_f32 v[90:91], v[90:91], v[98:99] op_sel_hi:[1,0]
	v_pk_add_f32 v[84:85], v[84:85], 1.0 op_sel_hi:[1,0]
	v_mul_f32_e32 v90, 0xbfb8aa3b, v90
	v_mul_f32_e32 v91, 0xbfb8aa3b, v91
	v_exp_f32_e32 v102, v90
	v_exp_f32_e32 v103, v91
	s_nop 0
	v_pk_add_f32 v[102:103], v[102:103], 1.0 op_sel_hi:[1,0]
	s_mov_b64 vcc, s[0:1]
	v_rcp_f32_e32 v99, v85
	s_nop 0
	v_mul_f32_e32 v85, 1.0, v99
	s_mov_b64 vcc, s[8:9]
	v_rcp_f32_e32 v99, v84
	s_nop 0
	v_mul_f32_e32 v84, 1.0, v99
	s_mov_b64 vcc, s[10:11]
	v_rcp_f32_e32 v99, v103
	s_nop 0
	v_mul_f32_e32 v103, 1.0, v99
	v_rcp_f32_e32 v99, v102
	s_nop 0
	v_mul_f32_e32 v102, 1.0, v99
	global_load_dwordx4 v[90:93], v[96:97], off offset:576
	v_pk_mul_f32 v[80:81], v[80:81], v[98:99] op_sel_hi:[1,0]
	v_pk_mul_f32 v[82:83], v[82:83], v[98:99] op_sel_hi:[1,0]
	v_mul_f32_e32 v80, 0xbfb8aa3b, v80
	v_mul_f32_e32 v81, 0xbfb8aa3b, v81
	v_exp_f32_e32 v80, v80
	v_exp_f32_e32 v81, v81
	s_waitcnt vmcnt(0)
	v_lshlrev_b32_e32 v104, 16, v94
	v_and_b32_e32 v105, 0xffff0000, v94
	v_lshlrev_b32_e32 v94, 16, v95
	v_and_b32_e32 v95, 0xffff0000, v95
	v_pk_fma_f32 v[84:85], v[84:85], v[104:105], v[86:87]
	v_pk_fma_f32 v[86:87], v[102:103], v[94:95], v[88:89]
	global_store_dwordx4 v[96:97], v[84:87], off offset:512
	global_load_dwordx2 v[84:85], v[100:101], off offset:288
	v_mul_f32_e32 v82, 0xbfb8aa3b, v82
	v_mul_f32_e32 v83, 0xbfb8aa3b, v83
	v_exp_f32_e32 v82, v82
	v_exp_f32_e32 v83, v83
	v_pk_add_f32 v[80:81], v[80:81], 1.0 op_sel_hi:[1,0]
	v_pk_add_f32 v[82:83], v[82:83], 1.0 op_sel_hi:[1,0]
	s_mov_b64 vcc, s[0:1]
	v_rcp_f32_e32 v86, v81
	s_nop 0
	v_mul_f32_e32 v81, 1.0, v86
	s_mov_b64 vcc, s[8:9]
	v_rcp_f32_e32 v86, v80
	s_nop 0
	v_mul_f32_e32 v80, 1.0, v86
	s_mov_b64 vcc, s[10:11]
	v_rcp_f32_e32 v86, v83
	s_nop 0
	v_mul_f32_e32 v83, 1.0, v86
	v_rcp_f32_e32 v86, v82
	s_nop 0
	v_mul_f32_e32 v82, 1.0, v86
	v_pk_mul_f32 v[94:95], v[76:77], v[128:129]
	s_waitcnt vmcnt(0)
	v_lshlrev_b32_e32 v86, 16, v84
	v_and_b32_e32 v87, 0xffff0000, v84
	v_lshlrev_b32_e32 v84, 16, v85
	v_and_b32_e32 v85, 0xffff0000, v85
	v_pk_fma_f32 v[80:81], v[80:81], v[86:87], v[90:91]
	v_pk_fma_f32 v[82:83], v[82:83], v[84:85], v[92:93]
	global_store_dwordx4 v[96:97], v[80:83], off offset:576
	global_load_dword v82, v[150:151], off offset:192
	v_lshl_add_u64 v[84:85], v[140:141], 1, s[46:47]
	global_load_dwordx2 v[90:91], v[84:85], off
	v_lshl_add_u64 v[80:81], v[140:141], 2, s[70:71]
	global_load_dwordx4 v[86:89], v[80:81], off
	v_pk_mul_f32 v[92:93], v[78:79], v[130:131]
	global_load_dwordx4 v[76:79], v[80:81], off offset:64
	s_waitcnt vmcnt(0)
	v_pk_mul_f32 v[94:95], v[94:95], v[82:83] op_sel_hi:[1,0]
	v_pk_mul_f32 v[92:93], v[92:93], v[82:83] op_sel_hi:[1,0]
	v_mul_f32_e32 v83, 0xbfb8aa3b, v94
	v_mul_f32_e32 v94, 0xbfb8aa3b, v95
	v_mul_f32_e32 v95, 0xbfb8aa3b, v92
	v_mul_f32_e32 v96, 0xbfb8aa3b, v93
	v_exp_f32_e32 v92, v83
	v_exp_f32_e32 v93, v94
	v_exp_f32_e32 v94, v95
	v_exp_f32_e32 v95, v96
	v_lshlrev_b32_e32 v96, 16, v90
	v_pk_add_f32 v[92:93], v[92:93], 1.0 op_sel_hi:[1,0]
	v_and_b32_e32 v97, 0xffff0000, v90
	v_pk_add_f32 v[94:95], v[94:95], 1.0 op_sel_hi:[1,0]
	s_mov_b64 vcc, s[0:1]
	v_rcp_f32_e32 v83, v93
	s_nop 0
	v_mul_f32_e32 v93, 1.0, v83
	s_mov_b64 vcc, s[8:9]
	v_rcp_f32_e32 v83, v92
	s_nop 0
	v_mul_f32_e32 v92, 1.0, v83
	s_mov_b64 vcc, s[10:11]
	v_pk_fma_f32 v[86:87], v[92:93], v[96:97], v[86:87]
	v_rcp_f32_e32 v83, v95
	s_nop 0
	v_mul_f32_e32 v93, 1.0, v83
	v_lshlrev_b32_e32 v90, 16, v91
	v_and_b32_e32 v91, 0xffff0000, v91
	v_rcp_f32_e32 v83, v94
	s_nop 0
	v_mul_f32_e32 v92, 1.0, v83
	v_pk_fma_f32 v[88:89], v[92:93], v[90:91], v[88:89]
	global_store_dwordx4 v[80:81], v[86:89], off
	global_load_dwordx2 v[86:87], v[84:85], off offset:32
	v_pk_mul_f32 v[72:73], v[72:73], v[82:83] op_sel_hi:[1,0]
	v_pk_mul_f32 v[74:75], v[74:75], v[82:83] op_sel_hi:[1,0]
	v_mul_f32_e32 v72, 0xbfb8aa3b, v72
	v_mul_f32_e32 v73, 0xbfb8aa3b, v73
	v_exp_f32_e32 v72, v72
	v_exp_f32_e32 v73, v73
	v_mul_f32_e32 v74, 0xbfb8aa3b, v74
	v_mul_f32_e32 v75, 0xbfb8aa3b, v75
	v_exp_f32_e32 v74, v74
	v_exp_f32_e32 v75, v75
	v_pk_add_f32 v[72:73], v[72:73], 1.0 op_sel_hi:[1,0]
	v_pk_add_f32 v[74:75], v[74:75], 1.0 op_sel_hi:[1,0]
	s_mov_b64 vcc, s[0:1]
	v_rcp_f32_e32 v83, v73
	s_nop 0
	v_mul_f32_e32 v73, 1.0, v83
	s_mov_b64 vcc, s[8:9]
	v_rcp_f32_e32 v83, v72
	s_nop 0
	v_mul_f32_e32 v72, 1.0, v83
	s_mov_b64 vcc, s[10:11]
	v_rcp_f32_e32 v83, v75
	s_nop 0
	v_mul_f32_e32 v75, 1.0, v83
	v_rcp_f32_e32 v83, v74
	s_nop 0
	v_mul_f32_e32 v74, 1.0, v83
	v_pk_mul_f32 v[68:69], v[68:69], v[82:83] op_sel_hi:[1,0]
	s_waitcnt vmcnt(0)
	v_lshlrev_b32_e32 v88, 16, v86
	v_and_b32_e32 v89, 0xffff0000, v86
	v_lshlrev_b32_e32 v86, 16, v87
	v_and_b32_e32 v87, 0xffff0000, v87
	v_pk_fma_f32 v[72:73], v[72:73], v[88:89], v[76:77]
	v_pk_fma_f32 v[74:75], v[74:75], v[86:87], v[78:79]
	global_store_dwordx4 v[80:81], v[72:75], off offset:64
	global_load_dwordx2 v[78:79], v[84:85], off offset:256
	v_mul_f32_e32 v68, 0xbfb8aa3b, v68
	v_cvt_f32_i32_e32 v74, v70
	v_cvt_f32_i32_e32 v75, v71
	global_load_dwordx4 v[70:73], v[80:81], off offset:512
	v_mul_f32_e32 v69, 0xbfb8aa3b, v69
	v_exp_f32_e32 v68, v68
	v_pk_mul_f32 v[74:75], v[74:75], v[116:117]
	v_exp_f32_e32 v69, v69
	v_pk_mul_f32 v[74:75], v[74:75], v[82:83] op_sel_hi:[1,0]
	v_pk_add_f32 v[68:69], v[68:69], 1.0 op_sel_hi:[1,0]
	v_mul_f32_e32 v74, 0xbfb8aa3b, v74
	v_mul_f32_e32 v75, 0xbfb8aa3b, v75
	v_exp_f32_e32 v86, v74
	v_exp_f32_e32 v87, v75
	s_nop 0
	v_pk_add_f32 v[86:87], v[86:87], 1.0 op_sel_hi:[1,0]
	s_mov_b64 vcc, s[0:1]
	v_rcp_f32_e32 v83, v69
	s_nop 0
	v_mul_f32_e32 v69, 1.0, v83
	s_mov_b64 vcc, s[8:9]
	v_rcp_f32_e32 v83, v68
	s_nop 0
	v_mul_f32_e32 v68, 1.0, v83
	s_mov_b64 vcc, s[10:11]
	v_rcp_f32_e32 v83, v87
	s_nop 0
	v_mul_f32_e32 v87, 1.0, v83
	v_rcp_f32_e32 v83, v86
	s_nop 0
	v_mul_f32_e32 v86, 1.0, v83
	global_load_dwordx4 v[74:77], v[80:81], off offset:576
	v_pk_mul_f32 v[64:65], v[64:65], v[82:83] op_sel_hi:[1,0]
	v_pk_mul_f32 v[66:67], v[66:67], v[82:83] op_sel_hi:[1,0]
	v_mul_f32_e32 v64, 0xbfb8aa3b, v64
	v_mul_f32_e32 v65, 0xbfb8aa3b, v65
	v_exp_f32_e32 v64, v64
	v_exp_f32_e32 v65, v65
	s_waitcnt vmcnt(0)
	v_lshlrev_b32_e32 v88, 16, v78
	v_and_b32_e32 v89, 0xffff0000, v78
	v_lshlrev_b32_e32 v78, 16, v79
	v_and_b32_e32 v79, 0xffff0000, v79
	v_pk_fma_f32 v[68:69], v[68:69], v[88:89], v[70:71]
	v_pk_fma_f32 v[70:71], v[86:87], v[78:79], v[72:73]
	global_store_dwordx4 v[80:81], v[68:71], off offset:512
	global_load_dwordx2 v[68:69], v[84:85], off offset:288
	v_mul_f32_e32 v66, 0xbfb8aa3b, v66
	v_mul_f32_e32 v67, 0xbfb8aa3b, v67
	v_exp_f32_e32 v70, v66
	v_exp_f32_e32 v71, v67
	v_pk_add_f32 v[64:65], v[64:65], 1.0 op_sel_hi:[1,0]
	v_add_u32_e32 v67, 0x10000, v140
	v_pk_add_f32 v[70:71], v[70:71], 1.0 op_sel_hi:[1,0]
	s_mov_b64 vcc, s[0:1]
	v_rcp_f32_e32 v66, v65
	s_nop 0
	v_mul_f32_e32 v65, 1.0, v66
	s_mov_b64 vcc, s[8:9]
	v_rcp_f32_e32 v66, v64
	s_nop 0
	v_mul_f32_e32 v64, 1.0, v66
	s_mov_b64 vcc, s[10:11]
	v_rcp_f32_e32 v66, v71
	s_nop 0
	v_mul_f32_e32 v71, 1.0, v66
	v_rcp_f32_e32 v66, v70
	s_nop 0
	v_mul_f32_e32 v70, 1.0, v66
	s_waitcnt vmcnt(0)
	v_lshlrev_b32_e32 v72, 16, v68
	v_and_b32_e32 v73, 0xffff0000, v68
	v_lshlrev_b32_e32 v78, 16, v69
	v_and_b32_e32 v79, 0xffff0000, v69
	v_pk_fma_f32 v[68:69], v[64:65], v[72:73], v[74:75]
	v_pk_fma_f32 v[70:71], v[70:71], v[78:79], v[76:77]
	global_store_dwordx4 v[80:81], v[68:71], off offset:576
	global_load_dword v66, v[150:151], off offset:512
	v_add_u32_e32 v140, 0x40000, v67
	v_lshl_add_u64 v[68:69], v[140:141], 1, s[46:47]
	global_load_dwordx2 v[74:75], v[68:69], off
	v_lshl_add_u64 v[64:65], v[140:141], 2, s[70:71]
	global_load_dwordx4 v[70:73], v[64:65], off
	v_pk_mul_f32 v[78:79], v[60:61], v[128:129]
	v_pk_mul_f32 v[76:77], v[62:63], v[130:131]
	global_load_dwordx4 v[60:63], v[64:65], off offset:64
	v_add_u32_e32 v140, 0x50000, v67
	s_waitcnt vmcnt(0)
	v_pk_mul_f32 v[78:79], v[78:79], v[66:67] op_sel_hi:[1,0]
	v_pk_mul_f32 v[76:77], v[76:77], v[66:67] op_sel_hi:[1,0]
	v_mul_f32_e32 v78, 0xbfb8aa3b, v78
	v_mul_f32_e32 v79, 0xbfb8aa3b, v79
	v_mul_f32_e32 v80, 0xbfb8aa3b, v76
	v_mul_f32_e32 v81, 0xbfb8aa3b, v77
	v_exp_f32_e32 v76, v78
	v_exp_f32_e32 v77, v79
	v_exp_f32_e32 v78, v80
	v_exp_f32_e32 v79, v81
	v_lshlrev_b32_e32 v80, 16, v74
	v_pk_add_f32 v[76:77], v[76:77], 1.0 op_sel_hi:[1,0]
	v_and_b32_e32 v81, 0xffff0000, v74
	v_pk_add_f32 v[78:79], v[78:79], 1.0 op_sel_hi:[1,0]
	s_mov_b64 vcc, s[0:1]
	v_rcp_f32_e32 v82, v77
	s_nop 0
	v_mul_f32_e32 v77, 1.0, v82
	s_mov_b64 vcc, s[8:9]
	v_rcp_f32_e32 v82, v76
	s_nop 0
	v_mul_f32_e32 v76, 1.0, v82
	s_mov_b64 vcc, s[10:11]
	v_pk_fma_f32 v[70:71], v[76:77], v[80:81], v[70:71]
	v_lshlrev_b32_e32 v74, 16, v75
	v_and_b32_e32 v75, 0xffff0000, v75
	v_rcp_f32_e32 v82, v79
	s_nop 0
	v_mul_f32_e32 v77, 1.0, v82
	v_rcp_f32_e32 v76, v78
	s_nop 0
	v_mul_f32_e32 v76, 1.0, v76
	v_pk_fma_f32 v[72:73], v[76:77], v[74:75], v[72:73]
	global_store_dwordx4 v[64:65], v[70:73], off
	global_load_dwordx2 v[70:71], v[68:69], off offset:32
	v_pk_mul_f32 v[56:57], v[56:57], v[66:67] op_sel_hi:[1,0]
	v_pk_mul_f32 v[58:59], v[58:59], v[66:67] op_sel_hi:[1,0]
	v_mul_f32_e32 v56, 0xbfb8aa3b, v56
	v_mul_f32_e32 v57, 0xbfb8aa3b, v57
	v_exp_f32_e32 v56, v56
	v_exp_f32_e32 v57, v57
	v_mul_f32_e32 v58, 0xbfb8aa3b, v58
	v_mul_f32_e32 v59, 0xbfb8aa3b, v59
	v_exp_f32_e32 v58, v58
	v_exp_f32_e32 v59, v59
	v_pk_add_f32 v[56:57], v[56:57], 1.0 op_sel_hi:[1,0]
	v_pk_mul_f32 v[52:53], v[52:53], v[66:67] op_sel_hi:[1,0]
	v_pk_add_f32 v[58:59], v[58:59], 1.0 op_sel_hi:[1,0]
	s_mov_b64 vcc, s[0:1]
	v_rcp_f32_e32 v72, v57
	s_nop 0
	v_mul_f32_e32 v57, 1.0, v72
	s_mov_b64 vcc, s[8:9]
	v_rcp_f32_e32 v72, v56
	s_nop 0
	v_mul_f32_e32 v56, 1.0, v72
	s_mov_b64 vcc, s[10:11]
	v_rcp_f32_e32 v72, v59
	s_nop 0
	v_mul_f32_e32 v59, 1.0, v72
	v_rcp_f32_e32 v72, v58
	s_nop 0
	v_mul_f32_e32 v58, 1.0, v72
	v_mul_f32_e32 v52, 0xbfb8aa3b, v52
	v_mul_f32_e32 v53, 0xbfb8aa3b, v53
	v_exp_f32_e32 v52, v52
	v_exp_f32_e32 v53, v53
	v_pk_mul_f32 v[48:49], v[48:49], v[66:67] op_sel_hi:[1,0]
	v_pk_mul_f32 v[50:51], v[50:51], v[66:67] op_sel_hi:[1,0]
	v_mul_f32_e32 v48, 0xbfb8aa3b, v48
	v_pk_add_f32 v[52:53], v[52:53], 1.0 op_sel_hi:[1,0]
	v_mul_f32_e32 v49, 0xbfb8aa3b, v49
	s_waitcnt vmcnt(0)
	v_lshlrev_b32_e32 v72, 16, v70
	v_and_b32_e32 v73, 0xffff0000, v70
	v_lshlrev_b32_e32 v70, 16, v71
	v_and_b32_e32 v71, 0xffff0000, v71
	v_pk_fma_f32 v[56:57], v[56:57], v[72:73], v[60:61]
	v_pk_fma_f32 v[58:59], v[58:59], v[70:71], v[62:63]
	global_store_dwordx4 v[64:65], v[56:59], off offset:64
	global_load_dwordx2 v[62:63], v[68:69], off offset:256
	s_nop 1
	v_cvt_f32_i32_e32 v58, v54
	v_cvt_f32_i32_e32 v59, v55
	global_load_dwordx4 v[54:57], v[64:65], off offset:512
	v_pk_mul_f32 v[58:59], v[58:59], v[116:117]
	v_pk_mul_f32 v[58:59], v[58:59], v[66:67] op_sel_hi:[1,0]
	v_mul_f32_e32 v58, 0xbfb8aa3b, v58
	v_mul_f32_e32 v59, 0xbfb8aa3b, v59
	v_exp_f32_e32 v70, v58
	v_exp_f32_e32 v71, v59
	s_nop 0
	v_pk_add_f32 v[70:71], v[70:71], 1.0 op_sel_hi:[1,0]
	s_mov_b64 vcc, s[0:1]
	v_rcp_f32_e32 v72, v53
	s_nop 0
	v_mul_f32_e32 v53, 1.0, v72
	s_mov_b64 vcc, s[8:9]
	v_rcp_f32_e32 v72, v52
	s_nop 0
	v_mul_f32_e32 v52, 1.0, v72
	s_mov_b64 vcc, s[10:11]
	v_rcp_f32_e32 v72, v71
	s_nop 0
	v_mul_f32_e32 v71, 1.0, v72
	v_rcp_f32_e32 v72, v70
	s_nop 0
	v_mul_f32_e32 v70, 1.0, v72
	global_load_dwordx4 v[58:61], v[64:65], off offset:576
	v_exp_f32_e32 v48, v48
	v_exp_f32_e32 v49, v49
	v_mul_f32_e32 v50, 0xbfb8aa3b, v50
	v_mul_f32_e32 v51, 0xbfb8aa3b, v51
	v_exp_f32_e32 v50, v50
	v_exp_f32_e32 v51, v51
	v_pk_add_f32 v[48:49], v[48:49], 1.0 op_sel_hi:[1,0]
	v_pk_add_f32 v[50:51], v[50:51], 1.0 op_sel_hi:[1,0]
	s_nop 0
	s_waitcnt vmcnt(0)
	v_lshlrev_b32_e32 v72, 16, v62
	v_and_b32_e32 v73, 0xffff0000, v62
	v_lshlrev_b32_e32 v62, 16, v63
	v_and_b32_e32 v63, 0xffff0000, v63
	v_pk_fma_f32 v[52:53], v[52:53], v[72:73], v[54:55]
	v_pk_fma_f32 v[54:55], v[70:71], v[62:63], v[56:57]
	global_store_dwordx4 v[64:65], v[52:55], off offset:512
	global_load_dwordx2 v[52:53], v[68:69], off offset:288
	s_mov_b64 vcc, s[0:1]
	v_rcp_f32_e32 v54, v49
	s_nop 0
	v_mul_f32_e32 v49, 1.0, v54
	s_mov_b64 vcc, s[8:9]
	v_rcp_f32_e32 v54, v48
	s_nop 0
	v_mul_f32_e32 v48, 1.0, v54
	s_mov_b64 vcc, s[10:11]
	v_rcp_f32_e32 v54, v51
	s_nop 0
	v_mul_f32_e32 v51, 1.0, v54
	v_rcp_f32_e32 v54, v50
	s_nop 0
	v_mul_f32_e32 v50, 1.0, v54
	v_pk_mul_f32 v[62:63], v[44:45], v[128:129]
	s_waitcnt vmcnt(0)
	v_lshlrev_b32_e32 v54, 16, v52
	v_and_b32_e32 v55, 0xffff0000, v52
	v_lshlrev_b32_e32 v52, 16, v53
	v_and_b32_e32 v53, 0xffff0000, v53
	v_pk_fma_f32 v[48:49], v[48:49], v[54:55], v[58:59]
	v_pk_fma_f32 v[50:51], v[50:51], v[52:53], v[60:61]
	global_store_dwordx4 v[64:65], v[48:51], off offset:576
	global_load_dword v50, v[150:151], off offset:576
	v_lshl_add_u64 v[52:53], v[140:141], 1, s[46:47]
	global_load_dwordx2 v[58:59], v[52:53], off
	v_lshl_add_u64 v[48:49], v[140:141], 2, s[70:71]
	global_load_dwordx4 v[54:57], v[48:49], off
	v_pk_mul_f32 v[60:61], v[46:47], v[130:131]
	global_load_dwordx4 v[44:47], v[48:49], off offset:64
	v_add_u32_e32 v140, 0x10000, v140
	s_waitcnt vmcnt(0)
	v_pk_mul_f32 v[62:63], v[62:63], v[50:51] op_sel_hi:[1,0]
	v_pk_mul_f32 v[60:61], v[60:61], v[50:51] op_sel_hi:[1,0]
	v_mul_f32_e32 v51, 0xbfb8aa3b, v62
	v_mul_f32_e32 v62, 0xbfb8aa3b, v63
	v_mul_f32_e32 v63, 0xbfb8aa3b, v60
	v_mul_f32_e32 v64, 0xbfb8aa3b, v61
	v_exp_f32_e32 v60, v51
	v_exp_f32_e32 v61, v62
	v_exp_f32_e32 v62, v63
	v_exp_f32_e32 v63, v64
	v_lshlrev_b32_e32 v64, 16, v58
	v_pk_add_f32 v[60:61], v[60:61], 1.0 op_sel_hi:[1,0]
	v_and_b32_e32 v65, 0xffff0000, v58
	v_pk_add_f32 v[62:63], v[62:63], 1.0 op_sel_hi:[1,0]
	s_mov_b64 vcc, s[0:1]
	v_rcp_f32_e32 v51, v61
	s_nop 0
	v_mul_f32_e32 v61, 1.0, v51
	s_mov_b64 vcc, s[8:9]
	v_rcp_f32_e32 v51, v60
	s_nop 0
	v_mul_f32_e32 v60, 1.0, v51
	s_mov_b64 vcc, s[10:11]
	v_pk_fma_f32 v[54:55], v[60:61], v[64:65], v[54:55]
	v_rcp_f32_e32 v51, v63
	s_nop 0
	v_mul_f32_e32 v61, 1.0, v51
	v_lshlrev_b32_e32 v58, 16, v59
	v_and_b32_e32 v59, 0xffff0000, v59
	v_rcp_f32_e32 v51, v62
	s_nop 0
	v_mul_f32_e32 v60, 1.0, v51
	v_pk_fma_f32 v[56:57], v[60:61], v[58:59], v[56:57]
	global_store_dwordx4 v[48:49], v[54:57], off
	global_load_dwordx2 v[54:55], v[52:53], off offset:32
	v_pk_mul_f32 v[40:41], v[40:41], v[50:51] op_sel_hi:[1,0]
	v_pk_mul_f32 v[42:43], v[42:43], v[50:51] op_sel_hi:[1,0]
	v_mul_f32_e32 v40, 0xbfb8aa3b, v40
	v_mul_f32_e32 v41, 0xbfb8aa3b, v41
	v_exp_f32_e32 v40, v40
	v_exp_f32_e32 v41, v41
	v_mul_f32_e32 v42, 0xbfb8aa3b, v42
	v_mul_f32_e32 v43, 0xbfb8aa3b, v43
	v_exp_f32_e32 v42, v42
	v_exp_f32_e32 v43, v43
	v_pk_add_f32 v[40:41], v[40:41], 1.0 op_sel_hi:[1,0]
	v_pk_add_f32 v[42:43], v[42:43], 1.0 op_sel_hi:[1,0]
	s_mov_b64 vcc, s[0:1]
	v_rcp_f32_e32 v51, v41
	s_nop 0
	v_mul_f32_e32 v41, 1.0, v51
	s_mov_b64 vcc, s[8:9]
	v_rcp_f32_e32 v51, v40
	s_nop 0
	v_mul_f32_e32 v40, 1.0, v51
	s_mov_b64 vcc, s[10:11]
	v_rcp_f32_e32 v51, v43
	s_nop 0
	v_mul_f32_e32 v43, 1.0, v51
	v_rcp_f32_e32 v51, v42
	s_nop 0
	v_mul_f32_e32 v42, 1.0, v51
	v_pk_mul_f32 v[36:37], v[36:37], v[50:51] op_sel_hi:[1,0]
	s_waitcnt vmcnt(0)
	v_lshlrev_b32_e32 v56, 16, v54
	v_and_b32_e32 v57, 0xffff0000, v54
	v_lshlrev_b32_e32 v54, 16, v55
	v_and_b32_e32 v55, 0xffff0000, v55
	v_pk_fma_f32 v[40:41], v[40:41], v[56:57], v[44:45]
	v_pk_fma_f32 v[42:43], v[42:43], v[54:55], v[46:47]
	global_store_dwordx4 v[48:49], v[40:43], off offset:64
	global_load_dwordx2 v[46:47], v[52:53], off offset:256
	v_mul_f32_e32 v36, 0xbfb8aa3b, v36
	v_cvt_f32_i32_e32 v42, v38
	v_cvt_f32_i32_e32 v43, v39
	global_load_dwordx4 v[38:41], v[48:49], off offset:512
	v_mul_f32_e32 v37, 0xbfb8aa3b, v37
	v_exp_f32_e32 v36, v36
	v_pk_mul_f32 v[42:43], v[42:43], v[116:117]
	v_exp_f32_e32 v37, v37
	v_pk_mul_f32 v[42:43], v[42:43], v[50:51] op_sel_hi:[1,0]
	v_pk_add_f32 v[36:37], v[36:37], 1.0 op_sel_hi:[1,0]
	v_mul_f32_e32 v42, 0xbfb8aa3b, v42
	v_mul_f32_e32 v43, 0xbfb8aa3b, v43
	v_exp_f32_e32 v54, v42
	v_exp_f32_e32 v55, v43
	s_nop 0
	v_pk_add_f32 v[54:55], v[54:55], 1.0 op_sel_hi:[1,0]
	s_mov_b64 vcc, s[0:1]
	v_rcp_f32_e32 v51, v37
	s_nop 0
	v_mul_f32_e32 v37, 1.0, v51
	s_mov_b64 vcc, s[8:9]
	v_rcp_f32_e32 v51, v36
	s_nop 0
	v_mul_f32_e32 v36, 1.0, v51
	s_mov_b64 vcc, s[10:11]
	v_rcp_f32_e32 v51, v55
	s_nop 0
	v_mul_f32_e32 v55, 1.0, v51
	v_rcp_f32_e32 v51, v54
	s_nop 0
	v_mul_f32_e32 v54, 1.0, v51
	global_load_dwordx4 v[42:45], v[48:49], off offset:576
	v_pk_mul_f32 v[32:33], v[32:33], v[50:51] op_sel_hi:[1,0]
	v_pk_mul_f32 v[34:35], v[34:35], v[50:51] op_sel_hi:[1,0]
	v_mul_f32_e32 v32, 0xbfb8aa3b, v32
	v_mul_f32_e32 v33, 0xbfb8aa3b, v33
	v_exp_f32_e32 v32, v32
	v_exp_f32_e32 v33, v33
	s_waitcnt vmcnt(0)
	v_lshlrev_b32_e32 v56, 16, v46
	v_and_b32_e32 v57, 0xffff0000, v46
	v_lshlrev_b32_e32 v46, 16, v47
	v_and_b32_e32 v47, 0xffff0000, v47
	v_pk_fma_f32 v[36:37], v[36:37], v[56:57], v[38:39]
	v_pk_fma_f32 v[38:39], v[54:55], v[46:47], v[40:41]
	global_store_dwordx4 v[48:49], v[36:39], off offset:512
	global_load_dwordx2 v[36:37], v[52:53], off offset:288
	v_mul_f32_e32 v34, 0xbfb8aa3b, v34
	v_mul_f32_e32 v35, 0xbfb8aa3b, v35
	v_exp_f32_e32 v34, v34
	v_exp_f32_e32 v35, v35
	v_pk_add_f32 v[32:33], v[32:33], 1.0 op_sel_hi:[1,0]
	v_pk_add_f32 v[34:35], v[34:35], 1.0 op_sel_hi:[1,0]
	s_mov_b64 vcc, s[0:1]
	v_rcp_f32_e32 v38, v33
	s_nop 0
	v_mul_f32_e32 v33, 1.0, v38
	s_mov_b64 vcc, s[8:9]
	v_rcp_f32_e32 v38, v32
	s_nop 0
	v_mul_f32_e32 v32, 1.0, v38
	s_mov_b64 vcc, s[10:11]
	v_rcp_f32_e32 v38, v35
	s_nop 0
	v_mul_f32_e32 v35, 1.0, v38
	v_rcp_f32_e32 v38, v34
	s_nop 0
	v_mul_f32_e32 v34, 1.0, v38
	v_pk_mul_f32 v[46:47], v[28:29], v[128:129]
	s_waitcnt vmcnt(0)
	v_lshlrev_b32_e32 v38, 16, v36
	v_and_b32_e32 v39, 0xffff0000, v36
	v_lshlrev_b32_e32 v36, 16, v37
	v_and_b32_e32 v37, 0xffff0000, v37
	v_pk_fma_f32 v[32:33], v[32:33], v[38:39], v[42:43]
	v_pk_fma_f32 v[34:35], v[34:35], v[36:37], v[44:45]
	global_store_dwordx4 v[48:49], v[32:35], off offset:576
	global_load_dword v34, v[150:151], off offset:640
	v_lshl_add_u64 v[36:37], v[140:141], 1, s[46:47]
	global_load_dwordx2 v[42:43], v[36:37], off
	v_lshl_add_u64 v[32:33], v[140:141], 2, s[70:71]
	global_load_dwordx4 v[38:41], v[32:33], off
	v_pk_mul_f32 v[44:45], v[30:31], v[130:131]
	global_load_dwordx4 v[28:31], v[32:33], off offset:64
	v_add_u32_e32 v140, 0x10000, v140
	s_waitcnt vmcnt(0)
	v_pk_mul_f32 v[46:47], v[46:47], v[34:35] op_sel_hi:[1,0]
	v_pk_mul_f32 v[44:45], v[44:45], v[34:35] op_sel_hi:[1,0]
	v_mul_f32_e32 v35, 0xbfb8aa3b, v46
	v_mul_f32_e32 v46, 0xbfb8aa3b, v47
	v_mul_f32_e32 v47, 0xbfb8aa3b, v44
	v_mul_f32_e32 v48, 0xbfb8aa3b, v45
	v_exp_f32_e32 v44, v35
	v_exp_f32_e32 v45, v46
	v_exp_f32_e32 v46, v47
	v_exp_f32_e32 v47, v48
	v_lshlrev_b32_e32 v48, 16, v42
	v_pk_add_f32 v[44:45], v[44:45], 1.0 op_sel_hi:[1,0]
	v_and_b32_e32 v49, 0xffff0000, v42
	v_pk_add_f32 v[46:47], v[46:47], 1.0 op_sel_hi:[1,0]
	s_mov_b64 vcc, s[0:1]
	v_rcp_f32_e32 v35, v45
	s_nop 0
	v_mul_f32_e32 v45, 1.0, v35
	s_mov_b64 vcc, s[8:9]
	v_rcp_f32_e32 v35, v44
	s_nop 0
	v_mul_f32_e32 v44, 1.0, v35
	s_mov_b64 vcc, s[10:11]
	v_pk_fma_f32 v[38:39], v[44:45], v[48:49], v[38:39]
	v_rcp_f32_e32 v35, v47
	s_nop 0
	v_mul_f32_e32 v45, 1.0, v35
	v_lshlrev_b32_e32 v42, 16, v43
	v_and_b32_e32 v43, 0xffff0000, v43
	v_rcp_f32_e32 v35, v46
	s_nop 0
	v_mul_f32_e32 v44, 1.0, v35
	v_pk_fma_f32 v[40:41], v[44:45], v[42:43], v[40:41]
	global_store_dwordx4 v[32:33], v[38:41], off
	global_load_dwordx2 v[38:39], v[36:37], off offset:32
	v_pk_mul_f32 v[24:25], v[24:25], v[34:35] op_sel_hi:[1,0]
	v_pk_mul_f32 v[26:27], v[26:27], v[34:35] op_sel_hi:[1,0]
	v_mul_f32_e32 v24, 0xbfb8aa3b, v24
	v_mul_f32_e32 v25, 0xbfb8aa3b, v25
	v_exp_f32_e32 v24, v24
	v_exp_f32_e32 v25, v25
	v_mul_f32_e32 v26, 0xbfb8aa3b, v26
	v_mul_f32_e32 v27, 0xbfb8aa3b, v27
	v_exp_f32_e32 v26, v26
	v_exp_f32_e32 v27, v27
	v_pk_add_f32 v[24:25], v[24:25], 1.0 op_sel_hi:[1,0]
	v_pk_add_f32 v[26:27], v[26:27], 1.0 op_sel_hi:[1,0]
	s_mov_b64 vcc, s[0:1]
	v_rcp_f32_e32 v35, v25
	s_nop 0
	v_mul_f32_e32 v25, 1.0, v35
	s_mov_b64 vcc, s[8:9]
	v_rcp_f32_e32 v35, v24
	s_nop 0
	v_mul_f32_e32 v24, 1.0, v35
	s_mov_b64 vcc, s[10:11]
	v_rcp_f32_e32 v35, v27
	s_nop 0
	v_mul_f32_e32 v27, 1.0, v35
	v_rcp_f32_e32 v35, v26
	s_nop 0
	v_mul_f32_e32 v26, 1.0, v35
	v_pk_mul_f32 v[20:21], v[20:21], v[34:35] op_sel_hi:[1,0]
	s_waitcnt vmcnt(0)
	v_lshlrev_b32_e32 v40, 16, v38
	v_and_b32_e32 v41, 0xffff0000, v38
	v_lshlrev_b32_e32 v38, 16, v39
	v_and_b32_e32 v39, 0xffff0000, v39
	v_pk_fma_f32 v[24:25], v[24:25], v[40:41], v[28:29]
	v_pk_fma_f32 v[26:27], v[26:27], v[38:39], v[30:31]
	global_store_dwordx4 v[32:33], v[24:27], off offset:64
	global_load_dwordx2 v[30:31], v[36:37], off offset:256
	v_mul_f32_e32 v20, 0xbfb8aa3b, v20
	v_cvt_f32_i32_e32 v26, v22
	v_cvt_f32_i32_e32 v27, v23
	global_load_dwordx4 v[22:25], v[32:33], off offset:512
	v_mul_f32_e32 v21, 0xbfb8aa3b, v21
	v_exp_f32_e32 v20, v20
	v_pk_mul_f32 v[26:27], v[26:27], v[116:117]
	v_exp_f32_e32 v21, v21
	v_pk_mul_f32 v[26:27], v[26:27], v[34:35] op_sel_hi:[1,0]
	v_pk_add_f32 v[20:21], v[20:21], 1.0 op_sel_hi:[1,0]
	v_mul_f32_e32 v26, 0xbfb8aa3b, v26
	v_mul_f32_e32 v27, 0xbfb8aa3b, v27
	v_exp_f32_e32 v38, v26
	v_exp_f32_e32 v39, v27
	s_nop 0
	v_pk_add_f32 v[38:39], v[38:39], 1.0 op_sel_hi:[1,0]
	s_mov_b64 vcc, s[0:1]
	v_rcp_f32_e32 v35, v21
	s_nop 0
	v_mul_f32_e32 v21, 1.0, v35
	s_mov_b64 vcc, s[8:9]
	v_rcp_f32_e32 v35, v20
	s_nop 0
	v_mul_f32_e32 v20, 1.0, v35
	s_mov_b64 vcc, s[10:11]
	v_rcp_f32_e32 v35, v39
	s_nop 0
	v_mul_f32_e32 v39, 1.0, v35
	v_rcp_f32_e32 v35, v38
	s_nop 0
	v_mul_f32_e32 v38, 1.0, v35
	global_load_dwordx4 v[26:29], v[32:33], off offset:576
	v_pk_mul_f32 v[16:17], v[16:17], v[34:35] op_sel_hi:[1,0]
	v_pk_mul_f32 v[18:19], v[18:19], v[34:35] op_sel_hi:[1,0]
	v_mul_f32_e32 v16, 0xbfb8aa3b, v16
	v_mul_f32_e32 v17, 0xbfb8aa3b, v17
	v_exp_f32_e32 v16, v16
	v_exp_f32_e32 v17, v17
	s_waitcnt vmcnt(0)
	v_lshlrev_b32_e32 v40, 16, v30
	v_and_b32_e32 v41, 0xffff0000, v30
	v_lshlrev_b32_e32 v30, 16, v31
	v_and_b32_e32 v31, 0xffff0000, v31
	v_pk_fma_f32 v[20:21], v[20:21], v[40:41], v[22:23]
	v_pk_fma_f32 v[22:23], v[38:39], v[30:31], v[24:25]
	global_store_dwordx4 v[32:33], v[20:23], off offset:512
	global_load_dwordx2 v[20:21], v[36:37], off offset:288
	v_mul_f32_e32 v18, 0xbfb8aa3b, v18
	v_mul_f32_e32 v19, 0xbfb8aa3b, v19
	v_exp_f32_e32 v18, v18
	v_exp_f32_e32 v19, v19
	v_pk_add_f32 v[16:17], v[16:17], 1.0 op_sel_hi:[1,0]
	v_pk_add_f32 v[18:19], v[18:19], 1.0 op_sel_hi:[1,0]
	s_mov_b64 vcc, s[0:1]
	v_rcp_f32_e32 v22, v17
	s_nop 0
	v_mul_f32_e32 v17, 1.0, v22
	s_mov_b64 vcc, s[8:9]
	v_rcp_f32_e32 v22, v16
	s_nop 0
	v_mul_f32_e32 v16, 1.0, v22
	s_mov_b64 vcc, s[10:11]
	v_rcp_f32_e32 v22, v19
	s_nop 0
	v_mul_f32_e32 v19, 1.0, v22
	v_rcp_f32_e32 v22, v18
	s_nop 0
	v_mul_f32_e32 v18, 1.0, v22
	v_pk_mul_f32 v[30:31], v[12:13], v[128:129]
	s_waitcnt vmcnt(0)
	v_lshlrev_b32_e32 v22, 16, v20
	v_and_b32_e32 v23, 0xffff0000, v20
	v_lshlrev_b32_e32 v20, 16, v21
	v_and_b32_e32 v21, 0xffff0000, v21
	v_pk_fma_f32 v[16:17], v[16:17], v[22:23], v[26:27]
	v_pk_fma_f32 v[18:19], v[18:19], v[20:21], v[28:29]
	global_store_dwordx4 v[32:33], v[16:19], off offset:576
	global_load_dword v18, v[150:151], off offset:704
	v_lshl_add_u64 v[20:21], v[140:141], 1, s[46:47]
	global_load_dwordx2 v[26:27], v[20:21], off
	v_lshl_add_u64 v[16:17], v[140:141], 2, s[70:71]
	global_load_dwordx4 v[22:25], v[16:17], off
	v_pk_mul_f32 v[28:29], v[14:15], v[130:131]
	global_load_dwordx4 v[12:15], v[16:17], off offset:64
	s_waitcnt vmcnt(0)
	v_pk_mul_f32 v[30:31], v[30:31], v[18:19] op_sel_hi:[1,0]
	v_pk_mul_f32 v[28:29], v[28:29], v[18:19] op_sel_hi:[1,0]
	v_mul_f32_e32 v19, 0xbfb8aa3b, v30
	v_mul_f32_e32 v30, 0xbfb8aa3b, v31
	v_mul_f32_e32 v31, 0xbfb8aa3b, v28
	v_mul_f32_e32 v32, 0xbfb8aa3b, v29
	v_exp_f32_e32 v28, v19
	v_exp_f32_e32 v29, v30
	v_exp_f32_e32 v30, v31
	v_exp_f32_e32 v31, v32
	v_lshlrev_b32_e32 v32, 16, v26
	v_pk_add_f32 v[28:29], v[28:29], 1.0 op_sel_hi:[1,0]
	v_and_b32_e32 v33, 0xffff0000, v26
	v_pk_add_f32 v[30:31], v[30:31], 1.0 op_sel_hi:[1,0]
	s_mov_b64 vcc, s[0:1]
	v_rcp_f32_e32 v19, v29
	s_nop 0
	v_mul_f32_e32 v29, 1.0, v19
	s_mov_b64 vcc, s[8:9]
	v_rcp_f32_e32 v19, v28
	s_nop 0
	v_mul_f32_e32 v28, 1.0, v19
	s_mov_b64 vcc, s[10:11]
	v_pk_fma_f32 v[22:23], v[28:29], v[32:33], v[22:23]
	v_rcp_f32_e32 v19, v31
	s_nop 0
	v_mul_f32_e32 v29, 1.0, v19
	v_lshlrev_b32_e32 v26, 16, v27
	v_and_b32_e32 v27, 0xffff0000, v27
	v_rcp_f32_e32 v19, v30
	s_nop 0
	v_mul_f32_e32 v28, 1.0, v19
	v_pk_fma_f32 v[24:25], v[28:29], v[26:27], v[24:25]
	global_store_dwordx4 v[16:17], v[22:25], off
	global_load_dwordx2 v[22:23], v[20:21], off offset:32
	v_pk_mul_f32 v[8:9], v[8:9], v[18:19] op_sel_hi:[1,0]
	v_pk_mul_f32 v[10:11], v[10:11], v[18:19] op_sel_hi:[1,0]
	v_mul_f32_e32 v8, 0xbfb8aa3b, v8
	v_mul_f32_e32 v9, 0xbfb8aa3b, v9
	v_exp_f32_e32 v8, v8
	v_exp_f32_e32 v9, v9
	v_mul_f32_e32 v10, 0xbfb8aa3b, v10
	v_mul_f32_e32 v11, 0xbfb8aa3b, v11
	v_exp_f32_e32 v10, v10
	v_exp_f32_e32 v11, v11
	v_pk_add_f32 v[8:9], v[8:9], 1.0 op_sel_hi:[1,0]
	v_pk_add_f32 v[10:11], v[10:11], 1.0 op_sel_hi:[1,0]
	s_mov_b64 vcc, s[0:1]
	v_rcp_f32_e32 v19, v9
	s_nop 0
	v_mul_f32_e32 v9, 1.0, v19
	s_mov_b64 vcc, s[8:9]
	v_rcp_f32_e32 v19, v8
	s_nop 0
	v_mul_f32_e32 v8, 1.0, v19
	s_mov_b64 vcc, s[10:11]
	v_rcp_f32_e32 v19, v11
	s_nop 0
	v_mul_f32_e32 v11, 1.0, v19
	v_rcp_f32_e32 v19, v10
	s_nop 0
	v_mul_f32_e32 v10, 1.0, v19
	v_pk_mul_f32 v[4:5], v[4:5], v[18:19] op_sel_hi:[1,0]
	s_waitcnt vmcnt(0)
	v_lshlrev_b32_e32 v24, 16, v22
	v_and_b32_e32 v25, 0xffff0000, v22
	v_lshlrev_b32_e32 v22, 16, v23
	v_and_b32_e32 v23, 0xffff0000, v23
	v_pk_fma_f32 v[8:9], v[8:9], v[24:25], v[12:13]
	v_pk_fma_f32 v[10:11], v[10:11], v[22:23], v[14:15]
	global_store_dwordx4 v[16:17], v[8:11], off offset:64
	global_load_dwordx2 v[14:15], v[20:21], off offset:256
	v_mul_f32_e32 v4, 0xbfb8aa3b, v4
	v_cvt_f32_i32_e32 v10, v6
	v_cvt_f32_i32_e32 v11, v7
	global_load_dwordx4 v[6:9], v[16:17], off offset:512
	v_mul_f32_e32 v5, 0xbfb8aa3b, v5
	v_exp_f32_e32 v4, v4
	v_pk_mul_f32 v[10:11], v[10:11], v[116:117]
	v_exp_f32_e32 v5, v5
	v_pk_mul_f32 v[10:11], v[10:11], v[18:19] op_sel_hi:[1,0]
	v_pk_add_f32 v[4:5], v[4:5], 1.0 op_sel_hi:[1,0]
	v_mul_f32_e32 v10, 0xbfb8aa3b, v10
	v_mul_f32_e32 v11, 0xbfb8aa3b, v11
	v_exp_f32_e32 v22, v10
	v_exp_f32_e32 v23, v11
	s_nop 0
	v_pk_add_f32 v[22:23], v[22:23], 1.0 op_sel_hi:[1,0]
	s_mov_b64 vcc, s[0:1]
	v_rcp_f32_e32 v19, v5
	s_nop 0
	v_mul_f32_e32 v5, 1.0, v19
	s_mov_b64 vcc, s[8:9]
	v_rcp_f32_e32 v19, v4
	s_nop 0
	v_mul_f32_e32 v4, 1.0, v19
	s_mov_b64 vcc, s[10:11]
	v_rcp_f32_e32 v19, v23
	s_nop 0
	v_mul_f32_e32 v23, 1.0, v19
	v_rcp_f32_e32 v19, v22
	s_nop 0
	v_mul_f32_e32 v22, 1.0, v19
	global_load_dwordx4 v[10:13], v[16:17], off offset:576
	v_pk_mul_f32 v[0:1], v[0:1], v[18:19] op_sel_hi:[1,0]
	v_pk_mul_f32 v[2:3], v[2:3], v[18:19] op_sel_hi:[1,0]
	v_mul_f32_e32 v0, 0xbfb8aa3b, v0
	v_mul_f32_e32 v1, 0xbfb8aa3b, v1
	v_exp_f32_e32 v0, v0
	v_exp_f32_e32 v1, v1
	s_waitcnt vmcnt(0)
	v_lshlrev_b32_e32 v24, 16, v14
	v_and_b32_e32 v25, 0xffff0000, v14
	v_lshlrev_b32_e32 v14, 16, v15
	v_and_b32_e32 v15, 0xffff0000, v15
	v_pk_fma_f32 v[4:5], v[4:5], v[24:25], v[6:7]
	v_pk_fma_f32 v[6:7], v[22:23], v[14:15], v[8:9]
	global_store_dwordx4 v[16:17], v[4:7], off offset:512
	global_load_dwordx2 v[4:5], v[20:21], off offset:288
	v_mul_f32_e32 v2, 0xbfb8aa3b, v2
	v_mul_f32_e32 v3, 0xbfb8aa3b, v3
	v_exp_f32_e32 v2, v2
	v_exp_f32_e32 v3, v3
	v_pk_add_f32 v[0:1], v[0:1], 1.0 op_sel_hi:[1,0]
	v_add_u32_e32 v8, 0x10000, v140
	v_pk_add_f32 v[2:3], v[2:3], 1.0 op_sel_hi:[1,0]
	s_mov_b64 vcc, s[0:1]
	v_rcp_f32_e32 v6, v1
	s_nop 0
	v_mul_f32_e32 v1, 1.0, v6
	s_mov_b64 vcc, s[8:9]
	v_rcp_f32_e32 v6, v0
	s_nop 0
	v_mul_f32_e32 v0, 1.0, v6
	s_mov_b64 vcc, s[10:11]
	v_rcp_f32_e32 v6, v3
	s_nop 0
	v_mul_f32_e32 v3, 1.0, v6
	v_rcp_f32_e32 v6, v2
	s_nop 0
	v_mul_f32_e32 v2, 1.0, v6
	s_andn2_b64 vcc, exec, s[6:7]
	s_mov_b64 s[0:1], -1
	s_waitcnt vmcnt(0)
	v_lshlrev_b32_e32 v6, 16, v4
	v_and_b32_e32 v7, 0xffff0000, v4
	v_lshlrev_b32_e32 v4, 16, v5
	v_and_b32_e32 v5, 0xffff0000, v5
	v_pk_fma_f32 v[0:1], v[0:1], v[6:7], v[10:11]
	v_pk_fma_f32 v[2:3], v[2:3], v[4:5], v[12:13]
	global_store_dwordx4 v[16:17], v[0:3], off offset:576
	s_waitcnt vmcnt(0)
	s_cbranch_vccnz .LBB0_2497
	s_andn2_b64 vcc, exec, s[12:13]
	s_cbranch_vccnz .LBB0_2496
	s_barrier
	s_branch .LBB0_2496

	.amdhsa_kernel _Z10fwd_kernel6Params
		.amdhsa_group_segment_fixed_size 0
		.amdhsa_private_segment_fixed_size 0
		.amdhsa_kernarg_size 440
		.amdhsa_user_sgpr_count 2
		.amdhsa_user_sgpr_dispatch_ptr 0
		.amdhsa_user_sgpr_queue_ptr 0
		.amdhsa_user_sgpr_kernarg_segment_ptr 1
		.amdhsa_user_sgpr_dispatch_id 0
		.amdhsa_user_sgpr_kernarg_preload_length 0
		.amdhsa_user_sgpr_kernarg_preload_offset 0
		.amdhsa_user_sgpr_private_segment_size 0
		.amdhsa_uses_dynamic_stack 0
		.amdhsa_enable_private_segment 0
		.amdhsa_system_sgpr_workgroup_id_x 1
		.amdhsa_system_sgpr_workgroup_id_y 0
		.amdhsa_system_sgpr_workgroup_id_z 0
		.amdhsa_system_sgpr_workgroup_info 0
		.amdhsa_system_vgpr_workitem_id 2
		.amdhsa_next_free_vgpr 256
		.amdhsa_next_free_sgpr 99
		.amdhsa_accum_offset 256
		.amdhsa_reserve_vcc 1
		.amdhsa_float_round_mode_32 0
		.amdhsa_float_round_mode_16_64 0
		.amdhsa_float_denorm_mode_32 3
		.amdhsa_float_denorm_mode_16_64 3
		.amdhsa_dx10_clamp 1
		.amdhsa_ieee_mode 1
		.amdhsa_fp16_overflow 0
		.amdhsa_tg_split 0
		.amdhsa_exception_fp_ieee_invalid_op 0
		.amdhsa_exception_fp_denorm_src 0
		.amdhsa_exception_fp_ieee_div_zero 0
		.amdhsa_exception_fp_ieee_overflow 0
		.amdhsa_exception_fp_ieee_underflow 0
		.amdhsa_exception_fp_ieee_inexact 0
		.amdhsa_exception_int_div_zero 0
	.end_amdhsa_kernel

amdhsa.kernels:
  - .agpr_count:     0
    .args:
      - .offset:         0
        .size:           184
        .value_kind:     by_value
      - .offset:         184
        .size:           4
        .value_kind:     hidden_block_count_x
      - .offset:         188
        .size:           4
        .value_kind:     hidden_block_count_y
      - .offset:         192
        .size:           4
        .value_kind:     hidden_block_count_z
      - .offset:         196
        .size:           2
        .value_kind:     hidden_group_size_x
      - .offset:         198
        .size:           2
        .value_kind:     hidden_group_size_y
      - .offset:         200
        .size:           2
        .value_kind:     hidden_group_size_z
      - .offset:         202
        .size:           2
        .value_kind:     hidden_remainder_x
      - .offset:         204
        .size:           2
        .value_kind:     hidden_remainder_y
      - .offset:         206
        .size:           2
        .value_kind:     hidden_remainder_z
      - .offset:         224
        .size:           8
        .value_kind:     hidden_global_offset_x
      - .offset:         232
        .size:           8
        .value_kind:     hidden_global_offset_y
      - .offset:         240
        .size:           8
        .value_kind:     hidden_global_offset_z
      - .offset:         248
        .size:           2
        .value_kind:     hidden_grid_dims
      - .offset:         272
        .size:           8
        .value_kind:     hidden_multigrid_sync_arg
      - .offset:         304
        .size:           4
        .value_kind:     hidden_dynamic_lds_size
    .group_segment_fixed_size: 0
    .kernarg_segment_align: 8
    .kernarg_segment_size: 440
    .language:       OpenCL C
    .language_version:
      - 2
      - 0
    .max_flat_workgroup_size: 512
    .name:           _Z10fwd_kernel6Params
    .private_segment_fixed_size: 0
    .sgpr_count:     105
    .sgpr_spill_count: 34
    .symbol:         _Z10fwd_kernel6Params.kd
    .uniform_work_group_size: 1
    .uses_dynamic_stack: false
    .vgpr_count:     256
    .vgpr_spill_count: 0
    .wavefront_size: 64
